# v29 + tail K sections: MFMAs interleaved with the next step's LDS-DMA issue (2 MFMAs per DMA) instead of DMA burst then MFMA burst
# baseline (speedup 1.0000x reference)
.LBB0_122:
	v_lshrrev_b32_e32 v122, 2, v214
	v_and_b32_e32 v123, 15, v214
	v_sub_u32_e32 v122, v122, v123
	v_mul_i32_i24_e32 v122, 0x1000, v122
	v_bfe_u32 v125, v214, 5, 1
	v_lshlrev_b32_e32 v125, 1, v125
	v_and_b32_e32 v124, 3, v214
	v_xor_b32_e32 v125, v125, v124
	v_lshrrev_b32_e32 v124, 4, v214
	v_sub_u32_e32 v125, v125, v124
	v_lshl_add_u32 v122, v125, 4, v122
	v_ashrrev_i32_e32 v125, 31, v122
	v_add_co_u32_e32 v118, vcc, v66, v122
	s_nop 1
	v_addc_co_u32_e32 v119, vcc, v67, v125, vcc
	v_add_co_u32_e32 v120, vcc, v64, v122
	s_nop 1
	v_addc_co_u32_e32 v121, vcc, v65, v125, vcc
	v_add_co_u32_e32 v82, vcc, s84, v118
	s_nop 1
	v_addc_co_u32_e32 v83, vcc, 0, v119, vcc
	v_add_co_u32_e32 v104, vcc, s85, v118
	s_nop 1
	v_addc_co_u32_e32 v105, vcc, 0, v119, vcc
	v_add_co_u32_e32 v106, vcc, s88, v118
	s_nop 1
	v_addc_co_u32_e32 v107, vcc, 0, v119, vcc
	v_add_co_u32_e32 v108, vcc, s89, v118
	s_nop 1
	v_addc_co_u32_e32 v109, vcc, 0, v119, vcc
	v_add_co_u32_e32 v110, vcc, 0x5808000, v120
	s_nop 1
	v_addc_co_u32_e32 v111, vcc, 0, v121, vcc
	v_add_co_u32_e32 v112, vcc, 0x5818000, v120
	s_nop 1
	v_addc_co_u32_e32 v113, vcc, 0, v121, vcc
	v_add_co_u32_e32 v114, vcc, 0x5888000, v120
	s_nop 1
	v_addc_co_u32_e32 v115, vcc, 0, v121, vcc
	v_add_co_u32_e32 v116, vcc, 0x5898000, v120
	s_nop 1
	v_addc_co_u32_e32 v117, vcc, 0, v121, vcc
	v_readfirstlane_b32 vcc_lo, v210
	v_bfe_u32 v125, v214, 3, 1
	v_lshlrev_b32_e32 v125, 1, v125
	v_xor_b32_e32 v125, v125, v124
	v_lshlrev_b32_e32 v125, 4, v125
	v_lshl_add_u32 v125, v123, 6, v125
	s_lshr_b32 vcc_lo, vcc_lo, 6
	s_lshl_b32 vcc_lo, vcc_lo, 14
	s_mov_b32 s94, 64
	v_add_u32_e32 v124, vcc_lo, v125
	s_add_i32 m0, vcc_lo, 0x0
	s_nop 0
	global_load_lds_dwordx4 v[82:83], off
	v_lshl_add_u64 v[82:83], v[82:83], 0, s[94:95]
	s_add_i32 m0, vcc_lo, 0x400
	s_nop 0
	global_load_lds_dwordx4 v[104:105], off
	v_lshl_add_u64 v[104:105], v[104:105], 0, s[94:95]
	s_add_i32 m0, vcc_lo, 0x800
	s_nop 0
	global_load_lds_dwordx4 v[106:107], off
	v_lshl_add_u64 v[106:107], v[106:107], 0, s[94:95]
	s_add_i32 m0, vcc_lo, 0xc00
	s_nop 0
	global_load_lds_dwordx4 v[108:109], off
	v_lshl_add_u64 v[108:109], v[108:109], 0, s[94:95]
	s_add_i32 m0, vcc_lo, 0x1000
	s_nop 0
	global_load_lds_dwordx4 v[110:111], off
	v_lshl_add_u64 v[110:111], v[110:111], 0, s[94:95]
	s_add_i32 m0, vcc_lo, 0x1400
	s_nop 0
	global_load_lds_dwordx4 v[112:113], off
	v_lshl_add_u64 v[112:113], v[112:113], 0, s[94:95]
	s_add_i32 m0, vcc_lo, 0x1800
	s_nop 0
	global_load_lds_dwordx4 v[114:115], off
	v_lshl_add_u64 v[114:115], v[114:115], 0, s[94:95]
	s_add_i32 m0, vcc_lo, 0x1c00
	s_nop 0
	global_load_lds_dwordx4 v[116:117], off
	v_lshl_add_u64 v[116:117], v[116:117], 0, s[94:95]
	s_add_i32 m0, vcc_lo, 0x2000
	s_nop 0
	global_load_lds_dwordx4 v[82:83], off
	v_lshl_add_u64 v[82:83], v[82:83], 0, s[94:95]
	s_add_i32 m0, vcc_lo, 0x2400
	s_nop 0
	global_load_lds_dwordx4 v[104:105], off
	v_lshl_add_u64 v[104:105], v[104:105], 0, s[94:95]
	s_add_i32 m0, vcc_lo, 0x2800
	s_nop 0
	global_load_lds_dwordx4 v[106:107], off
	v_lshl_add_u64 v[106:107], v[106:107], 0, s[94:95]
	s_add_i32 m0, vcc_lo, 0x2c00
	s_nop 0
	global_load_lds_dwordx4 v[108:109], off
	v_lshl_add_u64 v[108:109], v[108:109], 0, s[94:95]
	s_add_i32 m0, vcc_lo, 0x3000
	s_nop 0
	global_load_lds_dwordx4 v[110:111], off
	v_lshl_add_u64 v[110:111], v[110:111], 0, s[94:95]
	s_add_i32 m0, vcc_lo, 0x3400
	s_nop 0
	global_load_lds_dwordx4 v[112:113], off
	v_lshl_add_u64 v[112:113], v[112:113], 0, s[94:95]
	s_add_i32 m0, vcc_lo, 0x3800
	s_nop 0
	global_load_lds_dwordx4 v[114:115], off
	v_lshl_add_u64 v[114:115], v[114:115], 0, s[94:95]
	s_add_i32 m0, vcc_lo, 0x3c00
	s_nop 0
	global_load_lds_dwordx4 v[116:117], off
	v_lshl_add_u64 v[116:117], v[116:117], 0, s[94:95]
	s_waitcnt vmcnt(8)
	ds_read_b128 v[68:71], v124
	ds_read_b128 v[72:75], v124 offset:1024
	ds_read_b128 v[76:79], v124 offset:2048
	ds_read_b128 v[84:87], v124 offset:3072
	ds_read_b128 v[88:91], v124 offset:4096
	ds_read_b128 v[92:95], v124 offset:5120
	ds_read_b128 v[96:99], v124 offset:6144
	ds_read_b128 v[100:103], v124 offset:7168
	s_waitcnt lgkmcnt(0)
	v_mfma_f32_16x16x32_bf16 v[56:59], v[88:91], v[68:71], 0
	s_add_i32 m0, vcc_lo, 0x0
	v_mfma_f32_16x16x32_bf16 v[52:55], v[88:91], v[72:75], 0
	global_load_lds_dwordx4 v[82:83], off
	v_lshl_add_u64 v[82:83], v[82:83], 0, s[94:95]
	v_mfma_f32_16x16x32_bf16 v[48:51], v[88:91], v[76:79], 0
	s_add_i32 m0, vcc_lo, 0x400
	v_mfma_f32_16x16x32_bf16 v[44:47], v[88:91], v[84:87], 0
	global_load_lds_dwordx4 v[104:105], off
	v_lshl_add_u64 v[104:105], v[104:105], 0, s[94:95]
	v_mfma_f32_16x16x32_bf16 v[12:15], v[92:95], v[68:71], 0
	s_add_i32 m0, vcc_lo, 0x800
	v_mfma_f32_16x16x32_bf16 v[8:11], v[92:95], v[72:75], 0
	global_load_lds_dwordx4 v[106:107], off
	v_lshl_add_u64 v[106:107], v[106:107], 0, s[94:95]
	v_mfma_f32_16x16x32_bf16 v[4:7], v[92:95], v[76:79], 0
	s_add_i32 m0, vcc_lo, 0xc00
	v_mfma_f32_16x16x32_bf16 v[0:3], v[92:95], v[84:87], 0
	global_load_lds_dwordx4 v[108:109], off
	v_lshl_add_u64 v[108:109], v[108:109], 0, s[94:95]
	v_mfma_f32_16x16x32_bf16 v[16:19], v[96:99], v[68:71], 0
	s_add_i32 m0, vcc_lo, 0x1000
	v_mfma_f32_16x16x32_bf16 v[24:27], v[96:99], v[72:75], 0
	global_load_lds_dwordx4 v[110:111], off
	v_lshl_add_u64 v[110:111], v[110:111], 0, s[94:95]
	v_mfma_f32_16x16x32_bf16 v[28:31], v[96:99], v[76:79], 0
	s_add_i32 m0, vcc_lo, 0x1400
	v_mfma_f32_16x16x32_bf16 v[36:39], v[96:99], v[84:87], 0
	global_load_lds_dwordx4 v[112:113], off
	v_lshl_add_u64 v[112:113], v[112:113], 0, s[94:95]
	v_mfma_f32_16x16x32_bf16 v[20:23], v[100:103], v[68:71], 0
	s_add_i32 m0, vcc_lo, 0x1800
	v_mfma_f32_16x16x32_bf16 v[32:35], v[100:103], v[72:75], 0
	global_load_lds_dwordx4 v[114:115], off
	v_lshl_add_u64 v[114:115], v[114:115], 0, s[94:95]
	v_mfma_f32_16x16x32_bf16 v[40:43], v[100:103], v[76:79], 0
	s_add_i32 m0, vcc_lo, 0x1c00
	v_mfma_f32_16x16x32_bf16 v[60:63], v[100:103], v[84:87], 0
	global_load_lds_dwordx4 v[116:117], off
	v_lshl_add_u64 v[116:117], v[116:117], 0, s[94:95]
	s_waitcnt vmcnt(8)
	ds_read_b128 v[68:71], v124 offset:8192
	ds_read_b128 v[72:75], v124 offset:9216
	ds_read_b128 v[76:79], v124 offset:10240
	ds_read_b128 v[84:87], v124 offset:11264
	ds_read_b128 v[88:91], v124 offset:12288
	ds_read_b128 v[92:95], v124 offset:13312
	ds_read_b128 v[96:99], v124 offset:14336
	ds_read_b128 v[100:103], v124 offset:15360
	s_waitcnt lgkmcnt(0)
	v_mfma_f32_16x16x32_bf16 v[56:59], v[88:91], v[68:71], v[56:59]
	s_add_i32 m0, vcc_lo, 0x2000
	v_mfma_f32_16x16x32_bf16 v[52:55], v[88:91], v[72:75], v[52:55]
	global_load_lds_dwordx4 v[82:83], off
	v_lshl_add_u64 v[82:83], v[82:83], 0, s[94:95]
	v_mfma_f32_16x16x32_bf16 v[48:51], v[88:91], v[76:79], v[48:51]
	s_add_i32 m0, vcc_lo, 0x2400
	v_mfma_f32_16x16x32_bf16 v[44:47], v[88:91], v[84:87], v[44:47]
	global_load_lds_dwordx4 v[104:105], off
	v_lshl_add_u64 v[104:105], v[104:105], 0, s[94:95]
	v_mfma_f32_16x16x32_bf16 v[12:15], v[92:95], v[68:71], v[12:15]
	s_add_i32 m0, vcc_lo, 0x2800
	v_mfma_f32_16x16x32_bf16 v[8:11], v[92:95], v[72:75], v[8:11]
	global_load_lds_dwordx4 v[106:107], off
	v_lshl_add_u64 v[106:107], v[106:107], 0, s[94:95]
	v_mfma_f32_16x16x32_bf16 v[4:7], v[92:95], v[76:79], v[4:7]
	s_add_i32 m0, vcc_lo, 0x2c00
	v_mfma_f32_16x16x32_bf16 v[0:3], v[92:95], v[84:87], v[0:3]
	global_load_lds_dwordx4 v[108:109], off
	v_lshl_add_u64 v[108:109], v[108:109], 0, s[94:95]
	v_mfma_f32_16x16x32_bf16 v[16:19], v[96:99], v[68:71], v[16:19]
	s_add_i32 m0, vcc_lo, 0x3000
	v_mfma_f32_16x16x32_bf16 v[24:27], v[96:99], v[72:75], v[24:27]
	global_load_lds_dwordx4 v[110:111], off
	v_lshl_add_u64 v[110:111], v[110:111], 0, s[94:95]
	v_mfma_f32_16x16x32_bf16 v[28:31], v[96:99], v[76:79], v[28:31]
	s_add_i32 m0, vcc_lo, 0x3400
	v_mfma_f32_16x16x32_bf16 v[36:39], v[96:99], v[84:87], v[36:39]
	global_load_lds_dwordx4 v[112:113], off
	v_lshl_add_u64 v[112:113], v[112:113], 0, s[94:95]
	v_mfma_f32_16x16x32_bf16 v[20:23], v[100:103], v[68:71], v[20:23]
	s_add_i32 m0, vcc_lo, 0x3800
	v_mfma_f32_16x16x32_bf16 v[32:35], v[100:103], v[72:75], v[32:35]
	global_load_lds_dwordx4 v[114:115], off
	v_lshl_add_u64 v[114:115], v[114:115], 0, s[94:95]
	v_mfma_f32_16x16x32_bf16 v[40:43], v[100:103], v[76:79], v[40:43]
	s_add_i32 m0, vcc_lo, 0x3c00
	v_mfma_f32_16x16x32_bf16 v[60:63], v[100:103], v[84:87], v[60:63]
	global_load_lds_dwordx4 v[116:117], off
	v_lshl_add_u64 v[116:117], v[116:117], 0, s[94:95]
	s_waitcnt vmcnt(8)
	ds_read_b128 v[68:71], v124
	ds_read_b128 v[72:75], v124 offset:1024
	ds_read_b128 v[76:79], v124 offset:2048
	ds_read_b128 v[84:87], v124 offset:3072
	ds_read_b128 v[88:91], v124 offset:4096
	ds_read_b128 v[92:95], v124 offset:5120
	ds_read_b128 v[96:99], v124 offset:6144
	ds_read_b128 v[100:103], v124 offset:7168
	s_waitcnt lgkmcnt(0)
	v_mfma_f32_16x16x32_bf16 v[56:59], v[88:91], v[68:71], v[56:59]
	s_add_i32 m0, vcc_lo, 0x0
	v_mfma_f32_16x16x32_bf16 v[52:55], v[88:91], v[72:75], v[52:55]
	global_load_lds_dwordx4 v[82:83], off
	v_lshl_add_u64 v[82:83], v[82:83], 0, s[94:95]
	v_mfma_f32_16x16x32_bf16 v[48:51], v[88:91], v[76:79], v[48:51]
	s_add_i32 m0, vcc_lo, 0x400
	v_mfma_f32_16x16x32_bf16 v[44:47], v[88:91], v[84:87], v[44:47]
	global_load_lds_dwordx4 v[104:105], off
	v_lshl_add_u64 v[104:105], v[104:105], 0, s[94:95]
	v_mfma_f32_16x16x32_bf16 v[12:15], v[92:95], v[68:71], v[12:15]
	s_add_i32 m0, vcc_lo, 0x800
	v_mfma_f32_16x16x32_bf16 v[8:11], v[92:95], v[72:75], v[8:11]
	global_load_lds_dwordx4 v[106:107], off
	v_lshl_add_u64 v[106:107], v[106:107], 0, s[94:95]
	v_mfma_f32_16x16x32_bf16 v[4:7], v[92:95], v[76:79], v[4:7]
	s_add_i32 m0, vcc_lo, 0xc00
	v_mfma_f32_16x16x32_bf16 v[0:3], v[92:95], v[84:87], v[0:3]
	global_load_lds_dwordx4 v[108:109], off
	v_lshl_add_u64 v[108:109], v[108:109], 0, s[94:95]
	v_mfma_f32_16x16x32_bf16 v[16:19], v[96:99], v[68:71], v[16:19]
	s_add_i32 m0, vcc_lo, 0x1000
	v_mfma_f32_16x16x32_bf16 v[24:27], v[96:99], v[72:75], v[24:27]
	global_load_lds_dwordx4 v[110:111], off
	v_lshl_add_u64 v[110:111], v[110:111], 0, s[94:95]
	v_mfma_f32_16x16x32_bf16 v[28:31], v[96:99], v[76:79], v[28:31]
	s_add_i32 m0, vcc_lo, 0x1400
	v_mfma_f32_16x16x32_bf16 v[36:39], v[96:99], v[84:87], v[36:39]
	global_load_lds_dwordx4 v[112:113], off
	v_lshl_add_u64 v[112:113], v[112:113], 0, s[94:95]
	v_mfma_f32_16x16x32_bf16 v[20:23], v[100:103], v[68:71], v[20:23]
	s_add_i32 m0, vcc_lo, 0x1800
	v_mfma_f32_16x16x32_bf16 v[32:35], v[100:103], v[72:75], v[32:35]
	global_load_lds_dwordx4 v[114:115], off
	v_lshl_add_u64 v[114:115], v[114:115], 0, s[94:95]
	v_mfma_f32_16x16x32_bf16 v[40:43], v[100:103], v[76:79], v[40:43]
	s_add_i32 m0, vcc_lo, 0x1c00
	v_mfma_f32_16x16x32_bf16 v[60:63], v[100:103], v[84:87], v[60:63]
	global_load_lds_dwordx4 v[116:117], off
	v_lshl_add_u64 v[116:117], v[116:117], 0, s[94:95]
	s_waitcnt vmcnt(8)
	ds_read_b128 v[68:71], v124 offset:8192
	ds_read_b128 v[72:75], v124 offset:9216
	ds_read_b128 v[76:79], v124 offset:10240
	ds_read_b128 v[84:87], v124 offset:11264
	ds_read_b128 v[88:91], v124 offset:12288
	ds_read_b128 v[92:95], v124 offset:13312
	ds_read_b128 v[96:99], v124 offset:14336
	ds_read_b128 v[100:103], v124 offset:15360
	s_waitcnt lgkmcnt(0)
	v_mfma_f32_16x16x32_bf16 v[56:59], v[88:91], v[68:71], v[56:59]
	s_add_i32 m0, vcc_lo, 0x2000
	v_mfma_f32_16x16x32_bf16 v[52:55], v[88:91], v[72:75], v[52:55]
	global_load_lds_dwordx4 v[82:83], off
	v_lshl_add_u64 v[82:83], v[82:83], 0, s[94:95]
	v_mfma_f32_16x16x32_bf16 v[48:51], v[88:91], v[76:79], v[48:51]
	s_add_i32 m0, vcc_lo, 0x2400
	v_mfma_f32_16x16x32_bf16 v[44:47], v[88:91], v[84:87], v[44:47]
	global_load_lds_dwordx4 v[104:105], off
	v_lshl_add_u64 v[104:105], v[104:105], 0, s[94:95]
	v_mfma_f32_16x16x32_bf16 v[12:15], v[92:95], v[68:71], v[12:15]
	s_add_i32 m0, vcc_lo, 0x2800
	v_mfma_f32_16x16x32_bf16 v[8:11], v[92:95], v[72:75], v[8:11]
	global_load_lds_dwordx4 v[106:107], off
	v_lshl_add_u64 v[106:107], v[106:107], 0, s[94:95]
	v_mfma_f32_16x16x32_bf16 v[4:7], v[92:95], v[76:79], v[4:7]
	s_add_i32 m0, vcc_lo, 0x2c00
	v_mfma_f32_16x16x32_bf16 v[0:3], v[92:95], v[84:87], v[0:3]
	global_load_lds_dwordx4 v[108:109], off
	v_lshl_add_u64 v[108:109], v[108:109], 0, s[94:95]
	v_mfma_f32_16x16x32_bf16 v[16:19], v[96:99], v[68:71], v[16:19]
	s_add_i32 m0, vcc_lo, 0x3000
	v_mfma_f32_16x16x32_bf16 v[24:27], v[96:99], v[72:75], v[24:27]
	global_load_lds_dwordx4 v[110:111], off
	v_lshl_add_u64 v[110:111], v[110:111], 0, s[94:95]
	v_mfma_f32_16x16x32_bf16 v[28:31], v[96:99], v[76:79], v[28:31]
	s_add_i32 m0, vcc_lo, 0x3400
	v_mfma_f32_16x16x32_bf16 v[36:39], v[96:99], v[84:87], v[36:39]
	global_load_lds_dwordx4 v[112:113], off
	v_lshl_add_u64 v[112:113], v[112:113], 0, s[94:95]
	v_mfma_f32_16x16x32_bf16 v[20:23], v[100:103], v[68:71], v[20:23]
	s_add_i32 m0, vcc_lo, 0x3800
	v_mfma_f32_16x16x32_bf16 v[32:35], v[100:103], v[72:75], v[32:35]
	global_load_lds_dwordx4 v[114:115], off
	v_lshl_add_u64 v[114:115], v[114:115], 0, s[94:95]
	v_mfma_f32_16x16x32_bf16 v[40:43], v[100:103], v[76:79], v[40:43]
	s_add_i32 m0, vcc_lo, 0x3c00
	v_mfma_f32_16x16x32_bf16 v[60:63], v[100:103], v[84:87], v[60:63]
	global_load_lds_dwordx4 v[116:117], off
	v_lshl_add_u64 v[116:117], v[116:117], 0, s[94:95]
	s_waitcnt vmcnt(8)
	ds_read_b128 v[68:71], v124
	ds_read_b128 v[72:75], v124 offset:1024
	ds_read_b128 v[76:79], v124 offset:2048
	ds_read_b128 v[84:87], v124 offset:3072
	ds_read_b128 v[88:91], v124 offset:4096
	ds_read_b128 v[92:95], v124 offset:5120
	ds_read_b128 v[96:99], v124 offset:6144
	ds_read_b128 v[100:103], v124 offset:7168
	s_waitcnt lgkmcnt(0)
	v_mfma_f32_16x16x32_bf16 v[56:59], v[88:91], v[68:71], v[56:59]
	s_add_i32 m0, vcc_lo, 0x0
	v_mfma_f32_16x16x32_bf16 v[52:55], v[88:91], v[72:75], v[52:55]
	global_load_lds_dwordx4 v[82:83], off
	v_lshl_add_u64 v[82:83], v[82:83], 0, s[94:95]
	v_mfma_f32_16x16x32_bf16 v[48:51], v[88:91], v[76:79], v[48:51]
	s_add_i32 m0, vcc_lo, 0x400
	v_mfma_f32_16x16x32_bf16 v[44:47], v[88:91], v[84:87], v[44:47]
	global_load_lds_dwordx4 v[104:105], off
	v_lshl_add_u64 v[104:105], v[104:105], 0, s[94:95]
	v_mfma_f32_16x16x32_bf16 v[12:15], v[92:95], v[68:71], v[12:15]
	s_add_i32 m0, vcc_lo, 0x800
	v_mfma_f32_16x16x32_bf16 v[8:11], v[92:95], v[72:75], v[8:11]
	global_load_lds_dwordx4 v[106:107], off
	v_lshl_add_u64 v[106:107], v[106:107], 0, s[94:95]
	v_mfma_f32_16x16x32_bf16 v[4:7], v[92:95], v[76:79], v[4:7]
	s_add_i32 m0, vcc_lo, 0xc00
	v_mfma_f32_16x16x32_bf16 v[0:3], v[92:95], v[84:87], v[0:3]
	global_load_lds_dwordx4 v[108:109], off
	v_lshl_add_u64 v[108:109], v[108:109], 0, s[94:95]
	v_mfma_f32_16x16x32_bf16 v[16:19], v[96:99], v[68:71], v[16:19]
	s_add_i32 m0, vcc_lo, 0x1000
	v_mfma_f32_16x16x32_bf16 v[24:27], v[96:99], v[72:75], v[24:27]
	global_load_lds_dwordx4 v[110:111], off
	v_lshl_add_u64 v[110:111], v[110:111], 0, s[94:95]
	v_mfma_f32_16x16x32_bf16 v[28:31], v[96:99], v[76:79], v[28:31]
	s_add_i32 m0, vcc_lo, 0x1400
	v_mfma_f32_16x16x32_bf16 v[36:39], v[96:99], v[84:87], v[36:39]
	global_load_lds_dwordx4 v[112:113], off
	v_lshl_add_u64 v[112:113], v[112:113], 0, s[94:95]
	v_mfma_f32_16x16x32_bf16 v[20:23], v[100:103], v[68:71], v[20:23]
	s_add_i32 m0, vcc_lo, 0x1800
	v_mfma_f32_16x16x32_bf16 v[32:35], v[100:103], v[72:75], v[32:35]
	global_load_lds_dwordx4 v[114:115], off
	v_lshl_add_u64 v[114:115], v[114:115], 0, s[94:95]
	v_mfma_f32_16x16x32_bf16 v[40:43], v[100:103], v[76:79], v[40:43]
	s_add_i32 m0, vcc_lo, 0x1c00
	v_mfma_f32_16x16x32_bf16 v[60:63], v[100:103], v[84:87], v[60:63]
	global_load_lds_dwordx4 v[116:117], off
	v_lshl_add_u64 v[116:117], v[116:117], 0, s[94:95]
	s_waitcnt vmcnt(8)
	ds_read_b128 v[68:71], v124 offset:8192
	ds_read_b128 v[72:75], v124 offset:9216
	ds_read_b128 v[76:79], v124 offset:10240
	ds_read_b128 v[84:87], v124 offset:11264
	ds_read_b128 v[88:91], v124 offset:12288
	ds_read_b128 v[92:95], v124 offset:13312
	ds_read_b128 v[96:99], v124 offset:14336
	ds_read_b128 v[100:103], v124 offset:15360
	s_waitcnt lgkmcnt(0)
	v_mfma_f32_16x16x32_bf16 v[56:59], v[88:91], v[68:71], v[56:59]
	s_add_i32 m0, vcc_lo, 0x2000
	v_mfma_f32_16x16x32_bf16 v[52:55], v[88:91], v[72:75], v[52:55]
	global_load_lds_dwordx4 v[82:83], off
	v_lshl_add_u64 v[82:83], v[82:83], 0, s[94:95]
	v_mfma_f32_16x16x32_bf16 v[48:51], v[88:91], v[76:79], v[48:51]
	s_add_i32 m0, vcc_lo, 0x2400
	v_mfma_f32_16x16x32_bf16 v[44:47], v[88:91], v[84:87], v[44:47]
	global_load_lds_dwordx4 v[104:105], off
	v_lshl_add_u64 v[104:105], v[104:105], 0, s[94:95]
	v_mfma_f32_16x16x32_bf16 v[12:15], v[92:95], v[68:71], v[12:15]
	s_add_i32 m0, vcc_lo, 0x2800
	v_mfma_f32_16x16x32_bf16 v[8:11], v[92:95], v[72:75], v[8:11]
	global_load_lds_dwordx4 v[106:107], off
	v_lshl_add_u64 v[106:107], v[106:107], 0, s[94:95]
	v_mfma_f32_16x16x32_bf16 v[4:7], v[92:95], v[76:79], v[4:7]
	s_add_i32 m0, vcc_lo, 0x2c00
	v_mfma_f32_16x16x32_bf16 v[0:3], v[92:95], v[84:87], v[0:3]
	global_load_lds_dwordx4 v[108:109], off
	v_lshl_add_u64 v[108:109], v[108:109], 0, s[94:95]
	v_mfma_f32_16x16x32_bf16 v[16:19], v[96:99], v[68:71], v[16:19]
	s_add_i32 m0, vcc_lo, 0x3000
	v_mfma_f32_16x16x32_bf16 v[24:27], v[96:99], v[72:75], v[24:27]
	global_load_lds_dwordx4 v[110:111], off
	v_lshl_add_u64 v[110:111], v[110:111], 0, s[94:95]
	v_mfma_f32_16x16x32_bf16 v[28:31], v[96:99], v[76:79], v[28:31]
	s_add_i32 m0, vcc_lo, 0x3400
	v_mfma_f32_16x16x32_bf16 v[36:39], v[96:99], v[84:87], v[36:39]
	global_load_lds_dwordx4 v[112:113], off
	v_lshl_add_u64 v[112:113], v[112:113], 0, s[94:95]
	v_mfma_f32_16x16x32_bf16 v[20:23], v[100:103], v[68:71], v[20:23]
	s_add_i32 m0, vcc_lo, 0x3800
	v_mfma_f32_16x16x32_bf16 v[32:35], v[100:103], v[72:75], v[32:35]
	global_load_lds_dwordx4 v[114:115], off
	v_lshl_add_u64 v[114:115], v[114:115], 0, s[94:95]
	v_mfma_f32_16x16x32_bf16 v[40:43], v[100:103], v[76:79], v[40:43]
	s_add_i32 m0, vcc_lo, 0x3c00
	v_mfma_f32_16x16x32_bf16 v[60:63], v[100:103], v[84:87], v[60:63]
	global_load_lds_dwordx4 v[116:117], off
	v_lshl_add_u64 v[116:117], v[116:117], 0, s[94:95]
	s_waitcnt vmcnt(8)
	ds_read_b128 v[68:71], v124
	ds_read_b128 v[72:75], v124 offset:1024
	ds_read_b128 v[76:79], v124 offset:2048
	ds_read_b128 v[84:87], v124 offset:3072
	ds_read_b128 v[88:91], v124 offset:4096
	ds_read_b128 v[92:95], v124 offset:5120
	ds_read_b128 v[96:99], v124 offset:6144
	ds_read_b128 v[100:103], v124 offset:7168
	s_waitcnt lgkmcnt(0)
	v_mfma_f32_16x16x32_bf16 v[56:59], v[88:91], v[68:71], v[56:59]
	v_mfma_f32_16x16x32_bf16 v[52:55], v[88:91], v[72:75], v[52:55]
	v_mfma_f32_16x16x32_bf16 v[48:51], v[88:91], v[76:79], v[48:51]
	v_mfma_f32_16x16x32_bf16 v[44:47], v[88:91], v[84:87], v[44:47]
	v_mfma_f32_16x16x32_bf16 v[12:15], v[92:95], v[68:71], v[12:15]
	v_mfma_f32_16x16x32_bf16 v[8:11], v[92:95], v[72:75], v[8:11]
	v_mfma_f32_16x16x32_bf16 v[4:7], v[92:95], v[76:79], v[4:7]
	v_mfma_f32_16x16x32_bf16 v[0:3], v[92:95], v[84:87], v[0:3]
	v_mfma_f32_16x16x32_bf16 v[16:19], v[96:99], v[68:71], v[16:19]
	v_mfma_f32_16x16x32_bf16 v[24:27], v[96:99], v[72:75], v[24:27]
	v_mfma_f32_16x16x32_bf16 v[28:31], v[96:99], v[76:79], v[28:31]
	v_mfma_f32_16x16x32_bf16 v[36:39], v[96:99], v[84:87], v[36:39]
	v_mfma_f32_16x16x32_bf16 v[20:23], v[100:103], v[68:71], v[20:23]
	v_mfma_f32_16x16x32_bf16 v[32:35], v[100:103], v[72:75], v[32:35]
	v_mfma_f32_16x16x32_bf16 v[40:43], v[100:103], v[76:79], v[40:43]
	v_mfma_f32_16x16x32_bf16 v[60:63], v[100:103], v[84:87], v[60:63]
	s_waitcnt vmcnt(0)
	ds_read_b128 v[68:71], v124 offset:8192
	ds_read_b128 v[72:75], v124 offset:9216
	ds_read_b128 v[76:79], v124 offset:10240
	ds_read_b128 v[84:87], v124 offset:11264
	ds_read_b128 v[88:91], v124 offset:12288
	ds_read_b128 v[92:95], v124 offset:13312
	ds_read_b128 v[96:99], v124 offset:14336
	ds_read_b128 v[100:103], v124 offset:15360
	s_waitcnt lgkmcnt(0)
	v_mfma_f32_16x16x32_bf16 v[56:59], v[88:91], v[68:71], v[56:59]
	v_mfma_f32_16x16x32_bf16 v[52:55], v[88:91], v[72:75], v[52:55]
	v_mfma_f32_16x16x32_bf16 v[48:51], v[88:91], v[76:79], v[48:51]
	v_mfma_f32_16x16x32_bf16 v[44:47], v[88:91], v[84:87], v[44:47]
	v_mfma_f32_16x16x32_bf16 v[12:15], v[92:95], v[68:71], v[12:15]
	v_mfma_f32_16x16x32_bf16 v[8:11], v[92:95], v[72:75], v[8:11]
	v_mfma_f32_16x16x32_bf16 v[4:7], v[92:95], v[76:79], v[4:7]
	v_mfma_f32_16x16x32_bf16 v[0:3], v[92:95], v[84:87], v[0:3]
	v_mfma_f32_16x16x32_bf16 v[16:19], v[96:99], v[68:71], v[16:19]
	v_mfma_f32_16x16x32_bf16 v[24:27], v[96:99], v[72:75], v[24:27]
	v_mfma_f32_16x16x32_bf16 v[28:31], v[96:99], v[76:79], v[28:31]
	v_mfma_f32_16x16x32_bf16 v[36:39], v[96:99], v[84:87], v[36:39]
	v_mfma_f32_16x16x32_bf16 v[20:23], v[100:103], v[68:71], v[20:23]
	v_mfma_f32_16x16x32_bf16 v[32:35], v[100:103], v[72:75], v[32:35]
	v_mfma_f32_16x16x32_bf16 v[40:43], v[100:103], v[76:79], v[40:43]
	v_mfma_f32_16x16x32_bf16 v[60:63], v[100:103], v[84:87], v[60:63]
	s_nop 7
	s_nop 3
	v_and_b32_e32 v65, 63, v81
	s_ashr_i32 s2, s4, 7
	v_lshl_add_u32 v65, v65, 4, 0
	s_lshl_b32 s3, s2, 4
	v_lshl_add_u32 v66, s5, 14, v65
	s_addk_i32 s3, 0x4000
	ds_write_b128 v66, v[56:59]
	ds_write_b128 v66, v[52:55] offset:1024
	ds_write_b128 v66, v[48:51] offset:2048
	ds_write_b128 v66, v[44:47] offset:3072
	ds_write_b128 v66, v[12:15] offset:4096
	ds_write_b128 v66, v[8:11] offset:5120
	ds_write_b128 v66, v[4:7] offset:6144
	ds_write_b128 v66, v[0:3] offset:7168
	ds_write_b128 v66, v[16:19] offset:8192
	ds_write_b128 v66, v[24:27] offset:9216
	ds_write_b128 v66, v[28:31] offset:10240
	ds_write_b128 v66, v[36:39] offset:11264
	ds_write_b128 v66, v[20:23] offset:12288
	ds_write_b128 v66, v[32:35] offset:13312
	ds_write_b128 v66, v[40:43] offset:14336
	ds_write_b128 v66, v[60:63] offset:15360
	v_or_b32_e32 v0, s3, v80
	v_ashrrev_i32_e32 v1, 31, v0
	v_bfe_u32 v64, v81, 4, 2
	v_lshlrev_b64 v[2:3], 7, v[0:1]
	v_lshl_add_u64 v[2:3], s[8:9], 0, v[2:3]
	v_lshlrev_b32_e32 v128, 5, v64
	v_lshl_add_u64 v[6:7], v[2:3], 0, v[128:129]
	s_waitcnt lgkmcnt(0)
	s_barrier
	global_load_dwordx4 v[2:5], v[6:7], off
	s_nop 0
	global_load_dwordx4 v[6:9], v[6:7], off offset:16
	s_bfe_u32 s3, s4, 0x10006
	s_lshl_b32 s4, s3, 2
	s_add_i32 s4, s4, s2
	v_lshl_add_u32 v62, s4, 10, v65
	ds_read_b128 v[10:13], v62
	ds_read_b128 v[14:17], v62 offset:8192
	ds_read_b128 v[18:21], v62 offset:16384
	ds_read_b128 v[22:25], v62 offset:24576
	ds_read_b128 v[26:29], v62 offset:32768
	ds_read_b128 v[30:33], v62 offset:40960
	ds_read_b128 v[34:37], v62 offset:49152
	ds_read_b128 v[38:41], v62 offset:57344
	s_waitcnt lgkmcnt(0)
	v_pk_add_f32 v[10:11], v[10:11], 0 op_sel_hi:[1,0]
	v_pk_add_f32 v[12:13], v[12:13], 0 op_sel_hi:[1,0]
	v_pk_add_f32 v[10:11], v[10:11], v[18:19]
	v_pk_add_f32 v[12:13], v[12:13], v[20:21]
	v_add_u32_e32 v42, 0x10000, v62
	v_add_u32_e32 v46, 0x12000, v62
	v_add_u32_e32 v50, 0x14000, v62
	v_add_u32_e32 v54, 0x16000, v62
	v_add_u32_e32 v58, 0x18000, v62
	v_add_u32_e32 v63, 0x1a000, v62
	ds_read_b128 v[42:45], v42
	ds_read_b128 v[46:49], v46
	ds_read_b128 v[50:53], v50
	ds_read_b128 v[54:57], v54
	ds_read_b128 v[58:61], v58
	ds_read_b128 v[66:69], v63
	v_pk_add_f32 v[10:11], v[10:11], v[26:27]
	v_pk_add_f32 v[14:15], v[14:15], 0 op_sel_hi:[1,0]
	v_pk_add_f32 v[10:11], v[10:11], v[34:35]
	v_pk_add_f32 v[12:13], v[12:13], v[28:29]
	s_waitcnt lgkmcnt(0)
	v_pk_add_f32 v[10:11], v[10:11], v[42:43]
	v_pk_add_f32 v[16:17], v[16:17], 0 op_sel_hi:[1,0]
	v_pk_add_f32 v[10:11], v[10:11], v[50:51]
	v_pk_add_f32 v[14:15], v[14:15], v[22:23]
	v_pk_add_f32 v[10:11], v[10:11], v[58:59]
	v_pk_add_f32 v[12:13], v[12:13], v[36:37]
	v_pk_add_f32 v[16:17], v[16:17], v[24:25]
	v_pk_add_f32 v[14:15], v[14:15], v[30:31]
	v_pk_add_f32 v[12:13], v[12:13], v[44:45]
	v_pk_add_f32 v[16:17], v[16:17], v[32:33]
	v_pk_add_f32 v[14:15], v[14:15], v[38:39]
	v_pk_add_f32 v[12:13], v[12:13], v[52:53]
	v_pk_add_f32 v[16:17], v[16:17], v[40:41]
	v_pk_add_f32 v[14:15], v[14:15], v[46:47]
	v_pk_add_f32 v[12:13], v[12:13], v[60:61]
	v_pk_add_f32 v[16:17], v[16:17], v[48:49]
	v_pk_add_f32 v[14:15], v[14:15], v[54:55]
	v_lshlrev_b64 v[0:1], 12, v[0:1]
	s_and_b32 s0, s0, 0x700
	v_pk_add_f32 v[16:17], v[16:17], v[56:57]
	v_pk_add_f32 v[14:15], v[14:15], v[66:67]
	v_lshl_add_u64 v[0:1], s[6:7], 0, v[0:1]
	s_lshl_b32 s94, s0, 1
	v_pk_add_f32 v[16:17], v[16:17], v[68:69]
	v_lshl_add_u64 v[0:1], v[0:1], 0, s[94:95]
	s_waitcnt vmcnt(0)
	v_mov_b32_e32 v18, v2
	v_mov_b32_e32 v19, v6
	v_mov_b32_e32 v6, v3
	v_pk_add_f32 v[2:3], v[18:19], v[6:7]
	v_mov_b32_e32 v6, v4
	v_mov_b32_e32 v7, v8
	v_mov_b32_e32 v8, v5
	v_pk_add_f32 v[4:5], v[6:7], v[8:9]
	v_add_u32_e32 v6, 0x1e000, v62
	v_pk_add_f32 v[2:3], v[2:3], v[4:5]
	s_nop 0
	v_add_f32_e32 v18, v2, v3
	v_and_b32_e32 v3, 64, v214
	v_xor_b32_e32 v2, 16, v214
	v_add_u32_e32 v19, 64, v3
	v_cmp_lt_i32_e32 vcc, v2, v19
	s_nop 1
	v_cndmask_b32_e32 v2, v214, v2, vcc
	v_lshlrev_b32_e32 v2, 2, v2
	ds_bpermute_b32 v20, v2, v18
	v_add_u32_e32 v2, 0x1c000, v62
	ds_read_b128 v[2:5], v2
	ds_read_b128 v[6:9], v6
	s_waitcnt lgkmcnt(2)
	v_add_f32_e32 v18, v18, v20
	v_xor_b32_e32 v20, 32, v214
	v_cmp_lt_i32_e32 vcc, v20, v19
	s_waitcnt lgkmcnt(1)
	v_pk_add_f32 v[2:3], v[10:11], v[2:3]
	v_pk_add_f32 v[4:5], v[12:13], v[4:5]
	v_cndmask_b32_e32 v19, v214, v20, vcc
	v_lshlrev_b32_e32 v19, 2, v19
	ds_bpermute_b32 v19, v19, v18
	s_waitcnt lgkmcnt(1)
	v_pk_add_f32 v[6:7], v[14:15], v[6:7]
	v_pk_add_f32 v[8:9], v[16:17], v[8:9]
	s_waitcnt lgkmcnt(0)
	v_add_f32_e32 v10, v18, v19
	v_fmamk_f32 v10, v10, 0x3a000000, v190
	v_mul_f32_e32 v11, 0x4b800000, v10
	v_cmp_gt_f32_e32 vcc, s70, v10
	s_nop 1
	v_cndmask_b32_e32 v10, v10, v11, vcc
	v_rsq_f32_e32 v10, v10
	v_lshlrev_b32_e32 v11, 2, v64
	v_lshl_or_b32 v11, s3, 4, v11
	v_or_b32_e32 v11, s1, v11
	v_mul_f32_e32 v12, 0x45800000, v10
	v_cndmask_b32_e32 v10, v10, v12, vcc
	v_lshlrev_b32_e32 v128, 1, v11
	v_pk_mul_f32 v[4:5], v[4:5], v[10:11] op_sel_hi:[1,0]
	v_pk_mul_f32 v[2:3], v[2:3], v[10:11] op_sel_hi:[1,0]
	v_lshl_add_u64 v[0:1], v[0:1], 0, v[128:129]
	v_cvt_pk_bf16_f32 v2, v2, v3
	v_cvt_pk_bf16_f32 v3, v4, v5
	v_pk_mul_f32 v[4:5], v[6:7], v[10:11] op_sel_hi:[1,0]
	global_store_dwordx2 v[0:1], v[2:3], off
	v_pk_mul_f32 v[2:3], v[8:9], v[10:11] op_sel_hi:[1,0]
	v_cvt_pk_bf16_f32 v4, v4, v5
	s_nop 0
	v_cvt_pk_bf16_f32 v5, v2, v3
	global_store_dwordx2 v[0:1], v[4:5], off offset:256
	s_waitcnt lgkmcnt(0)
	s_barrier

.LBB0_199:
	v_lshrrev_b32_e32 v122, 2, v214
	v_and_b32_e32 v123, 15, v214
	v_sub_u32_e32 v122, v122, v123
	v_mul_i32_i24_e32 v122, 0x1000, v122
	v_bfe_u32 v125, v214, 5, 1
	v_lshlrev_b32_e32 v125, 1, v125
	v_and_b32_e32 v124, 3, v214
	v_xor_b32_e32 v125, v125, v124
	v_lshrrev_b32_e32 v124, 4, v214
	v_sub_u32_e32 v125, v125, v124
	v_lshl_add_u32 v122, v125, 4, v122
	v_ashrrev_i32_e32 v125, 31, v122
	v_add_co_u32_e32 v118, vcc, v66, v122
	s_nop 1
	v_addc_co_u32_e32 v119, vcc, v67, v125, vcc
	v_add_co_u32_e32 v120, vcc, v64, v122
	s_nop 1
	v_addc_co_u32_e32 v121, vcc, v65, v125, vcc
	v_add_co_u32_e32 v82, vcc, s84, v118
	s_nop 1
	v_addc_co_u32_e32 v83, vcc, 0, v119, vcc
	v_add_co_u32_e32 v104, vcc, s85, v118
	s_nop 1
	v_addc_co_u32_e32 v105, vcc, 0, v119, vcc
	v_add_co_u32_e32 v106, vcc, s88, v118
	s_nop 1
	v_addc_co_u32_e32 v107, vcc, 0, v119, vcc
	v_add_co_u32_e32 v108, vcc, s89, v118
	s_nop 1
	v_addc_co_u32_e32 v109, vcc, 0, v119, vcc
	v_add_co_u32_e32 v110, vcc, 0x4008000, v120
	s_nop 1
	v_addc_co_u32_e32 v111, vcc, 0, v121, vcc
	v_add_co_u32_e32 v112, vcc, 0x4018000, v120
	s_nop 1
	v_addc_co_u32_e32 v113, vcc, 0, v121, vcc
	v_add_co_u32_e32 v114, vcc, 0x4088000, v120
	s_nop 1
	v_addc_co_u32_e32 v115, vcc, 0, v121, vcc
	v_add_co_u32_e32 v116, vcc, 0x4098000, v120
	s_nop 1
	v_addc_co_u32_e32 v117, vcc, 0, v121, vcc
	v_readfirstlane_b32 vcc_lo, v210
	v_bfe_u32 v125, v214, 3, 1
	v_lshlrev_b32_e32 v125, 1, v125
	v_xor_b32_e32 v125, v125, v124
	v_lshlrev_b32_e32 v125, 4, v125
	v_lshl_add_u32 v125, v123, 6, v125
	s_lshr_b32 vcc_lo, vcc_lo, 6
	s_lshl_b32 vcc_lo, vcc_lo, 14
	s_mov_b32 s94, 64
	v_add_u32_e32 v124, vcc_lo, v125
	s_add_i32 m0, vcc_lo, 0x0
	s_nop 0
	global_load_lds_dwordx4 v[82:83], off
	v_lshl_add_u64 v[82:83], v[82:83], 0, s[94:95]
	s_add_i32 m0, vcc_lo, 0x400
	s_nop 0
	global_load_lds_dwordx4 v[104:105], off
	v_lshl_add_u64 v[104:105], v[104:105], 0, s[94:95]
	s_add_i32 m0, vcc_lo, 0x800
	s_nop 0
	global_load_lds_dwordx4 v[106:107], off
	v_lshl_add_u64 v[106:107], v[106:107], 0, s[94:95]
	s_add_i32 m0, vcc_lo, 0xc00
	s_nop 0
	global_load_lds_dwordx4 v[108:109], off
	v_lshl_add_u64 v[108:109], v[108:109], 0, s[94:95]
	s_add_i32 m0, vcc_lo, 0x1000
	s_nop 0
	global_load_lds_dwordx4 v[110:111], off
	v_lshl_add_u64 v[110:111], v[110:111], 0, s[94:95]
	s_add_i32 m0, vcc_lo, 0x1400
	s_nop 0
	global_load_lds_dwordx4 v[112:113], off
	v_lshl_add_u64 v[112:113], v[112:113], 0, s[94:95]
	s_add_i32 m0, vcc_lo, 0x1800
	s_nop 0
	global_load_lds_dwordx4 v[114:115], off
	v_lshl_add_u64 v[114:115], v[114:115], 0, s[94:95]
	s_add_i32 m0, vcc_lo, 0x1c00
	s_nop 0
	global_load_lds_dwordx4 v[116:117], off
	v_lshl_add_u64 v[116:117], v[116:117], 0, s[94:95]
	s_add_i32 m0, vcc_lo, 0x2000
	s_nop 0
	global_load_lds_dwordx4 v[82:83], off
	v_lshl_add_u64 v[82:83], v[82:83], 0, s[94:95]
	s_add_i32 m0, vcc_lo, 0x2400
	s_nop 0
	global_load_lds_dwordx4 v[104:105], off
	v_lshl_add_u64 v[104:105], v[104:105], 0, s[94:95]
	s_add_i32 m0, vcc_lo, 0x2800
	s_nop 0
	global_load_lds_dwordx4 v[106:107], off
	v_lshl_add_u64 v[106:107], v[106:107], 0, s[94:95]
	s_add_i32 m0, vcc_lo, 0x2c00
	s_nop 0
	global_load_lds_dwordx4 v[108:109], off
	v_lshl_add_u64 v[108:109], v[108:109], 0, s[94:95]
	s_add_i32 m0, vcc_lo, 0x3000
	s_nop 0
	global_load_lds_dwordx4 v[110:111], off
	v_lshl_add_u64 v[110:111], v[110:111], 0, s[94:95]
	s_add_i32 m0, vcc_lo, 0x3400
	s_nop 0
	global_load_lds_dwordx4 v[112:113], off
	v_lshl_add_u64 v[112:113], v[112:113], 0, s[94:95]
	s_add_i32 m0, vcc_lo, 0x3800
	s_nop 0
	global_load_lds_dwordx4 v[114:115], off
	v_lshl_add_u64 v[114:115], v[114:115], 0, s[94:95]
	s_add_i32 m0, vcc_lo, 0x3c00
	s_nop 0
	global_load_lds_dwordx4 v[116:117], off
	v_lshl_add_u64 v[116:117], v[116:117], 0, s[94:95]
	s_waitcnt vmcnt(8)
	ds_read_b128 v[68:71], v124
	ds_read_b128 v[72:75], v124 offset:1024
	ds_read_b128 v[76:79], v124 offset:2048
	ds_read_b128 v[84:87], v124 offset:3072
	ds_read_b128 v[88:91], v124 offset:4096
	ds_read_b128 v[92:95], v124 offset:5120
	ds_read_b128 v[96:99], v124 offset:6144
	ds_read_b128 v[100:103], v124 offset:7168
	s_waitcnt lgkmcnt(0)
	v_mfma_f32_16x16x32_bf16 v[56:59], v[88:91], v[68:71], 0
	s_add_i32 m0, vcc_lo, 0x0
	v_mfma_f32_16x16x32_bf16 v[52:55], v[88:91], v[72:75], 0
	global_load_lds_dwordx4 v[82:83], off
	v_lshl_add_u64 v[82:83], v[82:83], 0, s[94:95]
	v_mfma_f32_16x16x32_bf16 v[48:51], v[88:91], v[76:79], 0
	s_add_i32 m0, vcc_lo, 0x400
	v_mfma_f32_16x16x32_bf16 v[44:47], v[88:91], v[84:87], 0
	global_load_lds_dwordx4 v[104:105], off
	v_lshl_add_u64 v[104:105], v[104:105], 0, s[94:95]
	v_mfma_f32_16x16x32_bf16 v[12:15], v[92:95], v[68:71], 0
	s_add_i32 m0, vcc_lo, 0x800
	v_mfma_f32_16x16x32_bf16 v[8:11], v[92:95], v[72:75], 0
	global_load_lds_dwordx4 v[106:107], off
	v_lshl_add_u64 v[106:107], v[106:107], 0, s[94:95]
	v_mfma_f32_16x16x32_bf16 v[4:7], v[92:95], v[76:79], 0
	s_add_i32 m0, vcc_lo, 0xc00
	v_mfma_f32_16x16x32_bf16 v[0:3], v[92:95], v[84:87], 0
	global_load_lds_dwordx4 v[108:109], off
	v_lshl_add_u64 v[108:109], v[108:109], 0, s[94:95]
	v_mfma_f32_16x16x32_bf16 v[16:19], v[96:99], v[68:71], 0
	s_add_i32 m0, vcc_lo, 0x1000
	v_mfma_f32_16x16x32_bf16 v[24:27], v[96:99], v[72:75], 0
	global_load_lds_dwordx4 v[110:111], off
	v_lshl_add_u64 v[110:111], v[110:111], 0, s[94:95]
	v_mfma_f32_16x16x32_bf16 v[28:31], v[96:99], v[76:79], 0
	s_add_i32 m0, vcc_lo, 0x1400
	v_mfma_f32_16x16x32_bf16 v[36:39], v[96:99], v[84:87], 0
	global_load_lds_dwordx4 v[112:113], off
	v_lshl_add_u64 v[112:113], v[112:113], 0, s[94:95]
	v_mfma_f32_16x16x32_bf16 v[20:23], v[100:103], v[68:71], 0
	s_add_i32 m0, vcc_lo, 0x1800
	v_mfma_f32_16x16x32_bf16 v[32:35], v[100:103], v[72:75], 0
	global_load_lds_dwordx4 v[114:115], off
	v_lshl_add_u64 v[114:115], v[114:115], 0, s[94:95]
	v_mfma_f32_16x16x32_bf16 v[40:43], v[100:103], v[76:79], 0
	s_add_i32 m0, vcc_lo, 0x1c00
	v_mfma_f32_16x16x32_bf16 v[60:63], v[100:103], v[84:87], 0
	global_load_lds_dwordx4 v[116:117], off
	v_lshl_add_u64 v[116:117], v[116:117], 0, s[94:95]
	s_waitcnt vmcnt(8)
	ds_read_b128 v[68:71], v124 offset:8192
	ds_read_b128 v[72:75], v124 offset:9216
	ds_read_b128 v[76:79], v124 offset:10240
	ds_read_b128 v[84:87], v124 offset:11264
	ds_read_b128 v[88:91], v124 offset:12288
	ds_read_b128 v[92:95], v124 offset:13312
	ds_read_b128 v[96:99], v124 offset:14336
	ds_read_b128 v[100:103], v124 offset:15360
	s_waitcnt lgkmcnt(0)
	v_mfma_f32_16x16x32_bf16 v[56:59], v[88:91], v[68:71], v[56:59]
	s_add_i32 m0, vcc_lo, 0x2000
	v_mfma_f32_16x16x32_bf16 v[52:55], v[88:91], v[72:75], v[52:55]
	global_load_lds_dwordx4 v[82:83], off
	v_lshl_add_u64 v[82:83], v[82:83], 0, s[94:95]
	v_mfma_f32_16x16x32_bf16 v[48:51], v[88:91], v[76:79], v[48:51]
	s_add_i32 m0, vcc_lo, 0x2400
	v_mfma_f32_16x16x32_bf16 v[44:47], v[88:91], v[84:87], v[44:47]
	global_load_lds_dwordx4 v[104:105], off
	v_lshl_add_u64 v[104:105], v[104:105], 0, s[94:95]
	v_mfma_f32_16x16x32_bf16 v[12:15], v[92:95], v[68:71], v[12:15]
	s_add_i32 m0, vcc_lo, 0x2800
	v_mfma_f32_16x16x32_bf16 v[8:11], v[92:95], v[72:75], v[8:11]
	global_load_lds_dwordx4 v[106:107], off
	v_lshl_add_u64 v[106:107], v[106:107], 0, s[94:95]
	v_mfma_f32_16x16x32_bf16 v[4:7], v[92:95], v[76:79], v[4:7]
	s_add_i32 m0, vcc_lo, 0x2c00
	v_mfma_f32_16x16x32_bf16 v[0:3], v[92:95], v[84:87], v[0:3]
	global_load_lds_dwordx4 v[108:109], off
	v_lshl_add_u64 v[108:109], v[108:109], 0, s[94:95]
	v_mfma_f32_16x16x32_bf16 v[16:19], v[96:99], v[68:71], v[16:19]
	s_add_i32 m0, vcc_lo, 0x3000
	v_mfma_f32_16x16x32_bf16 v[24:27], v[96:99], v[72:75], v[24:27]
	global_load_lds_dwordx4 v[110:111], off
	v_lshl_add_u64 v[110:111], v[110:111], 0, s[94:95]
	v_mfma_f32_16x16x32_bf16 v[28:31], v[96:99], v[76:79], v[28:31]
	s_add_i32 m0, vcc_lo, 0x3400
	v_mfma_f32_16x16x32_bf16 v[36:39], v[96:99], v[84:87], v[36:39]
	global_load_lds_dwordx4 v[112:113], off
	v_lshl_add_u64 v[112:113], v[112:113], 0, s[94:95]
	v_mfma_f32_16x16x32_bf16 v[20:23], v[100:103], v[68:71], v[20:23]
	s_add_i32 m0, vcc_lo, 0x3800
	v_mfma_f32_16x16x32_bf16 v[32:35], v[100:103], v[72:75], v[32:35]
	global_load_lds_dwordx4 v[114:115], off
	v_lshl_add_u64 v[114:115], v[114:115], 0, s[94:95]
	v_mfma_f32_16x16x32_bf16 v[40:43], v[100:103], v[76:79], v[40:43]
	s_add_i32 m0, vcc_lo, 0x3c00
	v_mfma_f32_16x16x32_bf16 v[60:63], v[100:103], v[84:87], v[60:63]
	global_load_lds_dwordx4 v[116:117], off
	v_lshl_add_u64 v[116:117], v[116:117], 0, s[94:95]
	s_waitcnt vmcnt(8)
	ds_read_b128 v[68:71], v124
	ds_read_b128 v[72:75], v124 offset:1024
	ds_read_b128 v[76:79], v124 offset:2048
	ds_read_b128 v[84:87], v124 offset:3072
	ds_read_b128 v[88:91], v124 offset:4096
	ds_read_b128 v[92:95], v124 offset:5120
	ds_read_b128 v[96:99], v124 offset:6144
	ds_read_b128 v[100:103], v124 offset:7168
	s_waitcnt lgkmcnt(0)
	v_mfma_f32_16x16x32_bf16 v[56:59], v[88:91], v[68:71], v[56:59]
	s_add_i32 m0, vcc_lo, 0x0
	v_mfma_f32_16x16x32_bf16 v[52:55], v[88:91], v[72:75], v[52:55]
	global_load_lds_dwordx4 v[82:83], off
	v_lshl_add_u64 v[82:83], v[82:83], 0, s[94:95]
	v_mfma_f32_16x16x32_bf16 v[48:51], v[88:91], v[76:79], v[48:51]
	s_add_i32 m0, vcc_lo, 0x400
	v_mfma_f32_16x16x32_bf16 v[44:47], v[88:91], v[84:87], v[44:47]
	global_load_lds_dwordx4 v[104:105], off
	v_lshl_add_u64 v[104:105], v[104:105], 0, s[94:95]
	v_mfma_f32_16x16x32_bf16 v[12:15], v[92:95], v[68:71], v[12:15]
	s_add_i32 m0, vcc_lo, 0x800
	v_mfma_f32_16x16x32_bf16 v[8:11], v[92:95], v[72:75], v[8:11]
	global_load_lds_dwordx4 v[106:107], off
	v_lshl_add_u64 v[106:107], v[106:107], 0, s[94:95]
	v_mfma_f32_16x16x32_bf16 v[4:7], v[92:95], v[76:79], v[4:7]
	s_add_i32 m0, vcc_lo, 0xc00
	v_mfma_f32_16x16x32_bf16 v[0:3], v[92:95], v[84:87], v[0:3]
	global_load_lds_dwordx4 v[108:109], off
	v_lshl_add_u64 v[108:109], v[108:109], 0, s[94:95]
	v_mfma_f32_16x16x32_bf16 v[16:19], v[96:99], v[68:71], v[16:19]
	s_add_i32 m0, vcc_lo, 0x1000
	v_mfma_f32_16x16x32_bf16 v[24:27], v[96:99], v[72:75], v[24:27]
	global_load_lds_dwordx4 v[110:111], off
	v_lshl_add_u64 v[110:111], v[110:111], 0, s[94:95]
	v_mfma_f32_16x16x32_bf16 v[28:31], v[96:99], v[76:79], v[28:31]
	s_add_i32 m0, vcc_lo, 0x1400
	v_mfma_f32_16x16x32_bf16 v[36:39], v[96:99], v[84:87], v[36:39]
	global_load_lds_dwordx4 v[112:113], off
	v_lshl_add_u64 v[112:113], v[112:113], 0, s[94:95]
	v_mfma_f32_16x16x32_bf16 v[20:23], v[100:103], v[68:71], v[20:23]
	s_add_i32 m0, vcc_lo, 0x1800
	v_mfma_f32_16x16x32_bf16 v[32:35], v[100:103], v[72:75], v[32:35]
	global_load_lds_dwordx4 v[114:115], off
	v_lshl_add_u64 v[114:115], v[114:115], 0, s[94:95]
	v_mfma_f32_16x16x32_bf16 v[40:43], v[100:103], v[76:79], v[40:43]
	s_add_i32 m0, vcc_lo, 0x1c00
	v_mfma_f32_16x16x32_bf16 v[60:63], v[100:103], v[84:87], v[60:63]
	global_load_lds_dwordx4 v[116:117], off
	v_lshl_add_u64 v[116:117], v[116:117], 0, s[94:95]
	s_waitcnt vmcnt(8)
	ds_read_b128 v[68:71], v124 offset:8192
	ds_read_b128 v[72:75], v124 offset:9216
	ds_read_b128 v[76:79], v124 offset:10240
	ds_read_b128 v[84:87], v124 offset:11264
	ds_read_b128 v[88:91], v124 offset:12288
	ds_read_b128 v[92:95], v124 offset:13312
	ds_read_b128 v[96:99], v124 offset:14336
	ds_read_b128 v[100:103], v124 offset:15360
	s_waitcnt lgkmcnt(0)
	v_mfma_f32_16x16x32_bf16 v[56:59], v[88:91], v[68:71], v[56:59]
	s_add_i32 m0, vcc_lo, 0x2000
	v_mfma_f32_16x16x32_bf16 v[52:55], v[88:91], v[72:75], v[52:55]
	global_load_lds_dwordx4 v[82:83], off
	v_lshl_add_u64 v[82:83], v[82:83], 0, s[94:95]
	v_mfma_f32_16x16x32_bf16 v[48:51], v[88:91], v[76:79], v[48:51]
	s_add_i32 m0, vcc_lo, 0x2400
	v_mfma_f32_16x16x32_bf16 v[44:47], v[88:91], v[84:87], v[44:47]
	global_load_lds_dwordx4 v[104:105], off
	v_lshl_add_u64 v[104:105], v[104:105], 0, s[94:95]
	v_mfma_f32_16x16x32_bf16 v[12:15], v[92:95], v[68:71], v[12:15]
	s_add_i32 m0, vcc_lo, 0x2800
	v_mfma_f32_16x16x32_bf16 v[8:11], v[92:95], v[72:75], v[8:11]
	global_load_lds_dwordx4 v[106:107], off
	v_lshl_add_u64 v[106:107], v[106:107], 0, s[94:95]
	v_mfma_f32_16x16x32_bf16 v[4:7], v[92:95], v[76:79], v[4:7]
	s_add_i32 m0, vcc_lo, 0x2c00
	v_mfma_f32_16x16x32_bf16 v[0:3], v[92:95], v[84:87], v[0:3]
	global_load_lds_dwordx4 v[108:109], off
	v_lshl_add_u64 v[108:109], v[108:109], 0, s[94:95]
	v_mfma_f32_16x16x32_bf16 v[16:19], v[96:99], v[68:71], v[16:19]
	s_add_i32 m0, vcc_lo, 0x3000
	v_mfma_f32_16x16x32_bf16 v[24:27], v[96:99], v[72:75], v[24:27]
	global_load_lds_dwordx4 v[110:111], off
	v_lshl_add_u64 v[110:111], v[110:111], 0, s[94:95]
	v_mfma_f32_16x16x32_bf16 v[28:31], v[96:99], v[76:79], v[28:31]
	s_add_i32 m0, vcc_lo, 0x3400
	v_mfma_f32_16x16x32_bf16 v[36:39], v[96:99], v[84:87], v[36:39]
	global_load_lds_dwordx4 v[112:113], off
	v_lshl_add_u64 v[112:113], v[112:113], 0, s[94:95]
	v_mfma_f32_16x16x32_bf16 v[20:23], v[100:103], v[68:71], v[20:23]
	s_add_i32 m0, vcc_lo, 0x3800
	v_mfma_f32_16x16x32_bf16 v[32:35], v[100:103], v[72:75], v[32:35]
	global_load_lds_dwordx4 v[114:115], off
	v_lshl_add_u64 v[114:115], v[114:115], 0, s[94:95]
	v_mfma_f32_16x16x32_bf16 v[40:43], v[100:103], v[76:79], v[40:43]
	s_add_i32 m0, vcc_lo, 0x3c00
	v_mfma_f32_16x16x32_bf16 v[60:63], v[100:103], v[84:87], v[60:63]
	global_load_lds_dwordx4 v[116:117], off
	v_lshl_add_u64 v[116:117], v[116:117], 0, s[94:95]
	s_waitcnt vmcnt(8)
	ds_read_b128 v[68:71], v124
	ds_read_b128 v[72:75], v124 offset:1024
	ds_read_b128 v[76:79], v124 offset:2048
	ds_read_b128 v[84:87], v124 offset:3072
	ds_read_b128 v[88:91], v124 offset:4096
	ds_read_b128 v[92:95], v124 offset:5120
	ds_read_b128 v[96:99], v124 offset:6144
	ds_read_b128 v[100:103], v124 offset:7168
	s_waitcnt lgkmcnt(0)
	v_mfma_f32_16x16x32_bf16 v[56:59], v[88:91], v[68:71], v[56:59]
	s_add_i32 m0, vcc_lo, 0x0
	v_mfma_f32_16x16x32_bf16 v[52:55], v[88:91], v[72:75], v[52:55]
	global_load_lds_dwordx4 v[82:83], off
	v_lshl_add_u64 v[82:83], v[82:83], 0, s[94:95]
	v_mfma_f32_16x16x32_bf16 v[48:51], v[88:91], v[76:79], v[48:51]
	s_add_i32 m0, vcc_lo, 0x400
	v_mfma_f32_16x16x32_bf16 v[44:47], v[88:91], v[84:87], v[44:47]
	global_load_lds_dwordx4 v[104:105], off
	v_lshl_add_u64 v[104:105], v[104:105], 0, s[94:95]
	v_mfma_f32_16x16x32_bf16 v[12:15], v[92:95], v[68:71], v[12:15]
	s_add_i32 m0, vcc_lo, 0x800
	v_mfma_f32_16x16x32_bf16 v[8:11], v[92:95], v[72:75], v[8:11]
	global_load_lds_dwordx4 v[106:107], off
	v_lshl_add_u64 v[106:107], v[106:107], 0, s[94:95]
	v_mfma_f32_16x16x32_bf16 v[4:7], v[92:95], v[76:79], v[4:7]
	s_add_i32 m0, vcc_lo, 0xc00
	v_mfma_f32_16x16x32_bf16 v[0:3], v[92:95], v[84:87], v[0:3]
	global_load_lds_dwordx4 v[108:109], off
	v_lshl_add_u64 v[108:109], v[108:109], 0, s[94:95]
	v_mfma_f32_16x16x32_bf16 v[16:19], v[96:99], v[68:71], v[16:19]
	s_add_i32 m0, vcc_lo, 0x1000
	v_mfma_f32_16x16x32_bf16 v[24:27], v[96:99], v[72:75], v[24:27]
	global_load_lds_dwordx4 v[110:111], off
	v_lshl_add_u64 v[110:111], v[110:111], 0, s[94:95]
	v_mfma_f32_16x16x32_bf16 v[28:31], v[96:99], v[76:79], v[28:31]
	s_add_i32 m0, vcc_lo, 0x1400
	v_mfma_f32_16x16x32_bf16 v[36:39], v[96:99], v[84:87], v[36:39]
	global_load_lds_dwordx4 v[112:113], off
	v_lshl_add_u64 v[112:113], v[112:113], 0, s[94:95]
	v_mfma_f32_16x16x32_bf16 v[20:23], v[100:103], v[68:71], v[20:23]
	s_add_i32 m0, vcc_lo, 0x1800
	v_mfma_f32_16x16x32_bf16 v[32:35], v[100:103], v[72:75], v[32:35]
	global_load_lds_dwordx4 v[114:115], off
	v_lshl_add_u64 v[114:115], v[114:115], 0, s[94:95]
	v_mfma_f32_16x16x32_bf16 v[40:43], v[100:103], v[76:79], v[40:43]
	s_add_i32 m0, vcc_lo, 0x1c00
	v_mfma_f32_16x16x32_bf16 v[60:63], v[100:103], v[84:87], v[60:63]
	global_load_lds_dwordx4 v[116:117], off
	v_lshl_add_u64 v[116:117], v[116:117], 0, s[94:95]
	s_waitcnt vmcnt(8)
	ds_read_b128 v[68:71], v124 offset:8192
	ds_read_b128 v[72:75], v124 offset:9216
	ds_read_b128 v[76:79], v124 offset:10240
	ds_read_b128 v[84:87], v124 offset:11264
	ds_read_b128 v[88:91], v124 offset:12288
	ds_read_b128 v[92:95], v124 offset:13312
	ds_read_b128 v[96:99], v124 offset:14336
	ds_read_b128 v[100:103], v124 offset:15360
	s_waitcnt lgkmcnt(0)
	v_mfma_f32_16x16x32_bf16 v[56:59], v[88:91], v[68:71], v[56:59]
	s_add_i32 m0, vcc_lo, 0x2000
	v_mfma_f32_16x16x32_bf16 v[52:55], v[88:91], v[72:75], v[52:55]
	global_load_lds_dwordx4 v[82:83], off
	v_lshl_add_u64 v[82:83], v[82:83], 0, s[94:95]
	v_mfma_f32_16x16x32_bf16 v[48:51], v[88:91], v[76:79], v[48:51]
	s_add_i32 m0, vcc_lo, 0x2400
	v_mfma_f32_16x16x32_bf16 v[44:47], v[88:91], v[84:87], v[44:47]
	global_load_lds_dwordx4 v[104:105], off
	v_lshl_add_u64 v[104:105], v[104:105], 0, s[94:95]
	v_mfma_f32_16x16x32_bf16 v[12:15], v[92:95], v[68:71], v[12:15]
	s_add_i32 m0, vcc_lo, 0x2800
	v_mfma_f32_16x16x32_bf16 v[8:11], v[92:95], v[72:75], v[8:11]
	global_load_lds_dwordx4 v[106:107], off
	v_lshl_add_u64 v[106:107], v[106:107], 0, s[94:95]
	v_mfma_f32_16x16x32_bf16 v[4:7], v[92:95], v[76:79], v[4:7]
	s_add_i32 m0, vcc_lo, 0x2c00
	v_mfma_f32_16x16x32_bf16 v[0:3], v[92:95], v[84:87], v[0:3]
	global_load_lds_dwordx4 v[108:109], off
	v_lshl_add_u64 v[108:109], v[108:109], 0, s[94:95]
	v_mfma_f32_16x16x32_bf16 v[16:19], v[96:99], v[68:71], v[16:19]
	s_add_i32 m0, vcc_lo, 0x3000
	v_mfma_f32_16x16x32_bf16 v[24:27], v[96:99], v[72:75], v[24:27]
	global_load_lds_dwordx4 v[110:111], off
	v_lshl_add_u64 v[110:111], v[110:111], 0, s[94:95]
	v_mfma_f32_16x16x32_bf16 v[28:31], v[96:99], v[76:79], v[28:31]
	s_add_i32 m0, vcc_lo, 0x3400
	v_mfma_f32_16x16x32_bf16 v[36:39], v[96:99], v[84:87], v[36:39]
	global_load_lds_dwordx4 v[112:113], off
	v_lshl_add_u64 v[112:113], v[112:113], 0, s[94:95]
	v_mfma_f32_16x16x32_bf16 v[20:23], v[100:103], v[68:71], v[20:23]
	s_add_i32 m0, vcc_lo, 0x3800
	v_mfma_f32_16x16x32_bf16 v[32:35], v[100:103], v[72:75], v[32:35]
	global_load_lds_dwordx4 v[114:115], off
	v_lshl_add_u64 v[114:115], v[114:115], 0, s[94:95]
	v_mfma_f32_16x16x32_bf16 v[40:43], v[100:103], v[76:79], v[40:43]
	s_add_i32 m0, vcc_lo, 0x3c00
	v_mfma_f32_16x16x32_bf16 v[60:63], v[100:103], v[84:87], v[60:63]
	global_load_lds_dwordx4 v[116:117], off
	v_lshl_add_u64 v[116:117], v[116:117], 0, s[94:95]
	s_waitcnt vmcnt(8)
	ds_read_b128 v[68:71], v124
	ds_read_b128 v[72:75], v124 offset:1024
	ds_read_b128 v[76:79], v124 offset:2048
	ds_read_b128 v[84:87], v124 offset:3072
	ds_read_b128 v[88:91], v124 offset:4096
	ds_read_b128 v[92:95], v124 offset:5120
	ds_read_b128 v[96:99], v124 offset:6144
	ds_read_b128 v[100:103], v124 offset:7168
	s_waitcnt lgkmcnt(0)
	v_mfma_f32_16x16x32_bf16 v[56:59], v[88:91], v[68:71], v[56:59]
	v_mfma_f32_16x16x32_bf16 v[52:55], v[88:91], v[72:75], v[52:55]
	v_mfma_f32_16x16x32_bf16 v[48:51], v[88:91], v[76:79], v[48:51]
	v_mfma_f32_16x16x32_bf16 v[44:47], v[88:91], v[84:87], v[44:47]
	v_mfma_f32_16x16x32_bf16 v[12:15], v[92:95], v[68:71], v[12:15]
	v_mfma_f32_16x16x32_bf16 v[8:11], v[92:95], v[72:75], v[8:11]
	v_mfma_f32_16x16x32_bf16 v[4:7], v[92:95], v[76:79], v[4:7]
	v_mfma_f32_16x16x32_bf16 v[0:3], v[92:95], v[84:87], v[0:3]
	v_mfma_f32_16x16x32_bf16 v[16:19], v[96:99], v[68:71], v[16:19]
	v_mfma_f32_16x16x32_bf16 v[24:27], v[96:99], v[72:75], v[24:27]
	v_mfma_f32_16x16x32_bf16 v[28:31], v[96:99], v[76:79], v[28:31]
	v_mfma_f32_16x16x32_bf16 v[36:39], v[96:99], v[84:87], v[36:39]
	v_mfma_f32_16x16x32_bf16 v[20:23], v[100:103], v[68:71], v[20:23]
	v_mfma_f32_16x16x32_bf16 v[32:35], v[100:103], v[72:75], v[32:35]
	v_mfma_f32_16x16x32_bf16 v[40:43], v[100:103], v[76:79], v[40:43]
	v_mfma_f32_16x16x32_bf16 v[60:63], v[100:103], v[84:87], v[60:63]
	s_waitcnt vmcnt(0)
	ds_read_b128 v[68:71], v124 offset:8192
	ds_read_b128 v[72:75], v124 offset:9216
	ds_read_b128 v[76:79], v124 offset:10240
	ds_read_b128 v[84:87], v124 offset:11264
	ds_read_b128 v[88:91], v124 offset:12288
	ds_read_b128 v[92:95], v124 offset:13312
	ds_read_b128 v[96:99], v124 offset:14336
	ds_read_b128 v[100:103], v124 offset:15360
	s_waitcnt lgkmcnt(0)
	v_mfma_f32_16x16x32_bf16 v[56:59], v[88:91], v[68:71], v[56:59]
	v_mfma_f32_16x16x32_bf16 v[52:55], v[88:91], v[72:75], v[52:55]
	v_mfma_f32_16x16x32_bf16 v[48:51], v[88:91], v[76:79], v[48:51]
	v_mfma_f32_16x16x32_bf16 v[44:47], v[88:91], v[84:87], v[44:47]
	v_mfma_f32_16x16x32_bf16 v[12:15], v[92:95], v[68:71], v[12:15]
	v_mfma_f32_16x16x32_bf16 v[8:11], v[92:95], v[72:75], v[8:11]
	v_mfma_f32_16x16x32_bf16 v[4:7], v[92:95], v[76:79], v[4:7]
	v_mfma_f32_16x16x32_bf16 v[0:3], v[92:95], v[84:87], v[0:3]
	v_mfma_f32_16x16x32_bf16 v[16:19], v[96:99], v[68:71], v[16:19]
	v_mfma_f32_16x16x32_bf16 v[24:27], v[96:99], v[72:75], v[24:27]
	v_mfma_f32_16x16x32_bf16 v[28:31], v[96:99], v[76:79], v[28:31]
	v_mfma_f32_16x16x32_bf16 v[36:39], v[96:99], v[84:87], v[36:39]
	v_mfma_f32_16x16x32_bf16 v[20:23], v[100:103], v[68:71], v[20:23]
	v_mfma_f32_16x16x32_bf16 v[32:35], v[100:103], v[72:75], v[32:35]
	v_mfma_f32_16x16x32_bf16 v[40:43], v[100:103], v[76:79], v[40:43]
	v_mfma_f32_16x16x32_bf16 v[60:63], v[100:103], v[84:87], v[60:63]
	s_nop 7
	s_nop 3
	v_and_b32_e32 v65, 63, v81
	s_ashr_i32 s2, s11, 7
	v_lshl_add_u32 v65, v65, 4, 0
	s_lshl_b32 s3, s2, 4
	v_lshl_add_u32 v66, s12, 14, v65
	s_addk_i32 s3, 0x4000
	ds_write_b128 v66, v[56:59]
	ds_write_b128 v66, v[52:55] offset:1024
	ds_write_b128 v66, v[48:51] offset:2048
	ds_write_b128 v66, v[44:47] offset:3072
	ds_write_b128 v66, v[12:15] offset:4096
	ds_write_b128 v66, v[8:11] offset:5120
	ds_write_b128 v66, v[4:7] offset:6144
	ds_write_b128 v66, v[0:3] offset:7168
	ds_write_b128 v66, v[16:19] offset:8192
	ds_write_b128 v66, v[24:27] offset:9216
	ds_write_b128 v66, v[28:31] offset:10240
	ds_write_b128 v66, v[36:39] offset:11264
	ds_write_b128 v66, v[20:23] offset:12288
	ds_write_b128 v66, v[32:35] offset:13312
	ds_write_b128 v66, v[40:43] offset:14336
	ds_write_b128 v66, v[60:63] offset:15360
	v_or_b32_e32 v0, s3, v80
	v_ashrrev_i32_e32 v1, 31, v0
	v_bfe_u32 v64, v81, 4, 2
	v_lshlrev_b64 v[2:3], 7, v[0:1]
	v_lshl_add_u64 v[2:3], s[6:7], 0, v[2:3]
	v_lshlrev_b32_e32 v128, 5, v64
	v_lshl_add_u64 v[6:7], v[2:3], 0, v[128:129]
	s_waitcnt lgkmcnt(0)
	s_barrier
	global_load_dwordx4 v[2:5], v[6:7], off
	s_nop 0
	global_load_dwordx4 v[6:9], v[6:7], off offset:16
	s_bfe_u32 s3, s11, 0x10006
	s_lshl_b32 s6, s3, 2
	s_add_i32 s6, s6, s2
	v_lshl_add_u32 v62, s6, 10, v65
	ds_read_b128 v[10:13], v62
	ds_read_b128 v[14:17], v62 offset:8192
	ds_read_b128 v[18:21], v62 offset:16384
	ds_read_b128 v[22:25], v62 offset:24576
	ds_read_b128 v[26:29], v62 offset:32768
	ds_read_b128 v[30:33], v62 offset:40960
	ds_read_b128 v[34:37], v62 offset:49152
	ds_read_b128 v[38:41], v62 offset:57344
	s_waitcnt lgkmcnt(0)
	v_pk_add_f32 v[10:11], v[10:11], 0 op_sel_hi:[1,0]
	v_pk_add_f32 v[12:13], v[12:13], 0 op_sel_hi:[1,0]
	v_pk_add_f32 v[10:11], v[10:11], v[18:19]
	v_pk_add_f32 v[12:13], v[12:13], v[20:21]
	v_add_u32_e32 v42, 0x10000, v62
	v_add_u32_e32 v46, 0x12000, v62
	v_add_u32_e32 v50, 0x14000, v62
	v_add_u32_e32 v54, 0x16000, v62
	v_add_u32_e32 v58, 0x18000, v62
	v_add_u32_e32 v63, 0x1a000, v62
	ds_read_b128 v[42:45], v42
	ds_read_b128 v[46:49], v46
	ds_read_b128 v[50:53], v50
	ds_read_b128 v[54:57], v54
	ds_read_b128 v[58:61], v58
	ds_read_b128 v[66:69], v63
	v_pk_add_f32 v[10:11], v[10:11], v[26:27]
	v_pk_add_f32 v[14:15], v[14:15], 0 op_sel_hi:[1,0]
	v_pk_add_f32 v[10:11], v[10:11], v[34:35]
	v_pk_add_f32 v[12:13], v[12:13], v[28:29]
	s_waitcnt lgkmcnt(0)
	v_pk_add_f32 v[10:11], v[10:11], v[42:43]
	v_pk_add_f32 v[16:17], v[16:17], 0 op_sel_hi:[1,0]
	v_pk_add_f32 v[10:11], v[10:11], v[50:51]
	v_pk_add_f32 v[14:15], v[14:15], v[22:23]
	v_pk_add_f32 v[10:11], v[10:11], v[58:59]
	v_pk_add_f32 v[12:13], v[12:13], v[36:37]
	s_ashr_i32 s2, s5, 5
	v_pk_add_f32 v[16:17], v[16:17], v[24:25]
	v_pk_add_f32 v[14:15], v[14:15], v[30:31]
	v_pk_add_f32 v[12:13], v[12:13], v[44:45]
	v_pk_add_f32 v[16:17], v[16:17], v[32:33]
	v_pk_add_f32 v[14:15], v[14:15], v[38:39]
	v_pk_add_f32 v[12:13], v[12:13], v[52:53]
	v_pk_add_f32 v[16:17], v[16:17], v[40:41]
	v_pk_add_f32 v[14:15], v[14:15], v[46:47]
	v_pk_add_f32 v[12:13], v[12:13], v[60:61]
	v_lshlrev_b64 v[0:1], 12, v[0:1]
	v_pk_add_f32 v[16:17], v[16:17], v[48:49]
	v_pk_add_f32 v[14:15], v[14:15], v[54:55]
	v_pk_add_f32 v[16:17], v[16:17], v[56:57]
	v_pk_add_f32 v[14:15], v[14:15], v[66:67]
	v_pk_add_f32 v[16:17], v[16:17], v[68:69]
	s_waitcnt vmcnt(0)
	v_mov_b32_e32 v18, v2
	v_mov_b32_e32 v19, v6
	v_mov_b32_e32 v6, v3
	v_pk_add_f32 v[2:3], v[18:19], v[6:7]
	v_mov_b32_e32 v6, v4
	v_mov_b32_e32 v7, v8
	v_mov_b32_e32 v8, v5
	v_pk_add_f32 v[4:5], v[6:7], v[8:9]
	v_add_u32_e32 v6, 0x1e000, v62
	v_pk_add_f32 v[2:3], v[2:3], v[4:5]
	s_nop 0
	v_add_f32_e32 v18, v2, v3
	v_and_b32_e32 v3, 64, v214
	v_xor_b32_e32 v2, 16, v214
	v_add_u32_e32 v19, 64, v3
	v_cmp_lt_i32_e32 vcc, v2, v19
	s_nop 1
	v_cndmask_b32_e32 v2, v214, v2, vcc
	v_lshlrev_b32_e32 v2, 2, v2
	ds_bpermute_b32 v20, v2, v18
	v_add_u32_e32 v2, 0x1c000, v62
	ds_read_b128 v[2:5], v2
	ds_read_b128 v[6:9], v6
	s_waitcnt lgkmcnt(2)
	v_add_f32_e32 v18, v18, v20
	v_xor_b32_e32 v20, 32, v214
	v_cmp_lt_i32_e32 vcc, v20, v19
	s_waitcnt lgkmcnt(1)
	v_pk_add_f32 v[2:3], v[10:11], v[2:3]
	v_pk_add_f32 v[4:5], v[12:13], v[4:5]
	v_cndmask_b32_e32 v19, v214, v20, vcc
	v_lshlrev_b32_e32 v19, 2, v19
	ds_bpermute_b32 v19, v19, v18
	s_waitcnt lgkmcnt(1)
	v_pk_add_f32 v[6:7], v[14:15], v[6:7]
	v_pk_add_f32 v[8:9], v[16:17], v[8:9]
	s_waitcnt lgkmcnt(0)
	v_add_f32_e32 v10, v18, v19
	v_fmamk_f32 v10, v10, 0x3a000000, v190
	v_mul_f32_e32 v11, 0x4b800000, v10
	v_cmp_gt_f32_e32 vcc, s70, v10
	s_nop 1
	v_cndmask_b32_e32 v10, v10, v11, vcc
	v_rsq_f32_e32 v10, v10
	v_lshlrev_b32_e32 v11, 2, v64
	v_lshl_or_b32 v11, s3, 4, v11
	s_mul_hi_i32 s3, s2, 0x4200000
	s_mul_i32 s2, s2, 0x4200000
	s_add_u32 s0, s0, s2
	s_addc_u32 s1, s1, s3
	v_mul_f32_e32 v12, 0x45800000, v10
	v_lshl_add_u64 v[0:1], s[0:1], 0, v[0:1]
	s_and_b32 s0, s4, 0x700
	v_or_b32_e32 v11, s10, v11
	v_cndmask_b32_e32 v10, v10, v12, vcc
	s_lshl_b32 s94, s0, 1
	v_lshl_add_u64 v[0:1], v[0:1], 0, s[94:95]
	v_lshlrev_b32_e32 v128, 1, v11
	v_pk_mul_f32 v[4:5], v[4:5], v[10:11] op_sel_hi:[1,0]
	v_pk_mul_f32 v[2:3], v[2:3], v[10:11] op_sel_hi:[1,0]
	v_lshl_add_u64 v[0:1], v[0:1], 0, v[128:129]
	v_cvt_pk_bf16_f32 v2, v2, v3
	v_cvt_pk_bf16_f32 v3, v4, v5
	v_pk_mul_f32 v[4:5], v[6:7], v[10:11] op_sel_hi:[1,0]
	global_store_dwordx2 v[0:1], v[2:3], off
	v_pk_mul_f32 v[2:3], v[8:9], v[10:11] op_sel_hi:[1,0]
	v_cvt_pk_bf16_f32 v4, v4, v5
	s_nop 0
	v_cvt_pk_bf16_f32 v5, v2, v3
	global_store_dwordx2 v[0:1], v[4:5], off offset:256
	s_waitcnt lgkmcnt(0)
	s_barrier

.LBB0_797:
	v_lshrrev_b32_e32 v122, 2, v214
	v_and_b32_e32 v123, 15, v214
	v_sub_u32_e32 v122, v122, v123
	v_mul_i32_i24_e32 v122, 0x1000, v122
	v_bfe_u32 v125, v214, 5, 1
	v_lshlrev_b32_e32 v125, 1, v125
	v_and_b32_e32 v124, 3, v214
	v_xor_b32_e32 v125, v125, v124
	v_lshrrev_b32_e32 v124, 4, v214
	v_sub_u32_e32 v125, v125, v124
	v_lshl_add_u32 v122, v125, 4, v122
	v_ashrrev_i32_e32 v125, 31, v122
	v_add_co_u32_e32 v118, vcc, v66, v122
	s_nop 1
	v_addc_co_u32_e32 v119, vcc, v67, v125, vcc
	v_add_co_u32_e32 v120, vcc, v64, v122
	s_nop 1
	v_addc_co_u32_e32 v121, vcc, v65, v125, vcc
	v_add_co_u32_e32 v82, vcc, 0x3f5d0000, v118
	s_nop 1
	v_addc_co_u32_e32 v83, vcc, 0, v119, vcc
	v_add_co_u32_e32 v104, vcc, 0x3f5e0000, v118
	s_nop 1
	v_addc_co_u32_e32 v105, vcc, 0, v119, vcc
	v_add_co_u32_e32 v106, vcc, 0x3f5f0000, v118
	s_nop 1
	v_addc_co_u32_e32 v107, vcc, 0, v119, vcc
	v_add_co_u32_e32 v108, vcc, 0x3f600000, v118
	s_nop 1
	v_addc_co_u32_e32 v109, vcc, 0, v119, vcc
	v_add_co_u32_e32 v110, vcc, 0x6008000, v120
	s_nop 1
	v_addc_co_u32_e32 v111, vcc, 0, v121, vcc
	v_add_co_u32_e32 v112, vcc, 0x6018000, v120
	s_nop 1
	v_addc_co_u32_e32 v113, vcc, 0, v121, vcc
	v_add_co_u32_e32 v114, vcc, 0x6088000, v120
	s_nop 1
	v_addc_co_u32_e32 v115, vcc, 0, v121, vcc
	v_add_co_u32_e32 v116, vcc, 0x6098000, v120
	s_nop 1
	v_addc_co_u32_e32 v117, vcc, 0, v121, vcc
	v_readfirstlane_b32 vcc_lo, v210
	v_bfe_u32 v125, v214, 3, 1
	v_lshlrev_b32_e32 v125, 1, v125
	v_xor_b32_e32 v125, v125, v124
	v_lshlrev_b32_e32 v125, 4, v125
	v_lshl_add_u32 v125, v123, 6, v125
	s_lshr_b32 vcc_lo, vcc_lo, 6
	s_lshl_b32 vcc_lo, vcc_lo, 14
	s_mov_b32 s94, 64
	v_add_u32_e32 v124, vcc_lo, v125
	s_add_i32 m0, vcc_lo, 0x0
	s_nop 0
	global_load_lds_dwordx4 v[82:83], off
	v_lshl_add_u64 v[82:83], v[82:83], 0, s[94:95]
	s_add_i32 m0, vcc_lo, 0x400
	s_nop 0
	global_load_lds_dwordx4 v[104:105], off
	v_lshl_add_u64 v[104:105], v[104:105], 0, s[94:95]
	s_add_i32 m0, vcc_lo, 0x800
	s_nop 0
	global_load_lds_dwordx4 v[106:107], off
	v_lshl_add_u64 v[106:107], v[106:107], 0, s[94:95]
	s_add_i32 m0, vcc_lo, 0xc00
	s_nop 0
	global_load_lds_dwordx4 v[108:109], off
	v_lshl_add_u64 v[108:109], v[108:109], 0, s[94:95]
	s_add_i32 m0, vcc_lo, 0x1000
	s_nop 0
	global_load_lds_dwordx4 v[110:111], off
	v_lshl_add_u64 v[110:111], v[110:111], 0, s[94:95]
	s_add_i32 m0, vcc_lo, 0x1400
	s_nop 0
	global_load_lds_dwordx4 v[112:113], off
	v_lshl_add_u64 v[112:113], v[112:113], 0, s[94:95]
	s_add_i32 m0, vcc_lo, 0x1800
	s_nop 0
	global_load_lds_dwordx4 v[114:115], off
	v_lshl_add_u64 v[114:115], v[114:115], 0, s[94:95]
	s_add_i32 m0, vcc_lo, 0x1c00
	s_nop 0
	global_load_lds_dwordx4 v[116:117], off
	v_lshl_add_u64 v[116:117], v[116:117], 0, s[94:95]
	s_add_i32 m0, vcc_lo, 0x2000
	s_nop 0
	global_load_lds_dwordx4 v[82:83], off
	v_lshl_add_u64 v[82:83], v[82:83], 0, s[94:95]
	s_add_i32 m0, vcc_lo, 0x2400
	s_nop 0
	global_load_lds_dwordx4 v[104:105], off
	v_lshl_add_u64 v[104:105], v[104:105], 0, s[94:95]
	s_add_i32 m0, vcc_lo, 0x2800
	s_nop 0
	global_load_lds_dwordx4 v[106:107], off
	v_lshl_add_u64 v[106:107], v[106:107], 0, s[94:95]
	s_add_i32 m0, vcc_lo, 0x2c00
	s_nop 0
	global_load_lds_dwordx4 v[108:109], off
	v_lshl_add_u64 v[108:109], v[108:109], 0, s[94:95]
	s_add_i32 m0, vcc_lo, 0x3000
	s_nop 0
	global_load_lds_dwordx4 v[110:111], off
	v_lshl_add_u64 v[110:111], v[110:111], 0, s[94:95]
	s_add_i32 m0, vcc_lo, 0x3400
	s_nop 0
	global_load_lds_dwordx4 v[112:113], off
	v_lshl_add_u64 v[112:113], v[112:113], 0, s[94:95]
	s_add_i32 m0, vcc_lo, 0x3800
	s_nop 0
	global_load_lds_dwordx4 v[114:115], off
	v_lshl_add_u64 v[114:115], v[114:115], 0, s[94:95]
	s_add_i32 m0, vcc_lo, 0x3c00
	s_nop 0
	global_load_lds_dwordx4 v[116:117], off
	v_lshl_add_u64 v[116:117], v[116:117], 0, s[94:95]
	s_waitcnt vmcnt(8)
	ds_read_b128 v[68:71], v124
	ds_read_b128 v[72:75], v124 offset:1024
	ds_read_b128 v[76:79], v124 offset:2048
	ds_read_b128 v[84:87], v124 offset:3072
	ds_read_b128 v[88:91], v124 offset:4096
	ds_read_b128 v[92:95], v124 offset:5120
	ds_read_b128 v[96:99], v124 offset:6144
	ds_read_b128 v[100:103], v124 offset:7168
	s_waitcnt lgkmcnt(0)
	v_mfma_f32_16x16x32_bf16 v[56:59], v[88:91], v[68:71], 0
	s_add_i32 m0, vcc_lo, 0x0
	v_mfma_f32_16x16x32_bf16 v[52:55], v[88:91], v[72:75], 0
	global_load_lds_dwordx4 v[82:83], off
	v_lshl_add_u64 v[82:83], v[82:83], 0, s[94:95]
	v_mfma_f32_16x16x32_bf16 v[48:51], v[88:91], v[76:79], 0
	s_add_i32 m0, vcc_lo, 0x400
	v_mfma_f32_16x16x32_bf16 v[44:47], v[88:91], v[84:87], 0
	global_load_lds_dwordx4 v[104:105], off
	v_lshl_add_u64 v[104:105], v[104:105], 0, s[94:95]
	v_mfma_f32_16x16x32_bf16 v[12:15], v[92:95], v[68:71], 0
	s_add_i32 m0, vcc_lo, 0x800
	v_mfma_f32_16x16x32_bf16 v[8:11], v[92:95], v[72:75], 0
	global_load_lds_dwordx4 v[106:107], off
	v_lshl_add_u64 v[106:107], v[106:107], 0, s[94:95]
	v_mfma_f32_16x16x32_bf16 v[4:7], v[92:95], v[76:79], 0
	s_add_i32 m0, vcc_lo, 0xc00
	v_mfma_f32_16x16x32_bf16 v[0:3], v[92:95], v[84:87], 0
	global_load_lds_dwordx4 v[108:109], off
	v_lshl_add_u64 v[108:109], v[108:109], 0, s[94:95]
	v_mfma_f32_16x16x32_bf16 v[16:19], v[96:99], v[68:71], 0
	s_add_i32 m0, vcc_lo, 0x1000
	v_mfma_f32_16x16x32_bf16 v[24:27], v[96:99], v[72:75], 0
	global_load_lds_dwordx4 v[110:111], off
	v_lshl_add_u64 v[110:111], v[110:111], 0, s[94:95]
	v_mfma_f32_16x16x32_bf16 v[28:31], v[96:99], v[76:79], 0
	s_add_i32 m0, vcc_lo, 0x1400
	v_mfma_f32_16x16x32_bf16 v[36:39], v[96:99], v[84:87], 0
	global_load_lds_dwordx4 v[112:113], off
	v_lshl_add_u64 v[112:113], v[112:113], 0, s[94:95]
	v_mfma_f32_16x16x32_bf16 v[20:23], v[100:103], v[68:71], 0
	s_add_i32 m0, vcc_lo, 0x1800
	v_mfma_f32_16x16x32_bf16 v[32:35], v[100:103], v[72:75], 0
	global_load_lds_dwordx4 v[114:115], off
	v_lshl_add_u64 v[114:115], v[114:115], 0, s[94:95]
	v_mfma_f32_16x16x32_bf16 v[40:43], v[100:103], v[76:79], 0
	s_add_i32 m0, vcc_lo, 0x1c00
	v_mfma_f32_16x16x32_bf16 v[60:63], v[100:103], v[84:87], 0
	global_load_lds_dwordx4 v[116:117], off
	v_lshl_add_u64 v[116:117], v[116:117], 0, s[94:95]
	s_waitcnt vmcnt(8)
	ds_read_b128 v[68:71], v124 offset:8192
	ds_read_b128 v[72:75], v124 offset:9216
	ds_read_b128 v[76:79], v124 offset:10240
	ds_read_b128 v[84:87], v124 offset:11264
	ds_read_b128 v[88:91], v124 offset:12288
	ds_read_b128 v[92:95], v124 offset:13312
	ds_read_b128 v[96:99], v124 offset:14336
	ds_read_b128 v[100:103], v124 offset:15360
	s_waitcnt lgkmcnt(0)
	v_mfma_f32_16x16x32_bf16 v[56:59], v[88:91], v[68:71], v[56:59]
	s_add_i32 m0, vcc_lo, 0x2000
	v_mfma_f32_16x16x32_bf16 v[52:55], v[88:91], v[72:75], v[52:55]
	global_load_lds_dwordx4 v[82:83], off
	v_lshl_add_u64 v[82:83], v[82:83], 0, s[94:95]
	v_mfma_f32_16x16x32_bf16 v[48:51], v[88:91], v[76:79], v[48:51]
	s_add_i32 m0, vcc_lo, 0x2400
	v_mfma_f32_16x16x32_bf16 v[44:47], v[88:91], v[84:87], v[44:47]
	global_load_lds_dwordx4 v[104:105], off
	v_lshl_add_u64 v[104:105], v[104:105], 0, s[94:95]
	v_mfma_f32_16x16x32_bf16 v[12:15], v[92:95], v[68:71], v[12:15]
	s_add_i32 m0, vcc_lo, 0x2800
	v_mfma_f32_16x16x32_bf16 v[8:11], v[92:95], v[72:75], v[8:11]
	global_load_lds_dwordx4 v[106:107], off
	v_lshl_add_u64 v[106:107], v[106:107], 0, s[94:95]
	v_mfma_f32_16x16x32_bf16 v[4:7], v[92:95], v[76:79], v[4:7]
	s_add_i32 m0, vcc_lo, 0x2c00
	v_mfma_f32_16x16x32_bf16 v[0:3], v[92:95], v[84:87], v[0:3]
	global_load_lds_dwordx4 v[108:109], off
	v_lshl_add_u64 v[108:109], v[108:109], 0, s[94:95]
	v_mfma_f32_16x16x32_bf16 v[16:19], v[96:99], v[68:71], v[16:19]
	s_add_i32 m0, vcc_lo, 0x3000
	v_mfma_f32_16x16x32_bf16 v[24:27], v[96:99], v[72:75], v[24:27]
	global_load_lds_dwordx4 v[110:111], off
	v_lshl_add_u64 v[110:111], v[110:111], 0, s[94:95]
	v_mfma_f32_16x16x32_bf16 v[28:31], v[96:99], v[76:79], v[28:31]
	s_add_i32 m0, vcc_lo, 0x3400
	v_mfma_f32_16x16x32_bf16 v[36:39], v[96:99], v[84:87], v[36:39]
	global_load_lds_dwordx4 v[112:113], off
	v_lshl_add_u64 v[112:113], v[112:113], 0, s[94:95]
	v_mfma_f32_16x16x32_bf16 v[20:23], v[100:103], v[68:71], v[20:23]
	s_add_i32 m0, vcc_lo, 0x3800
	v_mfma_f32_16x16x32_bf16 v[32:35], v[100:103], v[72:75], v[32:35]
	global_load_lds_dwordx4 v[114:115], off
	v_lshl_add_u64 v[114:115], v[114:115], 0, s[94:95]
	v_mfma_f32_16x16x32_bf16 v[40:43], v[100:103], v[76:79], v[40:43]
	s_add_i32 m0, vcc_lo, 0x3c00
	v_mfma_f32_16x16x32_bf16 v[60:63], v[100:103], v[84:87], v[60:63]
	global_load_lds_dwordx4 v[116:117], off
	v_lshl_add_u64 v[116:117], v[116:117], 0, s[94:95]
	s_waitcnt vmcnt(8)
	ds_read_b128 v[68:71], v124
	ds_read_b128 v[72:75], v124 offset:1024
	ds_read_b128 v[76:79], v124 offset:2048
	ds_read_b128 v[84:87], v124 offset:3072
	ds_read_b128 v[88:91], v124 offset:4096
	ds_read_b128 v[92:95], v124 offset:5120
	ds_read_b128 v[96:99], v124 offset:6144
	ds_read_b128 v[100:103], v124 offset:7168
	s_waitcnt lgkmcnt(0)
	v_mfma_f32_16x16x32_bf16 v[56:59], v[88:91], v[68:71], v[56:59]
	s_add_i32 m0, vcc_lo, 0x0
	v_mfma_f32_16x16x32_bf16 v[52:55], v[88:91], v[72:75], v[52:55]
	global_load_lds_dwordx4 v[82:83], off
	v_lshl_add_u64 v[82:83], v[82:83], 0, s[94:95]
	v_mfma_f32_16x16x32_bf16 v[48:51], v[88:91], v[76:79], v[48:51]
	s_add_i32 m0, vcc_lo, 0x400
	v_mfma_f32_16x16x32_bf16 v[44:47], v[88:91], v[84:87], v[44:47]
	global_load_lds_dwordx4 v[104:105], off
	v_lshl_add_u64 v[104:105], v[104:105], 0, s[94:95]
	v_mfma_f32_16x16x32_bf16 v[12:15], v[92:95], v[68:71], v[12:15]
	s_add_i32 m0, vcc_lo, 0x800
	v_mfma_f32_16x16x32_bf16 v[8:11], v[92:95], v[72:75], v[8:11]
	global_load_lds_dwordx4 v[106:107], off
	v_lshl_add_u64 v[106:107], v[106:107], 0, s[94:95]
	v_mfma_f32_16x16x32_bf16 v[4:7], v[92:95], v[76:79], v[4:7]
	s_add_i32 m0, vcc_lo, 0xc00
	v_mfma_f32_16x16x32_bf16 v[0:3], v[92:95], v[84:87], v[0:3]
	global_load_lds_dwordx4 v[108:109], off
	v_lshl_add_u64 v[108:109], v[108:109], 0, s[94:95]
	v_mfma_f32_16x16x32_bf16 v[16:19], v[96:99], v[68:71], v[16:19]
	s_add_i32 m0, vcc_lo, 0x1000
	v_mfma_f32_16x16x32_bf16 v[24:27], v[96:99], v[72:75], v[24:27]
	global_load_lds_dwordx4 v[110:111], off
	v_lshl_add_u64 v[110:111], v[110:111], 0, s[94:95]
	v_mfma_f32_16x16x32_bf16 v[28:31], v[96:99], v[76:79], v[28:31]
	s_add_i32 m0, vcc_lo, 0x1400
	v_mfma_f32_16x16x32_bf16 v[36:39], v[96:99], v[84:87], v[36:39]
	global_load_lds_dwordx4 v[112:113], off
	v_lshl_add_u64 v[112:113], v[112:113], 0, s[94:95]
	v_mfma_f32_16x16x32_bf16 v[20:23], v[100:103], v[68:71], v[20:23]
	s_add_i32 m0, vcc_lo, 0x1800
	v_mfma_f32_16x16x32_bf16 v[32:35], v[100:103], v[72:75], v[32:35]
	global_load_lds_dwordx4 v[114:115], off
	v_lshl_add_u64 v[114:115], v[114:115], 0, s[94:95]
	v_mfma_f32_16x16x32_bf16 v[40:43], v[100:103], v[76:79], v[40:43]
	s_add_i32 m0, vcc_lo, 0x1c00
	v_mfma_f32_16x16x32_bf16 v[60:63], v[100:103], v[84:87], v[60:63]
	global_load_lds_dwordx4 v[116:117], off
	v_lshl_add_u64 v[116:117], v[116:117], 0, s[94:95]
	s_waitcnt vmcnt(8)
	ds_read_b128 v[68:71], v124 offset:8192
	ds_read_b128 v[72:75], v124 offset:9216
	ds_read_b128 v[76:79], v124 offset:10240
	ds_read_b128 v[84:87], v124 offset:11264
	ds_read_b128 v[88:91], v124 offset:12288
	ds_read_b128 v[92:95], v124 offset:13312
	ds_read_b128 v[96:99], v124 offset:14336
	ds_read_b128 v[100:103], v124 offset:15360
	s_waitcnt lgkmcnt(0)
	v_mfma_f32_16x16x32_bf16 v[56:59], v[88:91], v[68:71], v[56:59]
	s_add_i32 m0, vcc_lo, 0x2000
	v_mfma_f32_16x16x32_bf16 v[52:55], v[88:91], v[72:75], v[52:55]
	global_load_lds_dwordx4 v[82:83], off
	v_lshl_add_u64 v[82:83], v[82:83], 0, s[94:95]
	v_mfma_f32_16x16x32_bf16 v[48:51], v[88:91], v[76:79], v[48:51]
	s_add_i32 m0, vcc_lo, 0x2400
	v_mfma_f32_16x16x32_bf16 v[44:47], v[88:91], v[84:87], v[44:47]
	global_load_lds_dwordx4 v[104:105], off
	v_lshl_add_u64 v[104:105], v[104:105], 0, s[94:95]
	v_mfma_f32_16x16x32_bf16 v[12:15], v[92:95], v[68:71], v[12:15]
	s_add_i32 m0, vcc_lo, 0x2800
	v_mfma_f32_16x16x32_bf16 v[8:11], v[92:95], v[72:75], v[8:11]
	global_load_lds_dwordx4 v[106:107], off
	v_lshl_add_u64 v[106:107], v[106:107], 0, s[94:95]
	v_mfma_f32_16x16x32_bf16 v[4:7], v[92:95], v[76:79], v[4:7]
	s_add_i32 m0, vcc_lo, 0x2c00
	v_mfma_f32_16x16x32_bf16 v[0:3], v[92:95], v[84:87], v[0:3]
	global_load_lds_dwordx4 v[108:109], off
	v_lshl_add_u64 v[108:109], v[108:109], 0, s[94:95]
	v_mfma_f32_16x16x32_bf16 v[16:19], v[96:99], v[68:71], v[16:19]
	s_add_i32 m0, vcc_lo, 0x3000
	v_mfma_f32_16x16x32_bf16 v[24:27], v[96:99], v[72:75], v[24:27]
	global_load_lds_dwordx4 v[110:111], off
	v_lshl_add_u64 v[110:111], v[110:111], 0, s[94:95]
	v_mfma_f32_16x16x32_bf16 v[28:31], v[96:99], v[76:79], v[28:31]
	s_add_i32 m0, vcc_lo, 0x3400
	v_mfma_f32_16x16x32_bf16 v[36:39], v[96:99], v[84:87], v[36:39]
	global_load_lds_dwordx4 v[112:113], off
	v_lshl_add_u64 v[112:113], v[112:113], 0, s[94:95]
	v_mfma_f32_16x16x32_bf16 v[20:23], v[100:103], v[68:71], v[20:23]
	s_add_i32 m0, vcc_lo, 0x3800
	v_mfma_f32_16x16x32_bf16 v[32:35], v[100:103], v[72:75], v[32:35]
	global_load_lds_dwordx4 v[114:115], off
	v_lshl_add_u64 v[114:115], v[114:115], 0, s[94:95]
	v_mfma_f32_16x16x32_bf16 v[40:43], v[100:103], v[76:79], v[40:43]
	s_add_i32 m0, vcc_lo, 0x3c00
	v_mfma_f32_16x16x32_bf16 v[60:63], v[100:103], v[84:87], v[60:63]
	global_load_lds_dwordx4 v[116:117], off
	v_lshl_add_u64 v[116:117], v[116:117], 0, s[94:95]
	s_waitcnt vmcnt(8)
	ds_read_b128 v[68:71], v124
	ds_read_b128 v[72:75], v124 offset:1024
	ds_read_b128 v[76:79], v124 offset:2048
	ds_read_b128 v[84:87], v124 offset:3072
	ds_read_b128 v[88:91], v124 offset:4096
	ds_read_b128 v[92:95], v124 offset:5120
	ds_read_b128 v[96:99], v124 offset:6144
	ds_read_b128 v[100:103], v124 offset:7168
	s_waitcnt lgkmcnt(0)
	v_mfma_f32_16x16x32_bf16 v[56:59], v[88:91], v[68:71], v[56:59]
	s_add_i32 m0, vcc_lo, 0x0
	v_mfma_f32_16x16x32_bf16 v[52:55], v[88:91], v[72:75], v[52:55]
	global_load_lds_dwordx4 v[82:83], off
	v_lshl_add_u64 v[82:83], v[82:83], 0, s[94:95]
	v_mfma_f32_16x16x32_bf16 v[48:51], v[88:91], v[76:79], v[48:51]
	s_add_i32 m0, vcc_lo, 0x400
	v_mfma_f32_16x16x32_bf16 v[44:47], v[88:91], v[84:87], v[44:47]
	global_load_lds_dwordx4 v[104:105], off
	v_lshl_add_u64 v[104:105], v[104:105], 0, s[94:95]
	v_mfma_f32_16x16x32_bf16 v[12:15], v[92:95], v[68:71], v[12:15]
	s_add_i32 m0, vcc_lo, 0x800
	v_mfma_f32_16x16x32_bf16 v[8:11], v[92:95], v[72:75], v[8:11]
	global_load_lds_dwordx4 v[106:107], off
	v_lshl_add_u64 v[106:107], v[106:107], 0, s[94:95]
	v_mfma_f32_16x16x32_bf16 v[4:7], v[92:95], v[76:79], v[4:7]
	s_add_i32 m0, vcc_lo, 0xc00
	v_mfma_f32_16x16x32_bf16 v[0:3], v[92:95], v[84:87], v[0:3]
	global_load_lds_dwordx4 v[108:109], off
	v_lshl_add_u64 v[108:109], v[108:109], 0, s[94:95]
	v_mfma_f32_16x16x32_bf16 v[16:19], v[96:99], v[68:71], v[16:19]
	s_add_i32 m0, vcc_lo, 0x1000
	v_mfma_f32_16x16x32_bf16 v[24:27], v[96:99], v[72:75], v[24:27]
	global_load_lds_dwordx4 v[110:111], off
	v_lshl_add_u64 v[110:111], v[110:111], 0, s[94:95]
	v_mfma_f32_16x16x32_bf16 v[28:31], v[96:99], v[76:79], v[28:31]
	s_add_i32 m0, vcc_lo, 0x1400
	v_mfma_f32_16x16x32_bf16 v[36:39], v[96:99], v[84:87], v[36:39]
	global_load_lds_dwordx4 v[112:113], off
	v_lshl_add_u64 v[112:113], v[112:113], 0, s[94:95]
	v_mfma_f32_16x16x32_bf16 v[20:23], v[100:103], v[68:71], v[20:23]
	s_add_i32 m0, vcc_lo, 0x1800
	v_mfma_f32_16x16x32_bf16 v[32:35], v[100:103], v[72:75], v[32:35]
	global_load_lds_dwordx4 v[114:115], off
	v_lshl_add_u64 v[114:115], v[114:115], 0, s[94:95]
	v_mfma_f32_16x16x32_bf16 v[40:43], v[100:103], v[76:79], v[40:43]
	s_add_i32 m0, vcc_lo, 0x1c00
	v_mfma_f32_16x16x32_bf16 v[60:63], v[100:103], v[84:87], v[60:63]
	global_load_lds_dwordx4 v[116:117], off
	v_lshl_add_u64 v[116:117], v[116:117], 0, s[94:95]
	s_waitcnt vmcnt(8)
	ds_read_b128 v[68:71], v124 offset:8192
	ds_read_b128 v[72:75], v124 offset:9216
	ds_read_b128 v[76:79], v124 offset:10240
	ds_read_b128 v[84:87], v124 offset:11264
	ds_read_b128 v[88:91], v124 offset:12288
	ds_read_b128 v[92:95], v124 offset:13312
	ds_read_b128 v[96:99], v124 offset:14336
	ds_read_b128 v[100:103], v124 offset:15360
	s_waitcnt lgkmcnt(0)
	v_mfma_f32_16x16x32_bf16 v[56:59], v[88:91], v[68:71], v[56:59]
	s_add_i32 m0, vcc_lo, 0x2000
	v_mfma_f32_16x16x32_bf16 v[52:55], v[88:91], v[72:75], v[52:55]
	global_load_lds_dwordx4 v[82:83], off
	v_lshl_add_u64 v[82:83], v[82:83], 0, s[94:95]
	v_mfma_f32_16x16x32_bf16 v[48:51], v[88:91], v[76:79], v[48:51]
	s_add_i32 m0, vcc_lo, 0x2400
	v_mfma_f32_16x16x32_bf16 v[44:47], v[88:91], v[84:87], v[44:47]
	global_load_lds_dwordx4 v[104:105], off
	v_lshl_add_u64 v[104:105], v[104:105], 0, s[94:95]
	v_mfma_f32_16x16x32_bf16 v[12:15], v[92:95], v[68:71], v[12:15]
	s_add_i32 m0, vcc_lo, 0x2800
	v_mfma_f32_16x16x32_bf16 v[8:11], v[92:95], v[72:75], v[8:11]
	global_load_lds_dwordx4 v[106:107], off
	v_lshl_add_u64 v[106:107], v[106:107], 0, s[94:95]
	v_mfma_f32_16x16x32_bf16 v[4:7], v[92:95], v[76:79], v[4:7]
	s_add_i32 m0, vcc_lo, 0x2c00
	v_mfma_f32_16x16x32_bf16 v[0:3], v[92:95], v[84:87], v[0:3]
	global_load_lds_dwordx4 v[108:109], off
	v_lshl_add_u64 v[108:109], v[108:109], 0, s[94:95]
	v_mfma_f32_16x16x32_bf16 v[16:19], v[96:99], v[68:71], v[16:19]
	s_add_i32 m0, vcc_lo, 0x3000
	v_mfma_f32_16x16x32_bf16 v[24:27], v[96:99], v[72:75], v[24:27]
	global_load_lds_dwordx4 v[110:111], off
	v_lshl_add_u64 v[110:111], v[110:111], 0, s[94:95]
	v_mfma_f32_16x16x32_bf16 v[28:31], v[96:99], v[76:79], v[28:31]
	s_add_i32 m0, vcc_lo, 0x3400
	v_mfma_f32_16x16x32_bf16 v[36:39], v[96:99], v[84:87], v[36:39]
	global_load_lds_dwordx4 v[112:113], off
	v_lshl_add_u64 v[112:113], v[112:113], 0, s[94:95]
	v_mfma_f32_16x16x32_bf16 v[20:23], v[100:103], v[68:71], v[20:23]
	s_add_i32 m0, vcc_lo, 0x3800
	v_mfma_f32_16x16x32_bf16 v[32:35], v[100:103], v[72:75], v[32:35]
	global_load_lds_dwordx4 v[114:115], off
	v_lshl_add_u64 v[114:115], v[114:115], 0, s[94:95]
	v_mfma_f32_16x16x32_bf16 v[40:43], v[100:103], v[76:79], v[40:43]
	s_add_i32 m0, vcc_lo, 0x3c00
	v_mfma_f32_16x16x32_bf16 v[60:63], v[100:103], v[84:87], v[60:63]
	global_load_lds_dwordx4 v[116:117], off
	v_lshl_add_u64 v[116:117], v[116:117], 0, s[94:95]
	s_waitcnt vmcnt(8)
	ds_read_b128 v[68:71], v124
	ds_read_b128 v[72:75], v124 offset:1024
	ds_read_b128 v[76:79], v124 offset:2048
	ds_read_b128 v[84:87], v124 offset:3072
	ds_read_b128 v[88:91], v124 offset:4096
	ds_read_b128 v[92:95], v124 offset:5120
	ds_read_b128 v[96:99], v124 offset:6144
	ds_read_b128 v[100:103], v124 offset:7168
	s_waitcnt lgkmcnt(0)
	v_mfma_f32_16x16x32_bf16 v[56:59], v[88:91], v[68:71], v[56:59]
	v_mfma_f32_16x16x32_bf16 v[52:55], v[88:91], v[72:75], v[52:55]
	v_mfma_f32_16x16x32_bf16 v[48:51], v[88:91], v[76:79], v[48:51]
	v_mfma_f32_16x16x32_bf16 v[44:47], v[88:91], v[84:87], v[44:47]
	v_mfma_f32_16x16x32_bf16 v[12:15], v[92:95], v[68:71], v[12:15]
	v_mfma_f32_16x16x32_bf16 v[8:11], v[92:95], v[72:75], v[8:11]
	v_mfma_f32_16x16x32_bf16 v[4:7], v[92:95], v[76:79], v[4:7]
	v_mfma_f32_16x16x32_bf16 v[0:3], v[92:95], v[84:87], v[0:3]
	v_mfma_f32_16x16x32_bf16 v[16:19], v[96:99], v[68:71], v[16:19]
	v_mfma_f32_16x16x32_bf16 v[24:27], v[96:99], v[72:75], v[24:27]
	v_mfma_f32_16x16x32_bf16 v[28:31], v[96:99], v[76:79], v[28:31]
	v_mfma_f32_16x16x32_bf16 v[36:39], v[96:99], v[84:87], v[36:39]
	v_mfma_f32_16x16x32_bf16 v[20:23], v[100:103], v[68:71], v[20:23]
	v_mfma_f32_16x16x32_bf16 v[32:35], v[100:103], v[72:75], v[32:35]
	v_mfma_f32_16x16x32_bf16 v[40:43], v[100:103], v[76:79], v[40:43]
	v_mfma_f32_16x16x32_bf16 v[60:63], v[100:103], v[84:87], v[60:63]
	s_waitcnt vmcnt(0)
	ds_read_b128 v[68:71], v124 offset:8192
	ds_read_b128 v[72:75], v124 offset:9216
	ds_read_b128 v[76:79], v124 offset:10240
	ds_read_b128 v[84:87], v124 offset:11264
	ds_read_b128 v[88:91], v124 offset:12288
	ds_read_b128 v[92:95], v124 offset:13312
	ds_read_b128 v[96:99], v124 offset:14336
	ds_read_b128 v[100:103], v124 offset:15360
	s_waitcnt lgkmcnt(0)
	v_mfma_f32_16x16x32_bf16 v[56:59], v[88:91], v[68:71], v[56:59]
	v_mfma_f32_16x16x32_bf16 v[52:55], v[88:91], v[72:75], v[52:55]
	v_mfma_f32_16x16x32_bf16 v[48:51], v[88:91], v[76:79], v[48:51]
	v_mfma_f32_16x16x32_bf16 v[44:47], v[88:91], v[84:87], v[44:47]
	v_mfma_f32_16x16x32_bf16 v[12:15], v[92:95], v[68:71], v[12:15]
	v_mfma_f32_16x16x32_bf16 v[8:11], v[92:95], v[72:75], v[8:11]
	v_mfma_f32_16x16x32_bf16 v[4:7], v[92:95], v[76:79], v[4:7]
	v_mfma_f32_16x16x32_bf16 v[0:3], v[92:95], v[84:87], v[0:3]
	v_mfma_f32_16x16x32_bf16 v[16:19], v[96:99], v[68:71], v[16:19]
	v_mfma_f32_16x16x32_bf16 v[24:27], v[96:99], v[72:75], v[24:27]
	v_mfma_f32_16x16x32_bf16 v[28:31], v[96:99], v[76:79], v[28:31]
	v_mfma_f32_16x16x32_bf16 v[36:39], v[96:99], v[84:87], v[36:39]
	v_mfma_f32_16x16x32_bf16 v[20:23], v[100:103], v[68:71], v[20:23]
	v_mfma_f32_16x16x32_bf16 v[32:35], v[100:103], v[72:75], v[32:35]
	v_mfma_f32_16x16x32_bf16 v[40:43], v[100:103], v[76:79], v[40:43]
	v_mfma_f32_16x16x32_bf16 v[60:63], v[100:103], v[84:87], v[60:63]
	s_nop 7
	s_nop 3
	v_and_b32_e32 v65, 63, v81
	v_lshl_add_u32 v66, v65, 4, 0
	s_ashr_i32 s10, s0, 7
	v_bfe_u32 v64, v81, 4, 2
	v_lshl_add_u32 v67, s3, 14, v66
	s_lshl_b32 s5, s10, 4
	ds_write_b128 v67, v[56:59]
	ds_write_b128 v67, v[52:55] offset:1024
	ds_write_b128 v67, v[48:51] offset:2048
	ds_write_b128 v67, v[44:47] offset:3072
	ds_write_b128 v67, v[12:15] offset:4096
	ds_write_b128 v67, v[8:11] offset:5120
	ds_write_b128 v67, v[4:7] offset:6144
	ds_write_b128 v67, v[0:3] offset:7168
	ds_write_b128 v67, v[16:19] offset:8192
	ds_write_b128 v67, v[24:27] offset:9216
	ds_write_b128 v67, v[28:31] offset:10240
	ds_write_b128 v67, v[36:39] offset:11264
	ds_write_b128 v67, v[20:23] offset:12288
	ds_write_b128 v67, v[32:35] offset:13312
	ds_write_b128 v67, v[40:43] offset:14336
	ds_write_b128 v67, v[60:63] offset:15360
	s_bfe_u32 s3, s0, 0x10006
	s_addk_i32 s5, 0x4000
	v_lshlrev_b32_e32 v1, 2, v64
	v_or_b32_e32 v0, s5, v80
	v_lshl_or_b32 v1, s3, 4, v1
	v_or_b32_e32 v4, s1, v1
	v_ashrrev_i32_e32 v1, 31, v0
	v_lshlrev_b64 v[2:3], 12, v[0:1]
	s_ashr_i32 s5, s4, 31
	v_lshl_add_u64 v[2:3], s[8:9], 0, v[2:3]
	v_lshl_add_u64 v[2:3], s[4:5], 1, v[2:3]
	v_lshlrev_b32_e32 v128, 1, v4
	v_lshl_add_u64 v[14:15], v[2:3], 0, v[128:129]
	s_waitcnt lgkmcnt(0)
	s_barrier
	global_load_dwordx2 v[16:17], v[14:15], off
	global_load_dwordx2 v[18:19], v[14:15], off offset:256
	s_lshl_b32 s1, s3, 2
	s_add_i32 s1, s1, s10
	v_lshl_add_u32 v28, s1, 10, v66
	ds_read_b128 v[2:5], v28
	ds_read_b128 v[6:9], v28 offset:8192
	ds_read_b128 v[10:13], v28 offset:16384
	v_cmp_gt_u32_e32 vcc, 16, v65
	s_waitcnt lgkmcnt(0)
	v_pk_add_f32 v[20:21], v[4:5], 0 op_sel_hi:[1,0]
	v_pk_add_f32 v[22:23], v[2:3], 0 op_sel_hi:[1,0]
	ds_read_b128 v[2:5], v28 offset:24576
	v_pk_add_f32 v[24:25], v[8:9], 0 op_sel_hi:[1,0]
	v_pk_add_f32 v[26:27], v[6:7], 0 op_sel_hi:[1,0]
	ds_read_b128 v[6:9], v28 offset:32768
	v_pk_add_f32 v[22:23], v[22:23], v[10:11]
	s_waitcnt lgkmcnt(0)
	v_pk_add_f32 v[24:25], v[24:25], v[4:5]
	v_pk_add_f32 v[26:27], v[26:27], v[2:3]
	ds_read_b128 v[2:5], v28 offset:49152
	v_pk_add_f32 v[20:21], v[20:21], v[12:13]
	ds_read_b128 v[10:13], v28 offset:40960
	v_pk_add_f32 v[22:23], v[22:23], v[6:7]
	v_pk_add_f32 v[20:21], v[20:21], v[8:9]
	ds_read_b128 v[6:9], v28 offset:57344
	s_waitcnt lgkmcnt(0)
	v_pk_add_f32 v[22:23], v[22:23], v[2:3]
	v_add_u32_e32 v2, 0x10000, v28
	v_pk_add_f32 v[20:21], v[20:21], v[4:5]
	ds_read_b128 v[2:5], v2
	v_pk_add_f32 v[10:11], v[26:27], v[10:11]
	v_pk_add_f32 v[12:13], v[24:25], v[12:13]
	v_pk_add_f32 v[10:11], v[10:11], v[6:7]
	v_add_u32_e32 v6, 0x12000, v28
	v_pk_add_f32 v[12:13], v[12:13], v[8:9]
	ds_read_b128 v[6:9], v6
	s_waitcnt lgkmcnt(0)
	v_pk_add_f32 v[22:23], v[22:23], v[2:3]
	v_add_u32_e32 v2, 0x14000, v28
	v_pk_add_f32 v[20:21], v[20:21], v[4:5]
	ds_read_b128 v[2:5], v2
	v_pk_add_f32 v[10:11], v[10:11], v[6:7]
	v_add_u32_e32 v6, 0x16000, v28
	v_pk_add_f32 v[12:13], v[12:13], v[8:9]
	ds_read_b128 v[6:9], v6
	s_waitcnt lgkmcnt(0)
	v_pk_add_f32 v[22:23], v[22:23], v[2:3]
	v_add_u32_e32 v2, 0x18000, v28
	v_pk_add_f32 v[20:21], v[20:21], v[4:5]
	ds_read_b128 v[2:5], v2
	v_pk_add_f32 v[26:27], v[10:11], v[6:7]
	v_add_u32_e32 v6, 0x1a000, v28
	v_pk_add_f32 v[24:25], v[12:13], v[8:9]
	ds_read_b128 v[6:9], v6
	s_waitcnt lgkmcnt(0)
	v_pk_add_f32 v[22:23], v[22:23], v[2:3]
	v_add_u32_e32 v2, 0x1c000, v28
	v_add_u32_e32 v10, 0x1e000, v28
	v_pk_add_f32 v[20:21], v[20:21], v[4:5]
	ds_read_b128 v[2:5], v2
	ds_read_b128 v[10:13], v10
	v_pk_add_f32 v[6:7], v[26:27], v[6:7]
	v_pk_add_f32 v[8:9], v[24:25], v[8:9]
	s_waitcnt lgkmcnt(0)
	v_pk_add_f32 v[2:3], v[22:23], v[2:3]
	v_pk_add_f32 v[6:7], v[6:7], v[10:11]
	v_pk_add_f32 v[4:5], v[20:21], v[4:5]
	v_pk_add_f32 v[8:9], v[8:9], v[12:13]
	s_waitcnt vmcnt(0)
	v_lshlrev_b32_e32 v10, 16, v16
	v_and_b32_e32 v11, 0xffff0000, v16
	v_pk_add_f32 v[2:3], v[2:3], v[10:11]
	v_lshlrev_b32_e32 v10, 16, v18
	v_and_b32_e32 v11, 0xffff0000, v18
	v_lshlrev_b32_e32 v12, 16, v17
	v_and_b32_e32 v13, 0xffff0000, v17
	v_pk_add_f32 v[6:7], v[6:7], v[10:11]
	v_pk_add_f32 v[4:5], v[4:5], v[12:13]
	v_lshlrev_b32_e32 v12, 16, v19
	v_and_b32_e32 v13, 0xffff0000, v19
	v_mul_f32_e32 v10, v6, v6
	v_mul_f32_e32 v11, v7, v7
	v_pk_add_f32 v[8:9], v[8:9], v[12:13]
	v_fmac_f32_e32 v10, v2, v2
	v_fmac_f32_e32 v11, v3, v3
	v_add_f32_e32 v10, v10, v11
	v_mul_f32_e32 v11, v8, v8
	v_fmac_f32_e32 v11, v4, v4
	v_add_f32_e32 v10, v11, v10
	v_mul_f32_e32 v11, v9, v9
	v_fmac_f32_e32 v11, v5, v5
	v_add_f32_e32 v10, v11, v10
	ds_bpermute_b32 v11, v216, v10
	v_cvt_pk_bf16_f32 v2, v2, v3
	v_cvt_pk_bf16_f32 v3, v4, v5
	global_store_dwordx2 v[14:15], v[2:3], off
	v_cvt_pk_bf16_f32 v2, v6, v7
	s_waitcnt lgkmcnt(0)
	v_add_f32_e32 v4, v10, v11
	ds_bpermute_b32 v5, v217, v4
	v_cvt_pk_bf16_f32 v3, v8, v9
	global_store_dwordx2 v[14:15], v[2:3], off offset:256
	s_waitcnt lgkmcnt(0)
	v_add_f32_e32 v2, v4, v5
	s_and_saveexec_b64 s[4:5], vcc
	s_and_b32 s1, s0, 0xffffffc0
	s_add_i32 s1, s1, 0
	v_lshl_add_u32 v3, v80, 2, s1
	v_add_u32_e32 v3, 0x20100, v3
	ds_write_b32 v3, v2
	s_or_b64 exec, exec, s[4:5]
	v_or_b32_e32 v3, s3, v64
	v_cmp_eq_u32_e32 vcc, 0, v3
	s_waitcnt lgkmcnt(0)
	s_barrier
	s_and_saveexec_b64 s[4:5], vcc
	s_cbranch_execz .LBB0_802
	s_andn2_b32 s0, s0, 63
	s_add_i32 s0, s0, 0
	s_add_i32 s0, s0, 0x20100
	v_lshl_add_u32 v3, v80, 2, s0
	ds_read_b32 v3, v3 offset:64
	v_lshlrev_b64 v[0:1], 7, v[0:1]
	v_lshl_add_u64 v[0:1], s[6:7], 0, v[0:1]
	s_ashr_i32 s3, s2, 31
	v_lshl_add_u64 v[0:1], s[2:3], 2, v[0:1]
	s_waitcnt lgkmcnt(0)
	v_add_f32_e32 v2, v2, v3
	global_store_dword v[0:1], v2, off

.LBB0_884:
	v_lshrrev_b32_e32 v122, 2, v214
	v_and_b32_e32 v123, 15, v214
	v_sub_u32_e32 v122, v122, v123
	v_mul_i32_i24_e32 v122, 0x1000, v122
	v_bfe_u32 v125, v214, 5, 1
	v_lshlrev_b32_e32 v125, 1, v125
	v_and_b32_e32 v124, 3, v214
	v_xor_b32_e32 v125, v125, v124
	v_lshrrev_b32_e32 v124, 4, v214
	v_sub_u32_e32 v125, v125, v124
	v_lshl_add_u32 v122, v125, 4, v122
	v_ashrrev_i32_e32 v125, 31, v122
	v_add_co_u32_e32 v118, vcc, v66, v122
	s_nop 1
	v_addc_co_u32_e32 v119, vcc, v67, v125, vcc
	v_add_co_u32_e32 v120, vcc, v64, v122
	s_nop 1
	v_addc_co_u32_e32 v121, vcc, v65, v125, vcc
	v_add_co_u32_e32 v82, vcc, s84, v118
	s_nop 1
	v_addc_co_u32_e32 v83, vcc, 0, v119, vcc
	v_add_co_u32_e32 v104, vcc, s85, v118
	s_nop 1
	v_addc_co_u32_e32 v105, vcc, 0, v119, vcc
	v_add_co_u32_e32 v106, vcc, s88, v118
	s_nop 1
	v_addc_co_u32_e32 v107, vcc, 0, v119, vcc
	v_add_co_u32_e32 v108, vcc, s89, v118
	s_nop 1
	v_addc_co_u32_e32 v109, vcc, 0, v119, vcc
	v_add_co_u32_e32 v110, vcc, 0x8000, v120
	s_nop 1
	v_addc_co_u32_e32 v111, vcc, 0, v121, vcc
	v_add_co_u32_e32 v112, vcc, 0x18000, v120
	s_nop 1
	v_addc_co_u32_e32 v113, vcc, 0, v121, vcc
	v_add_co_u32_e32 v114, vcc, 0x88000, v120
	s_nop 1
	v_addc_co_u32_e32 v115, vcc, 0, v121, vcc
	v_add_co_u32_e32 v116, vcc, 0x98000, v120
	s_nop 1
	v_addc_co_u32_e32 v117, vcc, 0, v121, vcc
	v_readfirstlane_b32 vcc_lo, v210
	v_bfe_u32 v125, v214, 3, 1
	v_lshlrev_b32_e32 v125, 1, v125
	v_xor_b32_e32 v125, v125, v124
	v_lshlrev_b32_e32 v125, 4, v125
	v_lshl_add_u32 v125, v123, 6, v125
	s_lshr_b32 vcc_lo, vcc_lo, 6
	s_lshl_b32 vcc_lo, vcc_lo, 14
	s_mov_b32 s94, 64
	v_add_u32_e32 v124, vcc_lo, v125
	s_add_i32 m0, vcc_lo, 0x0
	s_nop 0
	global_load_lds_dwordx4 v[82:83], off
	v_lshl_add_u64 v[82:83], v[82:83], 0, s[94:95]
	s_add_i32 m0, vcc_lo, 0x400
	s_nop 0
	global_load_lds_dwordx4 v[104:105], off
	v_lshl_add_u64 v[104:105], v[104:105], 0, s[94:95]
	s_add_i32 m0, vcc_lo, 0x800
	s_nop 0
	global_load_lds_dwordx4 v[106:107], off
	v_lshl_add_u64 v[106:107], v[106:107], 0, s[94:95]
	s_add_i32 m0, vcc_lo, 0xc00
	s_nop 0
	global_load_lds_dwordx4 v[108:109], off
	v_lshl_add_u64 v[108:109], v[108:109], 0, s[94:95]
	s_add_i32 m0, vcc_lo, 0x1000
	s_nop 0
	global_load_lds_dwordx4 v[110:111], off
	v_lshl_add_u64 v[110:111], v[110:111], 0, s[94:95]
	s_add_i32 m0, vcc_lo, 0x1400
	s_nop 0
	global_load_lds_dwordx4 v[112:113], off
	v_lshl_add_u64 v[112:113], v[112:113], 0, s[94:95]
	s_add_i32 m0, vcc_lo, 0x1800
	s_nop 0
	global_load_lds_dwordx4 v[114:115], off
	v_lshl_add_u64 v[114:115], v[114:115], 0, s[94:95]
	s_add_i32 m0, vcc_lo, 0x1c00
	s_nop 0
	global_load_lds_dwordx4 v[116:117], off
	v_lshl_add_u64 v[116:117], v[116:117], 0, s[94:95]
	s_add_i32 m0, vcc_lo, 0x2000
	s_nop 0
	global_load_lds_dwordx4 v[82:83], off
	v_lshl_add_u64 v[82:83], v[82:83], 0, s[94:95]
	s_add_i32 m0, vcc_lo, 0x2400
	s_nop 0
	global_load_lds_dwordx4 v[104:105], off
	v_lshl_add_u64 v[104:105], v[104:105], 0, s[94:95]
	s_add_i32 m0, vcc_lo, 0x2800
	s_nop 0
	global_load_lds_dwordx4 v[106:107], off
	v_lshl_add_u64 v[106:107], v[106:107], 0, s[94:95]
	s_add_i32 m0, vcc_lo, 0x2c00
	s_nop 0
	global_load_lds_dwordx4 v[108:109], off
	v_lshl_add_u64 v[108:109], v[108:109], 0, s[94:95]
	s_add_i32 m0, vcc_lo, 0x3000
	s_nop 0
	global_load_lds_dwordx4 v[110:111], off
	v_lshl_add_u64 v[110:111], v[110:111], 0, s[94:95]
	s_add_i32 m0, vcc_lo, 0x3400
	s_nop 0
	global_load_lds_dwordx4 v[112:113], off
	v_lshl_add_u64 v[112:113], v[112:113], 0, s[94:95]
	s_add_i32 m0, vcc_lo, 0x3800
	s_nop 0
	global_load_lds_dwordx4 v[114:115], off
	v_lshl_add_u64 v[114:115], v[114:115], 0, s[94:95]
	s_add_i32 m0, vcc_lo, 0x3c00
	s_nop 0
	global_load_lds_dwordx4 v[116:117], off
	v_lshl_add_u64 v[116:117], v[116:117], 0, s[94:95]
	s_waitcnt vmcnt(8)
	ds_read_b128 v[68:71], v124
	ds_read_b128 v[72:75], v124 offset:1024
	ds_read_b128 v[76:79], v124 offset:2048
	ds_read_b128 v[84:87], v124 offset:3072
	ds_read_b128 v[88:91], v124 offset:4096
	ds_read_b128 v[92:95], v124 offset:5120
	ds_read_b128 v[96:99], v124 offset:6144
	ds_read_b128 v[100:103], v124 offset:7168
	s_waitcnt lgkmcnt(0)
	v_mfma_f32_16x16x32_bf16 v[56:59], v[88:91], v[68:71], 0
	s_add_i32 m0, vcc_lo, 0x0
	v_mfma_f32_16x16x32_bf16 v[52:55], v[88:91], v[72:75], 0
	global_load_lds_dwordx4 v[82:83], off
	v_lshl_add_u64 v[82:83], v[82:83], 0, s[94:95]
	v_mfma_f32_16x16x32_bf16 v[48:51], v[88:91], v[76:79], 0
	s_add_i32 m0, vcc_lo, 0x400
	v_mfma_f32_16x16x32_bf16 v[44:47], v[88:91], v[84:87], 0
	global_load_lds_dwordx4 v[104:105], off
	v_lshl_add_u64 v[104:105], v[104:105], 0, s[94:95]
	v_mfma_f32_16x16x32_bf16 v[12:15], v[92:95], v[68:71], 0
	s_add_i32 m0, vcc_lo, 0x800
	v_mfma_f32_16x16x32_bf16 v[8:11], v[92:95], v[72:75], 0
	global_load_lds_dwordx4 v[106:107], off
	v_lshl_add_u64 v[106:107], v[106:107], 0, s[94:95]
	v_mfma_f32_16x16x32_bf16 v[4:7], v[92:95], v[76:79], 0
	s_add_i32 m0, vcc_lo, 0xc00
	v_mfma_f32_16x16x32_bf16 v[0:3], v[92:95], v[84:87], 0
	global_load_lds_dwordx4 v[108:109], off
	v_lshl_add_u64 v[108:109], v[108:109], 0, s[94:95]
	v_mfma_f32_16x16x32_bf16 v[16:19], v[96:99], v[68:71], 0
	s_add_i32 m0, vcc_lo, 0x1000
	v_mfma_f32_16x16x32_bf16 v[24:27], v[96:99], v[72:75], 0
	global_load_lds_dwordx4 v[110:111], off
	v_lshl_add_u64 v[110:111], v[110:111], 0, s[94:95]
	v_mfma_f32_16x16x32_bf16 v[28:31], v[96:99], v[76:79], 0
	s_add_i32 m0, vcc_lo, 0x1400
	v_mfma_f32_16x16x32_bf16 v[36:39], v[96:99], v[84:87], 0
	global_load_lds_dwordx4 v[112:113], off
	v_lshl_add_u64 v[112:113], v[112:113], 0, s[94:95]
	v_mfma_f32_16x16x32_bf16 v[20:23], v[100:103], v[68:71], 0
	s_add_i32 m0, vcc_lo, 0x1800
	v_mfma_f32_16x16x32_bf16 v[32:35], v[100:103], v[72:75], 0
	global_load_lds_dwordx4 v[114:115], off
	v_lshl_add_u64 v[114:115], v[114:115], 0, s[94:95]
	v_mfma_f32_16x16x32_bf16 v[40:43], v[100:103], v[76:79], 0
	s_add_i32 m0, vcc_lo, 0x1c00
	v_mfma_f32_16x16x32_bf16 v[60:63], v[100:103], v[84:87], 0
	global_load_lds_dwordx4 v[116:117], off
	v_lshl_add_u64 v[116:117], v[116:117], 0, s[94:95]
	s_waitcnt vmcnt(8)
	ds_read_b128 v[68:71], v124 offset:8192
	ds_read_b128 v[72:75], v124 offset:9216
	ds_read_b128 v[76:79], v124 offset:10240
	ds_read_b128 v[84:87], v124 offset:11264
	ds_read_b128 v[88:91], v124 offset:12288
	ds_read_b128 v[92:95], v124 offset:13312
	ds_read_b128 v[96:99], v124 offset:14336
	ds_read_b128 v[100:103], v124 offset:15360
	s_waitcnt lgkmcnt(0)
	v_mfma_f32_16x16x32_bf16 v[56:59], v[88:91], v[68:71], v[56:59]
	s_add_i32 m0, vcc_lo, 0x2000
	v_mfma_f32_16x16x32_bf16 v[52:55], v[88:91], v[72:75], v[52:55]
	global_load_lds_dwordx4 v[82:83], off
	v_lshl_add_u64 v[82:83], v[82:83], 0, s[94:95]
	v_mfma_f32_16x16x32_bf16 v[48:51], v[88:91], v[76:79], v[48:51]
	s_add_i32 m0, vcc_lo, 0x2400
	v_mfma_f32_16x16x32_bf16 v[44:47], v[88:91], v[84:87], v[44:47]
	global_load_lds_dwordx4 v[104:105], off
	v_lshl_add_u64 v[104:105], v[104:105], 0, s[94:95]
	v_mfma_f32_16x16x32_bf16 v[12:15], v[92:95], v[68:71], v[12:15]
	s_add_i32 m0, vcc_lo, 0x2800
	v_mfma_f32_16x16x32_bf16 v[8:11], v[92:95], v[72:75], v[8:11]
	global_load_lds_dwordx4 v[106:107], off
	v_lshl_add_u64 v[106:107], v[106:107], 0, s[94:95]
	v_mfma_f32_16x16x32_bf16 v[4:7], v[92:95], v[76:79], v[4:7]
	s_add_i32 m0, vcc_lo, 0x2c00
	v_mfma_f32_16x16x32_bf16 v[0:3], v[92:95], v[84:87], v[0:3]
	global_load_lds_dwordx4 v[108:109], off
	v_lshl_add_u64 v[108:109], v[108:109], 0, s[94:95]
	v_mfma_f32_16x16x32_bf16 v[16:19], v[96:99], v[68:71], v[16:19]
	s_add_i32 m0, vcc_lo, 0x3000
	v_mfma_f32_16x16x32_bf16 v[24:27], v[96:99], v[72:75], v[24:27]
	global_load_lds_dwordx4 v[110:111], off
	v_lshl_add_u64 v[110:111], v[110:111], 0, s[94:95]
	v_mfma_f32_16x16x32_bf16 v[28:31], v[96:99], v[76:79], v[28:31]
	s_add_i32 m0, vcc_lo, 0x3400
	v_mfma_f32_16x16x32_bf16 v[36:39], v[96:99], v[84:87], v[36:39]
	global_load_lds_dwordx4 v[112:113], off
	v_lshl_add_u64 v[112:113], v[112:113], 0, s[94:95]
	v_mfma_f32_16x16x32_bf16 v[20:23], v[100:103], v[68:71], v[20:23]
	s_add_i32 m0, vcc_lo, 0x3800
	v_mfma_f32_16x16x32_bf16 v[32:35], v[100:103], v[72:75], v[32:35]
	global_load_lds_dwordx4 v[114:115], off
	v_lshl_add_u64 v[114:115], v[114:115], 0, s[94:95]
	v_mfma_f32_16x16x32_bf16 v[40:43], v[100:103], v[76:79], v[40:43]
	s_add_i32 m0, vcc_lo, 0x3c00
	v_mfma_f32_16x16x32_bf16 v[60:63], v[100:103], v[84:87], v[60:63]
	global_load_lds_dwordx4 v[116:117], off
	v_lshl_add_u64 v[116:117], v[116:117], 0, s[94:95]
	s_waitcnt vmcnt(8)
	ds_read_b128 v[68:71], v124
	ds_read_b128 v[72:75], v124 offset:1024
	ds_read_b128 v[76:79], v124 offset:2048
	ds_read_b128 v[84:87], v124 offset:3072
	ds_read_b128 v[88:91], v124 offset:4096
	ds_read_b128 v[92:95], v124 offset:5120
	ds_read_b128 v[96:99], v124 offset:6144
	ds_read_b128 v[100:103], v124 offset:7168
	s_waitcnt lgkmcnt(0)
	v_mfma_f32_16x16x32_bf16 v[56:59], v[88:91], v[68:71], v[56:59]
	s_add_i32 m0, vcc_lo, 0x0
	v_mfma_f32_16x16x32_bf16 v[52:55], v[88:91], v[72:75], v[52:55]
	global_load_lds_dwordx4 v[82:83], off
	v_lshl_add_u64 v[82:83], v[82:83], 0, s[94:95]
	v_mfma_f32_16x16x32_bf16 v[48:51], v[88:91], v[76:79], v[48:51]
	s_add_i32 m0, vcc_lo, 0x400
	v_mfma_f32_16x16x32_bf16 v[44:47], v[88:91], v[84:87], v[44:47]
	global_load_lds_dwordx4 v[104:105], off
	v_lshl_add_u64 v[104:105], v[104:105], 0, s[94:95]
	v_mfma_f32_16x16x32_bf16 v[12:15], v[92:95], v[68:71], v[12:15]
	s_add_i32 m0, vcc_lo, 0x800
	v_mfma_f32_16x16x32_bf16 v[8:11], v[92:95], v[72:75], v[8:11]
	global_load_lds_dwordx4 v[106:107], off
	v_lshl_add_u64 v[106:107], v[106:107], 0, s[94:95]
	v_mfma_f32_16x16x32_bf16 v[4:7], v[92:95], v[76:79], v[4:7]
	s_add_i32 m0, vcc_lo, 0xc00
	v_mfma_f32_16x16x32_bf16 v[0:3], v[92:95], v[84:87], v[0:3]
	global_load_lds_dwordx4 v[108:109], off
	v_lshl_add_u64 v[108:109], v[108:109], 0, s[94:95]
	v_mfma_f32_16x16x32_bf16 v[16:19], v[96:99], v[68:71], v[16:19]
	s_add_i32 m0, vcc_lo, 0x1000
	v_mfma_f32_16x16x32_bf16 v[24:27], v[96:99], v[72:75], v[24:27]
	global_load_lds_dwordx4 v[110:111], off
	v_lshl_add_u64 v[110:111], v[110:111], 0, s[94:95]
	v_mfma_f32_16x16x32_bf16 v[28:31], v[96:99], v[76:79], v[28:31]
	s_add_i32 m0, vcc_lo, 0x1400
	v_mfma_f32_16x16x32_bf16 v[36:39], v[96:99], v[84:87], v[36:39]
	global_load_lds_dwordx4 v[112:113], off
	v_lshl_add_u64 v[112:113], v[112:113], 0, s[94:95]
	v_mfma_f32_16x16x32_bf16 v[20:23], v[100:103], v[68:71], v[20:23]
	s_add_i32 m0, vcc_lo, 0x1800
	v_mfma_f32_16x16x32_bf16 v[32:35], v[100:103], v[72:75], v[32:35]
	global_load_lds_dwordx4 v[114:115], off
	v_lshl_add_u64 v[114:115], v[114:115], 0, s[94:95]
	v_mfma_f32_16x16x32_bf16 v[40:43], v[100:103], v[76:79], v[40:43]
	s_add_i32 m0, vcc_lo, 0x1c00
	v_mfma_f32_16x16x32_bf16 v[60:63], v[100:103], v[84:87], v[60:63]
	global_load_lds_dwordx4 v[116:117], off
	v_lshl_add_u64 v[116:117], v[116:117], 0, s[94:95]
	s_waitcnt vmcnt(8)
	ds_read_b128 v[68:71], v124 offset:8192
	ds_read_b128 v[72:75], v124 offset:9216
	ds_read_b128 v[76:79], v124 offset:10240
	ds_read_b128 v[84:87], v124 offset:11264
	ds_read_b128 v[88:91], v124 offset:12288
	ds_read_b128 v[92:95], v124 offset:13312
	ds_read_b128 v[96:99], v124 offset:14336
	ds_read_b128 v[100:103], v124 offset:15360
	s_waitcnt lgkmcnt(0)
	v_mfma_f32_16x16x32_bf16 v[56:59], v[88:91], v[68:71], v[56:59]
	s_add_i32 m0, vcc_lo, 0x2000
	v_mfma_f32_16x16x32_bf16 v[52:55], v[88:91], v[72:75], v[52:55]
	global_load_lds_dwordx4 v[82:83], off
	v_lshl_add_u64 v[82:83], v[82:83], 0, s[94:95]
	v_mfma_f32_16x16x32_bf16 v[48:51], v[88:91], v[76:79], v[48:51]
	s_add_i32 m0, vcc_lo, 0x2400
	v_mfma_f32_16x16x32_bf16 v[44:47], v[88:91], v[84:87], v[44:47]
	global_load_lds_dwordx4 v[104:105], off
	v_lshl_add_u64 v[104:105], v[104:105], 0, s[94:95]
	v_mfma_f32_16x16x32_bf16 v[12:15], v[92:95], v[68:71], v[12:15]
	s_add_i32 m0, vcc_lo, 0x2800
	v_mfma_f32_16x16x32_bf16 v[8:11], v[92:95], v[72:75], v[8:11]
	global_load_lds_dwordx4 v[106:107], off
	v_lshl_add_u64 v[106:107], v[106:107], 0, s[94:95]
	v_mfma_f32_16x16x32_bf16 v[4:7], v[92:95], v[76:79], v[4:7]
	s_add_i32 m0, vcc_lo, 0x2c00
	v_mfma_f32_16x16x32_bf16 v[0:3], v[92:95], v[84:87], v[0:3]
	global_load_lds_dwordx4 v[108:109], off
	v_lshl_add_u64 v[108:109], v[108:109], 0, s[94:95]
	v_mfma_f32_16x16x32_bf16 v[16:19], v[96:99], v[68:71], v[16:19]
	s_add_i32 m0, vcc_lo, 0x3000
	v_mfma_f32_16x16x32_bf16 v[24:27], v[96:99], v[72:75], v[24:27]
	global_load_lds_dwordx4 v[110:111], off
	v_lshl_add_u64 v[110:111], v[110:111], 0, s[94:95]
	v_mfma_f32_16x16x32_bf16 v[28:31], v[96:99], v[76:79], v[28:31]
	s_add_i32 m0, vcc_lo, 0x3400
	v_mfma_f32_16x16x32_bf16 v[36:39], v[96:99], v[84:87], v[36:39]
	global_load_lds_dwordx4 v[112:113], off
	v_lshl_add_u64 v[112:113], v[112:113], 0, s[94:95]
	v_mfma_f32_16x16x32_bf16 v[20:23], v[100:103], v[68:71], v[20:23]
	s_add_i32 m0, vcc_lo, 0x3800
	v_mfma_f32_16x16x32_bf16 v[32:35], v[100:103], v[72:75], v[32:35]
	global_load_lds_dwordx4 v[114:115], off
	v_lshl_add_u64 v[114:115], v[114:115], 0, s[94:95]
	v_mfma_f32_16x16x32_bf16 v[40:43], v[100:103], v[76:79], v[40:43]
	s_add_i32 m0, vcc_lo, 0x3c00
	v_mfma_f32_16x16x32_bf16 v[60:63], v[100:103], v[84:87], v[60:63]
	global_load_lds_dwordx4 v[116:117], off
	v_lshl_add_u64 v[116:117], v[116:117], 0, s[94:95]
	s_waitcnt vmcnt(8)
	ds_read_b128 v[68:71], v124
	ds_read_b128 v[72:75], v124 offset:1024
	ds_read_b128 v[76:79], v124 offset:2048
	ds_read_b128 v[84:87], v124 offset:3072
	ds_read_b128 v[88:91], v124 offset:4096
	ds_read_b128 v[92:95], v124 offset:5120
	ds_read_b128 v[96:99], v124 offset:6144
	ds_read_b128 v[100:103], v124 offset:7168
	s_waitcnt lgkmcnt(0)
	v_mfma_f32_16x16x32_bf16 v[56:59], v[88:91], v[68:71], v[56:59]
	s_add_i32 m0, vcc_lo, 0x0
	v_mfma_f32_16x16x32_bf16 v[52:55], v[88:91], v[72:75], v[52:55]
	global_load_lds_dwordx4 v[82:83], off
	v_lshl_add_u64 v[82:83], v[82:83], 0, s[94:95]
	v_mfma_f32_16x16x32_bf16 v[48:51], v[88:91], v[76:79], v[48:51]
	s_add_i32 m0, vcc_lo, 0x400
	v_mfma_f32_16x16x32_bf16 v[44:47], v[88:91], v[84:87], v[44:47]
	global_load_lds_dwordx4 v[104:105], off
	v_lshl_add_u64 v[104:105], v[104:105], 0, s[94:95]
	v_mfma_f32_16x16x32_bf16 v[12:15], v[92:95], v[68:71], v[12:15]
	s_add_i32 m0, vcc_lo, 0x800
	v_mfma_f32_16x16x32_bf16 v[8:11], v[92:95], v[72:75], v[8:11]
	global_load_lds_dwordx4 v[106:107], off
	v_lshl_add_u64 v[106:107], v[106:107], 0, s[94:95]
	v_mfma_f32_16x16x32_bf16 v[4:7], v[92:95], v[76:79], v[4:7]
	s_add_i32 m0, vcc_lo, 0xc00
	v_mfma_f32_16x16x32_bf16 v[0:3], v[92:95], v[84:87], v[0:3]
	global_load_lds_dwordx4 v[108:109], off
	v_lshl_add_u64 v[108:109], v[108:109], 0, s[94:95]
	v_mfma_f32_16x16x32_bf16 v[16:19], v[96:99], v[68:71], v[16:19]
	s_add_i32 m0, vcc_lo, 0x1000
	v_mfma_f32_16x16x32_bf16 v[24:27], v[96:99], v[72:75], v[24:27]
	global_load_lds_dwordx4 v[110:111], off
	v_lshl_add_u64 v[110:111], v[110:111], 0, s[94:95]
	v_mfma_f32_16x16x32_bf16 v[28:31], v[96:99], v[76:79], v[28:31]
	s_add_i32 m0, vcc_lo, 0x1400
	v_mfma_f32_16x16x32_bf16 v[36:39], v[96:99], v[84:87], v[36:39]
	global_load_lds_dwordx4 v[112:113], off
	v_lshl_add_u64 v[112:113], v[112:113], 0, s[94:95]
	v_mfma_f32_16x16x32_bf16 v[20:23], v[100:103], v[68:71], v[20:23]
	s_add_i32 m0, vcc_lo, 0x1800
	v_mfma_f32_16x16x32_bf16 v[32:35], v[100:103], v[72:75], v[32:35]
	global_load_lds_dwordx4 v[114:115], off
	v_lshl_add_u64 v[114:115], v[114:115], 0, s[94:95]
	v_mfma_f32_16x16x32_bf16 v[40:43], v[100:103], v[76:79], v[40:43]
	s_add_i32 m0, vcc_lo, 0x1c00
	v_mfma_f32_16x16x32_bf16 v[60:63], v[100:103], v[84:87], v[60:63]
	global_load_lds_dwordx4 v[116:117], off
	v_lshl_add_u64 v[116:117], v[116:117], 0, s[94:95]
	s_waitcnt vmcnt(8)
	ds_read_b128 v[68:71], v124 offset:8192
	ds_read_b128 v[72:75], v124 offset:9216
	ds_read_b128 v[76:79], v124 offset:10240
	ds_read_b128 v[84:87], v124 offset:11264
	ds_read_b128 v[88:91], v124 offset:12288
	ds_read_b128 v[92:95], v124 offset:13312
	ds_read_b128 v[96:99], v124 offset:14336
	ds_read_b128 v[100:103], v124 offset:15360
	s_waitcnt lgkmcnt(0)
	v_mfma_f32_16x16x32_bf16 v[56:59], v[88:91], v[68:71], v[56:59]
	s_add_i32 m0, vcc_lo, 0x2000
	v_mfma_f32_16x16x32_bf16 v[52:55], v[88:91], v[72:75], v[52:55]
	global_load_lds_dwordx4 v[82:83], off
	v_lshl_add_u64 v[82:83], v[82:83], 0, s[94:95]
	v_mfma_f32_16x16x32_bf16 v[48:51], v[88:91], v[76:79], v[48:51]
	s_add_i32 m0, vcc_lo, 0x2400
	v_mfma_f32_16x16x32_bf16 v[44:47], v[88:91], v[84:87], v[44:47]
	global_load_lds_dwordx4 v[104:105], off
	v_lshl_add_u64 v[104:105], v[104:105], 0, s[94:95]
	v_mfma_f32_16x16x32_bf16 v[12:15], v[92:95], v[68:71], v[12:15]
	s_add_i32 m0, vcc_lo, 0x2800
	v_mfma_f32_16x16x32_bf16 v[8:11], v[92:95], v[72:75], v[8:11]
	global_load_lds_dwordx4 v[106:107], off
	v_lshl_add_u64 v[106:107], v[106:107], 0, s[94:95]
	v_mfma_f32_16x16x32_bf16 v[4:7], v[92:95], v[76:79], v[4:7]
	s_add_i32 m0, vcc_lo, 0x2c00
	v_mfma_f32_16x16x32_bf16 v[0:3], v[92:95], v[84:87], v[0:3]
	global_load_lds_dwordx4 v[108:109], off
	v_lshl_add_u64 v[108:109], v[108:109], 0, s[94:95]
	v_mfma_f32_16x16x32_bf16 v[16:19], v[96:99], v[68:71], v[16:19]
	s_add_i32 m0, vcc_lo, 0x3000
	v_mfma_f32_16x16x32_bf16 v[24:27], v[96:99], v[72:75], v[24:27]
	global_load_lds_dwordx4 v[110:111], off
	v_lshl_add_u64 v[110:111], v[110:111], 0, s[94:95]
	v_mfma_f32_16x16x32_bf16 v[28:31], v[96:99], v[76:79], v[28:31]
	s_add_i32 m0, vcc_lo, 0x3400
	v_mfma_f32_16x16x32_bf16 v[36:39], v[96:99], v[84:87], v[36:39]
	global_load_lds_dwordx4 v[112:113], off
	v_lshl_add_u64 v[112:113], v[112:113], 0, s[94:95]
	v_mfma_f32_16x16x32_bf16 v[20:23], v[100:103], v[68:71], v[20:23]
	s_add_i32 m0, vcc_lo, 0x3800
	v_mfma_f32_16x16x32_bf16 v[32:35], v[100:103], v[72:75], v[32:35]
	global_load_lds_dwordx4 v[114:115], off
	v_lshl_add_u64 v[114:115], v[114:115], 0, s[94:95]
	v_mfma_f32_16x16x32_bf16 v[40:43], v[100:103], v[76:79], v[40:43]
	s_add_i32 m0, vcc_lo, 0x3c00
	v_mfma_f32_16x16x32_bf16 v[60:63], v[100:103], v[84:87], v[60:63]
	global_load_lds_dwordx4 v[116:117], off
	v_lshl_add_u64 v[116:117], v[116:117], 0, s[94:95]
	s_waitcnt vmcnt(8)
	ds_read_b128 v[68:71], v124
	ds_read_b128 v[72:75], v124 offset:1024
	ds_read_b128 v[76:79], v124 offset:2048
	ds_read_b128 v[84:87], v124 offset:3072
	ds_read_b128 v[88:91], v124 offset:4096
	ds_read_b128 v[92:95], v124 offset:5120
	ds_read_b128 v[96:99], v124 offset:6144
	ds_read_b128 v[100:103], v124 offset:7168
	s_waitcnt lgkmcnt(0)
	v_mfma_f32_16x16x32_bf16 v[56:59], v[88:91], v[68:71], v[56:59]
	v_mfma_f32_16x16x32_bf16 v[52:55], v[88:91], v[72:75], v[52:55]
	v_mfma_f32_16x16x32_bf16 v[48:51], v[88:91], v[76:79], v[48:51]
	v_mfma_f32_16x16x32_bf16 v[44:47], v[88:91], v[84:87], v[44:47]
	v_mfma_f32_16x16x32_bf16 v[12:15], v[92:95], v[68:71], v[12:15]
	v_mfma_f32_16x16x32_bf16 v[8:11], v[92:95], v[72:75], v[8:11]
	v_mfma_f32_16x16x32_bf16 v[4:7], v[92:95], v[76:79], v[4:7]
	v_mfma_f32_16x16x32_bf16 v[0:3], v[92:95], v[84:87], v[0:3]
	v_mfma_f32_16x16x32_bf16 v[16:19], v[96:99], v[68:71], v[16:19]
	v_mfma_f32_16x16x32_bf16 v[24:27], v[96:99], v[72:75], v[24:27]
	v_mfma_f32_16x16x32_bf16 v[28:31], v[96:99], v[76:79], v[28:31]
	v_mfma_f32_16x16x32_bf16 v[36:39], v[96:99], v[84:87], v[36:39]
	v_mfma_f32_16x16x32_bf16 v[20:23], v[100:103], v[68:71], v[20:23]
	v_mfma_f32_16x16x32_bf16 v[32:35], v[100:103], v[72:75], v[32:35]
	v_mfma_f32_16x16x32_bf16 v[40:43], v[100:103], v[76:79], v[40:43]
	v_mfma_f32_16x16x32_bf16 v[60:63], v[100:103], v[84:87], v[60:63]
	s_waitcnt vmcnt(0)
	ds_read_b128 v[68:71], v124 offset:8192
	ds_read_b128 v[72:75], v124 offset:9216
	ds_read_b128 v[76:79], v124 offset:10240
	ds_read_b128 v[84:87], v124 offset:11264
	ds_read_b128 v[88:91], v124 offset:12288
	ds_read_b128 v[92:95], v124 offset:13312
	ds_read_b128 v[96:99], v124 offset:14336
	ds_read_b128 v[100:103], v124 offset:15360
	s_waitcnt lgkmcnt(0)
	v_mfma_f32_16x16x32_bf16 v[56:59], v[88:91], v[68:71], v[56:59]
	v_mfma_f32_16x16x32_bf16 v[52:55], v[88:91], v[72:75], v[52:55]
	v_mfma_f32_16x16x32_bf16 v[48:51], v[88:91], v[76:79], v[48:51]
	v_mfma_f32_16x16x32_bf16 v[44:47], v[88:91], v[84:87], v[44:47]
	v_mfma_f32_16x16x32_bf16 v[12:15], v[92:95], v[68:71], v[12:15]
	v_mfma_f32_16x16x32_bf16 v[8:11], v[92:95], v[72:75], v[8:11]
	v_mfma_f32_16x16x32_bf16 v[4:7], v[92:95], v[76:79], v[4:7]
	v_mfma_f32_16x16x32_bf16 v[0:3], v[92:95], v[84:87], v[0:3]
	v_mfma_f32_16x16x32_bf16 v[16:19], v[96:99], v[68:71], v[16:19]
	v_mfma_f32_16x16x32_bf16 v[24:27], v[96:99], v[72:75], v[24:27]
	v_mfma_f32_16x16x32_bf16 v[28:31], v[96:99], v[76:79], v[28:31]
	v_mfma_f32_16x16x32_bf16 v[36:39], v[96:99], v[84:87], v[36:39]
	v_mfma_f32_16x16x32_bf16 v[20:23], v[100:103], v[68:71], v[20:23]
	v_mfma_f32_16x16x32_bf16 v[32:35], v[100:103], v[72:75], v[32:35]
	v_mfma_f32_16x16x32_bf16 v[40:43], v[100:103], v[76:79], v[40:43]
	v_mfma_f32_16x16x32_bf16 v[60:63], v[100:103], v[84:87], v[60:63]
	s_nop 7
	s_nop 3
	v_and_b32_e32 v65, 63, v81
	s_ashr_i32 s4, s3, 7
	v_lshl_add_u32 v65, v65, 4, 0
	s_lshl_b32 s5, s4, 4
	v_lshl_add_u32 v66, s14, 14, v65
	s_addk_i32 s5, 0x4000
	ds_write_b128 v66, v[56:59]
	ds_write_b128 v66, v[52:55] offset:1024
	ds_write_b128 v66, v[48:51] offset:2048
	ds_write_b128 v66, v[44:47] offset:3072
	ds_write_b128 v66, v[12:15] offset:4096
	ds_write_b128 v66, v[8:11] offset:5120
	ds_write_b128 v66, v[4:7] offset:6144
	ds_write_b128 v66, v[0:3] offset:7168
	ds_write_b128 v66, v[16:19] offset:8192
	ds_write_b128 v66, v[24:27] offset:9216
	ds_write_b128 v66, v[28:31] offset:10240
	ds_write_b128 v66, v[36:39] offset:11264
	ds_write_b128 v66, v[20:23] offset:12288
	ds_write_b128 v66, v[32:35] offset:13312
	ds_write_b128 v66, v[40:43] offset:14336
	ds_write_b128 v66, v[60:63] offset:15360
	v_or_b32_e32 v0, s5, v80
	v_ashrrev_i32_e32 v1, 31, v0
	v_bfe_u32 v64, v81, 4, 2
	v_lshlrev_b64 v[2:3], 7, v[0:1]
	v_lshl_add_u64 v[2:3], s[10:11], 0, v[2:3]
	v_lshlrev_b32_e32 v128, 5, v64
	v_lshl_add_u64 v[6:7], v[2:3], 0, v[128:129]
	s_waitcnt lgkmcnt(0)
	s_barrier
	global_load_dwordx4 v[2:5], v[6:7], off
	s_nop 0
	global_load_dwordx4 v[6:9], v[6:7], off offset:16
	s_bfe_u32 s3, s3, 0x10006
	s_lshl_b32 s5, s3, 2
	s_add_i32 s5, s5, s4
	v_lshl_add_u32 v62, s5, 10, v65
	ds_read_b128 v[10:13], v62
	ds_read_b128 v[14:17], v62 offset:8192
	ds_read_b128 v[18:21], v62 offset:16384
	ds_read_b128 v[22:25], v62 offset:24576
	ds_read_b128 v[26:29], v62 offset:32768
	ds_read_b128 v[30:33], v62 offset:40960
	ds_read_b128 v[34:37], v62 offset:49152
	ds_read_b128 v[38:41], v62 offset:57344
	s_waitcnt lgkmcnt(0)
	v_pk_add_f32 v[10:11], v[10:11], 0 op_sel_hi:[1,0]
	v_add_u32_e32 v42, 0x10000, v62
	v_add_u32_e32 v46, 0x12000, v62
	v_add_u32_e32 v50, 0x14000, v62
	v_add_u32_e32 v54, 0x16000, v62
	v_add_u32_e32 v58, 0x18000, v62
	v_pk_add_f32 v[10:11], v[10:11], v[18:19]
	v_add_u32_e32 v63, 0x1a000, v62
	ds_read_b128 v[42:45], v42
	ds_read_b128 v[46:49], v46
	ds_read_b128 v[50:53], v50
	ds_read_b128 v[54:57], v54
	ds_read_b128 v[58:61], v58
	ds_read_b128 v[66:69], v63
	v_pk_add_f32 v[10:11], v[10:11], v[26:27]
	v_pk_add_f32 v[12:13], v[12:13], 0 op_sel_hi:[1,0]
	v_pk_add_f32 v[10:11], v[10:11], v[34:35]
	v_pk_add_f32 v[12:13], v[12:13], v[20:21]
	s_waitcnt lgkmcnt(0)
	v_pk_add_f32 v[10:11], v[10:11], v[42:43]
	v_pk_add_f32 v[14:15], v[14:15], 0 op_sel_hi:[1,0]
	v_pk_add_f32 v[10:11], v[10:11], v[50:51]
	v_pk_add_f32 v[14:15], v[14:15], v[22:23]
	v_pk_add_f32 v[20:21], v[10:11], v[58:59]
	v_pk_add_f32 v[12:13], v[12:13], v[28:29]
	v_pk_add_f32 v[14:15], v[14:15], v[30:31]
	v_pk_add_f32 v[12:13], v[12:13], v[36:37]
	v_pk_add_f32 v[14:15], v[14:15], v[38:39]
	v_pk_add_f32 v[12:13], v[12:13], v[44:45]
	v_pk_add_f32 v[14:15], v[14:15], v[46:47]
	v_pk_add_f32 v[12:13], v[12:13], v[52:53]
	v_pk_add_f32 v[14:15], v[14:15], v[54:55]
	v_pk_add_f32 v[18:19], v[12:13], v[60:61]
	v_pk_add_f32 v[14:15], v[14:15], v[66:67]
	v_pk_add_f32 v[16:17], v[16:17], 0 op_sel_hi:[1,0]
	s_mov_b64 s[4:5], -1
	v_pk_add_f32 v[16:17], v[16:17], v[24:25]
	s_cmp_gt_i32 s0, 7
	v_pk_add_f32 v[16:17], v[16:17], v[32:33]
	v_lshlrev_b64 v[0:1], 12, v[0:1]
	v_pk_add_f32 v[16:17], v[16:17], v[40:41]
	s_waitcnt vmcnt(0)
	v_mov_b32_e32 v10, v2
	v_mov_b32_e32 v11, v6
	v_mov_b32_e32 v6, v3
	v_pk_add_f32 v[2:3], v[10:11], v[6:7]
	v_mov_b32_e32 v6, v4
	v_mov_b32_e32 v7, v8
	v_mov_b32_e32 v8, v5
	v_pk_add_f32 v[4:5], v[6:7], v[8:9]
	v_add_u32_e32 v9, 0x1e000, v62
	v_pk_add_f32 v[2:3], v[2:3], v[4:5]
	v_pk_add_f32 v[16:17], v[16:17], v[48:49]
	v_add_f32_e32 v6, v2, v3
	v_and_b32_e32 v3, 64, v214
	v_xor_b32_e32 v2, 16, v214
	v_add_u32_e32 v7, 64, v3
	v_cmp_lt_i32_e32 vcc, v2, v7
	v_pk_add_f32 v[16:17], v[16:17], v[56:57]
	s_nop 0
	v_cndmask_b32_e32 v2, v214, v2, vcc
	v_lshlrev_b32_e32 v2, 2, v2
	ds_bpermute_b32 v8, v2, v6
	v_add_u32_e32 v2, 0x1c000, v62
	ds_read_b128 v[2:5], v2
	ds_read_b128 v[10:13], v9
	v_pk_add_f32 v[16:17], v[16:17], v[68:69]
	s_waitcnt lgkmcnt(2)
	v_add_f32_e32 v22, v6, v8
	v_xor_b32_e32 v6, 32, v214
	v_cmp_lt_i32_e32 vcc, v6, v7
	s_waitcnt lgkmcnt(1)
	v_pk_add_f32 v[8:9], v[20:21], v[2:3]
	s_waitcnt lgkmcnt(0)
	v_pk_add_f32 v[2:3], v[16:17], v[12:13]
	v_cndmask_b32_e32 v6, v214, v6, vcc
	v_lshlrev_b32_e32 v6, 2, v6
	ds_bpermute_b32 v23, v6, v22
	v_pk_add_f32 v[6:7], v[18:19], v[4:5]
	v_pk_add_f32 v[4:5], v[14:15], v[10:11]
	s_waitcnt lgkmcnt(0)
	v_add_f32_e32 v10, v22, v23
	v_fmamk_f32 v10, v10, 0x3a000000, v190
	v_mul_f32_e32 v11, 0x4b800000, v10
	v_cmp_gt_f32_e32 vcc, s70, v10
	s_nop 1
	v_cndmask_b32_e32 v10, v10, v11, vcc
	v_rsq_f32_e32 v10, v10
	v_lshlrev_b32_e32 v11, 2, v64
	v_lshl_or_b32 v11, s3, 4, v11
	v_or_b32_e32 v11, s1, v11
	v_mul_f32_e32 v12, 0x45800000, v10
	v_cndmask_b32_e32 v10, v10, v12, vcc
	v_lshlrev_b32_e32 v128, 1, v11
	s_cbranch_scc0 .LBB0_887
	v_pk_mul_f32 v[12:13], v[6:7], v[2:3]
	v_pk_mul_f32 v[14:15], v[8:9], v[4:5]
	v_mul_f32_e32 v16, v10, v10
	v_pk_mul_f32 v[12:13], v[12:13], v[16:17] op_sel_hi:[1,0]
	v_pk_mul_f32 v[14:15], v[14:15], v[16:17] op_sel_hi:[1,0]
	s_mov_b32 s3, s95
	v_cvt_pk_bf16_f32 v14, v14, v15
	v_cvt_pk_bf16_f32 v15, v12, v13
	v_lshl_add_u64 v[12:13], s[8:9], 0, v[0:1]
	v_lshl_add_u64 v[12:13], v[12:13], 0, s[2:3]
	v_lshl_add_u64 v[12:13], v[12:13], 0, v[128:129]
	v_add_co_u32_e32 v12, vcc, 0xfffff800, v12
	s_mov_b64 s[4:5], 0
	s_nop 0
	v_addc_co_u32_e32 v13, vcc, -1, v13, vcc
	global_store_dwordx2 v[12:13], v[14:15], off

.LBB0_1031:
	v_lshrrev_b32_e32 v122, 2, v214
	v_and_b32_e32 v123, 15, v214
	v_sub_u32_e32 v122, v122, v123
	v_mul_i32_i24_e32 v122, 0x1000, v122
	v_bfe_u32 v125, v214, 5, 1
	v_lshlrev_b32_e32 v125, 1, v125
	v_and_b32_e32 v124, 3, v214
	v_xor_b32_e32 v125, v125, v124
	v_lshrrev_b32_e32 v124, 4, v214
	v_sub_u32_e32 v125, v125, v124
	v_lshl_add_u32 v122, v125, 4, v122
	v_ashrrev_i32_e32 v125, 31, v122
	v_add_co_u32_e32 v118, vcc, v66, v122
	s_nop 1
	v_addc_co_u32_e32 v119, vcc, v67, v125, vcc
	v_add_co_u32_e32 v120, vcc, v64, v122
	s_nop 1
	v_addc_co_u32_e32 v121, vcc, v65, v125, vcc
	v_add_co_u32_e32 v82, vcc, 0x3b1d0000, v118
	s_nop 1
	v_addc_co_u32_e32 v83, vcc, 0, v119, vcc
	v_add_co_u32_e32 v104, vcc, 0x3b1e0000, v118
	s_nop 1
	v_addc_co_u32_e32 v105, vcc, 0, v119, vcc
	v_add_co_u32_e32 v106, vcc, 0x3b1f0000, v118
	s_nop 1
	v_addc_co_u32_e32 v107, vcc, 0, v119, vcc
	v_add_co_u32_e32 v108, vcc, 0x3b200000, v118
	s_nop 1
	v_addc_co_u32_e32 v109, vcc, 0, v119, vcc
	v_add_co_u32_e32 v110, vcc, 0x3008000, v120
	s_nop 1
	v_addc_co_u32_e32 v111, vcc, 0, v121, vcc
	v_add_co_u32_e32 v112, vcc, 0x3018000, v120
	s_nop 1
	v_addc_co_u32_e32 v113, vcc, 0, v121, vcc
	v_add_co_u32_e32 v114, vcc, 0x3088000, v120
	s_nop 1
	v_addc_co_u32_e32 v115, vcc, 0, v121, vcc
	v_add_co_u32_e32 v116, vcc, 0x3098000, v120
	s_nop 1
	v_addc_co_u32_e32 v117, vcc, 0, v121, vcc
	v_readfirstlane_b32 vcc_lo, v210
	v_bfe_u32 v125, v214, 3, 1
	v_lshlrev_b32_e32 v125, 1, v125
	v_xor_b32_e32 v125, v125, v124
	v_lshlrev_b32_e32 v125, 4, v125
	v_lshl_add_u32 v125, v123, 6, v125
	s_lshr_b32 vcc_lo, vcc_lo, 6
	s_lshl_b32 vcc_lo, vcc_lo, 14
	s_mov_b32 s94, 64
	v_add_u32_e32 v124, vcc_lo, v125
	s_add_i32 m0, vcc_lo, 0x0
	s_nop 0
	global_load_lds_dwordx4 v[82:83], off
	v_lshl_add_u64 v[82:83], v[82:83], 0, s[94:95]
	s_add_i32 m0, vcc_lo, 0x400
	s_nop 0
	global_load_lds_dwordx4 v[104:105], off
	v_lshl_add_u64 v[104:105], v[104:105], 0, s[94:95]
	s_add_i32 m0, vcc_lo, 0x800
	s_nop 0
	global_load_lds_dwordx4 v[106:107], off
	v_lshl_add_u64 v[106:107], v[106:107], 0, s[94:95]
	s_add_i32 m0, vcc_lo, 0xc00
	s_nop 0
	global_load_lds_dwordx4 v[108:109], off
	v_lshl_add_u64 v[108:109], v[108:109], 0, s[94:95]
	s_add_i32 m0, vcc_lo, 0x1000
	s_nop 0
	global_load_lds_dwordx4 v[110:111], off
	v_lshl_add_u64 v[110:111], v[110:111], 0, s[94:95]
	s_add_i32 m0, vcc_lo, 0x1400
	s_nop 0
	global_load_lds_dwordx4 v[112:113], off
	v_lshl_add_u64 v[112:113], v[112:113], 0, s[94:95]
	s_add_i32 m0, vcc_lo, 0x1800
	s_nop 0
	global_load_lds_dwordx4 v[114:115], off
	v_lshl_add_u64 v[114:115], v[114:115], 0, s[94:95]
	s_add_i32 m0, vcc_lo, 0x1c00
	s_nop 0
	global_load_lds_dwordx4 v[116:117], off
	v_lshl_add_u64 v[116:117], v[116:117], 0, s[94:95]
	s_add_i32 m0, vcc_lo, 0x2000
	s_nop 0
	global_load_lds_dwordx4 v[82:83], off
	v_lshl_add_u64 v[82:83], v[82:83], 0, s[94:95]
	s_add_i32 m0, vcc_lo, 0x2400
	s_nop 0
	global_load_lds_dwordx4 v[104:105], off
	v_lshl_add_u64 v[104:105], v[104:105], 0, s[94:95]
	s_add_i32 m0, vcc_lo, 0x2800
	s_nop 0
	global_load_lds_dwordx4 v[106:107], off
	v_lshl_add_u64 v[106:107], v[106:107], 0, s[94:95]
	s_add_i32 m0, vcc_lo, 0x2c00
	s_nop 0
	global_load_lds_dwordx4 v[108:109], off
	v_lshl_add_u64 v[108:109], v[108:109], 0, s[94:95]
	s_add_i32 m0, vcc_lo, 0x3000
	s_nop 0
	global_load_lds_dwordx4 v[110:111], off
	v_lshl_add_u64 v[110:111], v[110:111], 0, s[94:95]
	s_add_i32 m0, vcc_lo, 0x3400
	s_nop 0
	global_load_lds_dwordx4 v[112:113], off
	v_lshl_add_u64 v[112:113], v[112:113], 0, s[94:95]
	s_add_i32 m0, vcc_lo, 0x3800
	s_nop 0
	global_load_lds_dwordx4 v[114:115], off
	v_lshl_add_u64 v[114:115], v[114:115], 0, s[94:95]
	s_add_i32 m0, vcc_lo, 0x3c00
	s_nop 0
	global_load_lds_dwordx4 v[116:117], off
	v_lshl_add_u64 v[116:117], v[116:117], 0, s[94:95]
	s_waitcnt vmcnt(8)
	ds_read_b128 v[68:71], v124
	ds_read_b128 v[72:75], v124 offset:1024
	ds_read_b128 v[76:79], v124 offset:2048
	ds_read_b128 v[84:87], v124 offset:3072
	ds_read_b128 v[88:91], v124 offset:4096
	ds_read_b128 v[92:95], v124 offset:5120
	ds_read_b128 v[96:99], v124 offset:6144
	ds_read_b128 v[100:103], v124 offset:7168
	s_waitcnt lgkmcnt(0)
	v_mfma_f32_16x16x32_bf16 v[56:59], v[88:91], v[68:71], 0
	s_add_i32 m0, vcc_lo, 0x0
	v_mfma_f32_16x16x32_bf16 v[52:55], v[88:91], v[72:75], 0
	global_load_lds_dwordx4 v[82:83], off
	v_lshl_add_u64 v[82:83], v[82:83], 0, s[94:95]
	v_mfma_f32_16x16x32_bf16 v[48:51], v[88:91], v[76:79], 0
	s_add_i32 m0, vcc_lo, 0x400
	v_mfma_f32_16x16x32_bf16 v[44:47], v[88:91], v[84:87], 0
	global_load_lds_dwordx4 v[104:105], off
	v_lshl_add_u64 v[104:105], v[104:105], 0, s[94:95]
	v_mfma_f32_16x16x32_bf16 v[12:15], v[92:95], v[68:71], 0
	s_add_i32 m0, vcc_lo, 0x800
	v_mfma_f32_16x16x32_bf16 v[8:11], v[92:95], v[72:75], 0
	global_load_lds_dwordx4 v[106:107], off
	v_lshl_add_u64 v[106:107], v[106:107], 0, s[94:95]
	v_mfma_f32_16x16x32_bf16 v[4:7], v[92:95], v[76:79], 0
	s_add_i32 m0, vcc_lo, 0xc00
	v_mfma_f32_16x16x32_bf16 v[0:3], v[92:95], v[84:87], 0
	global_load_lds_dwordx4 v[108:109], off
	v_lshl_add_u64 v[108:109], v[108:109], 0, s[94:95]
	v_mfma_f32_16x16x32_bf16 v[16:19], v[96:99], v[68:71], 0
	s_add_i32 m0, vcc_lo, 0x1000
	v_mfma_f32_16x16x32_bf16 v[24:27], v[96:99], v[72:75], 0
	global_load_lds_dwordx4 v[110:111], off
	v_lshl_add_u64 v[110:111], v[110:111], 0, s[94:95]
	v_mfma_f32_16x16x32_bf16 v[28:31], v[96:99], v[76:79], 0
	s_add_i32 m0, vcc_lo, 0x1400
	v_mfma_f32_16x16x32_bf16 v[36:39], v[96:99], v[84:87], 0
	global_load_lds_dwordx4 v[112:113], off
	v_lshl_add_u64 v[112:113], v[112:113], 0, s[94:95]
	v_mfma_f32_16x16x32_bf16 v[20:23], v[100:103], v[68:71], 0
	s_add_i32 m0, vcc_lo, 0x1800
	v_mfma_f32_16x16x32_bf16 v[32:35], v[100:103], v[72:75], 0
	global_load_lds_dwordx4 v[114:115], off
	v_lshl_add_u64 v[114:115], v[114:115], 0, s[94:95]
	v_mfma_f32_16x16x32_bf16 v[40:43], v[100:103], v[76:79], 0
	s_add_i32 m0, vcc_lo, 0x1c00
	v_mfma_f32_16x16x32_bf16 v[60:63], v[100:103], v[84:87], 0
	global_load_lds_dwordx4 v[116:117], off
	v_lshl_add_u64 v[116:117], v[116:117], 0, s[94:95]
	s_waitcnt vmcnt(8)
	ds_read_b128 v[68:71], v124 offset:8192
	ds_read_b128 v[72:75], v124 offset:9216
	ds_read_b128 v[76:79], v124 offset:10240
	ds_read_b128 v[84:87], v124 offset:11264
	ds_read_b128 v[88:91], v124 offset:12288
	ds_read_b128 v[92:95], v124 offset:13312
	ds_read_b128 v[96:99], v124 offset:14336
	ds_read_b128 v[100:103], v124 offset:15360
	s_waitcnt lgkmcnt(0)
	v_mfma_f32_16x16x32_bf16 v[56:59], v[88:91], v[68:71], v[56:59]
	s_add_i32 m0, vcc_lo, 0x2000
	v_mfma_f32_16x16x32_bf16 v[52:55], v[88:91], v[72:75], v[52:55]
	global_load_lds_dwordx4 v[82:83], off
	v_lshl_add_u64 v[82:83], v[82:83], 0, s[94:95]
	v_mfma_f32_16x16x32_bf16 v[48:51], v[88:91], v[76:79], v[48:51]
	s_add_i32 m0, vcc_lo, 0x2400
	v_mfma_f32_16x16x32_bf16 v[44:47], v[88:91], v[84:87], v[44:47]
	global_load_lds_dwordx4 v[104:105], off
	v_lshl_add_u64 v[104:105], v[104:105], 0, s[94:95]
	v_mfma_f32_16x16x32_bf16 v[12:15], v[92:95], v[68:71], v[12:15]
	s_add_i32 m0, vcc_lo, 0x2800
	v_mfma_f32_16x16x32_bf16 v[8:11], v[92:95], v[72:75], v[8:11]
	global_load_lds_dwordx4 v[106:107], off
	v_lshl_add_u64 v[106:107], v[106:107], 0, s[94:95]
	v_mfma_f32_16x16x32_bf16 v[4:7], v[92:95], v[76:79], v[4:7]
	s_add_i32 m0, vcc_lo, 0x2c00
	v_mfma_f32_16x16x32_bf16 v[0:3], v[92:95], v[84:87], v[0:3]
	global_load_lds_dwordx4 v[108:109], off
	v_lshl_add_u64 v[108:109], v[108:109], 0, s[94:95]
	v_mfma_f32_16x16x32_bf16 v[16:19], v[96:99], v[68:71], v[16:19]
	s_add_i32 m0, vcc_lo, 0x3000
	v_mfma_f32_16x16x32_bf16 v[24:27], v[96:99], v[72:75], v[24:27]
	global_load_lds_dwordx4 v[110:111], off
	v_lshl_add_u64 v[110:111], v[110:111], 0, s[94:95]
	v_mfma_f32_16x16x32_bf16 v[28:31], v[96:99], v[76:79], v[28:31]
	s_add_i32 m0, vcc_lo, 0x3400
	v_mfma_f32_16x16x32_bf16 v[36:39], v[96:99], v[84:87], v[36:39]
	global_load_lds_dwordx4 v[112:113], off
	v_lshl_add_u64 v[112:113], v[112:113], 0, s[94:95]
	v_mfma_f32_16x16x32_bf16 v[20:23], v[100:103], v[68:71], v[20:23]
	s_add_i32 m0, vcc_lo, 0x3800
	v_mfma_f32_16x16x32_bf16 v[32:35], v[100:103], v[72:75], v[32:35]
	global_load_lds_dwordx4 v[114:115], off
	v_lshl_add_u64 v[114:115], v[114:115], 0, s[94:95]
	v_mfma_f32_16x16x32_bf16 v[40:43], v[100:103], v[76:79], v[40:43]
	s_add_i32 m0, vcc_lo, 0x3c00
	v_mfma_f32_16x16x32_bf16 v[60:63], v[100:103], v[84:87], v[60:63]
	global_load_lds_dwordx4 v[116:117], off
	v_lshl_add_u64 v[116:117], v[116:117], 0, s[94:95]
	s_waitcnt vmcnt(8)
	ds_read_b128 v[68:71], v124
	ds_read_b128 v[72:75], v124 offset:1024
	ds_read_b128 v[76:79], v124 offset:2048
	ds_read_b128 v[84:87], v124 offset:3072
	ds_read_b128 v[88:91], v124 offset:4096
	ds_read_b128 v[92:95], v124 offset:5120
	ds_read_b128 v[96:99], v124 offset:6144
	ds_read_b128 v[100:103], v124 offset:7168
	s_waitcnt lgkmcnt(0)
	v_mfma_f32_16x16x32_bf16 v[56:59], v[88:91], v[68:71], v[56:59]
	s_add_i32 m0, vcc_lo, 0x0
	v_mfma_f32_16x16x32_bf16 v[52:55], v[88:91], v[72:75], v[52:55]
	global_load_lds_dwordx4 v[82:83], off
	v_lshl_add_u64 v[82:83], v[82:83], 0, s[94:95]
	v_mfma_f32_16x16x32_bf16 v[48:51], v[88:91], v[76:79], v[48:51]
	s_add_i32 m0, vcc_lo, 0x400
	v_mfma_f32_16x16x32_bf16 v[44:47], v[88:91], v[84:87], v[44:47]
	global_load_lds_dwordx4 v[104:105], off
	v_lshl_add_u64 v[104:105], v[104:105], 0, s[94:95]
	v_mfma_f32_16x16x32_bf16 v[12:15], v[92:95], v[68:71], v[12:15]
	s_add_i32 m0, vcc_lo, 0x800
	v_mfma_f32_16x16x32_bf16 v[8:11], v[92:95], v[72:75], v[8:11]
	global_load_lds_dwordx4 v[106:107], off
	v_lshl_add_u64 v[106:107], v[106:107], 0, s[94:95]
	v_mfma_f32_16x16x32_bf16 v[4:7], v[92:95], v[76:79], v[4:7]
	s_add_i32 m0, vcc_lo, 0xc00
	v_mfma_f32_16x16x32_bf16 v[0:3], v[92:95], v[84:87], v[0:3]
	global_load_lds_dwordx4 v[108:109], off
	v_lshl_add_u64 v[108:109], v[108:109], 0, s[94:95]
	v_mfma_f32_16x16x32_bf16 v[16:19], v[96:99], v[68:71], v[16:19]
	s_add_i32 m0, vcc_lo, 0x1000
	v_mfma_f32_16x16x32_bf16 v[24:27], v[96:99], v[72:75], v[24:27]
	global_load_lds_dwordx4 v[110:111], off
	v_lshl_add_u64 v[110:111], v[110:111], 0, s[94:95]
	v_mfma_f32_16x16x32_bf16 v[28:31], v[96:99], v[76:79], v[28:31]
	s_add_i32 m0, vcc_lo, 0x1400
	v_mfma_f32_16x16x32_bf16 v[36:39], v[96:99], v[84:87], v[36:39]
	global_load_lds_dwordx4 v[112:113], off
	v_lshl_add_u64 v[112:113], v[112:113], 0, s[94:95]
	v_mfma_f32_16x16x32_bf16 v[20:23], v[100:103], v[68:71], v[20:23]
	s_add_i32 m0, vcc_lo, 0x1800
	v_mfma_f32_16x16x32_bf16 v[32:35], v[100:103], v[72:75], v[32:35]
	global_load_lds_dwordx4 v[114:115], off
	v_lshl_add_u64 v[114:115], v[114:115], 0, s[94:95]
	v_mfma_f32_16x16x32_bf16 v[40:43], v[100:103], v[76:79], v[40:43]
	s_add_i32 m0, vcc_lo, 0x1c00
	v_mfma_f32_16x16x32_bf16 v[60:63], v[100:103], v[84:87], v[60:63]
	global_load_lds_dwordx4 v[116:117], off
	v_lshl_add_u64 v[116:117], v[116:117], 0, s[94:95]
	s_waitcnt vmcnt(8)
	ds_read_b128 v[68:71], v124 offset:8192
	ds_read_b128 v[72:75], v124 offset:9216
	ds_read_b128 v[76:79], v124 offset:10240
	ds_read_b128 v[84:87], v124 offset:11264
	ds_read_b128 v[88:91], v124 offset:12288
	ds_read_b128 v[92:95], v124 offset:13312
	ds_read_b128 v[96:99], v124 offset:14336
	ds_read_b128 v[100:103], v124 offset:15360
	s_waitcnt lgkmcnt(0)
	v_mfma_f32_16x16x32_bf16 v[56:59], v[88:91], v[68:71], v[56:59]
	s_add_i32 m0, vcc_lo, 0x2000
	v_mfma_f32_16x16x32_bf16 v[52:55], v[88:91], v[72:75], v[52:55]
	global_load_lds_dwordx4 v[82:83], off
	v_lshl_add_u64 v[82:83], v[82:83], 0, s[94:95]
	v_mfma_f32_16x16x32_bf16 v[48:51], v[88:91], v[76:79], v[48:51]
	s_add_i32 m0, vcc_lo, 0x2400
	v_mfma_f32_16x16x32_bf16 v[44:47], v[88:91], v[84:87], v[44:47]
	global_load_lds_dwordx4 v[104:105], off
	v_lshl_add_u64 v[104:105], v[104:105], 0, s[94:95]
	v_mfma_f32_16x16x32_bf16 v[12:15], v[92:95], v[68:71], v[12:15]
	s_add_i32 m0, vcc_lo, 0x2800
	v_mfma_f32_16x16x32_bf16 v[8:11], v[92:95], v[72:75], v[8:11]
	global_load_lds_dwordx4 v[106:107], off
	v_lshl_add_u64 v[106:107], v[106:107], 0, s[94:95]
	v_mfma_f32_16x16x32_bf16 v[4:7], v[92:95], v[76:79], v[4:7]
	s_add_i32 m0, vcc_lo, 0x2c00
	v_mfma_f32_16x16x32_bf16 v[0:3], v[92:95], v[84:87], v[0:3]
	global_load_lds_dwordx4 v[108:109], off
	v_lshl_add_u64 v[108:109], v[108:109], 0, s[94:95]
	v_mfma_f32_16x16x32_bf16 v[16:19], v[96:99], v[68:71], v[16:19]
	s_add_i32 m0, vcc_lo, 0x3000
	v_mfma_f32_16x16x32_bf16 v[24:27], v[96:99], v[72:75], v[24:27]
	global_load_lds_dwordx4 v[110:111], off
	v_lshl_add_u64 v[110:111], v[110:111], 0, s[94:95]
	v_mfma_f32_16x16x32_bf16 v[28:31], v[96:99], v[76:79], v[28:31]
	s_add_i32 m0, vcc_lo, 0x3400
	v_mfma_f32_16x16x32_bf16 v[36:39], v[96:99], v[84:87], v[36:39]
	global_load_lds_dwordx4 v[112:113], off
	v_lshl_add_u64 v[112:113], v[112:113], 0, s[94:95]
	v_mfma_f32_16x16x32_bf16 v[20:23], v[100:103], v[68:71], v[20:23]
	s_add_i32 m0, vcc_lo, 0x3800
	v_mfma_f32_16x16x32_bf16 v[32:35], v[100:103], v[72:75], v[32:35]
	global_load_lds_dwordx4 v[114:115], off
	v_lshl_add_u64 v[114:115], v[114:115], 0, s[94:95]
	v_mfma_f32_16x16x32_bf16 v[40:43], v[100:103], v[76:79], v[40:43]
	s_add_i32 m0, vcc_lo, 0x3c00
	v_mfma_f32_16x16x32_bf16 v[60:63], v[100:103], v[84:87], v[60:63]
	global_load_lds_dwordx4 v[116:117], off
	v_lshl_add_u64 v[116:117], v[116:117], 0, s[94:95]
	s_waitcnt vmcnt(8)
	ds_read_b128 v[68:71], v124
	ds_read_b128 v[72:75], v124 offset:1024
	ds_read_b128 v[76:79], v124 offset:2048
	ds_read_b128 v[84:87], v124 offset:3072
	ds_read_b128 v[88:91], v124 offset:4096
	ds_read_b128 v[92:95], v124 offset:5120
	ds_read_b128 v[96:99], v124 offset:6144
	ds_read_b128 v[100:103], v124 offset:7168
	s_waitcnt lgkmcnt(0)
	v_mfma_f32_16x16x32_bf16 v[56:59], v[88:91], v[68:71], v[56:59]
	s_add_i32 m0, vcc_lo, 0x0
	v_mfma_f32_16x16x32_bf16 v[52:55], v[88:91], v[72:75], v[52:55]
	global_load_lds_dwordx4 v[82:83], off
	v_lshl_add_u64 v[82:83], v[82:83], 0, s[94:95]
	v_mfma_f32_16x16x32_bf16 v[48:51], v[88:91], v[76:79], v[48:51]
	s_add_i32 m0, vcc_lo, 0x400
	v_mfma_f32_16x16x32_bf16 v[44:47], v[88:91], v[84:87], v[44:47]
	global_load_lds_dwordx4 v[104:105], off
	v_lshl_add_u64 v[104:105], v[104:105], 0, s[94:95]
	v_mfma_f32_16x16x32_bf16 v[12:15], v[92:95], v[68:71], v[12:15]
	s_add_i32 m0, vcc_lo, 0x800
	v_mfma_f32_16x16x32_bf16 v[8:11], v[92:95], v[72:75], v[8:11]
	global_load_lds_dwordx4 v[106:107], off
	v_lshl_add_u64 v[106:107], v[106:107], 0, s[94:95]
	v_mfma_f32_16x16x32_bf16 v[4:7], v[92:95], v[76:79], v[4:7]
	s_add_i32 m0, vcc_lo, 0xc00
	v_mfma_f32_16x16x32_bf16 v[0:3], v[92:95], v[84:87], v[0:3]
	global_load_lds_dwordx4 v[108:109], off
	v_lshl_add_u64 v[108:109], v[108:109], 0, s[94:95]
	v_mfma_f32_16x16x32_bf16 v[16:19], v[96:99], v[68:71], v[16:19]
	s_add_i32 m0, vcc_lo, 0x1000
	v_mfma_f32_16x16x32_bf16 v[24:27], v[96:99], v[72:75], v[24:27]
	global_load_lds_dwordx4 v[110:111], off
	v_lshl_add_u64 v[110:111], v[110:111], 0, s[94:95]
	v_mfma_f32_16x16x32_bf16 v[28:31], v[96:99], v[76:79], v[28:31]
	s_add_i32 m0, vcc_lo, 0x1400
	v_mfma_f32_16x16x32_bf16 v[36:39], v[96:99], v[84:87], v[36:39]
	global_load_lds_dwordx4 v[112:113], off
	v_lshl_add_u64 v[112:113], v[112:113], 0, s[94:95]
	v_mfma_f32_16x16x32_bf16 v[20:23], v[100:103], v[68:71], v[20:23]
	s_add_i32 m0, vcc_lo, 0x1800
	v_mfma_f32_16x16x32_bf16 v[32:35], v[100:103], v[72:75], v[32:35]
	global_load_lds_dwordx4 v[114:115], off
	v_lshl_add_u64 v[114:115], v[114:115], 0, s[94:95]
	v_mfma_f32_16x16x32_bf16 v[40:43], v[100:103], v[76:79], v[40:43]
	s_add_i32 m0, vcc_lo, 0x1c00
	v_mfma_f32_16x16x32_bf16 v[60:63], v[100:103], v[84:87], v[60:63]
	global_load_lds_dwordx4 v[116:117], off
	v_lshl_add_u64 v[116:117], v[116:117], 0, s[94:95]
	s_waitcnt vmcnt(8)
	ds_read_b128 v[68:71], v124 offset:8192
	ds_read_b128 v[72:75], v124 offset:9216
	ds_read_b128 v[76:79], v124 offset:10240
	ds_read_b128 v[84:87], v124 offset:11264
	ds_read_b128 v[88:91], v124 offset:12288
	ds_read_b128 v[92:95], v124 offset:13312
	ds_read_b128 v[96:99], v124 offset:14336
	ds_read_b128 v[100:103], v124 offset:15360
	s_waitcnt lgkmcnt(0)
	v_mfma_f32_16x16x32_bf16 v[56:59], v[88:91], v[68:71], v[56:59]
	s_add_i32 m0, vcc_lo, 0x2000
	v_mfma_f32_16x16x32_bf16 v[52:55], v[88:91], v[72:75], v[52:55]
	global_load_lds_dwordx4 v[82:83], off
	v_lshl_add_u64 v[82:83], v[82:83], 0, s[94:95]
	v_mfma_f32_16x16x32_bf16 v[48:51], v[88:91], v[76:79], v[48:51]
	s_add_i32 m0, vcc_lo, 0x2400
	v_mfma_f32_16x16x32_bf16 v[44:47], v[88:91], v[84:87], v[44:47]
	global_load_lds_dwordx4 v[104:105], off
	v_lshl_add_u64 v[104:105], v[104:105], 0, s[94:95]
	v_mfma_f32_16x16x32_bf16 v[12:15], v[92:95], v[68:71], v[12:15]
	s_add_i32 m0, vcc_lo, 0x2800
	v_mfma_f32_16x16x32_bf16 v[8:11], v[92:95], v[72:75], v[8:11]
	global_load_lds_dwordx4 v[106:107], off
	v_lshl_add_u64 v[106:107], v[106:107], 0, s[94:95]
	v_mfma_f32_16x16x32_bf16 v[4:7], v[92:95], v[76:79], v[4:7]
	s_add_i32 m0, vcc_lo, 0x2c00
	v_mfma_f32_16x16x32_bf16 v[0:3], v[92:95], v[84:87], v[0:3]
	global_load_lds_dwordx4 v[108:109], off
	v_lshl_add_u64 v[108:109], v[108:109], 0, s[94:95]
	v_mfma_f32_16x16x32_bf16 v[16:19], v[96:99], v[68:71], v[16:19]
	s_add_i32 m0, vcc_lo, 0x3000
	v_mfma_f32_16x16x32_bf16 v[24:27], v[96:99], v[72:75], v[24:27]
	global_load_lds_dwordx4 v[110:111], off
	v_lshl_add_u64 v[110:111], v[110:111], 0, s[94:95]
	v_mfma_f32_16x16x32_bf16 v[28:31], v[96:99], v[76:79], v[28:31]
	s_add_i32 m0, vcc_lo, 0x3400
	v_mfma_f32_16x16x32_bf16 v[36:39], v[96:99], v[84:87], v[36:39]
	global_load_lds_dwordx4 v[112:113], off
	v_lshl_add_u64 v[112:113], v[112:113], 0, s[94:95]
	v_mfma_f32_16x16x32_bf16 v[20:23], v[100:103], v[68:71], v[20:23]
	s_add_i32 m0, vcc_lo, 0x3800
	v_mfma_f32_16x16x32_bf16 v[32:35], v[100:103], v[72:75], v[32:35]
	global_load_lds_dwordx4 v[114:115], off
	v_lshl_add_u64 v[114:115], v[114:115], 0, s[94:95]
	v_mfma_f32_16x16x32_bf16 v[40:43], v[100:103], v[76:79], v[40:43]
	s_add_i32 m0, vcc_lo, 0x3c00
	v_mfma_f32_16x16x32_bf16 v[60:63], v[100:103], v[84:87], v[60:63]
	global_load_lds_dwordx4 v[116:117], off
	v_lshl_add_u64 v[116:117], v[116:117], 0, s[94:95]
	s_waitcnt vmcnt(8)
	ds_read_b128 v[68:71], v124
	ds_read_b128 v[72:75], v124 offset:1024
	ds_read_b128 v[76:79], v124 offset:2048
	ds_read_b128 v[84:87], v124 offset:3072
	ds_read_b128 v[88:91], v124 offset:4096
	ds_read_b128 v[92:95], v124 offset:5120
	ds_read_b128 v[96:99], v124 offset:6144
	ds_read_b128 v[100:103], v124 offset:7168
	s_waitcnt lgkmcnt(0)
	v_mfma_f32_16x16x32_bf16 v[56:59], v[88:91], v[68:71], v[56:59]
	v_mfma_f32_16x16x32_bf16 v[52:55], v[88:91], v[72:75], v[52:55]
	v_mfma_f32_16x16x32_bf16 v[48:51], v[88:91], v[76:79], v[48:51]
	v_mfma_f32_16x16x32_bf16 v[44:47], v[88:91], v[84:87], v[44:47]
	v_mfma_f32_16x16x32_bf16 v[12:15], v[92:95], v[68:71], v[12:15]
	v_mfma_f32_16x16x32_bf16 v[8:11], v[92:95], v[72:75], v[8:11]
	v_mfma_f32_16x16x32_bf16 v[4:7], v[92:95], v[76:79], v[4:7]
	v_mfma_f32_16x16x32_bf16 v[0:3], v[92:95], v[84:87], v[0:3]
	v_mfma_f32_16x16x32_bf16 v[16:19], v[96:99], v[68:71], v[16:19]
	v_mfma_f32_16x16x32_bf16 v[24:27], v[96:99], v[72:75], v[24:27]
	v_mfma_f32_16x16x32_bf16 v[28:31], v[96:99], v[76:79], v[28:31]
	v_mfma_f32_16x16x32_bf16 v[36:39], v[96:99], v[84:87], v[36:39]
	v_mfma_f32_16x16x32_bf16 v[20:23], v[100:103], v[68:71], v[20:23]
	v_mfma_f32_16x16x32_bf16 v[32:35], v[100:103], v[72:75], v[32:35]
	v_mfma_f32_16x16x32_bf16 v[40:43], v[100:103], v[76:79], v[40:43]
	v_mfma_f32_16x16x32_bf16 v[60:63], v[100:103], v[84:87], v[60:63]
	s_waitcnt vmcnt(0)
	ds_read_b128 v[68:71], v124 offset:8192
	ds_read_b128 v[72:75], v124 offset:9216
	ds_read_b128 v[76:79], v124 offset:10240
	ds_read_b128 v[84:87], v124 offset:11264
	ds_read_b128 v[88:91], v124 offset:12288
	ds_read_b128 v[92:95], v124 offset:13312
	ds_read_b128 v[96:99], v124 offset:14336
	ds_read_b128 v[100:103], v124 offset:15360
	s_waitcnt lgkmcnt(0)
	v_mfma_f32_16x16x32_bf16 v[56:59], v[88:91], v[68:71], v[56:59]
	v_mfma_f32_16x16x32_bf16 v[52:55], v[88:91], v[72:75], v[52:55]
	v_mfma_f32_16x16x32_bf16 v[48:51], v[88:91], v[76:79], v[48:51]
	v_mfma_f32_16x16x32_bf16 v[44:47], v[88:91], v[84:87], v[44:47]
	v_mfma_f32_16x16x32_bf16 v[12:15], v[92:95], v[68:71], v[12:15]
	v_mfma_f32_16x16x32_bf16 v[8:11], v[92:95], v[72:75], v[8:11]
	v_mfma_f32_16x16x32_bf16 v[4:7], v[92:95], v[76:79], v[4:7]
	v_mfma_f32_16x16x32_bf16 v[0:3], v[92:95], v[84:87], v[0:3]
	v_mfma_f32_16x16x32_bf16 v[16:19], v[96:99], v[68:71], v[16:19]
	v_mfma_f32_16x16x32_bf16 v[24:27], v[96:99], v[72:75], v[24:27]
	v_mfma_f32_16x16x32_bf16 v[28:31], v[96:99], v[76:79], v[28:31]
	v_mfma_f32_16x16x32_bf16 v[36:39], v[96:99], v[84:87], v[36:39]
	v_mfma_f32_16x16x32_bf16 v[20:23], v[100:103], v[68:71], v[20:23]
	v_mfma_f32_16x16x32_bf16 v[32:35], v[100:103], v[72:75], v[32:35]
	v_mfma_f32_16x16x32_bf16 v[40:43], v[100:103], v[76:79], v[40:43]
	v_mfma_f32_16x16x32_bf16 v[60:63], v[100:103], v[84:87], v[60:63]
	s_nop 7
	s_nop 3
	v_and_b32_e32 v65, 63, v81
	v_lshl_add_u32 v66, v65, 4, 0
	s_ashr_i32 s10, s0, 7
	v_bfe_u32 v64, v81, 4, 2
	v_lshl_add_u32 v67, s3, 14, v66
	s_lshl_b32 s5, s10, 4
	ds_write_b128 v67, v[56:59]
	ds_write_b128 v67, v[52:55] offset:1024
	ds_write_b128 v67, v[48:51] offset:2048
	ds_write_b128 v67, v[44:47] offset:3072
	ds_write_b128 v67, v[12:15] offset:4096
	ds_write_b128 v67, v[8:11] offset:5120
	ds_write_b128 v67, v[4:7] offset:6144
	ds_write_b128 v67, v[0:3] offset:7168
	ds_write_b128 v67, v[16:19] offset:8192
	ds_write_b128 v67, v[24:27] offset:9216
	ds_write_b128 v67, v[28:31] offset:10240
	ds_write_b128 v67, v[36:39] offset:11264
	ds_write_b128 v67, v[20:23] offset:12288
	ds_write_b128 v67, v[32:35] offset:13312
	ds_write_b128 v67, v[40:43] offset:14336
	ds_write_b128 v67, v[60:63] offset:15360
	s_bfe_u32 s3, s0, 0x10006
	s_addk_i32 s5, 0x4000
	v_lshlrev_b32_e32 v1, 2, v64
	v_or_b32_e32 v0, s5, v80
	v_lshl_or_b32 v1, s3, 4, v1
	v_or_b32_e32 v4, s1, v1
	v_ashrrev_i32_e32 v1, 31, v0
	v_lshlrev_b64 v[2:3], 12, v[0:1]
	s_ashr_i32 s5, s4, 31
	v_lshl_add_u64 v[2:3], s[8:9], 0, v[2:3]
	v_lshl_add_u64 v[2:3], s[4:5], 1, v[2:3]
	v_lshlrev_b32_e32 v128, 1, v4
	v_lshl_add_u64 v[14:15], v[2:3], 0, v[128:129]
	s_waitcnt lgkmcnt(0)
	s_barrier
	global_load_dwordx2 v[16:17], v[14:15], off
	global_load_dwordx2 v[18:19], v[14:15], off offset:256
	s_lshl_b32 s1, s3, 2
	s_add_i32 s1, s1, s10
	v_lshl_add_u32 v28, s1, 10, v66
	ds_read_b128 v[2:5], v28
	ds_read_b128 v[6:9], v28 offset:8192
	ds_read_b128 v[10:13], v28 offset:16384
	s_waitcnt lgkmcnt(0)
	v_pk_add_f32 v[20:21], v[4:5], 0 op_sel_hi:[1,0]
	v_pk_add_f32 v[22:23], v[2:3], 0 op_sel_hi:[1,0]
	ds_read_b128 v[2:5], v28 offset:24576
	v_pk_add_f32 v[24:25], v[8:9], 0 op_sel_hi:[1,0]
	v_pk_add_f32 v[26:27], v[6:7], 0 op_sel_hi:[1,0]
	ds_read_b128 v[6:9], v28 offset:32768
	v_pk_add_f32 v[22:23], v[22:23], v[10:11]
	s_waitcnt lgkmcnt(0)
	v_pk_add_f32 v[24:25], v[24:25], v[4:5]
	v_pk_add_f32 v[26:27], v[26:27], v[2:3]
	ds_read_b128 v[2:5], v28 offset:49152
	v_pk_add_f32 v[20:21], v[20:21], v[12:13]
	ds_read_b128 v[10:13], v28 offset:40960
	v_pk_add_f32 v[22:23], v[22:23], v[6:7]
	v_pk_add_f32 v[20:21], v[20:21], v[8:9]
	ds_read_b128 v[6:9], v28 offset:57344
	s_waitcnt lgkmcnt(0)
	v_pk_add_f32 v[22:23], v[22:23], v[2:3]
	v_add_u32_e32 v2, 0x10000, v28
	v_pk_add_f32 v[20:21], v[20:21], v[4:5]
	ds_read_b128 v[2:5], v2
	v_pk_add_f32 v[10:11], v[26:27], v[10:11]
	v_pk_add_f32 v[12:13], v[24:25], v[12:13]
	v_pk_add_f32 v[10:11], v[10:11], v[6:7]
	v_add_u32_e32 v6, 0x12000, v28
	v_pk_add_f32 v[12:13], v[12:13], v[8:9]
	ds_read_b128 v[6:9], v6
	s_waitcnt lgkmcnt(0)
	v_pk_add_f32 v[22:23], v[22:23], v[2:3]
	v_add_u32_e32 v2, 0x14000, v28
	v_pk_add_f32 v[20:21], v[20:21], v[4:5]
	ds_read_b128 v[2:5], v2
	v_pk_add_f32 v[10:11], v[10:11], v[6:7]
	v_add_u32_e32 v6, 0x16000, v28
	v_pk_add_f32 v[12:13], v[12:13], v[8:9]
	ds_read_b128 v[6:9], v6
	s_waitcnt lgkmcnt(0)
	v_pk_add_f32 v[22:23], v[22:23], v[2:3]
	v_add_u32_e32 v2, 0x18000, v28
	v_pk_add_f32 v[20:21], v[20:21], v[4:5]
	ds_read_b128 v[2:5], v2
	v_pk_add_f32 v[26:27], v[10:11], v[6:7]
	v_add_u32_e32 v6, 0x1a000, v28
	v_pk_add_f32 v[24:25], v[12:13], v[8:9]
	ds_read_b128 v[6:9], v6
	s_waitcnt lgkmcnt(0)
	v_pk_add_f32 v[22:23], v[22:23], v[2:3]
	v_add_u32_e32 v2, 0x1c000, v28
	v_add_u32_e32 v10, 0x1e000, v28
	v_pk_add_f32 v[20:21], v[20:21], v[4:5]
	ds_read_b128 v[2:5], v2
	ds_read_b128 v[10:13], v10
	v_pk_add_f32 v[6:7], v[26:27], v[6:7]
	v_pk_add_f32 v[8:9], v[24:25], v[8:9]
	s_waitcnt lgkmcnt(0)
	v_pk_add_f32 v[2:3], v[22:23], v[2:3]
	v_pk_add_f32 v[6:7], v[6:7], v[10:11]
	v_pk_add_f32 v[4:5], v[20:21], v[4:5]
	v_pk_add_f32 v[8:9], v[8:9], v[12:13]
	s_waitcnt vmcnt(0)
	v_lshlrev_b32_e32 v10, 16, v16
	v_and_b32_e32 v11, 0xffff0000, v16
	v_pk_add_f32 v[2:3], v[2:3], v[10:11]
	v_lshlrev_b32_e32 v10, 16, v18
	v_and_b32_e32 v11, 0xffff0000, v18
	v_lshlrev_b32_e32 v12, 16, v17
	v_and_b32_e32 v13, 0xffff0000, v17
	v_pk_add_f32 v[6:7], v[6:7], v[10:11]
	v_pk_add_f32 v[4:5], v[4:5], v[12:13]
	v_lshlrev_b32_e32 v12, 16, v19
	v_and_b32_e32 v13, 0xffff0000, v19
	v_mul_f32_e32 v10, v6, v6
	v_mul_f32_e32 v11, v7, v7
	v_pk_add_f32 v[8:9], v[8:9], v[12:13]
	v_fmac_f32_e32 v10, v2, v2
	v_fmac_f32_e32 v11, v3, v3
	v_add_f32_e32 v10, v10, v11
	v_mul_f32_e32 v11, v8, v8
	v_fmac_f32_e32 v11, v4, v4
	v_add_f32_e32 v10, v11, v10
	v_mul_f32_e32 v11, v9, v9
	v_fmac_f32_e32 v11, v5, v5
	v_and_b32_e32 v12, 64, v214
	v_add_f32_e32 v10, v11, v10
	v_xor_b32_e32 v11, 16, v214
	v_add_u32_e32 v12, 64, v12
	v_cmp_lt_i32_e32 vcc, v11, v12
	v_cvt_pk_bf16_f32 v2, v2, v3
	v_cvt_pk_bf16_f32 v3, v4, v5
	v_xor_b32_e32 v5, 32, v214
	global_store_dwordx2 v[14:15], v[2:3], off
	v_cndmask_b32_e32 v11, v214, v11, vcc
	v_lshlrev_b32_e32 v11, 2, v11
	ds_bpermute_b32 v11, v11, v10
	v_cmp_lt_i32_e32 vcc, v5, v12
	v_cvt_pk_bf16_f32 v2, v6, v7
	v_cvt_pk_bf16_f32 v3, v8, v9
	global_store_dwordx2 v[14:15], v[2:3], off offset:256
	s_waitcnt lgkmcnt(0)
	v_add_f32_e32 v4, v10, v11
	v_cndmask_b32_e32 v5, v214, v5, vcc
	v_lshlrev_b32_e32 v5, 2, v5
	ds_bpermute_b32 v5, v5, v4
	v_cmp_gt_u32_e32 vcc, 16, v65
	s_waitcnt lgkmcnt(0)
	v_add_f32_e32 v2, v4, v5
	s_and_saveexec_b64 s[4:5], vcc
	s_and_b32 s1, s0, 0xffffffc0
	s_add_i32 s1, s1, 0
	v_lshl_add_u32 v3, v80, 2, s1
	v_add_u32_e32 v3, 0x20100, v3
	ds_write_b32 v3, v2
	s_or_b64 exec, exec, s[4:5]
	v_or_b32_e32 v3, s3, v64
	v_cmp_eq_u32_e32 vcc, 0, v3
	s_waitcnt lgkmcnt(0)
	s_barrier
	s_and_saveexec_b64 s[4:5], vcc
	s_cbranch_execz .LBB0_1036
	s_andn2_b32 s0, s0, 63
	s_add_i32 s0, s0, 0
	s_add_i32 s0, s0, 0x20100
	v_lshl_add_u32 v3, v80, 2, s0
	ds_read_b32 v3, v3 offset:64
	v_lshlrev_b64 v[0:1], 7, v[0:1]
	v_lshl_add_u64 v[0:1], s[6:7], 0, v[0:1]
	s_ashr_i32 s3, s2, 31
	v_lshl_add_u64 v[0:1], s[2:3], 2, v[0:1]
	s_waitcnt lgkmcnt(0)
	v_add_f32_e32 v2, v2, v3
	global_store_dword v[0:1], v2, off

.LBB0_1111:
	v_lshrrev_b32_e32 v122, 2, v214
	v_and_b32_e32 v123, 15, v214
	v_sub_u32_e32 v122, v122, v123
	v_mul_i32_i24_e32 v122, 0x1000, v122
	v_bfe_u32 v125, v214, 5, 1
	v_lshlrev_b32_e32 v125, 1, v125
	v_and_b32_e32 v124, 3, v214
	v_xor_b32_e32 v125, v125, v124
	v_lshrrev_b32_e32 v124, 4, v214
	v_sub_u32_e32 v125, v125, v124
	v_lshl_add_u32 v122, v125, 4, v122
	v_ashrrev_i32_e32 v125, 31, v122
	v_add_co_u32_e32 v118, vcc, v66, v122
	s_nop 1
	v_addc_co_u32_e32 v119, vcc, v67, v125, vcc
	v_add_co_u32_e32 v120, vcc, v64, v122
	s_nop 1
	v_addc_co_u32_e32 v121, vcc, v65, v125, vcc
	v_add_co_u32_e32 v82, vcc, s84, v118
	s_nop 1
	v_addc_co_u32_e32 v83, vcc, 0, v119, vcc
	v_add_co_u32_e32 v104, vcc, s85, v118
	s_nop 1
	v_addc_co_u32_e32 v105, vcc, 0, v119, vcc
	v_add_co_u32_e32 v106, vcc, s88, v118
	s_nop 1
	v_addc_co_u32_e32 v107, vcc, 0, v119, vcc
	v_add_co_u32_e32 v108, vcc, s89, v118
	s_nop 1
	v_addc_co_u32_e32 v109, vcc, 0, v119, vcc
	v_add_co_u32_e32 v110, vcc, 0x7008000, v120
	s_nop 1
	v_addc_co_u32_e32 v111, vcc, 0, v121, vcc
	v_add_co_u32_e32 v112, vcc, 0x7018000, v120
	s_nop 1
	v_addc_co_u32_e32 v113, vcc, 0, v121, vcc
	v_add_co_u32_e32 v114, vcc, 0x7088000, v120
	s_nop 1
	v_addc_co_u32_e32 v115, vcc, 0, v121, vcc
	v_add_co_u32_e32 v116, vcc, 0x7098000, v120
	s_nop 1
	v_addc_co_u32_e32 v117, vcc, 0, v121, vcc
	v_readfirstlane_b32 vcc_lo, v210
	v_bfe_u32 v125, v214, 3, 1
	v_lshlrev_b32_e32 v125, 1, v125
	v_xor_b32_e32 v125, v125, v124
	v_lshlrev_b32_e32 v125, 4, v125
	v_lshl_add_u32 v125, v123, 6, v125
	s_lshr_b32 vcc_lo, vcc_lo, 6
	s_lshl_b32 vcc_lo, vcc_lo, 14
	s_mov_b32 s94, 64
	v_add_u32_e32 v124, vcc_lo, v125
	s_add_i32 m0, vcc_lo, 0x0
	s_nop 0
	global_load_lds_dwordx4 v[82:83], off
	v_lshl_add_u64 v[82:83], v[82:83], 0, s[94:95]
	s_add_i32 m0, vcc_lo, 0x400
	s_nop 0
	global_load_lds_dwordx4 v[104:105], off
	v_lshl_add_u64 v[104:105], v[104:105], 0, s[94:95]
	s_add_i32 m0, vcc_lo, 0x800
	s_nop 0
	global_load_lds_dwordx4 v[106:107], off
	v_lshl_add_u64 v[106:107], v[106:107], 0, s[94:95]
	s_add_i32 m0, vcc_lo, 0xc00
	s_nop 0
	global_load_lds_dwordx4 v[108:109], off
	v_lshl_add_u64 v[108:109], v[108:109], 0, s[94:95]
	s_add_i32 m0, vcc_lo, 0x1000
	s_nop 0
	global_load_lds_dwordx4 v[110:111], off
	v_lshl_add_u64 v[110:111], v[110:111], 0, s[94:95]
	s_add_i32 m0, vcc_lo, 0x1400
	s_nop 0
	global_load_lds_dwordx4 v[112:113], off
	v_lshl_add_u64 v[112:113], v[112:113], 0, s[94:95]
	s_add_i32 m0, vcc_lo, 0x1800
	s_nop 0
	global_load_lds_dwordx4 v[114:115], off
	v_lshl_add_u64 v[114:115], v[114:115], 0, s[94:95]
	s_add_i32 m0, vcc_lo, 0x1c00
	s_nop 0
	global_load_lds_dwordx4 v[116:117], off
	v_lshl_add_u64 v[116:117], v[116:117], 0, s[94:95]
	s_add_i32 m0, vcc_lo, 0x2000
	s_nop 0
	global_load_lds_dwordx4 v[82:83], off
	v_lshl_add_u64 v[82:83], v[82:83], 0, s[94:95]
	s_add_i32 m0, vcc_lo, 0x2400
	s_nop 0
	global_load_lds_dwordx4 v[104:105], off
	v_lshl_add_u64 v[104:105], v[104:105], 0, s[94:95]
	s_add_i32 m0, vcc_lo, 0x2800
	s_nop 0
	global_load_lds_dwordx4 v[106:107], off
	v_lshl_add_u64 v[106:107], v[106:107], 0, s[94:95]
	s_add_i32 m0, vcc_lo, 0x2c00
	s_nop 0
	global_load_lds_dwordx4 v[108:109], off
	v_lshl_add_u64 v[108:109], v[108:109], 0, s[94:95]
	s_add_i32 m0, vcc_lo, 0x3000
	s_nop 0
	global_load_lds_dwordx4 v[110:111], off
	v_lshl_add_u64 v[110:111], v[110:111], 0, s[94:95]
	s_add_i32 m0, vcc_lo, 0x3400
	s_nop 0
	global_load_lds_dwordx4 v[112:113], off
	v_lshl_add_u64 v[112:113], v[112:113], 0, s[94:95]
	s_add_i32 m0, vcc_lo, 0x3800
	s_nop 0
	global_load_lds_dwordx4 v[114:115], off
	v_lshl_add_u64 v[114:115], v[114:115], 0, s[94:95]
	s_add_i32 m0, vcc_lo, 0x3c00
	s_nop 0
	global_load_lds_dwordx4 v[116:117], off
	v_lshl_add_u64 v[116:117], v[116:117], 0, s[94:95]
	s_waitcnt vmcnt(8)
	ds_read_b128 v[68:71], v124
	ds_read_b128 v[72:75], v124 offset:1024
	ds_read_b128 v[76:79], v124 offset:2048
	ds_read_b128 v[84:87], v124 offset:3072
	ds_read_b128 v[88:91], v124 offset:4096
	ds_read_b128 v[92:95], v124 offset:5120
	ds_read_b128 v[96:99], v124 offset:6144
	ds_read_b128 v[100:103], v124 offset:7168
	s_waitcnt lgkmcnt(0)
	v_mfma_f32_16x16x32_bf16 v[56:59], v[88:91], v[68:71], 0
	s_add_i32 m0, vcc_lo, 0x0
	v_mfma_f32_16x16x32_bf16 v[52:55], v[88:91], v[72:75], 0
	global_load_lds_dwordx4 v[82:83], off
	v_lshl_add_u64 v[82:83], v[82:83], 0, s[94:95]
	v_mfma_f32_16x16x32_bf16 v[48:51], v[88:91], v[76:79], 0
	s_add_i32 m0, vcc_lo, 0x400
	v_mfma_f32_16x16x32_bf16 v[44:47], v[88:91], v[84:87], 0
	global_load_lds_dwordx4 v[104:105], off
	v_lshl_add_u64 v[104:105], v[104:105], 0, s[94:95]
	v_mfma_f32_16x16x32_bf16 v[12:15], v[92:95], v[68:71], 0
	s_add_i32 m0, vcc_lo, 0x800
	v_mfma_f32_16x16x32_bf16 v[8:11], v[92:95], v[72:75], 0
	global_load_lds_dwordx4 v[106:107], off
	v_lshl_add_u64 v[106:107], v[106:107], 0, s[94:95]
	v_mfma_f32_16x16x32_bf16 v[4:7], v[92:95], v[76:79], 0
	s_add_i32 m0, vcc_lo, 0xc00
	v_mfma_f32_16x16x32_bf16 v[0:3], v[92:95], v[84:87], 0
	global_load_lds_dwordx4 v[108:109], off
	v_lshl_add_u64 v[108:109], v[108:109], 0, s[94:95]
	v_mfma_f32_16x16x32_bf16 v[16:19], v[96:99], v[68:71], 0
	s_add_i32 m0, vcc_lo, 0x1000
	v_mfma_f32_16x16x32_bf16 v[24:27], v[96:99], v[72:75], 0
	global_load_lds_dwordx4 v[110:111], off
	v_lshl_add_u64 v[110:111], v[110:111], 0, s[94:95]
	v_mfma_f32_16x16x32_bf16 v[28:31], v[96:99], v[76:79], 0
	s_add_i32 m0, vcc_lo, 0x1400
	v_mfma_f32_16x16x32_bf16 v[36:39], v[96:99], v[84:87], 0
	global_load_lds_dwordx4 v[112:113], off
	v_lshl_add_u64 v[112:113], v[112:113], 0, s[94:95]
	v_mfma_f32_16x16x32_bf16 v[20:23], v[100:103], v[68:71], 0
	s_add_i32 m0, vcc_lo, 0x1800
	v_mfma_f32_16x16x32_bf16 v[32:35], v[100:103], v[72:75], 0
	global_load_lds_dwordx4 v[114:115], off
	v_lshl_add_u64 v[114:115], v[114:115], 0, s[94:95]
	v_mfma_f32_16x16x32_bf16 v[40:43], v[100:103], v[76:79], 0
	s_add_i32 m0, vcc_lo, 0x1c00
	v_mfma_f32_16x16x32_bf16 v[60:63], v[100:103], v[84:87], 0
	global_load_lds_dwordx4 v[116:117], off
	v_lshl_add_u64 v[116:117], v[116:117], 0, s[94:95]
	s_waitcnt vmcnt(8)
	ds_read_b128 v[68:71], v124 offset:8192
	ds_read_b128 v[72:75], v124 offset:9216
	ds_read_b128 v[76:79], v124 offset:10240
	ds_read_b128 v[84:87], v124 offset:11264
	ds_read_b128 v[88:91], v124 offset:12288
	ds_read_b128 v[92:95], v124 offset:13312
	ds_read_b128 v[96:99], v124 offset:14336
	ds_read_b128 v[100:103], v124 offset:15360
	s_waitcnt lgkmcnt(0)
	v_mfma_f32_16x16x32_bf16 v[56:59], v[88:91], v[68:71], v[56:59]
	s_add_i32 m0, vcc_lo, 0x2000
	v_mfma_f32_16x16x32_bf16 v[52:55], v[88:91], v[72:75], v[52:55]
	global_load_lds_dwordx4 v[82:83], off
	v_lshl_add_u64 v[82:83], v[82:83], 0, s[94:95]
	v_mfma_f32_16x16x32_bf16 v[48:51], v[88:91], v[76:79], v[48:51]
	s_add_i32 m0, vcc_lo, 0x2400
	v_mfma_f32_16x16x32_bf16 v[44:47], v[88:91], v[84:87], v[44:47]
	global_load_lds_dwordx4 v[104:105], off
	v_lshl_add_u64 v[104:105], v[104:105], 0, s[94:95]
	v_mfma_f32_16x16x32_bf16 v[12:15], v[92:95], v[68:71], v[12:15]
	s_add_i32 m0, vcc_lo, 0x2800
	v_mfma_f32_16x16x32_bf16 v[8:11], v[92:95], v[72:75], v[8:11]
	global_load_lds_dwordx4 v[106:107], off
	v_lshl_add_u64 v[106:107], v[106:107], 0, s[94:95]
	v_mfma_f32_16x16x32_bf16 v[4:7], v[92:95], v[76:79], v[4:7]
	s_add_i32 m0, vcc_lo, 0x2c00
	v_mfma_f32_16x16x32_bf16 v[0:3], v[92:95], v[84:87], v[0:3]
	global_load_lds_dwordx4 v[108:109], off
	v_lshl_add_u64 v[108:109], v[108:109], 0, s[94:95]
	v_mfma_f32_16x16x32_bf16 v[16:19], v[96:99], v[68:71], v[16:19]
	s_add_i32 m0, vcc_lo, 0x3000
	v_mfma_f32_16x16x32_bf16 v[24:27], v[96:99], v[72:75], v[24:27]
	global_load_lds_dwordx4 v[110:111], off
	v_lshl_add_u64 v[110:111], v[110:111], 0, s[94:95]
	v_mfma_f32_16x16x32_bf16 v[28:31], v[96:99], v[76:79], v[28:31]
	s_add_i32 m0, vcc_lo, 0x3400
	v_mfma_f32_16x16x32_bf16 v[36:39], v[96:99], v[84:87], v[36:39]
	global_load_lds_dwordx4 v[112:113], off
	v_lshl_add_u64 v[112:113], v[112:113], 0, s[94:95]
	v_mfma_f32_16x16x32_bf16 v[20:23], v[100:103], v[68:71], v[20:23]
	s_add_i32 m0, vcc_lo, 0x3800
	v_mfma_f32_16x16x32_bf16 v[32:35], v[100:103], v[72:75], v[32:35]
	global_load_lds_dwordx4 v[114:115], off
	v_lshl_add_u64 v[114:115], v[114:115], 0, s[94:95]
	v_mfma_f32_16x16x32_bf16 v[40:43], v[100:103], v[76:79], v[40:43]
	s_add_i32 m0, vcc_lo, 0x3c00
	v_mfma_f32_16x16x32_bf16 v[60:63], v[100:103], v[84:87], v[60:63]
	global_load_lds_dwordx4 v[116:117], off
	v_lshl_add_u64 v[116:117], v[116:117], 0, s[94:95]
	s_waitcnt vmcnt(8)
	ds_read_b128 v[68:71], v124
	ds_read_b128 v[72:75], v124 offset:1024
	ds_read_b128 v[76:79], v124 offset:2048
	ds_read_b128 v[84:87], v124 offset:3072
	ds_read_b128 v[88:91], v124 offset:4096
	ds_read_b128 v[92:95], v124 offset:5120
	ds_read_b128 v[96:99], v124 offset:6144
	ds_read_b128 v[100:103], v124 offset:7168
	s_waitcnt lgkmcnt(0)
	v_mfma_f32_16x16x32_bf16 v[56:59], v[88:91], v[68:71], v[56:59]
	s_add_i32 m0, vcc_lo, 0x0
	v_mfma_f32_16x16x32_bf16 v[52:55], v[88:91], v[72:75], v[52:55]
	global_load_lds_dwordx4 v[82:83], off
	v_lshl_add_u64 v[82:83], v[82:83], 0, s[94:95]
	v_mfma_f32_16x16x32_bf16 v[48:51], v[88:91], v[76:79], v[48:51]
	s_add_i32 m0, vcc_lo, 0x400
	v_mfma_f32_16x16x32_bf16 v[44:47], v[88:91], v[84:87], v[44:47]
	global_load_lds_dwordx4 v[104:105], off
	v_lshl_add_u64 v[104:105], v[104:105], 0, s[94:95]
	v_mfma_f32_16x16x32_bf16 v[12:15], v[92:95], v[68:71], v[12:15]
	s_add_i32 m0, vcc_lo, 0x800
	v_mfma_f32_16x16x32_bf16 v[8:11], v[92:95], v[72:75], v[8:11]
	global_load_lds_dwordx4 v[106:107], off
	v_lshl_add_u64 v[106:107], v[106:107], 0, s[94:95]
	v_mfma_f32_16x16x32_bf16 v[4:7], v[92:95], v[76:79], v[4:7]
	s_add_i32 m0, vcc_lo, 0xc00
	v_mfma_f32_16x16x32_bf16 v[0:3], v[92:95], v[84:87], v[0:3]
	global_load_lds_dwordx4 v[108:109], off
	v_lshl_add_u64 v[108:109], v[108:109], 0, s[94:95]
	v_mfma_f32_16x16x32_bf16 v[16:19], v[96:99], v[68:71], v[16:19]
	s_add_i32 m0, vcc_lo, 0x1000
	v_mfma_f32_16x16x32_bf16 v[24:27], v[96:99], v[72:75], v[24:27]
	global_load_lds_dwordx4 v[110:111], off
	v_lshl_add_u64 v[110:111], v[110:111], 0, s[94:95]
	v_mfma_f32_16x16x32_bf16 v[28:31], v[96:99], v[76:79], v[28:31]
	s_add_i32 m0, vcc_lo, 0x1400
	v_mfma_f32_16x16x32_bf16 v[36:39], v[96:99], v[84:87], v[36:39]
	global_load_lds_dwordx4 v[112:113], off
	v_lshl_add_u64 v[112:113], v[112:113], 0, s[94:95]
	v_mfma_f32_16x16x32_bf16 v[20:23], v[100:103], v[68:71], v[20:23]
	s_add_i32 m0, vcc_lo, 0x1800
	v_mfma_f32_16x16x32_bf16 v[32:35], v[100:103], v[72:75], v[32:35]
	global_load_lds_dwordx4 v[114:115], off
	v_lshl_add_u64 v[114:115], v[114:115], 0, s[94:95]
	v_mfma_f32_16x16x32_bf16 v[40:43], v[100:103], v[76:79], v[40:43]
	s_add_i32 m0, vcc_lo, 0x1c00
	v_mfma_f32_16x16x32_bf16 v[60:63], v[100:103], v[84:87], v[60:63]
	global_load_lds_dwordx4 v[116:117], off
	v_lshl_add_u64 v[116:117], v[116:117], 0, s[94:95]
	s_waitcnt vmcnt(8)
	ds_read_b128 v[68:71], v124 offset:8192
	ds_read_b128 v[72:75], v124 offset:9216
	ds_read_b128 v[76:79], v124 offset:10240
	ds_read_b128 v[84:87], v124 offset:11264
	ds_read_b128 v[88:91], v124 offset:12288
	ds_read_b128 v[92:95], v124 offset:13312
	ds_read_b128 v[96:99], v124 offset:14336
	ds_read_b128 v[100:103], v124 offset:15360
	s_waitcnt lgkmcnt(0)
	v_mfma_f32_16x16x32_bf16 v[56:59], v[88:91], v[68:71], v[56:59]
	s_add_i32 m0, vcc_lo, 0x2000
	v_mfma_f32_16x16x32_bf16 v[52:55], v[88:91], v[72:75], v[52:55]
	global_load_lds_dwordx4 v[82:83], off
	v_lshl_add_u64 v[82:83], v[82:83], 0, s[94:95]
	v_mfma_f32_16x16x32_bf16 v[48:51], v[88:91], v[76:79], v[48:51]
	s_add_i32 m0, vcc_lo, 0x2400
	v_mfma_f32_16x16x32_bf16 v[44:47], v[88:91], v[84:87], v[44:47]
	global_load_lds_dwordx4 v[104:105], off
	v_lshl_add_u64 v[104:105], v[104:105], 0, s[94:95]
	v_mfma_f32_16x16x32_bf16 v[12:15], v[92:95], v[68:71], v[12:15]
	s_add_i32 m0, vcc_lo, 0x2800
	v_mfma_f32_16x16x32_bf16 v[8:11], v[92:95], v[72:75], v[8:11]
	global_load_lds_dwordx4 v[106:107], off
	v_lshl_add_u64 v[106:107], v[106:107], 0, s[94:95]
	v_mfma_f32_16x16x32_bf16 v[4:7], v[92:95], v[76:79], v[4:7]
	s_add_i32 m0, vcc_lo, 0x2c00
	v_mfma_f32_16x16x32_bf16 v[0:3], v[92:95], v[84:87], v[0:3]
	global_load_lds_dwordx4 v[108:109], off
	v_lshl_add_u64 v[108:109], v[108:109], 0, s[94:95]
	v_mfma_f32_16x16x32_bf16 v[16:19], v[96:99], v[68:71], v[16:19]
	s_add_i32 m0, vcc_lo, 0x3000
	v_mfma_f32_16x16x32_bf16 v[24:27], v[96:99], v[72:75], v[24:27]
	global_load_lds_dwordx4 v[110:111], off
	v_lshl_add_u64 v[110:111], v[110:111], 0, s[94:95]
	v_mfma_f32_16x16x32_bf16 v[28:31], v[96:99], v[76:79], v[28:31]
	s_add_i32 m0, vcc_lo, 0x3400
	v_mfma_f32_16x16x32_bf16 v[36:39], v[96:99], v[84:87], v[36:39]
	global_load_lds_dwordx4 v[112:113], off
	v_lshl_add_u64 v[112:113], v[112:113], 0, s[94:95]
	v_mfma_f32_16x16x32_bf16 v[20:23], v[100:103], v[68:71], v[20:23]
	s_add_i32 m0, vcc_lo, 0x3800
	v_mfma_f32_16x16x32_bf16 v[32:35], v[100:103], v[72:75], v[32:35]
	global_load_lds_dwordx4 v[114:115], off
	v_lshl_add_u64 v[114:115], v[114:115], 0, s[94:95]
	v_mfma_f32_16x16x32_bf16 v[40:43], v[100:103], v[76:79], v[40:43]
	s_add_i32 m0, vcc_lo, 0x3c00
	v_mfma_f32_16x16x32_bf16 v[60:63], v[100:103], v[84:87], v[60:63]
	global_load_lds_dwordx4 v[116:117], off
	v_lshl_add_u64 v[116:117], v[116:117], 0, s[94:95]
	s_waitcnt vmcnt(8)
	ds_read_b128 v[68:71], v124
	ds_read_b128 v[72:75], v124 offset:1024
	ds_read_b128 v[76:79], v124 offset:2048
	ds_read_b128 v[84:87], v124 offset:3072
	ds_read_b128 v[88:91], v124 offset:4096
	ds_read_b128 v[92:95], v124 offset:5120
	ds_read_b128 v[96:99], v124 offset:6144
	ds_read_b128 v[100:103], v124 offset:7168
	s_waitcnt lgkmcnt(0)
	v_mfma_f32_16x16x32_bf16 v[56:59], v[88:91], v[68:71], v[56:59]
	s_add_i32 m0, vcc_lo, 0x0
	v_mfma_f32_16x16x32_bf16 v[52:55], v[88:91], v[72:75], v[52:55]
	global_load_lds_dwordx4 v[82:83], off
	v_lshl_add_u64 v[82:83], v[82:83], 0, s[94:95]
	v_mfma_f32_16x16x32_bf16 v[48:51], v[88:91], v[76:79], v[48:51]
	s_add_i32 m0, vcc_lo, 0x400
	v_mfma_f32_16x16x32_bf16 v[44:47], v[88:91], v[84:87], v[44:47]
	global_load_lds_dwordx4 v[104:105], off
	v_lshl_add_u64 v[104:105], v[104:105], 0, s[94:95]
	v_mfma_f32_16x16x32_bf16 v[12:15], v[92:95], v[68:71], v[12:15]
	s_add_i32 m0, vcc_lo, 0x800
	v_mfma_f32_16x16x32_bf16 v[8:11], v[92:95], v[72:75], v[8:11]
	global_load_lds_dwordx4 v[106:107], off
	v_lshl_add_u64 v[106:107], v[106:107], 0, s[94:95]
	v_mfma_f32_16x16x32_bf16 v[4:7], v[92:95], v[76:79], v[4:7]
	s_add_i32 m0, vcc_lo, 0xc00
	v_mfma_f32_16x16x32_bf16 v[0:3], v[92:95], v[84:87], v[0:3]
	global_load_lds_dwordx4 v[108:109], off
	v_lshl_add_u64 v[108:109], v[108:109], 0, s[94:95]
	v_mfma_f32_16x16x32_bf16 v[16:19], v[96:99], v[68:71], v[16:19]
	s_add_i32 m0, vcc_lo, 0x1000
	v_mfma_f32_16x16x32_bf16 v[24:27], v[96:99], v[72:75], v[24:27]
	global_load_lds_dwordx4 v[110:111], off
	v_lshl_add_u64 v[110:111], v[110:111], 0, s[94:95]
	v_mfma_f32_16x16x32_bf16 v[28:31], v[96:99], v[76:79], v[28:31]
	s_add_i32 m0, vcc_lo, 0x1400
	v_mfma_f32_16x16x32_bf16 v[36:39], v[96:99], v[84:87], v[36:39]
	global_load_lds_dwordx4 v[112:113], off
	v_lshl_add_u64 v[112:113], v[112:113], 0, s[94:95]
	v_mfma_f32_16x16x32_bf16 v[20:23], v[100:103], v[68:71], v[20:23]
	s_add_i32 m0, vcc_lo, 0x1800
	v_mfma_f32_16x16x32_bf16 v[32:35], v[100:103], v[72:75], v[32:35]
	global_load_lds_dwordx4 v[114:115], off
	v_lshl_add_u64 v[114:115], v[114:115], 0, s[94:95]
	v_mfma_f32_16x16x32_bf16 v[40:43], v[100:103], v[76:79], v[40:43]
	s_add_i32 m0, vcc_lo, 0x1c00
	v_mfma_f32_16x16x32_bf16 v[60:63], v[100:103], v[84:87], v[60:63]
	global_load_lds_dwordx4 v[116:117], off
	v_lshl_add_u64 v[116:117], v[116:117], 0, s[94:95]
	s_waitcnt vmcnt(8)
	ds_read_b128 v[68:71], v124 offset:8192
	ds_read_b128 v[72:75], v124 offset:9216
	ds_read_b128 v[76:79], v124 offset:10240
	ds_read_b128 v[84:87], v124 offset:11264
	ds_read_b128 v[88:91], v124 offset:12288
	ds_read_b128 v[92:95], v124 offset:13312
	ds_read_b128 v[96:99], v124 offset:14336
	ds_read_b128 v[100:103], v124 offset:15360
	s_waitcnt lgkmcnt(0)
	v_mfma_f32_16x16x32_bf16 v[56:59], v[88:91], v[68:71], v[56:59]
	s_add_i32 m0, vcc_lo, 0x2000
	v_mfma_f32_16x16x32_bf16 v[52:55], v[88:91], v[72:75], v[52:55]
	global_load_lds_dwordx4 v[82:83], off
	v_lshl_add_u64 v[82:83], v[82:83], 0, s[94:95]
	v_mfma_f32_16x16x32_bf16 v[48:51], v[88:91], v[76:79], v[48:51]
	s_add_i32 m0, vcc_lo, 0x2400
	v_mfma_f32_16x16x32_bf16 v[44:47], v[88:91], v[84:87], v[44:47]
	global_load_lds_dwordx4 v[104:105], off
	v_lshl_add_u64 v[104:105], v[104:105], 0, s[94:95]
	v_mfma_f32_16x16x32_bf16 v[12:15], v[92:95], v[68:71], v[12:15]
	s_add_i32 m0, vcc_lo, 0x2800
	v_mfma_f32_16x16x32_bf16 v[8:11], v[92:95], v[72:75], v[8:11]
	global_load_lds_dwordx4 v[106:107], off
	v_lshl_add_u64 v[106:107], v[106:107], 0, s[94:95]
	v_mfma_f32_16x16x32_bf16 v[4:7], v[92:95], v[76:79], v[4:7]
	s_add_i32 m0, vcc_lo, 0x2c00
	v_mfma_f32_16x16x32_bf16 v[0:3], v[92:95], v[84:87], v[0:3]
	global_load_lds_dwordx4 v[108:109], off
	v_lshl_add_u64 v[108:109], v[108:109], 0, s[94:95]
	v_mfma_f32_16x16x32_bf16 v[16:19], v[96:99], v[68:71], v[16:19]
	s_add_i32 m0, vcc_lo, 0x3000
	v_mfma_f32_16x16x32_bf16 v[24:27], v[96:99], v[72:75], v[24:27]
	global_load_lds_dwordx4 v[110:111], off
	v_lshl_add_u64 v[110:111], v[110:111], 0, s[94:95]
	v_mfma_f32_16x16x32_bf16 v[28:31], v[96:99], v[76:79], v[28:31]
	s_add_i32 m0, vcc_lo, 0x3400
	v_mfma_f32_16x16x32_bf16 v[36:39], v[96:99], v[84:87], v[36:39]
	global_load_lds_dwordx4 v[112:113], off
	v_lshl_add_u64 v[112:113], v[112:113], 0, s[94:95]
	v_mfma_f32_16x16x32_bf16 v[20:23], v[100:103], v[68:71], v[20:23]
	s_add_i32 m0, vcc_lo, 0x3800
	v_mfma_f32_16x16x32_bf16 v[32:35], v[100:103], v[72:75], v[32:35]
	global_load_lds_dwordx4 v[114:115], off
	v_lshl_add_u64 v[114:115], v[114:115], 0, s[94:95]
	v_mfma_f32_16x16x32_bf16 v[40:43], v[100:103], v[76:79], v[40:43]
	s_add_i32 m0, vcc_lo, 0x3c00
	v_mfma_f32_16x16x32_bf16 v[60:63], v[100:103], v[84:87], v[60:63]
	global_load_lds_dwordx4 v[116:117], off
	v_lshl_add_u64 v[116:117], v[116:117], 0, s[94:95]
	s_waitcnt vmcnt(8)
	ds_read_b128 v[68:71], v124
	ds_read_b128 v[72:75], v124 offset:1024
	ds_read_b128 v[76:79], v124 offset:2048
	ds_read_b128 v[84:87], v124 offset:3072
	ds_read_b128 v[88:91], v124 offset:4096
	ds_read_b128 v[92:95], v124 offset:5120
	ds_read_b128 v[96:99], v124 offset:6144
	ds_read_b128 v[100:103], v124 offset:7168
	s_waitcnt lgkmcnt(0)
	v_mfma_f32_16x16x32_bf16 v[56:59], v[88:91], v[68:71], v[56:59]
	v_mfma_f32_16x16x32_bf16 v[52:55], v[88:91], v[72:75], v[52:55]
	v_mfma_f32_16x16x32_bf16 v[48:51], v[88:91], v[76:79], v[48:51]
	v_mfma_f32_16x16x32_bf16 v[44:47], v[88:91], v[84:87], v[44:47]
	v_mfma_f32_16x16x32_bf16 v[12:15], v[92:95], v[68:71], v[12:15]
	v_mfma_f32_16x16x32_bf16 v[8:11], v[92:95], v[72:75], v[8:11]
	v_mfma_f32_16x16x32_bf16 v[4:7], v[92:95], v[76:79], v[4:7]
	v_mfma_f32_16x16x32_bf16 v[0:3], v[92:95], v[84:87], v[0:3]
	v_mfma_f32_16x16x32_bf16 v[16:19], v[96:99], v[68:71], v[16:19]
	v_mfma_f32_16x16x32_bf16 v[24:27], v[96:99], v[72:75], v[24:27]
	v_mfma_f32_16x16x32_bf16 v[28:31], v[96:99], v[76:79], v[28:31]
	v_mfma_f32_16x16x32_bf16 v[36:39], v[96:99], v[84:87], v[36:39]
	v_mfma_f32_16x16x32_bf16 v[20:23], v[100:103], v[68:71], v[20:23]
	v_mfma_f32_16x16x32_bf16 v[32:35], v[100:103], v[72:75], v[32:35]
	v_mfma_f32_16x16x32_bf16 v[40:43], v[100:103], v[76:79], v[40:43]
	v_mfma_f32_16x16x32_bf16 v[60:63], v[100:103], v[84:87], v[60:63]
	s_waitcnt vmcnt(0)
	ds_read_b128 v[68:71], v124 offset:8192
	ds_read_b128 v[72:75], v124 offset:9216
	ds_read_b128 v[76:79], v124 offset:10240
	ds_read_b128 v[84:87], v124 offset:11264
	ds_read_b128 v[88:91], v124 offset:12288
	ds_read_b128 v[92:95], v124 offset:13312
	ds_read_b128 v[96:99], v124 offset:14336
	ds_read_b128 v[100:103], v124 offset:15360
	s_waitcnt lgkmcnt(0)
	v_mfma_f32_16x16x32_bf16 v[56:59], v[88:91], v[68:71], v[56:59]
	v_mfma_f32_16x16x32_bf16 v[52:55], v[88:91], v[72:75], v[52:55]
	v_mfma_f32_16x16x32_bf16 v[48:51], v[88:91], v[76:79], v[48:51]
	v_mfma_f32_16x16x32_bf16 v[44:47], v[88:91], v[84:87], v[44:47]
	v_mfma_f32_16x16x32_bf16 v[12:15], v[92:95], v[68:71], v[12:15]
	v_mfma_f32_16x16x32_bf16 v[8:11], v[92:95], v[72:75], v[8:11]
	v_mfma_f32_16x16x32_bf16 v[4:7], v[92:95], v[76:79], v[4:7]
	v_mfma_f32_16x16x32_bf16 v[0:3], v[92:95], v[84:87], v[0:3]
	v_mfma_f32_16x16x32_bf16 v[16:19], v[96:99], v[68:71], v[16:19]
	v_mfma_f32_16x16x32_bf16 v[24:27], v[96:99], v[72:75], v[24:27]
	v_mfma_f32_16x16x32_bf16 v[28:31], v[96:99], v[76:79], v[28:31]
	v_mfma_f32_16x16x32_bf16 v[36:39], v[96:99], v[84:87], v[36:39]
	v_mfma_f32_16x16x32_bf16 v[20:23], v[100:103], v[68:71], v[20:23]
	v_mfma_f32_16x16x32_bf16 v[32:35], v[100:103], v[72:75], v[32:35]
	v_mfma_f32_16x16x32_bf16 v[40:43], v[100:103], v[76:79], v[40:43]
	v_mfma_f32_16x16x32_bf16 v[60:63], v[100:103], v[84:87], v[60:63]
	s_nop 7
	s_nop 3
	v_and_b32_e32 v65, 63, v81
	s_ashr_i32 s2, s4, 7
	v_lshl_add_u32 v65, v65, 4, 0
	s_lshl_b32 s3, s2, 4
	v_lshl_add_u32 v66, s5, 14, v65
	s_addk_i32 s3, 0x4000
	ds_write_b128 v66, v[56:59]
	ds_write_b128 v66, v[52:55] offset:1024
	ds_write_b128 v66, v[48:51] offset:2048
	ds_write_b128 v66, v[44:47] offset:3072
	ds_write_b128 v66, v[12:15] offset:4096
	ds_write_b128 v66, v[8:11] offset:5120
	ds_write_b128 v66, v[4:7] offset:6144
	ds_write_b128 v66, v[0:3] offset:7168
	ds_write_b128 v66, v[16:19] offset:8192
	ds_write_b128 v66, v[24:27] offset:9216
	ds_write_b128 v66, v[28:31] offset:10240
	ds_write_b128 v66, v[36:39] offset:11264
	ds_write_b128 v66, v[20:23] offset:12288
	ds_write_b128 v66, v[32:35] offset:13312
	ds_write_b128 v66, v[40:43] offset:14336
	ds_write_b128 v66, v[60:63] offset:15360
	v_or_b32_e32 v0, s3, v80
	v_ashrrev_i32_e32 v1, 31, v0
	v_bfe_u32 v64, v81, 4, 2
	v_lshlrev_b64 v[2:3], 7, v[0:1]
	v_lshl_add_u64 v[2:3], s[8:9], 0, v[2:3]
	v_lshlrev_b32_e32 v128, 5, v64
	v_lshl_add_u64 v[6:7], v[2:3], 0, v[128:129]
	s_waitcnt lgkmcnt(0)
	s_barrier
	global_load_dwordx4 v[2:5], v[6:7], off
	s_nop 0
	global_load_dwordx4 v[6:9], v[6:7], off offset:16
	s_bfe_u32 s3, s4, 0x10006
	s_lshl_b32 s4, s3, 2
	s_add_i32 s4, s4, s2
	v_lshl_add_u32 v1, s4, 10, v65
	ds_read_b128 v[10:13], v1
	ds_read_b128 v[14:17], v1 offset:8192
	ds_read_b128 v[18:21], v1 offset:16384
	ds_read_b128 v[22:25], v1 offset:24576
	ds_read_b128 v[26:29], v1 offset:32768
	ds_read_b128 v[30:33], v1 offset:40960
	ds_read_b128 v[34:37], v1 offset:49152
	ds_read_b128 v[38:41], v1 offset:57344
	s_waitcnt lgkmcnt(0)
	v_pk_add_f32 v[10:11], v[10:11], 0 op_sel_hi:[1,0]
	v_add_u32_e32 v42, 0x10000, v1
	v_pk_add_f32 v[10:11], v[10:11], v[18:19]
	v_add_u32_e32 v46, 0x12000, v1
	v_add_u32_e32 v50, 0x14000, v1
	v_add_u32_e32 v54, 0x16000, v1
	v_add_u32_e32 v58, 0x18000, v1
	v_add_u32_e32 v62, 0x1a000, v1
	ds_read_b128 v[42:45], v42
	ds_read_b128 v[46:49], v46
	ds_read_b128 v[50:53], v50
	ds_read_b128 v[54:57], v54
	ds_read_b128 v[58:61], v58
	ds_read_b128 v[66:69], v62
	v_pk_add_f32 v[14:15], v[14:15], 0 op_sel_hi:[1,0]
	v_pk_add_f32 v[12:13], v[12:13], 0 op_sel_hi:[1,0]
	v_pk_add_f32 v[14:15], v[14:15], v[22:23]
	v_pk_add_f32 v[12:13], v[12:13], v[20:21]
	v_pk_add_f32 v[10:11], v[10:11], v[26:27]
	v_pk_add_f32 v[14:15], v[14:15], v[30:31]
	v_pk_add_f32 v[12:13], v[12:13], v[28:29]
	v_pk_add_f32 v[10:11], v[10:11], v[34:35]
	v_pk_add_f32 v[14:15], v[14:15], v[38:39]
	v_pk_add_f32 v[12:13], v[12:13], v[36:37]
	s_waitcnt lgkmcnt(0)
	v_pk_add_f32 v[10:11], v[10:11], v[42:43]
	v_pk_add_f32 v[14:15], v[14:15], v[46:47]
	v_pk_add_f32 v[12:13], v[12:13], v[44:45]
	v_pk_add_f32 v[10:11], v[10:11], v[50:51]
	v_pk_add_f32 v[14:15], v[14:15], v[54:55]
	v_pk_add_f32 v[12:13], v[12:13], v[52:53]
	v_pk_add_f32 v[10:11], v[10:11], v[58:59]
	v_pk_add_f32 v[14:15], v[14:15], v[66:67]
	v_pk_add_f32 v[12:13], v[12:13], v[60:61]
	v_pk_add_f32 v[16:17], v[16:17], 0 op_sel_hi:[1,0]
	s_lshl_b32 s0, s0, 7
	v_pk_add_f32 v[16:17], v[16:17], v[24:25]
	s_waitcnt vmcnt(0)
	v_mov_b32_e32 v18, v2
	v_mov_b32_e32 v19, v6
	v_mov_b32_e32 v6, v3
	v_mov_b32_e32 v2, v4
	v_mov_b32_e32 v3, v8
	v_mov_b32_e32 v8, v5
	v_pk_add_f32 v[4:5], v[18:19], v[6:7]
	v_pk_add_f32 v[2:3], v[2:3], v[8:9]
	v_pk_add_f32 v[16:17], v[16:17], v[32:33]
	v_pk_add_f32 v[2:3], v[4:5], v[2:3]
	v_and_b32_e32 v4, 64, v214
	v_add_f32_e32 v2, v2, v3
	v_xor_b32_e32 v3, 16, v214
	v_add_u32_e32 v4, 64, v4
	v_cmp_lt_i32_e32 vcc, v3, v4
	v_pk_add_f32 v[16:17], v[16:17], v[40:41]
	s_nop 0
	v_cndmask_b32_e32 v3, v214, v3, vcc
	v_lshlrev_b32_e32 v3, 2, v3
	ds_bpermute_b32 v3, v3, v2
	v_pk_add_f32 v[16:17], v[16:17], v[48:49]
	s_waitcnt lgkmcnt(0)
	v_add_f32_e32 v18, v2, v3
	v_xor_b32_e32 v2, 32, v214
	v_cmp_lt_i32_e32 vcc, v2, v4
	v_pk_add_f32 v[16:17], v[16:17], v[56:57]
	s_nop 0
	v_cndmask_b32_e32 v2, v214, v2, vcc
	v_lshlrev_b32_e32 v2, 2, v2
	ds_bpermute_b32 v19, v2, v18
	v_add_u32_e32 v2, 0x1c000, v1
	v_add_u32_e32 v1, 0x1e000, v1
	ds_read_b128 v[2:5], v2
	ds_read_b128 v[6:9], v1
	v_pk_add_f32 v[16:17], v[16:17], v[68:69]
	s_waitcnt lgkmcnt(2)
	v_add_f32_e32 v1, v18, v19
	v_fmamk_f32 v1, v1, 0x3a000000, v190
	v_mul_f32_e32 v18, 0x4b800000, v1
	v_cmp_gt_f32_e32 vcc, s70, v1
	s_waitcnt lgkmcnt(1)
	v_pk_add_f32 v[2:3], v[10:11], v[2:3]
	s_waitcnt lgkmcnt(0)
	v_pk_add_f32 v[6:7], v[14:15], v[6:7]
	v_cndmask_b32_e32 v1, v1, v18, vcc
	v_rsq_f32_e32 v1, v1
	v_pk_add_f32 v[4:5], v[12:13], v[4:5]
	v_mov_b32_e32 v12, v6
	v_mov_b32_e32 v13, v2
	v_mul_f32_e32 v10, 0x45800000, v1
	v_cndmask_b32_e32 v10, v1, v10, vcc
	v_pk_mul_f32 v[12:13], v[12:13], v[10:11] op_sel_hi:[1,0]
	v_lshlrev_b32_e32 v2, 2, v64
	v_mul_f32_e32 v1, 0xbfb8aa3b, v13
	v_exp_f32_e32 v1, v1
	v_lshl_or_b32 v6, s3, 4, v2
	v_mov_b32_e32 v2, v7
	v_pk_mul_f32 v[2:3], v[2:3], v[10:11] op_sel_hi:[1,0]
	v_add_f32_e32 v1, 1.0, v1
	v_mul_f32_e32 v7, 0xbfb8aa3b, v3
	v_rcp_f32_e32 v1, v1
	v_exp_f32_e32 v7, v7
	v_pk_add_f32 v[8:9], v[16:17], v[8:9]
	v_or_b32_e32 v11, s1, v6
	v_mul_f32_e32 v1, v13, v1
	v_add_f32_e32 v6, 1.0, v7
	v_mul_f32_e32 v1, v12, v1
	v_rcp_f32_e32 v12, v6
	v_mov_b32_e32 v6, v8
	v_mov_b32_e32 v7, v4
	v_pk_mul_f32 v[6:7], v[6:7], v[10:11] op_sel_hi:[1,0]
	v_mul_f32_e32 v3, v3, v12
	v_mul_f32_e32 v4, 0xbfb8aa3b, v7
	v_exp_f32_e32 v8, v4
	v_mov_b32_e32 v4, v9
	v_pk_mul_f32 v[4:5], v[4:5], v[10:11] op_sel_hi:[1,0]
	v_mul_f32_e32 v2, v2, v3
	v_mul_f32_e32 v9, 0xbfb8aa3b, v5
	v_exp_f32_e32 v9, v9
	v_add_f32_e32 v8, 1.0, v8
	v_rcp_f32_e32 v8, v8
	v_cvt_pk_bf16_f32 v2, v1, v2
	v_add_f32_e32 v9, 1.0, v9
	v_rcp_f32_e32 v9, v9
	v_mul_f32_e32 v3, v7, v8
	v_mul_f32_e32 v3, v6, v3
	s_movk_i32 s1, 0x2c00
	v_mul_f32_e32 v5, v5, v9
	v_mul_f32_e32 v4, v4, v5
	v_cvt_pk_bf16_f32 v3, v3, v4
	v_mov_b64_e32 v[4:5], s[6:7]
	v_mad_i64_i32 v[0:1], s[2:3], v0, s1, v[4:5]
	s_ashr_i32 s1, s0, 31
	v_lshl_add_u64 v[0:1], s[0:1], 1, v[0:1]
	v_lshlrev_b32_e32 v128, 1, v11
	v_lshl_add_u64 v[0:1], v[0:1], 0, v[128:129]
	global_store_dwordx2 v[0:1], v[2:3], off
	s_waitcnt lgkmcnt(0)
	s_barrier

.LBB0_1205:
	v_mov_b32_e32 v97, v210
	s_mov_b32 s2, s73
	s_cmp_gt_i32 s2, 31
	v_readfirstlane_b32 s1, v97
	s_cbranch_scc1 .LBB0_1211
	v_and_b32_e32 v96, 15, v97
	s_ashr_i32 s5, s1, 6
	v_mul_u32_u24_e32 v0, 0x1600, v96
	v_lshlrev_b32_e32 v128, 1, v0
	s_mul_i32 s6, s5, 0x2c0
	s_lshl_b32 s3, s2, 5
	s_waitcnt lgkmcnt(0)
	v_lshl_add_u64 v[0:1], s[14:15], 0, v[128:129]
	v_and_b32_e32 v128, 48, v97
	s_ashr_i32 s7, s6, 31
	s_lshl_b32 s4, s2, 6
	s_and_b32 s3, s3, 0x60
	v_lshl_add_u64 v[0:1], v[0:1], 0, v[128:129]
	s_lshl_b64 s[6:7], s[6:7], 1
	s_and_b32 s4, s4, 0xffffff00
	v_lshl_add_u64 v[28:29], v[0:1], 0, s[6:7]
	v_or_b32_e32 v0, s3, v96
	v_or_b32_e32 v2, s4, v0
	v_mov_b64_e32 v[0:1], s[12:13]
	s_movk_i32 s12, 0x2c00
	v_mad_i64_i32 v[0:1], s[12:13], v2, s12, v[0:1]
	v_lshl_add_u64 v[0:1], v[0:1], 0, v[128:129]
	v_lshl_add_u64 v[24:25], v[0:1], 0, s[6:7]
	s_mov_b32 s6, 0xb000000
	s_mov_b32 s6, 0xb02c000
	s_mov_b32 s6, 0xb058000
	s_mov_b64 s[6:7], 0xb000000
	s_mov_b32 s6, 0xb084000
	s_mov_b32 s6, 0x2c000
	s_mov_b32 s6, 0x160000
	s_mov_b32 s6, 0x18c000
	s_ashr_i32 s7, s1, 7
	s_and_b32 s6, s5, 1
	v_lshrrev_b32_e32 v130, 2, v214
	v_and_b32_e32 v131, 15, v214
	v_sub_u32_e32 v130, v130, v131
	v_mul_i32_i24_e32 v130, 0x2c00, v130
	v_bfe_u32 v133, v214, 5, 1
	v_lshlrev_b32_e32 v133, 1, v133
	v_and_b32_e32 v132, 3, v214
	v_xor_b32_e32 v133, v133, v132
	v_lshrrev_b32_e32 v132, 4, v214
	v_sub_u32_e32 v133, v133, v132
	v_lshl_add_u32 v130, v133, 4, v130
	v_ashrrev_i32_e32 v133, 31, v130
	v_add_co_u32_e32 v124, vcc, v28, v130
	s_nop 1
	v_addc_co_u32_e32 v125, vcc, v29, v133, vcc
	v_add_co_u32_e32 v126, vcc, v24, v130
	s_nop 1
	v_addc_co_u32_e32 v127, vcc, v25, v133, vcc
	v_add_co_u32_e32 v26, vcc, 0xb000000, v124
	s_nop 1
	v_addc_co_u32_e32 v27, vcc, 0, v125, vcc
	v_add_co_u32_e32 v30, vcc, 0xb02c000, v124
	s_nop 1
	v_addc_co_u32_e32 v31, vcc, 0, v125, vcc
	v_add_co_u32_e32 v70, vcc, 0xb058000, v124
	s_nop 1
	v_addc_co_u32_e32 v71, vcc, 0, v125, vcc
	v_add_co_u32_e32 v98, vcc, 0xb084000, v124
	s_nop 1
	v_addc_co_u32_e32 v99, vcc, 0, v125, vcc
	v_mov_b32_e32 v116, v126
	v_mov_b32_e32 v117, v127
	v_add_co_u32_e32 v118, vcc, 0x2c000, v126
	s_nop 1
	v_addc_co_u32_e32 v119, vcc, 0, v127, vcc
	v_add_co_u32_e32 v120, vcc, 0x160000, v126
	s_nop 1
	v_addc_co_u32_e32 v121, vcc, 0, v127, vcc
	v_add_co_u32_e32 v122, vcc, 0x18c000, v126
	s_nop 1
	v_addc_co_u32_e32 v123, vcc, 0, v127, vcc
	v_readfirstlane_b32 vcc_lo, v210
	v_bfe_u32 v133, v214, 3, 1
	v_lshlrev_b32_e32 v133, 1, v133
	v_xor_b32_e32 v133, v133, v132
	v_lshlrev_b32_e32 v133, 4, v133
	v_lshl_add_u32 v133, v131, 6, v133
	s_lshr_b32 vcc_lo, vcc_lo, 6
	s_lshl_b32 vcc_lo, vcc_lo, 14
	s_mov_b32 s94, 64
	v_add_u32_e32 v132, vcc_lo, v133
	s_add_i32 m0, vcc_lo, 0x0
	s_nop 0
	global_load_lds_dwordx4 v[26:27], off
	v_lshl_add_u64 v[26:27], v[26:27], 0, s[94:95]
	s_add_i32 m0, vcc_lo, 0x400
	s_nop 0
	global_load_lds_dwordx4 v[30:31], off
	v_lshl_add_u64 v[30:31], v[30:31], 0, s[94:95]
	s_add_i32 m0, vcc_lo, 0x800
	s_nop 0
	global_load_lds_dwordx4 v[70:71], off
	v_lshl_add_u64 v[70:71], v[70:71], 0, s[94:95]
	s_add_i32 m0, vcc_lo, 0xc00
	s_nop 0
	global_load_lds_dwordx4 v[98:99], off
	v_lshl_add_u64 v[98:99], v[98:99], 0, s[94:95]
	s_add_i32 m0, vcc_lo, 0x1000
	s_nop 0
	global_load_lds_dwordx4 v[116:117], off
	v_lshl_add_u64 v[116:117], v[116:117], 0, s[94:95]
	s_add_i32 m0, vcc_lo, 0x1400
	s_nop 0
	global_load_lds_dwordx4 v[118:119], off
	v_lshl_add_u64 v[118:119], v[118:119], 0, s[94:95]
	s_add_i32 m0, vcc_lo, 0x1800
	s_nop 0
	global_load_lds_dwordx4 v[120:121], off
	v_lshl_add_u64 v[120:121], v[120:121], 0, s[94:95]
	s_add_i32 m0, vcc_lo, 0x1c00
	s_nop 0
	global_load_lds_dwordx4 v[122:123], off
	v_lshl_add_u64 v[122:123], v[122:123], 0, s[94:95]
	s_add_i32 m0, vcc_lo, 0x2000
	s_nop 0
	global_load_lds_dwordx4 v[26:27], off
	v_lshl_add_u64 v[26:27], v[26:27], 0, s[94:95]
	s_add_i32 m0, vcc_lo, 0x2400
	s_nop 0
	global_load_lds_dwordx4 v[30:31], off
	v_lshl_add_u64 v[30:31], v[30:31], 0, s[94:95]
	s_add_i32 m0, vcc_lo, 0x2800
	s_nop 0
	global_load_lds_dwordx4 v[70:71], off
	v_lshl_add_u64 v[70:71], v[70:71], 0, s[94:95]
	s_add_i32 m0, vcc_lo, 0x2c00
	s_nop 0
	global_load_lds_dwordx4 v[98:99], off
	v_lshl_add_u64 v[98:99], v[98:99], 0, s[94:95]
	s_add_i32 m0, vcc_lo, 0x3000
	s_nop 0
	global_load_lds_dwordx4 v[116:117], off
	v_lshl_add_u64 v[116:117], v[116:117], 0, s[94:95]
	s_add_i32 m0, vcc_lo, 0x3400
	s_nop 0
	global_load_lds_dwordx4 v[118:119], off
	v_lshl_add_u64 v[118:119], v[118:119], 0, s[94:95]
	s_add_i32 m0, vcc_lo, 0x3800
	s_nop 0
	global_load_lds_dwordx4 v[120:121], off
	v_lshl_add_u64 v[120:121], v[120:121], 0, s[94:95]
	s_add_i32 m0, vcc_lo, 0x3c00
	s_nop 0
	global_load_lds_dwordx4 v[122:123], off
	v_lshl_add_u64 v[122:123], v[122:123], 0, s[94:95]
	s_waitcnt vmcnt(8)
	ds_read_b128 v[80:83], v132
	ds_read_b128 v[84:87], v132 offset:1024
	ds_read_b128 v[88:91], v132 offset:2048
	ds_read_b128 v[92:95], v132 offset:3072
	ds_read_b128 v[100:103], v132 offset:4096
	ds_read_b128 v[104:107], v132 offset:5120
	ds_read_b128 v[108:111], v132 offset:6144
	ds_read_b128 v[112:115], v132 offset:7168
	s_waitcnt lgkmcnt(0)
	v_mfma_f32_16x16x32_bf16 v[4:7], v[100:103], v[80:83], 0
	s_add_i32 m0, vcc_lo, 0x0
	v_mfma_f32_16x16x32_bf16 v[8:11], v[100:103], v[84:87], 0
	global_load_lds_dwordx4 v[26:27], off
	v_lshl_add_u64 v[26:27], v[26:27], 0, s[94:95]
	v_mfma_f32_16x16x32_bf16 v[12:15], v[100:103], v[88:91], 0
	s_add_i32 m0, vcc_lo, 0x400
	v_mfma_f32_16x16x32_bf16 v[16:19], v[100:103], v[92:95], 0
	global_load_lds_dwordx4 v[30:31], off
	v_lshl_add_u64 v[30:31], v[30:31], 0, s[94:95]
	v_mfma_f32_16x16x32_bf16 v[20:23], v[104:107], v[80:83], 0
	s_add_i32 m0, vcc_lo, 0x800
	v_mfma_f32_16x16x32_bf16 v[32:35], v[104:107], v[84:87], 0
	global_load_lds_dwordx4 v[70:71], off
	v_lshl_add_u64 v[70:71], v[70:71], 0, s[94:95]
	v_mfma_f32_16x16x32_bf16 v[36:39], v[104:107], v[88:91], 0
	s_add_i32 m0, vcc_lo, 0xc00
	v_mfma_f32_16x16x32_bf16 v[40:43], v[104:107], v[92:95], 0
	global_load_lds_dwordx4 v[98:99], off
	v_lshl_add_u64 v[98:99], v[98:99], 0, s[94:95]
	v_mfma_f32_16x16x32_bf16 v[44:47], v[108:111], v[80:83], 0
	s_add_i32 m0, vcc_lo, 0x1000
	v_mfma_f32_16x16x32_bf16 v[48:51], v[108:111], v[84:87], 0
	global_load_lds_dwordx4 v[116:117], off
	v_lshl_add_u64 v[116:117], v[116:117], 0, s[94:95]
	v_mfma_f32_16x16x32_bf16 v[52:55], v[108:111], v[88:91], 0
	s_add_i32 m0, vcc_lo, 0x1400
	v_mfma_f32_16x16x32_bf16 v[56:59], v[108:111], v[92:95], 0
	global_load_lds_dwordx4 v[118:119], off
	v_lshl_add_u64 v[118:119], v[118:119], 0, s[94:95]
	v_mfma_f32_16x16x32_bf16 v[60:63], v[112:115], v[80:83], 0
	s_add_i32 m0, vcc_lo, 0x1800
	v_mfma_f32_16x16x32_bf16 v[64:67], v[112:115], v[84:87], 0
	global_load_lds_dwordx4 v[120:121], off
	v_lshl_add_u64 v[120:121], v[120:121], 0, s[94:95]
	v_mfma_f32_16x16x32_bf16 v[72:75], v[112:115], v[88:91], 0
	s_add_i32 m0, vcc_lo, 0x1c00
	v_mfma_f32_16x16x32_bf16 v[76:79], v[112:115], v[92:95], 0
	global_load_lds_dwordx4 v[122:123], off
	v_lshl_add_u64 v[122:123], v[122:123], 0, s[94:95]
	s_waitcnt vmcnt(8)
	ds_read_b128 v[80:83], v132 offset:8192
	ds_read_b128 v[84:87], v132 offset:9216
	ds_read_b128 v[88:91], v132 offset:10240
	ds_read_b128 v[92:95], v132 offset:11264
	ds_read_b128 v[100:103], v132 offset:12288
	ds_read_b128 v[104:107], v132 offset:13312
	ds_read_b128 v[108:111], v132 offset:14336
	ds_read_b128 v[112:115], v132 offset:15360
	s_waitcnt lgkmcnt(0)
	v_mfma_f32_16x16x32_bf16 v[4:7], v[100:103], v[80:83], v[4:7]
	s_add_i32 m0, vcc_lo, 0x2000
	v_mfma_f32_16x16x32_bf16 v[8:11], v[100:103], v[84:87], v[8:11]
	global_load_lds_dwordx4 v[26:27], off
	v_lshl_add_u64 v[26:27], v[26:27], 0, s[94:95]
	v_mfma_f32_16x16x32_bf16 v[12:15], v[100:103], v[88:91], v[12:15]
	s_add_i32 m0, vcc_lo, 0x2400
	v_mfma_f32_16x16x32_bf16 v[16:19], v[100:103], v[92:95], v[16:19]
	global_load_lds_dwordx4 v[30:31], off
	v_lshl_add_u64 v[30:31], v[30:31], 0, s[94:95]
	v_mfma_f32_16x16x32_bf16 v[20:23], v[104:107], v[80:83], v[20:23]
	s_add_i32 m0, vcc_lo, 0x2800
	v_mfma_f32_16x16x32_bf16 v[32:35], v[104:107], v[84:87], v[32:35]
	global_load_lds_dwordx4 v[70:71], off
	v_lshl_add_u64 v[70:71], v[70:71], 0, s[94:95]
	v_mfma_f32_16x16x32_bf16 v[36:39], v[104:107], v[88:91], v[36:39]
	s_add_i32 m0, vcc_lo, 0x2c00
	v_mfma_f32_16x16x32_bf16 v[40:43], v[104:107], v[92:95], v[40:43]
	global_load_lds_dwordx4 v[98:99], off
	v_lshl_add_u64 v[98:99], v[98:99], 0, s[94:95]
	v_mfma_f32_16x16x32_bf16 v[44:47], v[108:111], v[80:83], v[44:47]
	s_add_i32 m0, vcc_lo, 0x3000
	v_mfma_f32_16x16x32_bf16 v[48:51], v[108:111], v[84:87], v[48:51]
	global_load_lds_dwordx4 v[116:117], off
	v_lshl_add_u64 v[116:117], v[116:117], 0, s[94:95]
	v_mfma_f32_16x16x32_bf16 v[52:55], v[108:111], v[88:91], v[52:55]
	s_add_i32 m0, vcc_lo, 0x3400
	v_mfma_f32_16x16x32_bf16 v[56:59], v[108:111], v[92:95], v[56:59]
	global_load_lds_dwordx4 v[118:119], off
	v_lshl_add_u64 v[118:119], v[118:119], 0, s[94:95]
	v_mfma_f32_16x16x32_bf16 v[60:63], v[112:115], v[80:83], v[60:63]
	s_add_i32 m0, vcc_lo, 0x3800
	v_mfma_f32_16x16x32_bf16 v[64:67], v[112:115], v[84:87], v[64:67]
	global_load_lds_dwordx4 v[120:121], off
	v_lshl_add_u64 v[120:121], v[120:121], 0, s[94:95]
	v_mfma_f32_16x16x32_bf16 v[72:75], v[112:115], v[88:91], v[72:75]
	s_add_i32 m0, vcc_lo, 0x3c00
	v_mfma_f32_16x16x32_bf16 v[76:79], v[112:115], v[92:95], v[76:79]
	global_load_lds_dwordx4 v[122:123], off
	v_lshl_add_u64 v[122:123], v[122:123], 0, s[94:95]
	s_waitcnt vmcnt(8)
	ds_read_b128 v[80:83], v132
	ds_read_b128 v[84:87], v132 offset:1024
	ds_read_b128 v[88:91], v132 offset:2048
	ds_read_b128 v[92:95], v132 offset:3072
	ds_read_b128 v[100:103], v132 offset:4096
	ds_read_b128 v[104:107], v132 offset:5120
	ds_read_b128 v[108:111], v132 offset:6144
	ds_read_b128 v[112:115], v132 offset:7168
	s_waitcnt lgkmcnt(0)
	v_mfma_f32_16x16x32_bf16 v[4:7], v[100:103], v[80:83], v[4:7]
	s_add_i32 m0, vcc_lo, 0x0
	v_mfma_f32_16x16x32_bf16 v[8:11], v[100:103], v[84:87], v[8:11]
	global_load_lds_dwordx4 v[26:27], off
	v_lshl_add_u64 v[26:27], v[26:27], 0, s[94:95]
	v_mfma_f32_16x16x32_bf16 v[12:15], v[100:103], v[88:91], v[12:15]
	s_add_i32 m0, vcc_lo, 0x400
	v_mfma_f32_16x16x32_bf16 v[16:19], v[100:103], v[92:95], v[16:19]
	global_load_lds_dwordx4 v[30:31], off
	v_lshl_add_u64 v[30:31], v[30:31], 0, s[94:95]
	v_mfma_f32_16x16x32_bf16 v[20:23], v[104:107], v[80:83], v[20:23]
	s_add_i32 m0, vcc_lo, 0x800
	v_mfma_f32_16x16x32_bf16 v[32:35], v[104:107], v[84:87], v[32:35]
	global_load_lds_dwordx4 v[70:71], off
	v_lshl_add_u64 v[70:71], v[70:71], 0, s[94:95]
	v_mfma_f32_16x16x32_bf16 v[36:39], v[104:107], v[88:91], v[36:39]
	s_add_i32 m0, vcc_lo, 0xc00
	v_mfma_f32_16x16x32_bf16 v[40:43], v[104:107], v[92:95], v[40:43]
	global_load_lds_dwordx4 v[98:99], off
	v_lshl_add_u64 v[98:99], v[98:99], 0, s[94:95]
	v_mfma_f32_16x16x32_bf16 v[44:47], v[108:111], v[80:83], v[44:47]
	s_add_i32 m0, vcc_lo, 0x1000
	v_mfma_f32_16x16x32_bf16 v[48:51], v[108:111], v[84:87], v[48:51]
	global_load_lds_dwordx4 v[116:117], off
	v_lshl_add_u64 v[116:117], v[116:117], 0, s[94:95]
	v_mfma_f32_16x16x32_bf16 v[52:55], v[108:111], v[88:91], v[52:55]
	s_add_i32 m0, vcc_lo, 0x1400
	v_mfma_f32_16x16x32_bf16 v[56:59], v[108:111], v[92:95], v[56:59]
	global_load_lds_dwordx4 v[118:119], off
	v_lshl_add_u64 v[118:119], v[118:119], 0, s[94:95]
	v_mfma_f32_16x16x32_bf16 v[60:63], v[112:115], v[80:83], v[60:63]
	s_add_i32 m0, vcc_lo, 0x1800
	v_mfma_f32_16x16x32_bf16 v[64:67], v[112:115], v[84:87], v[64:67]
	global_load_lds_dwordx4 v[120:121], off
	v_lshl_add_u64 v[120:121], v[120:121], 0, s[94:95]
	v_mfma_f32_16x16x32_bf16 v[72:75], v[112:115], v[88:91], v[72:75]
	s_add_i32 m0, vcc_lo, 0x1c00
	v_mfma_f32_16x16x32_bf16 v[76:79], v[112:115], v[92:95], v[76:79]
	global_load_lds_dwordx4 v[122:123], off
	v_lshl_add_u64 v[122:123], v[122:123], 0, s[94:95]
	s_waitcnt vmcnt(8)
	ds_read_b128 v[80:83], v132 offset:8192
	ds_read_b128 v[84:87], v132 offset:9216
	ds_read_b128 v[88:91], v132 offset:10240
	ds_read_b128 v[92:95], v132 offset:11264
	ds_read_b128 v[100:103], v132 offset:12288
	ds_read_b128 v[104:107], v132 offset:13312
	ds_read_b128 v[108:111], v132 offset:14336
	ds_read_b128 v[112:115], v132 offset:15360
	s_waitcnt lgkmcnt(0)
	v_mfma_f32_16x16x32_bf16 v[4:7], v[100:103], v[80:83], v[4:7]
	s_add_i32 m0, vcc_lo, 0x2000
	v_mfma_f32_16x16x32_bf16 v[8:11], v[100:103], v[84:87], v[8:11]
	global_load_lds_dwordx4 v[26:27], off
	v_lshl_add_u64 v[26:27], v[26:27], 0, s[94:95]
	v_mfma_f32_16x16x32_bf16 v[12:15], v[100:103], v[88:91], v[12:15]
	s_add_i32 m0, vcc_lo, 0x2400
	v_mfma_f32_16x16x32_bf16 v[16:19], v[100:103], v[92:95], v[16:19]
	global_load_lds_dwordx4 v[30:31], off
	v_lshl_add_u64 v[30:31], v[30:31], 0, s[94:95]
	v_mfma_f32_16x16x32_bf16 v[20:23], v[104:107], v[80:83], v[20:23]
	s_add_i32 m0, vcc_lo, 0x2800
	v_mfma_f32_16x16x32_bf16 v[32:35], v[104:107], v[84:87], v[32:35]
	global_load_lds_dwordx4 v[70:71], off
	v_lshl_add_u64 v[70:71], v[70:71], 0, s[94:95]
	v_mfma_f32_16x16x32_bf16 v[36:39], v[104:107], v[88:91], v[36:39]
	s_add_i32 m0, vcc_lo, 0x2c00
	v_mfma_f32_16x16x32_bf16 v[40:43], v[104:107], v[92:95], v[40:43]
	global_load_lds_dwordx4 v[98:99], off
	v_lshl_add_u64 v[98:99], v[98:99], 0, s[94:95]
	v_mfma_f32_16x16x32_bf16 v[44:47], v[108:111], v[80:83], v[44:47]
	s_add_i32 m0, vcc_lo, 0x3000
	v_mfma_f32_16x16x32_bf16 v[48:51], v[108:111], v[84:87], v[48:51]
	global_load_lds_dwordx4 v[116:117], off
	v_lshl_add_u64 v[116:117], v[116:117], 0, s[94:95]
	v_mfma_f32_16x16x32_bf16 v[52:55], v[108:111], v[88:91], v[52:55]
	s_add_i32 m0, vcc_lo, 0x3400
	v_mfma_f32_16x16x32_bf16 v[56:59], v[108:111], v[92:95], v[56:59]
	global_load_lds_dwordx4 v[118:119], off
	v_lshl_add_u64 v[118:119], v[118:119], 0, s[94:95]
	v_mfma_f32_16x16x32_bf16 v[60:63], v[112:115], v[80:83], v[60:63]
	s_add_i32 m0, vcc_lo, 0x3800
	v_mfma_f32_16x16x32_bf16 v[64:67], v[112:115], v[84:87], v[64:67]
	global_load_lds_dwordx4 v[120:121], off
	v_lshl_add_u64 v[120:121], v[120:121], 0, s[94:95]
	v_mfma_f32_16x16x32_bf16 v[72:75], v[112:115], v[88:91], v[72:75]
	s_add_i32 m0, vcc_lo, 0x3c00
	v_mfma_f32_16x16x32_bf16 v[76:79], v[112:115], v[92:95], v[76:79]
	global_load_lds_dwordx4 v[122:123], off
	v_lshl_add_u64 v[122:123], v[122:123], 0, s[94:95]
	s_waitcnt vmcnt(8)
	ds_read_b128 v[80:83], v132
	ds_read_b128 v[84:87], v132 offset:1024
	ds_read_b128 v[88:91], v132 offset:2048
	ds_read_b128 v[92:95], v132 offset:3072
	ds_read_b128 v[100:103], v132 offset:4096
	ds_read_b128 v[104:107], v132 offset:5120
	ds_read_b128 v[108:111], v132 offset:6144
	ds_read_b128 v[112:115], v132 offset:7168
	s_waitcnt lgkmcnt(0)
	v_mfma_f32_16x16x32_bf16 v[4:7], v[100:103], v[80:83], v[4:7]
	s_add_i32 m0, vcc_lo, 0x0
	v_mfma_f32_16x16x32_bf16 v[8:11], v[100:103], v[84:87], v[8:11]
	global_load_lds_dwordx4 v[26:27], off
	v_lshl_add_u64 v[26:27], v[26:27], 0, s[94:95]
	v_mfma_f32_16x16x32_bf16 v[12:15], v[100:103], v[88:91], v[12:15]
	s_add_i32 m0, vcc_lo, 0x400
	v_mfma_f32_16x16x32_bf16 v[16:19], v[100:103], v[92:95], v[16:19]
	global_load_lds_dwordx4 v[30:31], off
	v_lshl_add_u64 v[30:31], v[30:31], 0, s[94:95]
	v_mfma_f32_16x16x32_bf16 v[20:23], v[104:107], v[80:83], v[20:23]
	s_add_i32 m0, vcc_lo, 0x800
	v_mfma_f32_16x16x32_bf16 v[32:35], v[104:107], v[84:87], v[32:35]
	global_load_lds_dwordx4 v[70:71], off
	v_lshl_add_u64 v[70:71], v[70:71], 0, s[94:95]
	v_mfma_f32_16x16x32_bf16 v[36:39], v[104:107], v[88:91], v[36:39]
	s_add_i32 m0, vcc_lo, 0xc00
	v_mfma_f32_16x16x32_bf16 v[40:43], v[104:107], v[92:95], v[40:43]
	global_load_lds_dwordx4 v[98:99], off
	v_lshl_add_u64 v[98:99], v[98:99], 0, s[94:95]
	v_mfma_f32_16x16x32_bf16 v[44:47], v[108:111], v[80:83], v[44:47]
	s_add_i32 m0, vcc_lo, 0x1000
	v_mfma_f32_16x16x32_bf16 v[48:51], v[108:111], v[84:87], v[48:51]
	global_load_lds_dwordx4 v[116:117], off
	v_lshl_add_u64 v[116:117], v[116:117], 0, s[94:95]
	v_mfma_f32_16x16x32_bf16 v[52:55], v[108:111], v[88:91], v[52:55]
	s_add_i32 m0, vcc_lo, 0x1400
	v_mfma_f32_16x16x32_bf16 v[56:59], v[108:111], v[92:95], v[56:59]
	global_load_lds_dwordx4 v[118:119], off
	v_lshl_add_u64 v[118:119], v[118:119], 0, s[94:95]
	v_mfma_f32_16x16x32_bf16 v[60:63], v[112:115], v[80:83], v[60:63]
	s_add_i32 m0, vcc_lo, 0x1800
	v_mfma_f32_16x16x32_bf16 v[64:67], v[112:115], v[84:87], v[64:67]
	global_load_lds_dwordx4 v[120:121], off
	v_lshl_add_u64 v[120:121], v[120:121], 0, s[94:95]
	v_mfma_f32_16x16x32_bf16 v[72:75], v[112:115], v[88:91], v[72:75]
	s_add_i32 m0, vcc_lo, 0x1c00
	v_mfma_f32_16x16x32_bf16 v[76:79], v[112:115], v[92:95], v[76:79]
	global_load_lds_dwordx4 v[122:123], off
	v_lshl_add_u64 v[122:123], v[122:123], 0, s[94:95]
	s_waitcnt vmcnt(8)
	ds_read_b128 v[80:83], v132 offset:8192
	ds_read_b128 v[84:87], v132 offset:9216
	ds_read_b128 v[88:91], v132 offset:10240
	ds_read_b128 v[92:95], v132 offset:11264
	ds_read_b128 v[100:103], v132 offset:12288
	ds_read_b128 v[104:107], v132 offset:13312
	ds_read_b128 v[108:111], v132 offset:14336
	ds_read_b128 v[112:115], v132 offset:15360
	s_waitcnt lgkmcnt(0)
	v_mfma_f32_16x16x32_bf16 v[4:7], v[100:103], v[80:83], v[4:7]
	s_add_i32 m0, vcc_lo, 0x2000
	v_mfma_f32_16x16x32_bf16 v[8:11], v[100:103], v[84:87], v[8:11]
	global_load_lds_dwordx4 v[26:27], off
	v_lshl_add_u64 v[26:27], v[26:27], 0, s[94:95]
	v_mfma_f32_16x16x32_bf16 v[12:15], v[100:103], v[88:91], v[12:15]
	s_add_i32 m0, vcc_lo, 0x2400
	v_mfma_f32_16x16x32_bf16 v[16:19], v[100:103], v[92:95], v[16:19]
	global_load_lds_dwordx4 v[30:31], off
	v_lshl_add_u64 v[30:31], v[30:31], 0, s[94:95]
	v_mfma_f32_16x16x32_bf16 v[20:23], v[104:107], v[80:83], v[20:23]
	s_add_i32 m0, vcc_lo, 0x2800
	v_mfma_f32_16x16x32_bf16 v[32:35], v[104:107], v[84:87], v[32:35]
	global_load_lds_dwordx4 v[70:71], off
	v_lshl_add_u64 v[70:71], v[70:71], 0, s[94:95]
	v_mfma_f32_16x16x32_bf16 v[36:39], v[104:107], v[88:91], v[36:39]
	s_add_i32 m0, vcc_lo, 0x2c00
	v_mfma_f32_16x16x32_bf16 v[40:43], v[104:107], v[92:95], v[40:43]
	global_load_lds_dwordx4 v[98:99], off
	v_lshl_add_u64 v[98:99], v[98:99], 0, s[94:95]
	v_mfma_f32_16x16x32_bf16 v[44:47], v[108:111], v[80:83], v[44:47]
	s_add_i32 m0, vcc_lo, 0x3000
	v_mfma_f32_16x16x32_bf16 v[48:51], v[108:111], v[84:87], v[48:51]
	global_load_lds_dwordx4 v[116:117], off
	v_lshl_add_u64 v[116:117], v[116:117], 0, s[94:95]
	v_mfma_f32_16x16x32_bf16 v[52:55], v[108:111], v[88:91], v[52:55]
	s_add_i32 m0, vcc_lo, 0x3400
	v_mfma_f32_16x16x32_bf16 v[56:59], v[108:111], v[92:95], v[56:59]
	global_load_lds_dwordx4 v[118:119], off
	v_lshl_add_u64 v[118:119], v[118:119], 0, s[94:95]
	v_mfma_f32_16x16x32_bf16 v[60:63], v[112:115], v[80:83], v[60:63]
	s_add_i32 m0, vcc_lo, 0x3800
	v_mfma_f32_16x16x32_bf16 v[64:67], v[112:115], v[84:87], v[64:67]
	global_load_lds_dwordx4 v[120:121], off
	v_lshl_add_u64 v[120:121], v[120:121], 0, s[94:95]
	v_mfma_f32_16x16x32_bf16 v[72:75], v[112:115], v[88:91], v[72:75]
	s_add_i32 m0, vcc_lo, 0x3c00
	v_mfma_f32_16x16x32_bf16 v[76:79], v[112:115], v[92:95], v[76:79]
	global_load_lds_dwordx4 v[122:123], off
	v_lshl_add_u64 v[122:123], v[122:123], 0, s[94:95]
	s_waitcnt vmcnt(8)
	ds_read_b128 v[80:83], v132
	ds_read_b128 v[84:87], v132 offset:1024
	ds_read_b128 v[88:91], v132 offset:2048
	ds_read_b128 v[92:95], v132 offset:3072
	ds_read_b128 v[100:103], v132 offset:4096
	ds_read_b128 v[104:107], v132 offset:5120
	ds_read_b128 v[108:111], v132 offset:6144
	ds_read_b128 v[112:115], v132 offset:7168
	s_waitcnt lgkmcnt(0)
	v_mfma_f32_16x16x32_bf16 v[4:7], v[100:103], v[80:83], v[4:7]
	s_add_i32 m0, vcc_lo, 0x0
	v_mfma_f32_16x16x32_bf16 v[8:11], v[100:103], v[84:87], v[8:11]
	global_load_lds_dwordx4 v[26:27], off
	v_lshl_add_u64 v[26:27], v[26:27], 0, s[94:95]
	v_mfma_f32_16x16x32_bf16 v[12:15], v[100:103], v[88:91], v[12:15]
	s_add_i32 m0, vcc_lo, 0x400
	v_mfma_f32_16x16x32_bf16 v[16:19], v[100:103], v[92:95], v[16:19]
	global_load_lds_dwordx4 v[30:31], off
	v_lshl_add_u64 v[30:31], v[30:31], 0, s[94:95]
	v_mfma_f32_16x16x32_bf16 v[20:23], v[104:107], v[80:83], v[20:23]
	s_add_i32 m0, vcc_lo, 0x800
	v_mfma_f32_16x16x32_bf16 v[32:35], v[104:107], v[84:87], v[32:35]
	global_load_lds_dwordx4 v[70:71], off
	v_lshl_add_u64 v[70:71], v[70:71], 0, s[94:95]
	v_mfma_f32_16x16x32_bf16 v[36:39], v[104:107], v[88:91], v[36:39]
	s_add_i32 m0, vcc_lo, 0xc00
	v_mfma_f32_16x16x32_bf16 v[40:43], v[104:107], v[92:95], v[40:43]
	global_load_lds_dwordx4 v[98:99], off
	v_lshl_add_u64 v[98:99], v[98:99], 0, s[94:95]
	v_mfma_f32_16x16x32_bf16 v[44:47], v[108:111], v[80:83], v[44:47]
	s_add_i32 m0, vcc_lo, 0x1000
	v_mfma_f32_16x16x32_bf16 v[48:51], v[108:111], v[84:87], v[48:51]
	global_load_lds_dwordx4 v[116:117], off
	v_lshl_add_u64 v[116:117], v[116:117], 0, s[94:95]
	v_mfma_f32_16x16x32_bf16 v[52:55], v[108:111], v[88:91], v[52:55]
	s_add_i32 m0, vcc_lo, 0x1400
	v_mfma_f32_16x16x32_bf16 v[56:59], v[108:111], v[92:95], v[56:59]
	global_load_lds_dwordx4 v[118:119], off
	v_lshl_add_u64 v[118:119], v[118:119], 0, s[94:95]
	v_mfma_f32_16x16x32_bf16 v[60:63], v[112:115], v[80:83], v[60:63]
	s_add_i32 m0, vcc_lo, 0x1800
	v_mfma_f32_16x16x32_bf16 v[64:67], v[112:115], v[84:87], v[64:67]
	global_load_lds_dwordx4 v[120:121], off
	v_lshl_add_u64 v[120:121], v[120:121], 0, s[94:95]
	v_mfma_f32_16x16x32_bf16 v[72:75], v[112:115], v[88:91], v[72:75]
	s_add_i32 m0, vcc_lo, 0x1c00
	v_mfma_f32_16x16x32_bf16 v[76:79], v[112:115], v[92:95], v[76:79]
	global_load_lds_dwordx4 v[122:123], off
	v_lshl_add_u64 v[122:123], v[122:123], 0, s[94:95]
	s_waitcnt vmcnt(8)
	ds_read_b128 v[80:83], v132 offset:8192
	ds_read_b128 v[84:87], v132 offset:9216
	ds_read_b128 v[88:91], v132 offset:10240
	ds_read_b128 v[92:95], v132 offset:11264
	ds_read_b128 v[100:103], v132 offset:12288
	ds_read_b128 v[104:107], v132 offset:13312
	ds_read_b128 v[108:111], v132 offset:14336
	ds_read_b128 v[112:115], v132 offset:15360
	s_waitcnt lgkmcnt(0)
	v_mfma_f32_16x16x32_bf16 v[4:7], v[100:103], v[80:83], v[4:7]
	s_add_i32 m0, vcc_lo, 0x2000
	v_mfma_f32_16x16x32_bf16 v[8:11], v[100:103], v[84:87], v[8:11]
	global_load_lds_dwordx4 v[26:27], off
	v_lshl_add_u64 v[26:27], v[26:27], 0, s[94:95]
	v_mfma_f32_16x16x32_bf16 v[12:15], v[100:103], v[88:91], v[12:15]
	s_add_i32 m0, vcc_lo, 0x2400
	v_mfma_f32_16x16x32_bf16 v[16:19], v[100:103], v[92:95], v[16:19]
	global_load_lds_dwordx4 v[30:31], off
	v_lshl_add_u64 v[30:31], v[30:31], 0, s[94:95]
	v_mfma_f32_16x16x32_bf16 v[20:23], v[104:107], v[80:83], v[20:23]
	s_add_i32 m0, vcc_lo, 0x2800
	v_mfma_f32_16x16x32_bf16 v[32:35], v[104:107], v[84:87], v[32:35]
	global_load_lds_dwordx4 v[70:71], off
	v_lshl_add_u64 v[70:71], v[70:71], 0, s[94:95]
	v_mfma_f32_16x16x32_bf16 v[36:39], v[104:107], v[88:91], v[36:39]
	s_add_i32 m0, vcc_lo, 0x2c00
	v_mfma_f32_16x16x32_bf16 v[40:43], v[104:107], v[92:95], v[40:43]
	global_load_lds_dwordx4 v[98:99], off
	v_lshl_add_u64 v[98:99], v[98:99], 0, s[94:95]
	v_mfma_f32_16x16x32_bf16 v[44:47], v[108:111], v[80:83], v[44:47]
	s_add_i32 m0, vcc_lo, 0x3000
	v_mfma_f32_16x16x32_bf16 v[48:51], v[108:111], v[84:87], v[48:51]
	global_load_lds_dwordx4 v[116:117], off
	v_lshl_add_u64 v[116:117], v[116:117], 0, s[94:95]
	v_mfma_f32_16x16x32_bf16 v[52:55], v[108:111], v[88:91], v[52:55]
	s_add_i32 m0, vcc_lo, 0x3400
	v_mfma_f32_16x16x32_bf16 v[56:59], v[108:111], v[92:95], v[56:59]
	global_load_lds_dwordx4 v[118:119], off
	v_lshl_add_u64 v[118:119], v[118:119], 0, s[94:95]
	v_mfma_f32_16x16x32_bf16 v[60:63], v[112:115], v[80:83], v[60:63]
	s_add_i32 m0, vcc_lo, 0x3800
	v_mfma_f32_16x16x32_bf16 v[64:67], v[112:115], v[84:87], v[64:67]
	global_load_lds_dwordx4 v[120:121], off
	v_lshl_add_u64 v[120:121], v[120:121], 0, s[94:95]
	v_mfma_f32_16x16x32_bf16 v[72:75], v[112:115], v[88:91], v[72:75]
	s_add_i32 m0, vcc_lo, 0x3c00
	v_mfma_f32_16x16x32_bf16 v[76:79], v[112:115], v[92:95], v[76:79]
	global_load_lds_dwordx4 v[122:123], off
	v_lshl_add_u64 v[122:123], v[122:123], 0, s[94:95]
	s_waitcnt vmcnt(8)
	ds_read_b128 v[80:83], v132
	ds_read_b128 v[84:87], v132 offset:1024
	ds_read_b128 v[88:91], v132 offset:2048
	ds_read_b128 v[92:95], v132 offset:3072
	ds_read_b128 v[100:103], v132 offset:4096
	ds_read_b128 v[104:107], v132 offset:5120
	ds_read_b128 v[108:111], v132 offset:6144
	ds_read_b128 v[112:115], v132 offset:7168
	s_waitcnt lgkmcnt(0)
	v_mfma_f32_16x16x32_bf16 v[4:7], v[100:103], v[80:83], v[4:7]
	s_add_i32 m0, vcc_lo, 0x0
	v_mfma_f32_16x16x32_bf16 v[8:11], v[100:103], v[84:87], v[8:11]
	global_load_lds_dwordx4 v[26:27], off
	v_lshl_add_u64 v[26:27], v[26:27], 0, s[94:95]
	v_mfma_f32_16x16x32_bf16 v[12:15], v[100:103], v[88:91], v[12:15]
	s_add_i32 m0, vcc_lo, 0x400
	v_mfma_f32_16x16x32_bf16 v[16:19], v[100:103], v[92:95], v[16:19]
	global_load_lds_dwordx4 v[30:31], off
	v_lshl_add_u64 v[30:31], v[30:31], 0, s[94:95]
	v_mfma_f32_16x16x32_bf16 v[20:23], v[104:107], v[80:83], v[20:23]
	s_add_i32 m0, vcc_lo, 0x800
	v_mfma_f32_16x16x32_bf16 v[32:35], v[104:107], v[84:87], v[32:35]
	global_load_lds_dwordx4 v[70:71], off
	v_lshl_add_u64 v[70:71], v[70:71], 0, s[94:95]
	v_mfma_f32_16x16x32_bf16 v[36:39], v[104:107], v[88:91], v[36:39]
	s_add_i32 m0, vcc_lo, 0xc00
	v_mfma_f32_16x16x32_bf16 v[40:43], v[104:107], v[92:95], v[40:43]
	global_load_lds_dwordx4 v[98:99], off
	v_lshl_add_u64 v[98:99], v[98:99], 0, s[94:95]
	v_mfma_f32_16x16x32_bf16 v[44:47], v[108:111], v[80:83], v[44:47]
	s_add_i32 m0, vcc_lo, 0x1000
	v_mfma_f32_16x16x32_bf16 v[48:51], v[108:111], v[84:87], v[48:51]
	global_load_lds_dwordx4 v[116:117], off
	v_lshl_add_u64 v[116:117], v[116:117], 0, s[94:95]
	v_mfma_f32_16x16x32_bf16 v[52:55], v[108:111], v[88:91], v[52:55]
	s_add_i32 m0, vcc_lo, 0x1400
	v_mfma_f32_16x16x32_bf16 v[56:59], v[108:111], v[92:95], v[56:59]
	global_load_lds_dwordx4 v[118:119], off
	v_lshl_add_u64 v[118:119], v[118:119], 0, s[94:95]
	v_mfma_f32_16x16x32_bf16 v[60:63], v[112:115], v[80:83], v[60:63]
	s_add_i32 m0, vcc_lo, 0x1800
	v_mfma_f32_16x16x32_bf16 v[64:67], v[112:115], v[84:87], v[64:67]
	global_load_lds_dwordx4 v[120:121], off
	v_lshl_add_u64 v[120:121], v[120:121], 0, s[94:95]
	v_mfma_f32_16x16x32_bf16 v[72:75], v[112:115], v[88:91], v[72:75]
	s_add_i32 m0, vcc_lo, 0x1c00
	v_mfma_f32_16x16x32_bf16 v[76:79], v[112:115], v[92:95], v[76:79]
	global_load_lds_dwordx4 v[122:123], off
	v_lshl_add_u64 v[122:123], v[122:123], 0, s[94:95]
	s_waitcnt vmcnt(8)
	ds_read_b128 v[80:83], v132 offset:8192
	ds_read_b128 v[84:87], v132 offset:9216
	ds_read_b128 v[88:91], v132 offset:10240
	ds_read_b128 v[92:95], v132 offset:11264
	ds_read_b128 v[100:103], v132 offset:12288
	ds_read_b128 v[104:107], v132 offset:13312
	ds_read_b128 v[108:111], v132 offset:14336
	ds_read_b128 v[112:115], v132 offset:15360
	s_waitcnt lgkmcnt(0)
	v_mfma_f32_16x16x32_bf16 v[4:7], v[100:103], v[80:83], v[4:7]
	s_add_i32 m0, vcc_lo, 0x2000
	v_mfma_f32_16x16x32_bf16 v[8:11], v[100:103], v[84:87], v[8:11]
	global_load_lds_dwordx4 v[26:27], off
	v_lshl_add_u64 v[26:27], v[26:27], 0, s[94:95]
	v_mfma_f32_16x16x32_bf16 v[12:15], v[100:103], v[88:91], v[12:15]
	s_add_i32 m0, vcc_lo, 0x2400
	v_mfma_f32_16x16x32_bf16 v[16:19], v[100:103], v[92:95], v[16:19]
	global_load_lds_dwordx4 v[30:31], off
	v_lshl_add_u64 v[30:31], v[30:31], 0, s[94:95]
	v_mfma_f32_16x16x32_bf16 v[20:23], v[104:107], v[80:83], v[20:23]
	s_add_i32 m0, vcc_lo, 0x2800
	v_mfma_f32_16x16x32_bf16 v[32:35], v[104:107], v[84:87], v[32:35]
	global_load_lds_dwordx4 v[70:71], off
	v_lshl_add_u64 v[70:71], v[70:71], 0, s[94:95]
	v_mfma_f32_16x16x32_bf16 v[36:39], v[104:107], v[88:91], v[36:39]
	s_add_i32 m0, vcc_lo, 0x2c00
	v_mfma_f32_16x16x32_bf16 v[40:43], v[104:107], v[92:95], v[40:43]
	global_load_lds_dwordx4 v[98:99], off
	v_lshl_add_u64 v[98:99], v[98:99], 0, s[94:95]
	v_mfma_f32_16x16x32_bf16 v[44:47], v[108:111], v[80:83], v[44:47]
	s_add_i32 m0, vcc_lo, 0x3000
	v_mfma_f32_16x16x32_bf16 v[48:51], v[108:111], v[84:87], v[48:51]
	global_load_lds_dwordx4 v[116:117], off
	v_lshl_add_u64 v[116:117], v[116:117], 0, s[94:95]
	v_mfma_f32_16x16x32_bf16 v[52:55], v[108:111], v[88:91], v[52:55]
	s_add_i32 m0, vcc_lo, 0x3400
	v_mfma_f32_16x16x32_bf16 v[56:59], v[108:111], v[92:95], v[56:59]
	global_load_lds_dwordx4 v[118:119], off
	v_lshl_add_u64 v[118:119], v[118:119], 0, s[94:95]
	v_mfma_f32_16x16x32_bf16 v[60:63], v[112:115], v[80:83], v[60:63]
	s_add_i32 m0, vcc_lo, 0x3800
	v_mfma_f32_16x16x32_bf16 v[64:67], v[112:115], v[84:87], v[64:67]
	global_load_lds_dwordx4 v[120:121], off
	v_lshl_add_u64 v[120:121], v[120:121], 0, s[94:95]
	v_mfma_f32_16x16x32_bf16 v[72:75], v[112:115], v[88:91], v[72:75]
	s_add_i32 m0, vcc_lo, 0x3c00
	v_mfma_f32_16x16x32_bf16 v[76:79], v[112:115], v[92:95], v[76:79]
	global_load_lds_dwordx4 v[122:123], off
	v_lshl_add_u64 v[122:123], v[122:123], 0, s[94:95]
	s_waitcnt vmcnt(8)
	ds_read_b128 v[80:83], v132
	ds_read_b128 v[84:87], v132 offset:1024
	ds_read_b128 v[88:91], v132 offset:2048
	ds_read_b128 v[92:95], v132 offset:3072
	ds_read_b128 v[100:103], v132 offset:4096
	ds_read_b128 v[104:107], v132 offset:5120
	ds_read_b128 v[108:111], v132 offset:6144
	ds_read_b128 v[112:115], v132 offset:7168
	s_waitcnt lgkmcnt(0)
	v_mfma_f32_16x16x32_bf16 v[4:7], v[100:103], v[80:83], v[4:7]
	s_add_i32 m0, vcc_lo, 0x0
	v_mfma_f32_16x16x32_bf16 v[8:11], v[100:103], v[84:87], v[8:11]
	global_load_lds_dwordx4 v[26:27], off
	v_lshl_add_u64 v[26:27], v[26:27], 0, s[94:95]
	v_mfma_f32_16x16x32_bf16 v[12:15], v[100:103], v[88:91], v[12:15]
	s_add_i32 m0, vcc_lo, 0x400
	v_mfma_f32_16x16x32_bf16 v[16:19], v[100:103], v[92:95], v[16:19]
	global_load_lds_dwordx4 v[30:31], off
	v_lshl_add_u64 v[30:31], v[30:31], 0, s[94:95]
	v_mfma_f32_16x16x32_bf16 v[20:23], v[104:107], v[80:83], v[20:23]
	s_add_i32 m0, vcc_lo, 0x800
	v_mfma_f32_16x16x32_bf16 v[32:35], v[104:107], v[84:87], v[32:35]
	global_load_lds_dwordx4 v[70:71], off
	v_lshl_add_u64 v[70:71], v[70:71], 0, s[94:95]
	v_mfma_f32_16x16x32_bf16 v[36:39], v[104:107], v[88:91], v[36:39]
	s_add_i32 m0, vcc_lo, 0xc00
	v_mfma_f32_16x16x32_bf16 v[40:43], v[104:107], v[92:95], v[40:43]
	global_load_lds_dwordx4 v[98:99], off
	v_lshl_add_u64 v[98:99], v[98:99], 0, s[94:95]
	v_mfma_f32_16x16x32_bf16 v[44:47], v[108:111], v[80:83], v[44:47]
	s_add_i32 m0, vcc_lo, 0x1000
	v_mfma_f32_16x16x32_bf16 v[48:51], v[108:111], v[84:87], v[48:51]
	global_load_lds_dwordx4 v[116:117], off
	v_lshl_add_u64 v[116:117], v[116:117], 0, s[94:95]
	v_mfma_f32_16x16x32_bf16 v[52:55], v[108:111], v[88:91], v[52:55]
	s_add_i32 m0, vcc_lo, 0x1400
	v_mfma_f32_16x16x32_bf16 v[56:59], v[108:111], v[92:95], v[56:59]
	global_load_lds_dwordx4 v[118:119], off
	v_lshl_add_u64 v[118:119], v[118:119], 0, s[94:95]
	v_mfma_f32_16x16x32_bf16 v[60:63], v[112:115], v[80:83], v[60:63]
	s_add_i32 m0, vcc_lo, 0x1800
	v_mfma_f32_16x16x32_bf16 v[64:67], v[112:115], v[84:87], v[64:67]
	global_load_lds_dwordx4 v[120:121], off
	v_lshl_add_u64 v[120:121], v[120:121], 0, s[94:95]
	v_mfma_f32_16x16x32_bf16 v[72:75], v[112:115], v[88:91], v[72:75]
	s_add_i32 m0, vcc_lo, 0x1c00
	v_mfma_f32_16x16x32_bf16 v[76:79], v[112:115], v[92:95], v[76:79]
	global_load_lds_dwordx4 v[122:123], off
	v_lshl_add_u64 v[122:123], v[122:123], 0, s[94:95]
	s_waitcnt vmcnt(8)
	ds_read_b128 v[80:83], v132 offset:8192
	ds_read_b128 v[84:87], v132 offset:9216
	ds_read_b128 v[88:91], v132 offset:10240
	ds_read_b128 v[92:95], v132 offset:11264
	ds_read_b128 v[100:103], v132 offset:12288
	ds_read_b128 v[104:107], v132 offset:13312
	ds_read_b128 v[108:111], v132 offset:14336
	ds_read_b128 v[112:115], v132 offset:15360
	s_waitcnt lgkmcnt(0)
	v_mfma_f32_16x16x32_bf16 v[4:7], v[100:103], v[80:83], v[4:7]
	s_add_i32 m0, vcc_lo, 0x2000
	v_mfma_f32_16x16x32_bf16 v[8:11], v[100:103], v[84:87], v[8:11]
	global_load_lds_dwordx4 v[26:27], off
	v_lshl_add_u64 v[26:27], v[26:27], 0, s[94:95]
	v_mfma_f32_16x16x32_bf16 v[12:15], v[100:103], v[88:91], v[12:15]
	s_add_i32 m0, vcc_lo, 0x2400
	v_mfma_f32_16x16x32_bf16 v[16:19], v[100:103], v[92:95], v[16:19]
	global_load_lds_dwordx4 v[30:31], off
	v_lshl_add_u64 v[30:31], v[30:31], 0, s[94:95]
	v_mfma_f32_16x16x32_bf16 v[20:23], v[104:107], v[80:83], v[20:23]
	s_add_i32 m0, vcc_lo, 0x2800
	v_mfma_f32_16x16x32_bf16 v[32:35], v[104:107], v[84:87], v[32:35]
	global_load_lds_dwordx4 v[70:71], off
	v_lshl_add_u64 v[70:71], v[70:71], 0, s[94:95]
	v_mfma_f32_16x16x32_bf16 v[36:39], v[104:107], v[88:91], v[36:39]
	s_add_i32 m0, vcc_lo, 0x2c00
	v_mfma_f32_16x16x32_bf16 v[40:43], v[104:107], v[92:95], v[40:43]
	global_load_lds_dwordx4 v[98:99], off
	v_lshl_add_u64 v[98:99], v[98:99], 0, s[94:95]
	v_mfma_f32_16x16x32_bf16 v[44:47], v[108:111], v[80:83], v[44:47]
	s_add_i32 m0, vcc_lo, 0x3000
	v_mfma_f32_16x16x32_bf16 v[48:51], v[108:111], v[84:87], v[48:51]
	global_load_lds_dwordx4 v[116:117], off
	v_lshl_add_u64 v[116:117], v[116:117], 0, s[94:95]
	v_mfma_f32_16x16x32_bf16 v[52:55], v[108:111], v[88:91], v[52:55]
	s_add_i32 m0, vcc_lo, 0x3400
	v_mfma_f32_16x16x32_bf16 v[56:59], v[108:111], v[92:95], v[56:59]
	global_load_lds_dwordx4 v[118:119], off
	v_lshl_add_u64 v[118:119], v[118:119], 0, s[94:95]
	v_mfma_f32_16x16x32_bf16 v[60:63], v[112:115], v[80:83], v[60:63]
	s_add_i32 m0, vcc_lo, 0x3800
	v_mfma_f32_16x16x32_bf16 v[64:67], v[112:115], v[84:87], v[64:67]
	global_load_lds_dwordx4 v[120:121], off
	v_lshl_add_u64 v[120:121], v[120:121], 0, s[94:95]
	v_mfma_f32_16x16x32_bf16 v[72:75], v[112:115], v[88:91], v[72:75]
	s_add_i32 m0, vcc_lo, 0x3c00
	v_mfma_f32_16x16x32_bf16 v[76:79], v[112:115], v[92:95], v[76:79]
	global_load_lds_dwordx4 v[122:123], off
	v_lshl_add_u64 v[122:123], v[122:123], 0, s[94:95]
	s_waitcnt vmcnt(8)
	ds_read_b128 v[80:83], v132
	ds_read_b128 v[84:87], v132 offset:1024
	ds_read_b128 v[88:91], v132 offset:2048
	ds_read_b128 v[92:95], v132 offset:3072
	ds_read_b128 v[100:103], v132 offset:4096
	ds_read_b128 v[104:107], v132 offset:5120
	ds_read_b128 v[108:111], v132 offset:6144
	ds_read_b128 v[112:115], v132 offset:7168
	s_waitcnt lgkmcnt(0)
	v_mfma_f32_16x16x32_bf16 v[4:7], v[100:103], v[80:83], v[4:7]
	s_add_i32 m0, vcc_lo, 0x0
	v_mfma_f32_16x16x32_bf16 v[8:11], v[100:103], v[84:87], v[8:11]
	global_load_lds_dwordx4 v[26:27], off
	v_lshl_add_u64 v[26:27], v[26:27], 0, s[94:95]
	v_mfma_f32_16x16x32_bf16 v[12:15], v[100:103], v[88:91], v[12:15]
	s_add_i32 m0, vcc_lo, 0x400
	v_mfma_f32_16x16x32_bf16 v[16:19], v[100:103], v[92:95], v[16:19]
	global_load_lds_dwordx4 v[30:31], off
	v_lshl_add_u64 v[30:31], v[30:31], 0, s[94:95]
	v_mfma_f32_16x16x32_bf16 v[20:23], v[104:107], v[80:83], v[20:23]
	s_add_i32 m0, vcc_lo, 0x800
	v_mfma_f32_16x16x32_bf16 v[32:35], v[104:107], v[84:87], v[32:35]
	global_load_lds_dwordx4 v[70:71], off
	v_lshl_add_u64 v[70:71], v[70:71], 0, s[94:95]
	v_mfma_f32_16x16x32_bf16 v[36:39], v[104:107], v[88:91], v[36:39]
	s_add_i32 m0, vcc_lo, 0xc00
	v_mfma_f32_16x16x32_bf16 v[40:43], v[104:107], v[92:95], v[40:43]
	global_load_lds_dwordx4 v[98:99], off
	v_lshl_add_u64 v[98:99], v[98:99], 0, s[94:95]
	v_mfma_f32_16x16x32_bf16 v[44:47], v[108:111], v[80:83], v[44:47]
	s_add_i32 m0, vcc_lo, 0x1000
	v_mfma_f32_16x16x32_bf16 v[48:51], v[108:111], v[84:87], v[48:51]
	global_load_lds_dwordx4 v[116:117], off
	v_lshl_add_u64 v[116:117], v[116:117], 0, s[94:95]
	v_mfma_f32_16x16x32_bf16 v[52:55], v[108:111], v[88:91], v[52:55]
	s_add_i32 m0, vcc_lo, 0x1400
	v_mfma_f32_16x16x32_bf16 v[56:59], v[108:111], v[92:95], v[56:59]
	global_load_lds_dwordx4 v[118:119], off
	v_lshl_add_u64 v[118:119], v[118:119], 0, s[94:95]
	v_mfma_f32_16x16x32_bf16 v[60:63], v[112:115], v[80:83], v[60:63]
	s_add_i32 m0, vcc_lo, 0x1800
	v_mfma_f32_16x16x32_bf16 v[64:67], v[112:115], v[84:87], v[64:67]
	global_load_lds_dwordx4 v[120:121], off
	v_lshl_add_u64 v[120:121], v[120:121], 0, s[94:95]
	v_mfma_f32_16x16x32_bf16 v[72:75], v[112:115], v[88:91], v[72:75]
	s_add_i32 m0, vcc_lo, 0x1c00
	v_mfma_f32_16x16x32_bf16 v[76:79], v[112:115], v[92:95], v[76:79]
	global_load_lds_dwordx4 v[122:123], off
	v_lshl_add_u64 v[122:123], v[122:123], 0, s[94:95]
	s_waitcnt vmcnt(8)
	ds_read_b128 v[80:83], v132 offset:8192
	ds_read_b128 v[84:87], v132 offset:9216
	ds_read_b128 v[88:91], v132 offset:10240
	ds_read_b128 v[92:95], v132 offset:11264
	ds_read_b128 v[100:103], v132 offset:12288
	ds_read_b128 v[104:107], v132 offset:13312
	ds_read_b128 v[108:111], v132 offset:14336
	ds_read_b128 v[112:115], v132 offset:15360
	s_waitcnt lgkmcnt(0)
	v_mfma_f32_16x16x32_bf16 v[4:7], v[100:103], v[80:83], v[4:7]
	s_add_i32 m0, vcc_lo, 0x2000
	v_mfma_f32_16x16x32_bf16 v[8:11], v[100:103], v[84:87], v[8:11]
	global_load_lds_dwordx4 v[26:27], off
	v_lshl_add_u64 v[26:27], v[26:27], 0, s[94:95]
	v_mfma_f32_16x16x32_bf16 v[12:15], v[100:103], v[88:91], v[12:15]
	s_add_i32 m0, vcc_lo, 0x2400
	v_mfma_f32_16x16x32_bf16 v[16:19], v[100:103], v[92:95], v[16:19]
	global_load_lds_dwordx4 v[30:31], off
	v_lshl_add_u64 v[30:31], v[30:31], 0, s[94:95]
	v_mfma_f32_16x16x32_bf16 v[20:23], v[104:107], v[80:83], v[20:23]
	s_add_i32 m0, vcc_lo, 0x2800
	v_mfma_f32_16x16x32_bf16 v[32:35], v[104:107], v[84:87], v[32:35]
	global_load_lds_dwordx4 v[70:71], off
	v_lshl_add_u64 v[70:71], v[70:71], 0, s[94:95]
	v_mfma_f32_16x16x32_bf16 v[36:39], v[104:107], v[88:91], v[36:39]
	s_add_i32 m0, vcc_lo, 0x2c00
	v_mfma_f32_16x16x32_bf16 v[40:43], v[104:107], v[92:95], v[40:43]
	global_load_lds_dwordx4 v[98:99], off
	v_lshl_add_u64 v[98:99], v[98:99], 0, s[94:95]
	v_mfma_f32_16x16x32_bf16 v[44:47], v[108:111], v[80:83], v[44:47]
	s_add_i32 m0, vcc_lo, 0x3000
	v_mfma_f32_16x16x32_bf16 v[48:51], v[108:111], v[84:87], v[48:51]
	global_load_lds_dwordx4 v[116:117], off
	v_lshl_add_u64 v[116:117], v[116:117], 0, s[94:95]
	v_mfma_f32_16x16x32_bf16 v[52:55], v[108:111], v[88:91], v[52:55]
	s_add_i32 m0, vcc_lo, 0x3400
	v_mfma_f32_16x16x32_bf16 v[56:59], v[108:111], v[92:95], v[56:59]
	global_load_lds_dwordx4 v[118:119], off
	v_lshl_add_u64 v[118:119], v[118:119], 0, s[94:95]
	v_mfma_f32_16x16x32_bf16 v[60:63], v[112:115], v[80:83], v[60:63]
	s_add_i32 m0, vcc_lo, 0x3800
	v_mfma_f32_16x16x32_bf16 v[64:67], v[112:115], v[84:87], v[64:67]
	global_load_lds_dwordx4 v[120:121], off
	v_lshl_add_u64 v[120:121], v[120:121], 0, s[94:95]
	v_mfma_f32_16x16x32_bf16 v[72:75], v[112:115], v[88:91], v[72:75]
	s_add_i32 m0, vcc_lo, 0x3c00
	v_mfma_f32_16x16x32_bf16 v[76:79], v[112:115], v[92:95], v[76:79]
	global_load_lds_dwordx4 v[122:123], off
	v_lshl_add_u64 v[122:123], v[122:123], 0, s[94:95]
	s_waitcnt vmcnt(8)
	ds_read_b128 v[80:83], v132
	ds_read_b128 v[84:87], v132 offset:1024
	ds_read_b128 v[88:91], v132 offset:2048
	ds_read_b128 v[92:95], v132 offset:3072
	ds_read_b128 v[100:103], v132 offset:4096
	ds_read_b128 v[104:107], v132 offset:5120
	ds_read_b128 v[108:111], v132 offset:6144
	ds_read_b128 v[112:115], v132 offset:7168
	s_waitcnt lgkmcnt(0)
	v_mfma_f32_16x16x32_bf16 v[4:7], v[100:103], v[80:83], v[4:7]
	s_add_i32 m0, vcc_lo, 0x0
	v_mfma_f32_16x16x32_bf16 v[8:11], v[100:103], v[84:87], v[8:11]
	global_load_lds_dwordx4 v[26:27], off
	v_lshl_add_u64 v[26:27], v[26:27], 0, s[94:95]
	v_mfma_f32_16x16x32_bf16 v[12:15], v[100:103], v[88:91], v[12:15]
	s_add_i32 m0, vcc_lo, 0x400
	v_mfma_f32_16x16x32_bf16 v[16:19], v[100:103], v[92:95], v[16:19]
	global_load_lds_dwordx4 v[30:31], off
	v_lshl_add_u64 v[30:31], v[30:31], 0, s[94:95]
	v_mfma_f32_16x16x32_bf16 v[20:23], v[104:107], v[80:83], v[20:23]
	s_add_i32 m0, vcc_lo, 0x800
	v_mfma_f32_16x16x32_bf16 v[32:35], v[104:107], v[84:87], v[32:35]
	global_load_lds_dwordx4 v[70:71], off
	v_lshl_add_u64 v[70:71], v[70:71], 0, s[94:95]
	v_mfma_f32_16x16x32_bf16 v[36:39], v[104:107], v[88:91], v[36:39]
	s_add_i32 m0, vcc_lo, 0xc00
	v_mfma_f32_16x16x32_bf16 v[40:43], v[104:107], v[92:95], v[40:43]
	global_load_lds_dwordx4 v[98:99], off
	v_lshl_add_u64 v[98:99], v[98:99], 0, s[94:95]
	v_mfma_f32_16x16x32_bf16 v[44:47], v[108:111], v[80:83], v[44:47]
	s_add_i32 m0, vcc_lo, 0x1000
	v_mfma_f32_16x16x32_bf16 v[48:51], v[108:111], v[84:87], v[48:51]
	global_load_lds_dwordx4 v[116:117], off
	v_lshl_add_u64 v[116:117], v[116:117], 0, s[94:95]
	v_mfma_f32_16x16x32_bf16 v[52:55], v[108:111], v[88:91], v[52:55]
	s_add_i32 m0, vcc_lo, 0x1400
	v_mfma_f32_16x16x32_bf16 v[56:59], v[108:111], v[92:95], v[56:59]
	global_load_lds_dwordx4 v[118:119], off
	v_lshl_add_u64 v[118:119], v[118:119], 0, s[94:95]
	v_mfma_f32_16x16x32_bf16 v[60:63], v[112:115], v[80:83], v[60:63]
	s_add_i32 m0, vcc_lo, 0x1800
	v_mfma_f32_16x16x32_bf16 v[64:67], v[112:115], v[84:87], v[64:67]
	global_load_lds_dwordx4 v[120:121], off
	v_lshl_add_u64 v[120:121], v[120:121], 0, s[94:95]
	v_mfma_f32_16x16x32_bf16 v[72:75], v[112:115], v[88:91], v[72:75]
	s_add_i32 m0, vcc_lo, 0x1c00
	v_mfma_f32_16x16x32_bf16 v[76:79], v[112:115], v[92:95], v[76:79]
	global_load_lds_dwordx4 v[122:123], off
	v_lshl_add_u64 v[122:123], v[122:123], 0, s[94:95]
	s_waitcnt vmcnt(8)
	ds_read_b128 v[80:83], v132 offset:8192
	ds_read_b128 v[84:87], v132 offset:9216
	ds_read_b128 v[88:91], v132 offset:10240
	ds_read_b128 v[92:95], v132 offset:11264
	ds_read_b128 v[100:103], v132 offset:12288
	ds_read_b128 v[104:107], v132 offset:13312
	ds_read_b128 v[108:111], v132 offset:14336
	ds_read_b128 v[112:115], v132 offset:15360
	s_waitcnt lgkmcnt(0)
	v_mfma_f32_16x16x32_bf16 v[4:7], v[100:103], v[80:83], v[4:7]
	s_add_i32 m0, vcc_lo, 0x2000
	v_mfma_f32_16x16x32_bf16 v[8:11], v[100:103], v[84:87], v[8:11]
	global_load_lds_dwordx4 v[26:27], off
	v_lshl_add_u64 v[26:27], v[26:27], 0, s[94:95]
	v_mfma_f32_16x16x32_bf16 v[12:15], v[100:103], v[88:91], v[12:15]
	s_add_i32 m0, vcc_lo, 0x2400
	v_mfma_f32_16x16x32_bf16 v[16:19], v[100:103], v[92:95], v[16:19]
	global_load_lds_dwordx4 v[30:31], off
	v_lshl_add_u64 v[30:31], v[30:31], 0, s[94:95]
	v_mfma_f32_16x16x32_bf16 v[20:23], v[104:107], v[80:83], v[20:23]
	s_add_i32 m0, vcc_lo, 0x2800
	v_mfma_f32_16x16x32_bf16 v[32:35], v[104:107], v[84:87], v[32:35]
	global_load_lds_dwordx4 v[70:71], off
	v_lshl_add_u64 v[70:71], v[70:71], 0, s[94:95]
	v_mfma_f32_16x16x32_bf16 v[36:39], v[104:107], v[88:91], v[36:39]
	s_add_i32 m0, vcc_lo, 0x2c00
	v_mfma_f32_16x16x32_bf16 v[40:43], v[104:107], v[92:95], v[40:43]
	global_load_lds_dwordx4 v[98:99], off
	v_lshl_add_u64 v[98:99], v[98:99], 0, s[94:95]
	v_mfma_f32_16x16x32_bf16 v[44:47], v[108:111], v[80:83], v[44:47]
	s_add_i32 m0, vcc_lo, 0x3000
	v_mfma_f32_16x16x32_bf16 v[48:51], v[108:111], v[84:87], v[48:51]
	global_load_lds_dwordx4 v[116:117], off
	v_lshl_add_u64 v[116:117], v[116:117], 0, s[94:95]
	v_mfma_f32_16x16x32_bf16 v[52:55], v[108:111], v[88:91], v[52:55]
	s_add_i32 m0, vcc_lo, 0x3400
	v_mfma_f32_16x16x32_bf16 v[56:59], v[108:111], v[92:95], v[56:59]
	global_load_lds_dwordx4 v[118:119], off
	v_lshl_add_u64 v[118:119], v[118:119], 0, s[94:95]
	v_mfma_f32_16x16x32_bf16 v[60:63], v[112:115], v[80:83], v[60:63]
	s_add_i32 m0, vcc_lo, 0x3800
	v_mfma_f32_16x16x32_bf16 v[64:67], v[112:115], v[84:87], v[64:67]
	global_load_lds_dwordx4 v[120:121], off
	v_lshl_add_u64 v[120:121], v[120:121], 0, s[94:95]
	v_mfma_f32_16x16x32_bf16 v[72:75], v[112:115], v[88:91], v[72:75]
	s_add_i32 m0, vcc_lo, 0x3c00
	v_mfma_f32_16x16x32_bf16 v[76:79], v[112:115], v[92:95], v[76:79]
	global_load_lds_dwordx4 v[122:123], off
	v_lshl_add_u64 v[122:123], v[122:123], 0, s[94:95]
	s_waitcnt vmcnt(8)
	ds_read_b128 v[80:83], v132
	ds_read_b128 v[84:87], v132 offset:1024
	ds_read_b128 v[88:91], v132 offset:2048
	ds_read_b128 v[92:95], v132 offset:3072
	ds_read_b128 v[100:103], v132 offset:4096
	ds_read_b128 v[104:107], v132 offset:5120
	ds_read_b128 v[108:111], v132 offset:6144
	ds_read_b128 v[112:115], v132 offset:7168
	s_waitcnt lgkmcnt(0)
	v_mfma_f32_16x16x32_bf16 v[4:7], v[100:103], v[80:83], v[4:7]
	s_add_i32 m0, vcc_lo, 0x0
	v_mfma_f32_16x16x32_bf16 v[8:11], v[100:103], v[84:87], v[8:11]
	global_load_lds_dwordx4 v[26:27], off
	v_lshl_add_u64 v[26:27], v[26:27], 0, s[94:95]
	v_mfma_f32_16x16x32_bf16 v[12:15], v[100:103], v[88:91], v[12:15]
	s_add_i32 m0, vcc_lo, 0x400
	v_mfma_f32_16x16x32_bf16 v[16:19], v[100:103], v[92:95], v[16:19]
	global_load_lds_dwordx4 v[30:31], off
	v_lshl_add_u64 v[30:31], v[30:31], 0, s[94:95]
	v_mfma_f32_16x16x32_bf16 v[20:23], v[104:107], v[80:83], v[20:23]
	s_add_i32 m0, vcc_lo, 0x800
	v_mfma_f32_16x16x32_bf16 v[32:35], v[104:107], v[84:87], v[32:35]
	global_load_lds_dwordx4 v[70:71], off
	v_lshl_add_u64 v[70:71], v[70:71], 0, s[94:95]
	v_mfma_f32_16x16x32_bf16 v[36:39], v[104:107], v[88:91], v[36:39]
	s_add_i32 m0, vcc_lo, 0xc00
	v_mfma_f32_16x16x32_bf16 v[40:43], v[104:107], v[92:95], v[40:43]
	global_load_lds_dwordx4 v[98:99], off
	v_lshl_add_u64 v[98:99], v[98:99], 0, s[94:95]
	v_mfma_f32_16x16x32_bf16 v[44:47], v[108:111], v[80:83], v[44:47]
	s_add_i32 m0, vcc_lo, 0x1000
	v_mfma_f32_16x16x32_bf16 v[48:51], v[108:111], v[84:87], v[48:51]
	global_load_lds_dwordx4 v[116:117], off
	v_lshl_add_u64 v[116:117], v[116:117], 0, s[94:95]
	v_mfma_f32_16x16x32_bf16 v[52:55], v[108:111], v[88:91], v[52:55]
	s_add_i32 m0, vcc_lo, 0x1400
	v_mfma_f32_16x16x32_bf16 v[56:59], v[108:111], v[92:95], v[56:59]
	global_load_lds_dwordx4 v[118:119], off
	v_lshl_add_u64 v[118:119], v[118:119], 0, s[94:95]
	v_mfma_f32_16x16x32_bf16 v[60:63], v[112:115], v[80:83], v[60:63]
	s_add_i32 m0, vcc_lo, 0x1800
	v_mfma_f32_16x16x32_bf16 v[64:67], v[112:115], v[84:87], v[64:67]
	global_load_lds_dwordx4 v[120:121], off
	v_lshl_add_u64 v[120:121], v[120:121], 0, s[94:95]
	v_mfma_f32_16x16x32_bf16 v[72:75], v[112:115], v[88:91], v[72:75]
	s_add_i32 m0, vcc_lo, 0x1c00
	v_mfma_f32_16x16x32_bf16 v[76:79], v[112:115], v[92:95], v[76:79]
	global_load_lds_dwordx4 v[122:123], off
	v_lshl_add_u64 v[122:123], v[122:123], 0, s[94:95]
	s_waitcnt vmcnt(8)
	ds_read_b128 v[80:83], v132 offset:8192
	ds_read_b128 v[84:87], v132 offset:9216
	ds_read_b128 v[88:91], v132 offset:10240
	ds_read_b128 v[92:95], v132 offset:11264
	ds_read_b128 v[100:103], v132 offset:12288
	ds_read_b128 v[104:107], v132 offset:13312
	ds_read_b128 v[108:111], v132 offset:14336
	ds_read_b128 v[112:115], v132 offset:15360
	s_waitcnt lgkmcnt(0)
	v_mfma_f32_16x16x32_bf16 v[4:7], v[100:103], v[80:83], v[4:7]
	s_add_i32 m0, vcc_lo, 0x2000
	v_mfma_f32_16x16x32_bf16 v[8:11], v[100:103], v[84:87], v[8:11]
	global_load_lds_dwordx4 v[26:27], off
	v_lshl_add_u64 v[26:27], v[26:27], 0, s[94:95]
	v_mfma_f32_16x16x32_bf16 v[12:15], v[100:103], v[88:91], v[12:15]
	s_add_i32 m0, vcc_lo, 0x2400
	v_mfma_f32_16x16x32_bf16 v[16:19], v[100:103], v[92:95], v[16:19]
	global_load_lds_dwordx4 v[30:31], off
	v_lshl_add_u64 v[30:31], v[30:31], 0, s[94:95]
	v_mfma_f32_16x16x32_bf16 v[20:23], v[104:107], v[80:83], v[20:23]
	s_add_i32 m0, vcc_lo, 0x2800
	v_mfma_f32_16x16x32_bf16 v[32:35], v[104:107], v[84:87], v[32:35]
	global_load_lds_dwordx4 v[70:71], off
	v_lshl_add_u64 v[70:71], v[70:71], 0, s[94:95]
	v_mfma_f32_16x16x32_bf16 v[36:39], v[104:107], v[88:91], v[36:39]
	s_add_i32 m0, vcc_lo, 0x2c00
	v_mfma_f32_16x16x32_bf16 v[40:43], v[104:107], v[92:95], v[40:43]
	global_load_lds_dwordx4 v[98:99], off
	v_lshl_add_u64 v[98:99], v[98:99], 0, s[94:95]
	v_mfma_f32_16x16x32_bf16 v[44:47], v[108:111], v[80:83], v[44:47]
	s_add_i32 m0, vcc_lo, 0x3000
	v_mfma_f32_16x16x32_bf16 v[48:51], v[108:111], v[84:87], v[48:51]
	global_load_lds_dwordx4 v[116:117], off
	v_lshl_add_u64 v[116:117], v[116:117], 0, s[94:95]
	v_mfma_f32_16x16x32_bf16 v[52:55], v[108:111], v[88:91], v[52:55]
	s_add_i32 m0, vcc_lo, 0x3400
	v_mfma_f32_16x16x32_bf16 v[56:59], v[108:111], v[92:95], v[56:59]
	global_load_lds_dwordx4 v[118:119], off
	v_lshl_add_u64 v[118:119], v[118:119], 0, s[94:95]
	v_mfma_f32_16x16x32_bf16 v[60:63], v[112:115], v[80:83], v[60:63]
	s_add_i32 m0, vcc_lo, 0x3800
	v_mfma_f32_16x16x32_bf16 v[64:67], v[112:115], v[84:87], v[64:67]
	global_load_lds_dwordx4 v[120:121], off
	v_lshl_add_u64 v[120:121], v[120:121], 0, s[94:95]
	v_mfma_f32_16x16x32_bf16 v[72:75], v[112:115], v[88:91], v[72:75]
	s_add_i32 m0, vcc_lo, 0x3c00
	v_mfma_f32_16x16x32_bf16 v[76:79], v[112:115], v[92:95], v[76:79]
	global_load_lds_dwordx4 v[122:123], off
	v_lshl_add_u64 v[122:123], v[122:123], 0, s[94:95]
	s_waitcnt vmcnt(8)
	ds_read_b128 v[80:83], v132
	ds_read_b128 v[84:87], v132 offset:1024
	ds_read_b128 v[88:91], v132 offset:2048
	ds_read_b128 v[92:95], v132 offset:3072
	ds_read_b128 v[100:103], v132 offset:4096
	ds_read_b128 v[104:107], v132 offset:5120
	ds_read_b128 v[108:111], v132 offset:6144
	ds_read_b128 v[112:115], v132 offset:7168
	s_waitcnt lgkmcnt(0)
	v_mfma_f32_16x16x32_bf16 v[4:7], v[100:103], v[80:83], v[4:7]
	s_add_i32 m0, vcc_lo, 0x0
	v_mfma_f32_16x16x32_bf16 v[8:11], v[100:103], v[84:87], v[8:11]
	global_load_lds_dwordx4 v[26:27], off
	v_lshl_add_u64 v[26:27], v[26:27], 0, s[94:95]
	v_mfma_f32_16x16x32_bf16 v[12:15], v[100:103], v[88:91], v[12:15]
	s_add_i32 m0, vcc_lo, 0x400
	v_mfma_f32_16x16x32_bf16 v[16:19], v[100:103], v[92:95], v[16:19]
	global_load_lds_dwordx4 v[30:31], off
	v_lshl_add_u64 v[30:31], v[30:31], 0, s[94:95]
	v_mfma_f32_16x16x32_bf16 v[20:23], v[104:107], v[80:83], v[20:23]
	s_add_i32 m0, vcc_lo, 0x800
	v_mfma_f32_16x16x32_bf16 v[32:35], v[104:107], v[84:87], v[32:35]
	global_load_lds_dwordx4 v[70:71], off
	v_lshl_add_u64 v[70:71], v[70:71], 0, s[94:95]
	v_mfma_f32_16x16x32_bf16 v[36:39], v[104:107], v[88:91], v[36:39]
	s_add_i32 m0, vcc_lo, 0xc00
	v_mfma_f32_16x16x32_bf16 v[40:43], v[104:107], v[92:95], v[40:43]
	global_load_lds_dwordx4 v[98:99], off
	v_lshl_add_u64 v[98:99], v[98:99], 0, s[94:95]
	v_mfma_f32_16x16x32_bf16 v[44:47], v[108:111], v[80:83], v[44:47]
	s_add_i32 m0, vcc_lo, 0x1000
	v_mfma_f32_16x16x32_bf16 v[48:51], v[108:111], v[84:87], v[48:51]
	global_load_lds_dwordx4 v[116:117], off
	v_lshl_add_u64 v[116:117], v[116:117], 0, s[94:95]
	v_mfma_f32_16x16x32_bf16 v[52:55], v[108:111], v[88:91], v[52:55]
	s_add_i32 m0, vcc_lo, 0x1400
	v_mfma_f32_16x16x32_bf16 v[56:59], v[108:111], v[92:95], v[56:59]
	global_load_lds_dwordx4 v[118:119], off
	v_lshl_add_u64 v[118:119], v[118:119], 0, s[94:95]
	v_mfma_f32_16x16x32_bf16 v[60:63], v[112:115], v[80:83], v[60:63]
	s_add_i32 m0, vcc_lo, 0x1800
	v_mfma_f32_16x16x32_bf16 v[64:67], v[112:115], v[84:87], v[64:67]
	global_load_lds_dwordx4 v[120:121], off
	v_lshl_add_u64 v[120:121], v[120:121], 0, s[94:95]
	v_mfma_f32_16x16x32_bf16 v[72:75], v[112:115], v[88:91], v[72:75]
	s_add_i32 m0, vcc_lo, 0x1c00
	v_mfma_f32_16x16x32_bf16 v[76:79], v[112:115], v[92:95], v[76:79]
	global_load_lds_dwordx4 v[122:123], off
	v_lshl_add_u64 v[122:123], v[122:123], 0, s[94:95]
	s_waitcnt vmcnt(8)
	ds_read_b128 v[80:83], v132 offset:8192
	ds_read_b128 v[84:87], v132 offset:9216
	ds_read_b128 v[88:91], v132 offset:10240
	ds_read_b128 v[92:95], v132 offset:11264
	ds_read_b128 v[100:103], v132 offset:12288
	ds_read_b128 v[104:107], v132 offset:13312
	ds_read_b128 v[108:111], v132 offset:14336
	ds_read_b128 v[112:115], v132 offset:15360
	s_waitcnt lgkmcnt(0)
	v_mfma_f32_16x16x32_bf16 v[4:7], v[100:103], v[80:83], v[4:7]
	s_add_i32 m0, vcc_lo, 0x2000
	v_mfma_f32_16x16x32_bf16 v[8:11], v[100:103], v[84:87], v[8:11]
	global_load_lds_dwordx4 v[26:27], off
	v_lshl_add_u64 v[26:27], v[26:27], 0, s[94:95]
	v_mfma_f32_16x16x32_bf16 v[12:15], v[100:103], v[88:91], v[12:15]
	s_add_i32 m0, vcc_lo, 0x2400
	v_mfma_f32_16x16x32_bf16 v[16:19], v[100:103], v[92:95], v[16:19]
	global_load_lds_dwordx4 v[30:31], off
	v_lshl_add_u64 v[30:31], v[30:31], 0, s[94:95]
	v_mfma_f32_16x16x32_bf16 v[20:23], v[104:107], v[80:83], v[20:23]
	s_add_i32 m0, vcc_lo, 0x2800
	v_mfma_f32_16x16x32_bf16 v[32:35], v[104:107], v[84:87], v[32:35]
	global_load_lds_dwordx4 v[70:71], off
	v_lshl_add_u64 v[70:71], v[70:71], 0, s[94:95]
	v_mfma_f32_16x16x32_bf16 v[36:39], v[104:107], v[88:91], v[36:39]
	s_add_i32 m0, vcc_lo, 0x2c00
	v_mfma_f32_16x16x32_bf16 v[40:43], v[104:107], v[92:95], v[40:43]
	global_load_lds_dwordx4 v[98:99], off
	v_lshl_add_u64 v[98:99], v[98:99], 0, s[94:95]
	v_mfma_f32_16x16x32_bf16 v[44:47], v[108:111], v[80:83], v[44:47]
	s_add_i32 m0, vcc_lo, 0x3000
	v_mfma_f32_16x16x32_bf16 v[48:51], v[108:111], v[84:87], v[48:51]
	global_load_lds_dwordx4 v[116:117], off
	v_lshl_add_u64 v[116:117], v[116:117], 0, s[94:95]
	v_mfma_f32_16x16x32_bf16 v[52:55], v[108:111], v[88:91], v[52:55]
	s_add_i32 m0, vcc_lo, 0x3400
	v_mfma_f32_16x16x32_bf16 v[56:59], v[108:111], v[92:95], v[56:59]
	global_load_lds_dwordx4 v[118:119], off
	v_lshl_add_u64 v[118:119], v[118:119], 0, s[94:95]
	v_mfma_f32_16x16x32_bf16 v[60:63], v[112:115], v[80:83], v[60:63]
	s_add_i32 m0, vcc_lo, 0x3800
	v_mfma_f32_16x16x32_bf16 v[64:67], v[112:115], v[84:87], v[64:67]
	global_load_lds_dwordx4 v[120:121], off
	v_lshl_add_u64 v[120:121], v[120:121], 0, s[94:95]
	v_mfma_f32_16x16x32_bf16 v[72:75], v[112:115], v[88:91], v[72:75]
	s_add_i32 m0, vcc_lo, 0x3c00
	v_mfma_f32_16x16x32_bf16 v[76:79], v[112:115], v[92:95], v[76:79]
	global_load_lds_dwordx4 v[122:123], off
	v_lshl_add_u64 v[122:123], v[122:123], 0, s[94:95]
	s_waitcnt vmcnt(8)
	ds_read_b128 v[80:83], v132
	ds_read_b128 v[84:87], v132 offset:1024
	ds_read_b128 v[88:91], v132 offset:2048
	ds_read_b128 v[92:95], v132 offset:3072
	ds_read_b128 v[100:103], v132 offset:4096
	ds_read_b128 v[104:107], v132 offset:5120
	ds_read_b128 v[108:111], v132 offset:6144
	ds_read_b128 v[112:115], v132 offset:7168
	s_waitcnt lgkmcnt(0)
	v_mfma_f32_16x16x32_bf16 v[4:7], v[100:103], v[80:83], v[4:7]
	v_mfma_f32_16x16x32_bf16 v[8:11], v[100:103], v[84:87], v[8:11]
	v_mfma_f32_16x16x32_bf16 v[12:15], v[100:103], v[88:91], v[12:15]
	v_mfma_f32_16x16x32_bf16 v[16:19], v[100:103], v[92:95], v[16:19]
	v_mfma_f32_16x16x32_bf16 v[20:23], v[104:107], v[80:83], v[20:23]
	v_mfma_f32_16x16x32_bf16 v[32:35], v[104:107], v[84:87], v[32:35]
	v_mfma_f32_16x16x32_bf16 v[36:39], v[104:107], v[88:91], v[36:39]
	v_mfma_f32_16x16x32_bf16 v[40:43], v[104:107], v[92:95], v[40:43]
	v_mfma_f32_16x16x32_bf16 v[44:47], v[108:111], v[80:83], v[44:47]
	v_mfma_f32_16x16x32_bf16 v[48:51], v[108:111], v[84:87], v[48:51]
	v_mfma_f32_16x16x32_bf16 v[52:55], v[108:111], v[88:91], v[52:55]
	v_mfma_f32_16x16x32_bf16 v[56:59], v[108:111], v[92:95], v[56:59]
	v_mfma_f32_16x16x32_bf16 v[60:63], v[112:115], v[80:83], v[60:63]
	v_mfma_f32_16x16x32_bf16 v[64:67], v[112:115], v[84:87], v[64:67]
	v_mfma_f32_16x16x32_bf16 v[72:75], v[112:115], v[88:91], v[72:75]
	v_mfma_f32_16x16x32_bf16 v[76:79], v[112:115], v[92:95], v[76:79]
	s_waitcnt vmcnt(0)
	ds_read_b128 v[80:83], v132 offset:8192
	ds_read_b128 v[84:87], v132 offset:9216
	ds_read_b128 v[88:91], v132 offset:10240
	ds_read_b128 v[92:95], v132 offset:11264
	ds_read_b128 v[100:103], v132 offset:12288
	ds_read_b128 v[104:107], v132 offset:13312
	ds_read_b128 v[108:111], v132 offset:14336
	ds_read_b128 v[112:115], v132 offset:15360
	s_waitcnt lgkmcnt(0)
	v_mfma_f32_16x16x32_bf16 v[4:7], v[100:103], v[80:83], v[4:7]
	v_mfma_f32_16x16x32_bf16 v[8:11], v[100:103], v[84:87], v[8:11]
	v_mfma_f32_16x16x32_bf16 v[12:15], v[100:103], v[88:91], v[12:15]
	v_mfma_f32_16x16x32_bf16 v[16:19], v[100:103], v[92:95], v[16:19]
	v_mfma_f32_16x16x32_bf16 v[20:23], v[104:107], v[80:83], v[20:23]
	v_mfma_f32_16x16x32_bf16 v[32:35], v[104:107], v[84:87], v[32:35]
	v_mfma_f32_16x16x32_bf16 v[36:39], v[104:107], v[88:91], v[36:39]
	v_mfma_f32_16x16x32_bf16 v[40:43], v[104:107], v[92:95], v[40:43]
	v_mfma_f32_16x16x32_bf16 v[44:47], v[108:111], v[80:83], v[44:47]
	v_mfma_f32_16x16x32_bf16 v[48:51], v[108:111], v[84:87], v[48:51]
	v_mfma_f32_16x16x32_bf16 v[52:55], v[108:111], v[88:91], v[52:55]
	v_mfma_f32_16x16x32_bf16 v[56:59], v[108:111], v[92:95], v[56:59]
	v_mfma_f32_16x16x32_bf16 v[60:63], v[112:115], v[80:83], v[60:63]
	v_mfma_f32_16x16x32_bf16 v[64:67], v[112:115], v[84:87], v[64:67]
	v_mfma_f32_16x16x32_bf16 v[72:75], v[112:115], v[88:91], v[72:75]
	v_mfma_f32_16x16x32_bf16 v[76:79], v[112:115], v[92:95], v[76:79]
	s_nop 7
	s_nop 3
	v_bfe_u32 v2, v97, 4, 2
	v_lshlrev_b32_e32 v1, 2, v2
	v_lshl_or_b32 v1, s6, 4, v1
	s_nop 2
	v_and_b32_e32 v68, 63, v97
	v_lshl_add_u32 v3, v68, 4, 0
	v_lshl_add_u32 v0, s5, 14, v3
	ds_write_b128 v0, v[4:7]
	ds_write_b128 v0, v[8:11] offset:1024
	ds_write_b128 v0, v[12:15] offset:2048
	ds_write_b128 v0, v[16:19] offset:3072
	ds_write_b128 v0, v[20:23] offset:4096
	ds_write_b128 v0, v[32:35] offset:5120
	ds_write_b128 v0, v[36:39] offset:6144
	ds_write_b128 v0, v[40:43] offset:7168
	ds_write_b128 v0, v[44:47] offset:8192
	ds_write_b128 v0, v[48:51] offset:9216
	ds_write_b128 v0, v[52:55] offset:10240
	ds_write_b128 v0, v[56:59] offset:11264
	ds_write_b128 v0, v[60:63] offset:12288
	ds_write_b128 v0, v[64:67] offset:13312
	ds_write_b128 v0, v[72:75] offset:14336
	ds_write_b128 v0, v[76:79] offset:15360
	s_lshl_b32 s5, s7, 4
	s_addk_i32 s5, 0x4000
	s_waitcnt vmcnt(0) lgkmcnt(0)
	s_nop 2
	s_nop 2
	s_nop 5
	s_nop 5
	s_nop 5
	s_nop 7
	v_or_b32_e32 v0, s5, v96
	v_or_b32_e32 v6, s3, v1
	v_ashrrev_i32_e32 v1, 31, v0
	v_lshlrev_b64 v[4:5], 12, v[0:1]
	s_ashr_i32 s5, s4, 31
	v_lshl_add_u64 v[4:5], s[10:11], 0, v[4:5]
	v_lshl_add_u64 v[4:5], s[4:5], 1, v[4:5]
	v_lshlrev_b32_e32 v128, 1, v6
	v_lshl_add_u64 v[16:17], v[4:5], 0, v[128:129]
	s_waitcnt lgkmcnt(0)
	s_barrier
	global_load_dwordx2 v[18:19], v[16:17], off
	global_load_dwordx2 v[20:21], v[16:17], off offset:256
	s_lshl_b32 s3, s6, 2
	s_add_i32 s3, s3, s7
	v_lshl_add_u32 v3, s3, 10, v3
	ds_read_b128 v[4:7], v3
	ds_read_b128 v[8:11], v3 offset:8192
	ds_read_b128 v[12:15], v3 offset:16384
	s_waitcnt lgkmcnt(0)
	v_pk_add_f32 v[22:23], v[6:7], 0 op_sel_hi:[1,0]
	v_pk_add_f32 v[24:25], v[4:5], 0 op_sel_hi:[1,0]
	ds_read_b128 v[4:7], v3 offset:24576
	v_pk_add_f32 v[26:27], v[10:11], 0 op_sel_hi:[1,0]
	v_pk_add_f32 v[28:29], v[8:9], 0 op_sel_hi:[1,0]
	v_pk_add_f32 v[22:23], v[22:23], v[14:15]
	v_pk_add_f32 v[24:25], v[24:25], v[12:13]
	ds_read_b128 v[8:11], v3 offset:32768
	ds_read_b128 v[12:15], v3 offset:40960
	s_waitcnt lgkmcnt(0)
	v_pk_add_f32 v[26:27], v[26:27], v[6:7]
	v_pk_add_f32 v[28:29], v[28:29], v[4:5]
	ds_read_b128 v[4:7], v3 offset:49152
	v_pk_add_f32 v[22:23], v[22:23], v[10:11]
	v_pk_add_f32 v[24:25], v[24:25], v[8:9]
	v_pk_add_f32 v[28:29], v[28:29], v[12:13]
	ds_read_b128 v[8:11], v3 offset:57344
	v_add_u32_e32 v12, 0x12000, v3
	v_pk_add_f32 v[26:27], v[26:27], v[14:15]
	s_waitcnt lgkmcnt(0)
	v_pk_add_f32 v[24:25], v[24:25], v[4:5]
	v_add_u32_e32 v4, 0x10000, v3
	ds_read_b128 v[12:15], v12
	v_pk_add_f32 v[22:23], v[22:23], v[6:7]
	ds_read_b128 v[4:7], v4
	v_pk_add_f32 v[8:9], v[28:29], v[8:9]
	v_pk_add_f32 v[10:11], v[26:27], v[10:11]
	s_waitcnt lgkmcnt(0)
	v_pk_add_f32 v[28:29], v[8:9], v[12:13]
	v_add_u32_e32 v8, 0x16000, v3
	v_pk_add_f32 v[26:27], v[10:11], v[14:15]
	ds_read_b128 v[8:11], v8
	v_pk_add_f32 v[24:25], v[24:25], v[4:5]
	v_add_u32_e32 v4, 0x14000, v3
	v_pk_add_f32 v[22:23], v[22:23], v[6:7]
	ds_read_b128 v[4:7], v4
	v_add_u32_e32 v12, 0x18000, v3
	ds_read_b128 v[12:15], v12
	s_waitcnt lgkmcnt(0)
	v_pk_add_f32 v[28:29], v[28:29], v[8:9]
	v_add_u32_e32 v8, 0x1c000, v3
	v_pk_add_f32 v[26:27], v[26:27], v[10:11]
	ds_read_b128 v[8:11], v8
	v_pk_add_f32 v[24:25], v[24:25], v[4:5]
	v_add_u32_e32 v4, 0x1a000, v3
	v_pk_add_f32 v[22:23], v[22:23], v[6:7]
	ds_read_b128 v[4:7], v4
	v_add_u32_e32 v3, 0x1e000, v3
	v_pk_add_f32 v[22:23], v[22:23], v[14:15]
	v_pk_add_f32 v[24:25], v[24:25], v[12:13]
	ds_read_b128 v[12:15], v3
	s_waitcnt lgkmcnt(0)
	v_pk_add_f32 v[4:5], v[28:29], v[4:5]
	v_pk_add_f32 v[8:9], v[24:25], v[8:9]
	v_pk_add_f32 v[6:7], v[26:27], v[6:7]
	v_pk_add_f32 v[10:11], v[22:23], v[10:11]
	v_pk_add_f32 v[4:5], v[4:5], v[12:13]
	v_pk_add_f32 v[6:7], v[6:7], v[14:15]
	s_waitcnt vmcnt(0)
	v_lshlrev_b32_e32 v12, 16, v18
	v_and_b32_e32 v13, 0xffff0000, v18
	v_pk_add_f32 v[8:9], v[8:9], v[12:13]
	v_lshlrev_b32_e32 v12, 16, v20
	v_and_b32_e32 v13, 0xffff0000, v20
	v_lshlrev_b32_e32 v14, 16, v19
	v_and_b32_e32 v15, 0xffff0000, v19
	v_pk_add_f32 v[4:5], v[4:5], v[12:13]
	v_pk_add_f32 v[10:11], v[10:11], v[14:15]
	v_lshlrev_b32_e32 v14, 16, v21
	v_and_b32_e32 v15, 0xffff0000, v21
	v_mul_f32_e32 v3, v4, v4
	v_mul_f32_e32 v12, v5, v5
	v_pk_add_f32 v[6:7], v[6:7], v[14:15]
	v_fmac_f32_e32 v3, v8, v8
	v_fmac_f32_e32 v12, v9, v9
	v_add_f32_e32 v3, v3, v12
	v_mul_f32_e32 v12, v6, v6
	v_fmac_f32_e32 v12, v10, v10
	v_add_f32_e32 v3, v12, v3
	v_mul_f32_e32 v12, v7, v7
	v_fmac_f32_e32 v12, v11, v11
	v_and_b32_e32 v13, 64, v214
	v_add_f32_e32 v3, v12, v3
	v_xor_b32_e32 v12, 16, v214
	v_add_u32_e32 v13, 64, v13
	v_cmp_lt_i32_e32 vcc, v12, v13
	v_cvt_pk_bf16_f32 v8, v8, v9
	v_cvt_pk_bf16_f32 v9, v10, v11
	v_xor_b32_e32 v10, 32, v214
	global_store_dwordx2 v[16:17], v[8:9], off
	v_cndmask_b32_e32 v12, v214, v12, vcc
	v_lshlrev_b32_e32 v12, 2, v12
	ds_bpermute_b32 v12, v12, v3
	v_cmp_lt_i32_e32 vcc, v10, v13
	v_cvt_pk_bf16_f32 v4, v4, v5
	v_cvt_pk_bf16_f32 v5, v6, v7
	global_store_dwordx2 v[16:17], v[4:5], off offset:256
	s_waitcnt lgkmcnt(0)
	v_add_f32_e32 v3, v3, v12
	v_cndmask_b32_e32 v10, v214, v10, vcc
	v_lshlrev_b32_e32 v10, 2, v10
	ds_bpermute_b32 v10, v10, v3
	v_cmp_gt_u32_e32 vcc, 16, v68
	s_waitcnt lgkmcnt(0)
	v_add_f32_e32 v3, v3, v10
	s_and_saveexec_b64 s[4:5], vcc
	s_and_b32 s3, s1, 0xffffffc0
	s_add_i32 s3, s3, 0
	v_lshl_add_u32 v4, v96, 2, s3
	v_add_u32_e32 v4, 0x20100, v4
	ds_write_b32 v4, v3
	s_or_b64 exec, exec, s[4:5]
	v_or_b32_e32 v2, s6, v2
	v_cmp_eq_u32_e32 vcc, 0, v2
	s_waitcnt lgkmcnt(0)
	s_barrier
	s_and_saveexec_b64 s[4:5], vcc
	s_cbranch_execz .LBB0_1210
	s_andn2_b32 s1, s1, 63
	s_add_i32 s1, s1, 0
	s_add_i32 s1, s1, 0x20100
	v_lshl_add_u32 v2, v96, 2, s1
	ds_read_b32 v2, v2 offset:64
	v_lshlrev_b64 v[0:1], 7, v[0:1]
	v_lshl_add_u64 v[0:1], s[8:9], 0, v[0:1]
	s_ashr_i32 s3, s2, 31
	v_lshl_add_u64 v[0:1], s[2:3], 2, v[0:1]
	s_waitcnt lgkmcnt(0)
	v_add_f32_e32 v2, v3, v2
	global_store_dword v[0:1], v2, off

.LBB0_1302:
	s_waitcnt vmcnt(0) lgkmcnt(0)
	v_mov_b32_e32 v96, v210
	s_mov_b32 s0, s73
	s_cmp_gt_i32 s0, 31
	v_readfirstlane_b32 s1, v96
	s_cbranch_scc1 .LBB0_1304
	v_and_b32_e32 v97, 15, v96
	s_ashr_i32 s3, s1, 6
	v_mul_u32_u24_e32 v0, 0x1600, v97
	v_lshlrev_b32_e32 v128, 1, v0
	s_mul_i32 s4, s3, 0x2c0
	s_lshl_b32 s2, s0, 6
	s_lshl_b32 s0, s0, 5
	v_lshl_add_u64 v[0:1], s[14:15], 0, v[128:129]
	v_and_b32_e32 v128, 48, v96
	s_ashr_i32 s5, s4, 31
	s_and_b32 s0, s0, 0x60
	v_lshl_add_u64 v[0:1], v[0:1], 0, v[128:129]
	s_lshl_b64 s[4:5], s[4:5], 1
	s_and_b32 s2, s2, 0xffffff00
	v_lshl_add_u64 v[28:29], v[0:1], 0, s[4:5]
	v_or_b32_e32 v0, s0, v97
	v_or_b32_e32 v2, s2, v0
	v_mov_b64_e32 v[0:1], s[12:13]
	s_movk_i32 s10, 0x2c00
	v_mad_i64_i32 v[0:1], s[10:11], v2, s10, v[0:1]
	v_lshl_add_u64 v[0:1], v[0:1], 0, v[128:129]
	v_lshl_add_u64 v[24:25], v[0:1], 0, s[4:5]
	s_mov_b32 s4, 0xb000000
	s_mov_b32 s4, 0xb02c000
	s_mov_b32 s4, 0xb058000
	s_mov_b64 s[4:5], 0xb000000
	s_mov_b32 s4, 0xb084000
	s_mov_b32 s4, 0x2c000
	s_mov_b32 s4, 0x160000
	s_mov_b32 s4, 0x18c000
	s_ashr_i32 s1, s1, 7
	s_and_b32 s4, s3, 1
	s_mov_b64 s[10:11], -1
	v_lshrrev_b32_e32 v126, 2, v214
	v_and_b32_e32 v127, 15, v214
	v_sub_u32_e32 v126, v126, v127
	v_mul_i32_i24_e32 v126, 0x2c00, v126
	v_bfe_u32 v131, v214, 5, 1
	v_lshlrev_b32_e32 v131, 1, v131
	v_and_b32_e32 v130, 3, v214
	v_xor_b32_e32 v131, v131, v130
	v_lshrrev_b32_e32 v130, 4, v214
	v_sub_u32_e32 v131, v131, v130
	v_lshl_add_u32 v126, v131, 4, v126
	v_ashrrev_i32_e32 v131, 31, v126
	v_add_co_u32_e32 v122, vcc, v28, v126
	s_nop 1
	v_addc_co_u32_e32 v123, vcc, v29, v131, vcc
	v_add_co_u32_e32 v124, vcc, v24, v126
	s_nop 1
	v_addc_co_u32_e32 v125, vcc, v25, v131, vcc
	v_add_co_u32_e32 v14, vcc, 0xb000000, v122
	s_nop 1
	v_addc_co_u32_e32 v15, vcc, 0, v123, vcc
	v_add_co_u32_e32 v26, vcc, 0xb02c000, v122
	s_nop 1
	v_addc_co_u32_e32 v27, vcc, 0, v123, vcc
	v_add_co_u32_e32 v30, vcc, 0xb058000, v122
	s_nop 1
	v_addc_co_u32_e32 v31, vcc, 0, v123, vcc
	v_add_co_u32_e32 v70, vcc, 0xb084000, v122
	s_nop 1
	v_addc_co_u32_e32 v71, vcc, 0, v123, vcc
	v_mov_b32_e32 v98, v124
	v_mov_b32_e32 v99, v125
	v_add_co_u32_e32 v116, vcc, 0x2c000, v124
	s_nop 1
	v_addc_co_u32_e32 v117, vcc, 0, v125, vcc
	v_add_co_u32_e32 v118, vcc, 0x160000, v124
	s_nop 1
	v_addc_co_u32_e32 v119, vcc, 0, v125, vcc
	v_add_co_u32_e32 v120, vcc, 0x18c000, v124
	s_nop 1
	v_addc_co_u32_e32 v121, vcc, 0, v125, vcc
	v_readfirstlane_b32 vcc_lo, v210
	v_bfe_u32 v131, v214, 3, 1
	v_lshlrev_b32_e32 v131, 1, v131
	v_xor_b32_e32 v131, v131, v130
	v_lshlrev_b32_e32 v131, 4, v131
	v_lshl_add_u32 v131, v127, 6, v131
	s_lshr_b32 vcc_lo, vcc_lo, 6
	s_lshl_b32 vcc_lo, vcc_lo, 14
	s_mov_b32 s94, 64
	v_add_u32_e32 v130, vcc_lo, v131
	s_add_i32 m0, vcc_lo, 0x0
	s_nop 0
	global_load_lds_dwordx4 v[14:15], off
	v_lshl_add_u64 v[14:15], v[14:15], 0, s[94:95]
	s_add_i32 m0, vcc_lo, 0x400
	s_nop 0
	global_load_lds_dwordx4 v[26:27], off
	v_lshl_add_u64 v[26:27], v[26:27], 0, s[94:95]
	s_add_i32 m0, vcc_lo, 0x800
	s_nop 0
	global_load_lds_dwordx4 v[30:31], off
	v_lshl_add_u64 v[30:31], v[30:31], 0, s[94:95]
	s_add_i32 m0, vcc_lo, 0xc00
	s_nop 0
	global_load_lds_dwordx4 v[70:71], off
	v_lshl_add_u64 v[70:71], v[70:71], 0, s[94:95]
	s_add_i32 m0, vcc_lo, 0x1000
	s_nop 0
	global_load_lds_dwordx4 v[98:99], off
	v_lshl_add_u64 v[98:99], v[98:99], 0, s[94:95]
	s_add_i32 m0, vcc_lo, 0x1400
	s_nop 0
	global_load_lds_dwordx4 v[116:117], off
	v_lshl_add_u64 v[116:117], v[116:117], 0, s[94:95]
	s_add_i32 m0, vcc_lo, 0x1800
	s_nop 0
	global_load_lds_dwordx4 v[118:119], off
	v_lshl_add_u64 v[118:119], v[118:119], 0, s[94:95]
	s_add_i32 m0, vcc_lo, 0x1c00
	s_nop 0
	global_load_lds_dwordx4 v[120:121], off
	v_lshl_add_u64 v[120:121], v[120:121], 0, s[94:95]
	s_add_i32 m0, vcc_lo, 0x2000
	s_nop 0
	global_load_lds_dwordx4 v[14:15], off
	v_lshl_add_u64 v[14:15], v[14:15], 0, s[94:95]
	s_add_i32 m0, vcc_lo, 0x2400
	s_nop 0
	global_load_lds_dwordx4 v[26:27], off
	v_lshl_add_u64 v[26:27], v[26:27], 0, s[94:95]
	s_add_i32 m0, vcc_lo, 0x2800
	s_nop 0
	global_load_lds_dwordx4 v[30:31], off
	v_lshl_add_u64 v[30:31], v[30:31], 0, s[94:95]
	s_add_i32 m0, vcc_lo, 0x2c00
	s_nop 0
	global_load_lds_dwordx4 v[70:71], off
	v_lshl_add_u64 v[70:71], v[70:71], 0, s[94:95]
	s_add_i32 m0, vcc_lo, 0x3000
	s_nop 0
	global_load_lds_dwordx4 v[98:99], off
	v_lshl_add_u64 v[98:99], v[98:99], 0, s[94:95]
	s_add_i32 m0, vcc_lo, 0x3400
	s_nop 0
	global_load_lds_dwordx4 v[116:117], off
	v_lshl_add_u64 v[116:117], v[116:117], 0, s[94:95]
	s_add_i32 m0, vcc_lo, 0x3800
	s_nop 0
	global_load_lds_dwordx4 v[118:119], off
	v_lshl_add_u64 v[118:119], v[118:119], 0, s[94:95]
	s_add_i32 m0, vcc_lo, 0x3c00
	s_nop 0
	global_load_lds_dwordx4 v[120:121], off
	v_lshl_add_u64 v[120:121], v[120:121], 0, s[94:95]
	s_waitcnt vmcnt(8)
	ds_read_b128 v[80:83], v130
	ds_read_b128 v[84:87], v130 offset:1024
	ds_read_b128 v[88:91], v130 offset:2048
	ds_read_b128 v[92:95], v130 offset:3072
	ds_read_b128 v[100:103], v130 offset:4096
	ds_read_b128 v[104:107], v130 offset:5120
	ds_read_b128 v[108:111], v130 offset:6144
	ds_read_b128 v[112:115], v130 offset:7168
	s_waitcnt lgkmcnt(0)
	v_mfma_f32_16x16x32_bf16 v[0:3], v[100:103], v[80:83], 0
	s_add_i32 m0, vcc_lo, 0x0
	v_mfma_f32_16x16x32_bf16 v[4:7], v[100:103], v[84:87], 0
	global_load_lds_dwordx4 v[14:15], off
	v_lshl_add_u64 v[14:15], v[14:15], 0, s[94:95]
	v_mfma_f32_16x16x32_bf16 v[8:11], v[100:103], v[88:91], 0
	s_add_i32 m0, vcc_lo, 0x400
	v_mfma_f32_16x16x32_bf16 v[16:19], v[100:103], v[92:95], 0
	global_load_lds_dwordx4 v[26:27], off
	v_lshl_add_u64 v[26:27], v[26:27], 0, s[94:95]
	v_mfma_f32_16x16x32_bf16 v[20:23], v[104:107], v[80:83], 0
	s_add_i32 m0, vcc_lo, 0x800
	v_mfma_f32_16x16x32_bf16 v[32:35], v[104:107], v[84:87], 0
	global_load_lds_dwordx4 v[30:31], off
	v_lshl_add_u64 v[30:31], v[30:31], 0, s[94:95]
	v_mfma_f32_16x16x32_bf16 v[36:39], v[104:107], v[88:91], 0
	s_add_i32 m0, vcc_lo, 0xc00
	v_mfma_f32_16x16x32_bf16 v[40:43], v[104:107], v[92:95], 0
	global_load_lds_dwordx4 v[70:71], off
	v_lshl_add_u64 v[70:71], v[70:71], 0, s[94:95]
	v_mfma_f32_16x16x32_bf16 v[44:47], v[108:111], v[80:83], 0
	s_add_i32 m0, vcc_lo, 0x1000
	v_mfma_f32_16x16x32_bf16 v[48:51], v[108:111], v[84:87], 0
	global_load_lds_dwordx4 v[98:99], off
	v_lshl_add_u64 v[98:99], v[98:99], 0, s[94:95]
	v_mfma_f32_16x16x32_bf16 v[52:55], v[108:111], v[88:91], 0
	s_add_i32 m0, vcc_lo, 0x1400
	v_mfma_f32_16x16x32_bf16 v[56:59], v[108:111], v[92:95], 0
	global_load_lds_dwordx4 v[116:117], off
	v_lshl_add_u64 v[116:117], v[116:117], 0, s[94:95]
	v_mfma_f32_16x16x32_bf16 v[60:63], v[112:115], v[80:83], 0
	s_add_i32 m0, vcc_lo, 0x1800
	v_mfma_f32_16x16x32_bf16 v[64:67], v[112:115], v[84:87], 0
	global_load_lds_dwordx4 v[118:119], off
	v_lshl_add_u64 v[118:119], v[118:119], 0, s[94:95]
	v_mfma_f32_16x16x32_bf16 v[72:75], v[112:115], v[88:91], 0
	s_add_i32 m0, vcc_lo, 0x1c00
	v_mfma_f32_16x16x32_bf16 v[76:79], v[112:115], v[92:95], 0
	global_load_lds_dwordx4 v[120:121], off
	v_lshl_add_u64 v[120:121], v[120:121], 0, s[94:95]
	s_waitcnt vmcnt(8)
	ds_read_b128 v[80:83], v130 offset:8192
	ds_read_b128 v[84:87], v130 offset:9216
	ds_read_b128 v[88:91], v130 offset:10240
	ds_read_b128 v[92:95], v130 offset:11264
	ds_read_b128 v[100:103], v130 offset:12288
	ds_read_b128 v[104:107], v130 offset:13312
	ds_read_b128 v[108:111], v130 offset:14336
	ds_read_b128 v[112:115], v130 offset:15360
	s_waitcnt lgkmcnt(0)
	v_mfma_f32_16x16x32_bf16 v[0:3], v[100:103], v[80:83], v[0:3]
	s_add_i32 m0, vcc_lo, 0x2000
	v_mfma_f32_16x16x32_bf16 v[4:7], v[100:103], v[84:87], v[4:7]
	global_load_lds_dwordx4 v[14:15], off
	v_lshl_add_u64 v[14:15], v[14:15], 0, s[94:95]
	v_mfma_f32_16x16x32_bf16 v[8:11], v[100:103], v[88:91], v[8:11]
	s_add_i32 m0, vcc_lo, 0x2400
	v_mfma_f32_16x16x32_bf16 v[16:19], v[100:103], v[92:95], v[16:19]
	global_load_lds_dwordx4 v[26:27], off
	v_lshl_add_u64 v[26:27], v[26:27], 0, s[94:95]
	v_mfma_f32_16x16x32_bf16 v[20:23], v[104:107], v[80:83], v[20:23]
	s_add_i32 m0, vcc_lo, 0x2800
	v_mfma_f32_16x16x32_bf16 v[32:35], v[104:107], v[84:87], v[32:35]
	global_load_lds_dwordx4 v[30:31], off
	v_lshl_add_u64 v[30:31], v[30:31], 0, s[94:95]
	v_mfma_f32_16x16x32_bf16 v[36:39], v[104:107], v[88:91], v[36:39]
	s_add_i32 m0, vcc_lo, 0x2c00
	v_mfma_f32_16x16x32_bf16 v[40:43], v[104:107], v[92:95], v[40:43]
	global_load_lds_dwordx4 v[70:71], off
	v_lshl_add_u64 v[70:71], v[70:71], 0, s[94:95]
	v_mfma_f32_16x16x32_bf16 v[44:47], v[108:111], v[80:83], v[44:47]
	s_add_i32 m0, vcc_lo, 0x3000
	v_mfma_f32_16x16x32_bf16 v[48:51], v[108:111], v[84:87], v[48:51]
	global_load_lds_dwordx4 v[98:99], off
	v_lshl_add_u64 v[98:99], v[98:99], 0, s[94:95]
	v_mfma_f32_16x16x32_bf16 v[52:55], v[108:111], v[88:91], v[52:55]
	s_add_i32 m0, vcc_lo, 0x3400
	v_mfma_f32_16x16x32_bf16 v[56:59], v[108:111], v[92:95], v[56:59]
	global_load_lds_dwordx4 v[116:117], off
	v_lshl_add_u64 v[116:117], v[116:117], 0, s[94:95]
	v_mfma_f32_16x16x32_bf16 v[60:63], v[112:115], v[80:83], v[60:63]
	s_add_i32 m0, vcc_lo, 0x3800
	v_mfma_f32_16x16x32_bf16 v[64:67], v[112:115], v[84:87], v[64:67]
	global_load_lds_dwordx4 v[118:119], off
	v_lshl_add_u64 v[118:119], v[118:119], 0, s[94:95]
	v_mfma_f32_16x16x32_bf16 v[72:75], v[112:115], v[88:91], v[72:75]
	s_add_i32 m0, vcc_lo, 0x3c00
	v_mfma_f32_16x16x32_bf16 v[76:79], v[112:115], v[92:95], v[76:79]
	global_load_lds_dwordx4 v[120:121], off
	v_lshl_add_u64 v[120:121], v[120:121], 0, s[94:95]
	s_waitcnt vmcnt(8)
	ds_read_b128 v[80:83], v130
	ds_read_b128 v[84:87], v130 offset:1024
	ds_read_b128 v[88:91], v130 offset:2048
	ds_read_b128 v[92:95], v130 offset:3072
	ds_read_b128 v[100:103], v130 offset:4096
	ds_read_b128 v[104:107], v130 offset:5120
	ds_read_b128 v[108:111], v130 offset:6144
	ds_read_b128 v[112:115], v130 offset:7168
	s_waitcnt lgkmcnt(0)
	v_mfma_f32_16x16x32_bf16 v[0:3], v[100:103], v[80:83], v[0:3]
	s_add_i32 m0, vcc_lo, 0x0
	v_mfma_f32_16x16x32_bf16 v[4:7], v[100:103], v[84:87], v[4:7]
	global_load_lds_dwordx4 v[14:15], off
	v_lshl_add_u64 v[14:15], v[14:15], 0, s[94:95]
	v_mfma_f32_16x16x32_bf16 v[8:11], v[100:103], v[88:91], v[8:11]
	s_add_i32 m0, vcc_lo, 0x400
	v_mfma_f32_16x16x32_bf16 v[16:19], v[100:103], v[92:95], v[16:19]
	global_load_lds_dwordx4 v[26:27], off
	v_lshl_add_u64 v[26:27], v[26:27], 0, s[94:95]
	v_mfma_f32_16x16x32_bf16 v[20:23], v[104:107], v[80:83], v[20:23]
	s_add_i32 m0, vcc_lo, 0x800
	v_mfma_f32_16x16x32_bf16 v[32:35], v[104:107], v[84:87], v[32:35]
	global_load_lds_dwordx4 v[30:31], off
	v_lshl_add_u64 v[30:31], v[30:31], 0, s[94:95]
	v_mfma_f32_16x16x32_bf16 v[36:39], v[104:107], v[88:91], v[36:39]
	s_add_i32 m0, vcc_lo, 0xc00
	v_mfma_f32_16x16x32_bf16 v[40:43], v[104:107], v[92:95], v[40:43]
	global_load_lds_dwordx4 v[70:71], off
	v_lshl_add_u64 v[70:71], v[70:71], 0, s[94:95]
	v_mfma_f32_16x16x32_bf16 v[44:47], v[108:111], v[80:83], v[44:47]
	s_add_i32 m0, vcc_lo, 0x1000
	v_mfma_f32_16x16x32_bf16 v[48:51], v[108:111], v[84:87], v[48:51]
	global_load_lds_dwordx4 v[98:99], off
	v_lshl_add_u64 v[98:99], v[98:99], 0, s[94:95]
	v_mfma_f32_16x16x32_bf16 v[52:55], v[108:111], v[88:91], v[52:55]
	s_add_i32 m0, vcc_lo, 0x1400
	v_mfma_f32_16x16x32_bf16 v[56:59], v[108:111], v[92:95], v[56:59]
	global_load_lds_dwordx4 v[116:117], off
	v_lshl_add_u64 v[116:117], v[116:117], 0, s[94:95]
	v_mfma_f32_16x16x32_bf16 v[60:63], v[112:115], v[80:83], v[60:63]
	s_add_i32 m0, vcc_lo, 0x1800
	v_mfma_f32_16x16x32_bf16 v[64:67], v[112:115], v[84:87], v[64:67]
	global_load_lds_dwordx4 v[118:119], off
	v_lshl_add_u64 v[118:119], v[118:119], 0, s[94:95]
	v_mfma_f32_16x16x32_bf16 v[72:75], v[112:115], v[88:91], v[72:75]
	s_add_i32 m0, vcc_lo, 0x1c00
	v_mfma_f32_16x16x32_bf16 v[76:79], v[112:115], v[92:95], v[76:79]
	global_load_lds_dwordx4 v[120:121], off
	v_lshl_add_u64 v[120:121], v[120:121], 0, s[94:95]
	s_waitcnt vmcnt(8)
	ds_read_b128 v[80:83], v130 offset:8192
	ds_read_b128 v[84:87], v130 offset:9216
	ds_read_b128 v[88:91], v130 offset:10240
	ds_read_b128 v[92:95], v130 offset:11264
	ds_read_b128 v[100:103], v130 offset:12288
	ds_read_b128 v[104:107], v130 offset:13312
	ds_read_b128 v[108:111], v130 offset:14336
	ds_read_b128 v[112:115], v130 offset:15360
	s_waitcnt lgkmcnt(0)
	v_mfma_f32_16x16x32_bf16 v[0:3], v[100:103], v[80:83], v[0:3]
	s_add_i32 m0, vcc_lo, 0x2000
	v_mfma_f32_16x16x32_bf16 v[4:7], v[100:103], v[84:87], v[4:7]
	global_load_lds_dwordx4 v[14:15], off
	v_lshl_add_u64 v[14:15], v[14:15], 0, s[94:95]
	v_mfma_f32_16x16x32_bf16 v[8:11], v[100:103], v[88:91], v[8:11]
	s_add_i32 m0, vcc_lo, 0x2400
	v_mfma_f32_16x16x32_bf16 v[16:19], v[100:103], v[92:95], v[16:19]
	global_load_lds_dwordx4 v[26:27], off
	v_lshl_add_u64 v[26:27], v[26:27], 0, s[94:95]
	v_mfma_f32_16x16x32_bf16 v[20:23], v[104:107], v[80:83], v[20:23]
	s_add_i32 m0, vcc_lo, 0x2800
	v_mfma_f32_16x16x32_bf16 v[32:35], v[104:107], v[84:87], v[32:35]
	global_load_lds_dwordx4 v[30:31], off
	v_lshl_add_u64 v[30:31], v[30:31], 0, s[94:95]
	v_mfma_f32_16x16x32_bf16 v[36:39], v[104:107], v[88:91], v[36:39]
	s_add_i32 m0, vcc_lo, 0x2c00
	v_mfma_f32_16x16x32_bf16 v[40:43], v[104:107], v[92:95], v[40:43]
	global_load_lds_dwordx4 v[70:71], off
	v_lshl_add_u64 v[70:71], v[70:71], 0, s[94:95]
	v_mfma_f32_16x16x32_bf16 v[44:47], v[108:111], v[80:83], v[44:47]
	s_add_i32 m0, vcc_lo, 0x3000
	v_mfma_f32_16x16x32_bf16 v[48:51], v[108:111], v[84:87], v[48:51]
	global_load_lds_dwordx4 v[98:99], off
	v_lshl_add_u64 v[98:99], v[98:99], 0, s[94:95]
	v_mfma_f32_16x16x32_bf16 v[52:55], v[108:111], v[88:91], v[52:55]
	s_add_i32 m0, vcc_lo, 0x3400
	v_mfma_f32_16x16x32_bf16 v[56:59], v[108:111], v[92:95], v[56:59]
	global_load_lds_dwordx4 v[116:117], off
	v_lshl_add_u64 v[116:117], v[116:117], 0, s[94:95]
	v_mfma_f32_16x16x32_bf16 v[60:63], v[112:115], v[80:83], v[60:63]
	s_add_i32 m0, vcc_lo, 0x3800
	v_mfma_f32_16x16x32_bf16 v[64:67], v[112:115], v[84:87], v[64:67]
	global_load_lds_dwordx4 v[118:119], off
	v_lshl_add_u64 v[118:119], v[118:119], 0, s[94:95]
	v_mfma_f32_16x16x32_bf16 v[72:75], v[112:115], v[88:91], v[72:75]
	s_add_i32 m0, vcc_lo, 0x3c00
	v_mfma_f32_16x16x32_bf16 v[76:79], v[112:115], v[92:95], v[76:79]
	global_load_lds_dwordx4 v[120:121], off
	v_lshl_add_u64 v[120:121], v[120:121], 0, s[94:95]
	s_waitcnt vmcnt(8)
	ds_read_b128 v[80:83], v130
	ds_read_b128 v[84:87], v130 offset:1024
	ds_read_b128 v[88:91], v130 offset:2048
	ds_read_b128 v[92:95], v130 offset:3072
	ds_read_b128 v[100:103], v130 offset:4096
	ds_read_b128 v[104:107], v130 offset:5120
	ds_read_b128 v[108:111], v130 offset:6144
	ds_read_b128 v[112:115], v130 offset:7168
	s_waitcnt lgkmcnt(0)
	v_mfma_f32_16x16x32_bf16 v[0:3], v[100:103], v[80:83], v[0:3]
	s_add_i32 m0, vcc_lo, 0x0
	v_mfma_f32_16x16x32_bf16 v[4:7], v[100:103], v[84:87], v[4:7]
	global_load_lds_dwordx4 v[14:15], off
	v_lshl_add_u64 v[14:15], v[14:15], 0, s[94:95]
	v_mfma_f32_16x16x32_bf16 v[8:11], v[100:103], v[88:91], v[8:11]
	s_add_i32 m0, vcc_lo, 0x400
	v_mfma_f32_16x16x32_bf16 v[16:19], v[100:103], v[92:95], v[16:19]
	global_load_lds_dwordx4 v[26:27], off
	v_lshl_add_u64 v[26:27], v[26:27], 0, s[94:95]
	v_mfma_f32_16x16x32_bf16 v[20:23], v[104:107], v[80:83], v[20:23]
	s_add_i32 m0, vcc_lo, 0x800
	v_mfma_f32_16x16x32_bf16 v[32:35], v[104:107], v[84:87], v[32:35]
	global_load_lds_dwordx4 v[30:31], off
	v_lshl_add_u64 v[30:31], v[30:31], 0, s[94:95]
	v_mfma_f32_16x16x32_bf16 v[36:39], v[104:107], v[88:91], v[36:39]
	s_add_i32 m0, vcc_lo, 0xc00
	v_mfma_f32_16x16x32_bf16 v[40:43], v[104:107], v[92:95], v[40:43]
	global_load_lds_dwordx4 v[70:71], off
	v_lshl_add_u64 v[70:71], v[70:71], 0, s[94:95]
	v_mfma_f32_16x16x32_bf16 v[44:47], v[108:111], v[80:83], v[44:47]
	s_add_i32 m0, vcc_lo, 0x1000
	v_mfma_f32_16x16x32_bf16 v[48:51], v[108:111], v[84:87], v[48:51]
	global_load_lds_dwordx4 v[98:99], off
	v_lshl_add_u64 v[98:99], v[98:99], 0, s[94:95]
	v_mfma_f32_16x16x32_bf16 v[52:55], v[108:111], v[88:91], v[52:55]
	s_add_i32 m0, vcc_lo, 0x1400
	v_mfma_f32_16x16x32_bf16 v[56:59], v[108:111], v[92:95], v[56:59]
	global_load_lds_dwordx4 v[116:117], off
	v_lshl_add_u64 v[116:117], v[116:117], 0, s[94:95]
	v_mfma_f32_16x16x32_bf16 v[60:63], v[112:115], v[80:83], v[60:63]
	s_add_i32 m0, vcc_lo, 0x1800
	v_mfma_f32_16x16x32_bf16 v[64:67], v[112:115], v[84:87], v[64:67]
	global_load_lds_dwordx4 v[118:119], off
	v_lshl_add_u64 v[118:119], v[118:119], 0, s[94:95]
	v_mfma_f32_16x16x32_bf16 v[72:75], v[112:115], v[88:91], v[72:75]
	s_add_i32 m0, vcc_lo, 0x1c00
	v_mfma_f32_16x16x32_bf16 v[76:79], v[112:115], v[92:95], v[76:79]
	global_load_lds_dwordx4 v[120:121], off
	v_lshl_add_u64 v[120:121], v[120:121], 0, s[94:95]
	s_waitcnt vmcnt(8)
	ds_read_b128 v[80:83], v130 offset:8192
	ds_read_b128 v[84:87], v130 offset:9216
	ds_read_b128 v[88:91], v130 offset:10240
	ds_read_b128 v[92:95], v130 offset:11264
	ds_read_b128 v[100:103], v130 offset:12288
	ds_read_b128 v[104:107], v130 offset:13312
	ds_read_b128 v[108:111], v130 offset:14336
	ds_read_b128 v[112:115], v130 offset:15360
	s_waitcnt lgkmcnt(0)
	v_mfma_f32_16x16x32_bf16 v[0:3], v[100:103], v[80:83], v[0:3]
	s_add_i32 m0, vcc_lo, 0x2000
	v_mfma_f32_16x16x32_bf16 v[4:7], v[100:103], v[84:87], v[4:7]
	global_load_lds_dwordx4 v[14:15], off
	v_lshl_add_u64 v[14:15], v[14:15], 0, s[94:95]
	v_mfma_f32_16x16x32_bf16 v[8:11], v[100:103], v[88:91], v[8:11]
	s_add_i32 m0, vcc_lo, 0x2400
	v_mfma_f32_16x16x32_bf16 v[16:19], v[100:103], v[92:95], v[16:19]
	global_load_lds_dwordx4 v[26:27], off
	v_lshl_add_u64 v[26:27], v[26:27], 0, s[94:95]
	v_mfma_f32_16x16x32_bf16 v[20:23], v[104:107], v[80:83], v[20:23]
	s_add_i32 m0, vcc_lo, 0x2800
	v_mfma_f32_16x16x32_bf16 v[32:35], v[104:107], v[84:87], v[32:35]
	global_load_lds_dwordx4 v[30:31], off
	v_lshl_add_u64 v[30:31], v[30:31], 0, s[94:95]
	v_mfma_f32_16x16x32_bf16 v[36:39], v[104:107], v[88:91], v[36:39]
	s_add_i32 m0, vcc_lo, 0x2c00
	v_mfma_f32_16x16x32_bf16 v[40:43], v[104:107], v[92:95], v[40:43]
	global_load_lds_dwordx4 v[70:71], off
	v_lshl_add_u64 v[70:71], v[70:71], 0, s[94:95]
	v_mfma_f32_16x16x32_bf16 v[44:47], v[108:111], v[80:83], v[44:47]
	s_add_i32 m0, vcc_lo, 0x3000
	v_mfma_f32_16x16x32_bf16 v[48:51], v[108:111], v[84:87], v[48:51]
	global_load_lds_dwordx4 v[98:99], off
	v_lshl_add_u64 v[98:99], v[98:99], 0, s[94:95]
	v_mfma_f32_16x16x32_bf16 v[52:55], v[108:111], v[88:91], v[52:55]
	s_add_i32 m0, vcc_lo, 0x3400
	v_mfma_f32_16x16x32_bf16 v[56:59], v[108:111], v[92:95], v[56:59]
	global_load_lds_dwordx4 v[116:117], off
	v_lshl_add_u64 v[116:117], v[116:117], 0, s[94:95]
	v_mfma_f32_16x16x32_bf16 v[60:63], v[112:115], v[80:83], v[60:63]
	s_add_i32 m0, vcc_lo, 0x3800
	v_mfma_f32_16x16x32_bf16 v[64:67], v[112:115], v[84:87], v[64:67]
	global_load_lds_dwordx4 v[118:119], off
	v_lshl_add_u64 v[118:119], v[118:119], 0, s[94:95]
	v_mfma_f32_16x16x32_bf16 v[72:75], v[112:115], v[88:91], v[72:75]
	s_add_i32 m0, vcc_lo, 0x3c00
	v_mfma_f32_16x16x32_bf16 v[76:79], v[112:115], v[92:95], v[76:79]
	global_load_lds_dwordx4 v[120:121], off
	v_lshl_add_u64 v[120:121], v[120:121], 0, s[94:95]
	s_waitcnt vmcnt(8)
	ds_read_b128 v[80:83], v130
	ds_read_b128 v[84:87], v130 offset:1024
	ds_read_b128 v[88:91], v130 offset:2048
	ds_read_b128 v[92:95], v130 offset:3072
	ds_read_b128 v[100:103], v130 offset:4096
	ds_read_b128 v[104:107], v130 offset:5120
	ds_read_b128 v[108:111], v130 offset:6144
	ds_read_b128 v[112:115], v130 offset:7168
	s_waitcnt lgkmcnt(0)
	v_mfma_f32_16x16x32_bf16 v[0:3], v[100:103], v[80:83], v[0:3]
	s_add_i32 m0, vcc_lo, 0x0
	v_mfma_f32_16x16x32_bf16 v[4:7], v[100:103], v[84:87], v[4:7]
	global_load_lds_dwordx4 v[14:15], off
	v_lshl_add_u64 v[14:15], v[14:15], 0, s[94:95]
	v_mfma_f32_16x16x32_bf16 v[8:11], v[100:103], v[88:91], v[8:11]
	s_add_i32 m0, vcc_lo, 0x400
	v_mfma_f32_16x16x32_bf16 v[16:19], v[100:103], v[92:95], v[16:19]
	global_load_lds_dwordx4 v[26:27], off
	v_lshl_add_u64 v[26:27], v[26:27], 0, s[94:95]
	v_mfma_f32_16x16x32_bf16 v[20:23], v[104:107], v[80:83], v[20:23]
	s_add_i32 m0, vcc_lo, 0x800
	v_mfma_f32_16x16x32_bf16 v[32:35], v[104:107], v[84:87], v[32:35]
	global_load_lds_dwordx4 v[30:31], off
	v_lshl_add_u64 v[30:31], v[30:31], 0, s[94:95]
	v_mfma_f32_16x16x32_bf16 v[36:39], v[104:107], v[88:91], v[36:39]
	s_add_i32 m0, vcc_lo, 0xc00
	v_mfma_f32_16x16x32_bf16 v[40:43], v[104:107], v[92:95], v[40:43]
	global_load_lds_dwordx4 v[70:71], off
	v_lshl_add_u64 v[70:71], v[70:71], 0, s[94:95]
	v_mfma_f32_16x16x32_bf16 v[44:47], v[108:111], v[80:83], v[44:47]
	s_add_i32 m0, vcc_lo, 0x1000
	v_mfma_f32_16x16x32_bf16 v[48:51], v[108:111], v[84:87], v[48:51]
	global_load_lds_dwordx4 v[98:99], off
	v_lshl_add_u64 v[98:99], v[98:99], 0, s[94:95]
	v_mfma_f32_16x16x32_bf16 v[52:55], v[108:111], v[88:91], v[52:55]
	s_add_i32 m0, vcc_lo, 0x1400
	v_mfma_f32_16x16x32_bf16 v[56:59], v[108:111], v[92:95], v[56:59]
	global_load_lds_dwordx4 v[116:117], off
	v_lshl_add_u64 v[116:117], v[116:117], 0, s[94:95]
	v_mfma_f32_16x16x32_bf16 v[60:63], v[112:115], v[80:83], v[60:63]
	s_add_i32 m0, vcc_lo, 0x1800
	v_mfma_f32_16x16x32_bf16 v[64:67], v[112:115], v[84:87], v[64:67]
	global_load_lds_dwordx4 v[118:119], off
	v_lshl_add_u64 v[118:119], v[118:119], 0, s[94:95]
	v_mfma_f32_16x16x32_bf16 v[72:75], v[112:115], v[88:91], v[72:75]
	s_add_i32 m0, vcc_lo, 0x1c00
	v_mfma_f32_16x16x32_bf16 v[76:79], v[112:115], v[92:95], v[76:79]
	global_load_lds_dwordx4 v[120:121], off
	v_lshl_add_u64 v[120:121], v[120:121], 0, s[94:95]
	s_waitcnt vmcnt(8)
	ds_read_b128 v[80:83], v130 offset:8192
	ds_read_b128 v[84:87], v130 offset:9216
	ds_read_b128 v[88:91], v130 offset:10240
	ds_read_b128 v[92:95], v130 offset:11264
	ds_read_b128 v[100:103], v130 offset:12288
	ds_read_b128 v[104:107], v130 offset:13312
	ds_read_b128 v[108:111], v130 offset:14336
	ds_read_b128 v[112:115], v130 offset:15360
	s_waitcnt lgkmcnt(0)
	v_mfma_f32_16x16x32_bf16 v[0:3], v[100:103], v[80:83], v[0:3]
	s_add_i32 m0, vcc_lo, 0x2000
	v_mfma_f32_16x16x32_bf16 v[4:7], v[100:103], v[84:87], v[4:7]
	global_load_lds_dwordx4 v[14:15], off
	v_lshl_add_u64 v[14:15], v[14:15], 0, s[94:95]
	v_mfma_f32_16x16x32_bf16 v[8:11], v[100:103], v[88:91], v[8:11]
	s_add_i32 m0, vcc_lo, 0x2400
	v_mfma_f32_16x16x32_bf16 v[16:19], v[100:103], v[92:95], v[16:19]
	global_load_lds_dwordx4 v[26:27], off
	v_lshl_add_u64 v[26:27], v[26:27], 0, s[94:95]
	v_mfma_f32_16x16x32_bf16 v[20:23], v[104:107], v[80:83], v[20:23]
	s_add_i32 m0, vcc_lo, 0x2800
	v_mfma_f32_16x16x32_bf16 v[32:35], v[104:107], v[84:87], v[32:35]
	global_load_lds_dwordx4 v[30:31], off
	v_lshl_add_u64 v[30:31], v[30:31], 0, s[94:95]
	v_mfma_f32_16x16x32_bf16 v[36:39], v[104:107], v[88:91], v[36:39]
	s_add_i32 m0, vcc_lo, 0x2c00
	v_mfma_f32_16x16x32_bf16 v[40:43], v[104:107], v[92:95], v[40:43]
	global_load_lds_dwordx4 v[70:71], off
	v_lshl_add_u64 v[70:71], v[70:71], 0, s[94:95]
	v_mfma_f32_16x16x32_bf16 v[44:47], v[108:111], v[80:83], v[44:47]
	s_add_i32 m0, vcc_lo, 0x3000
	v_mfma_f32_16x16x32_bf16 v[48:51], v[108:111], v[84:87], v[48:51]
	global_load_lds_dwordx4 v[98:99], off
	v_lshl_add_u64 v[98:99], v[98:99], 0, s[94:95]
	v_mfma_f32_16x16x32_bf16 v[52:55], v[108:111], v[88:91], v[52:55]
	s_add_i32 m0, vcc_lo, 0x3400
	v_mfma_f32_16x16x32_bf16 v[56:59], v[108:111], v[92:95], v[56:59]
	global_load_lds_dwordx4 v[116:117], off
	v_lshl_add_u64 v[116:117], v[116:117], 0, s[94:95]
	v_mfma_f32_16x16x32_bf16 v[60:63], v[112:115], v[80:83], v[60:63]
	s_add_i32 m0, vcc_lo, 0x3800
	v_mfma_f32_16x16x32_bf16 v[64:67], v[112:115], v[84:87], v[64:67]
	global_load_lds_dwordx4 v[118:119], off
	v_lshl_add_u64 v[118:119], v[118:119], 0, s[94:95]
	v_mfma_f32_16x16x32_bf16 v[72:75], v[112:115], v[88:91], v[72:75]
	s_add_i32 m0, vcc_lo, 0x3c00
	v_mfma_f32_16x16x32_bf16 v[76:79], v[112:115], v[92:95], v[76:79]
	global_load_lds_dwordx4 v[120:121], off
	v_lshl_add_u64 v[120:121], v[120:121], 0, s[94:95]
	s_waitcnt vmcnt(8)
	ds_read_b128 v[80:83], v130
	ds_read_b128 v[84:87], v130 offset:1024
	ds_read_b128 v[88:91], v130 offset:2048
	ds_read_b128 v[92:95], v130 offset:3072
	ds_read_b128 v[100:103], v130 offset:4096
	ds_read_b128 v[104:107], v130 offset:5120
	ds_read_b128 v[108:111], v130 offset:6144
	ds_read_b128 v[112:115], v130 offset:7168
	s_waitcnt lgkmcnt(0)
	v_mfma_f32_16x16x32_bf16 v[0:3], v[100:103], v[80:83], v[0:3]
	s_add_i32 m0, vcc_lo, 0x0
	v_mfma_f32_16x16x32_bf16 v[4:7], v[100:103], v[84:87], v[4:7]
	global_load_lds_dwordx4 v[14:15], off
	v_lshl_add_u64 v[14:15], v[14:15], 0, s[94:95]
	v_mfma_f32_16x16x32_bf16 v[8:11], v[100:103], v[88:91], v[8:11]
	s_add_i32 m0, vcc_lo, 0x400
	v_mfma_f32_16x16x32_bf16 v[16:19], v[100:103], v[92:95], v[16:19]
	global_load_lds_dwordx4 v[26:27], off
	v_lshl_add_u64 v[26:27], v[26:27], 0, s[94:95]
	v_mfma_f32_16x16x32_bf16 v[20:23], v[104:107], v[80:83], v[20:23]
	s_add_i32 m0, vcc_lo, 0x800
	v_mfma_f32_16x16x32_bf16 v[32:35], v[104:107], v[84:87], v[32:35]
	global_load_lds_dwordx4 v[30:31], off
	v_lshl_add_u64 v[30:31], v[30:31], 0, s[94:95]
	v_mfma_f32_16x16x32_bf16 v[36:39], v[104:107], v[88:91], v[36:39]
	s_add_i32 m0, vcc_lo, 0xc00
	v_mfma_f32_16x16x32_bf16 v[40:43], v[104:107], v[92:95], v[40:43]
	global_load_lds_dwordx4 v[70:71], off
	v_lshl_add_u64 v[70:71], v[70:71], 0, s[94:95]
	v_mfma_f32_16x16x32_bf16 v[44:47], v[108:111], v[80:83], v[44:47]
	s_add_i32 m0, vcc_lo, 0x1000
	v_mfma_f32_16x16x32_bf16 v[48:51], v[108:111], v[84:87], v[48:51]
	global_load_lds_dwordx4 v[98:99], off
	v_lshl_add_u64 v[98:99], v[98:99], 0, s[94:95]
	v_mfma_f32_16x16x32_bf16 v[52:55], v[108:111], v[88:91], v[52:55]
	s_add_i32 m0, vcc_lo, 0x1400
	v_mfma_f32_16x16x32_bf16 v[56:59], v[108:111], v[92:95], v[56:59]
	global_load_lds_dwordx4 v[116:117], off
	v_lshl_add_u64 v[116:117], v[116:117], 0, s[94:95]
	v_mfma_f32_16x16x32_bf16 v[60:63], v[112:115], v[80:83], v[60:63]
	s_add_i32 m0, vcc_lo, 0x1800
	v_mfma_f32_16x16x32_bf16 v[64:67], v[112:115], v[84:87], v[64:67]
	global_load_lds_dwordx4 v[118:119], off
	v_lshl_add_u64 v[118:119], v[118:119], 0, s[94:95]
	v_mfma_f32_16x16x32_bf16 v[72:75], v[112:115], v[88:91], v[72:75]
	s_add_i32 m0, vcc_lo, 0x1c00
	v_mfma_f32_16x16x32_bf16 v[76:79], v[112:115], v[92:95], v[76:79]
	global_load_lds_dwordx4 v[120:121], off
	v_lshl_add_u64 v[120:121], v[120:121], 0, s[94:95]
	s_waitcnt vmcnt(8)
	ds_read_b128 v[80:83], v130 offset:8192
	ds_read_b128 v[84:87], v130 offset:9216
	ds_read_b128 v[88:91], v130 offset:10240
	ds_read_b128 v[92:95], v130 offset:11264
	ds_read_b128 v[100:103], v130 offset:12288
	ds_read_b128 v[104:107], v130 offset:13312
	ds_read_b128 v[108:111], v130 offset:14336
	ds_read_b128 v[112:115], v130 offset:15360
	s_waitcnt lgkmcnt(0)
	v_mfma_f32_16x16x32_bf16 v[0:3], v[100:103], v[80:83], v[0:3]
	s_add_i32 m0, vcc_lo, 0x2000
	v_mfma_f32_16x16x32_bf16 v[4:7], v[100:103], v[84:87], v[4:7]
	global_load_lds_dwordx4 v[14:15], off
	v_lshl_add_u64 v[14:15], v[14:15], 0, s[94:95]
	v_mfma_f32_16x16x32_bf16 v[8:11], v[100:103], v[88:91], v[8:11]
	s_add_i32 m0, vcc_lo, 0x2400
	v_mfma_f32_16x16x32_bf16 v[16:19], v[100:103], v[92:95], v[16:19]
	global_load_lds_dwordx4 v[26:27], off
	v_lshl_add_u64 v[26:27], v[26:27], 0, s[94:95]
	v_mfma_f32_16x16x32_bf16 v[20:23], v[104:107], v[80:83], v[20:23]
	s_add_i32 m0, vcc_lo, 0x2800
	v_mfma_f32_16x16x32_bf16 v[32:35], v[104:107], v[84:87], v[32:35]
	global_load_lds_dwordx4 v[30:31], off
	v_lshl_add_u64 v[30:31], v[30:31], 0, s[94:95]
	v_mfma_f32_16x16x32_bf16 v[36:39], v[104:107], v[88:91], v[36:39]
	s_add_i32 m0, vcc_lo, 0x2c00
	v_mfma_f32_16x16x32_bf16 v[40:43], v[104:107], v[92:95], v[40:43]
	global_load_lds_dwordx4 v[70:71], off
	v_lshl_add_u64 v[70:71], v[70:71], 0, s[94:95]
	v_mfma_f32_16x16x32_bf16 v[44:47], v[108:111], v[80:83], v[44:47]
	s_add_i32 m0, vcc_lo, 0x3000
	v_mfma_f32_16x16x32_bf16 v[48:51], v[108:111], v[84:87], v[48:51]
	global_load_lds_dwordx4 v[98:99], off
	v_lshl_add_u64 v[98:99], v[98:99], 0, s[94:95]
	v_mfma_f32_16x16x32_bf16 v[52:55], v[108:111], v[88:91], v[52:55]
	s_add_i32 m0, vcc_lo, 0x3400
	v_mfma_f32_16x16x32_bf16 v[56:59], v[108:111], v[92:95], v[56:59]
	global_load_lds_dwordx4 v[116:117], off
	v_lshl_add_u64 v[116:117], v[116:117], 0, s[94:95]
	v_mfma_f32_16x16x32_bf16 v[60:63], v[112:115], v[80:83], v[60:63]
	s_add_i32 m0, vcc_lo, 0x3800
	v_mfma_f32_16x16x32_bf16 v[64:67], v[112:115], v[84:87], v[64:67]
	global_load_lds_dwordx4 v[118:119], off
	v_lshl_add_u64 v[118:119], v[118:119], 0, s[94:95]
	v_mfma_f32_16x16x32_bf16 v[72:75], v[112:115], v[88:91], v[72:75]
	s_add_i32 m0, vcc_lo, 0x3c00
	v_mfma_f32_16x16x32_bf16 v[76:79], v[112:115], v[92:95], v[76:79]
	global_load_lds_dwordx4 v[120:121], off
	v_lshl_add_u64 v[120:121], v[120:121], 0, s[94:95]
	s_waitcnt vmcnt(8)
	ds_read_b128 v[80:83], v130
	ds_read_b128 v[84:87], v130 offset:1024
	ds_read_b128 v[88:91], v130 offset:2048
	ds_read_b128 v[92:95], v130 offset:3072
	ds_read_b128 v[100:103], v130 offset:4096
	ds_read_b128 v[104:107], v130 offset:5120
	ds_read_b128 v[108:111], v130 offset:6144
	ds_read_b128 v[112:115], v130 offset:7168
	s_waitcnt lgkmcnt(0)
	v_mfma_f32_16x16x32_bf16 v[0:3], v[100:103], v[80:83], v[0:3]
	s_add_i32 m0, vcc_lo, 0x0
	v_mfma_f32_16x16x32_bf16 v[4:7], v[100:103], v[84:87], v[4:7]
	global_load_lds_dwordx4 v[14:15], off
	v_lshl_add_u64 v[14:15], v[14:15], 0, s[94:95]
	v_mfma_f32_16x16x32_bf16 v[8:11], v[100:103], v[88:91], v[8:11]
	s_add_i32 m0, vcc_lo, 0x400
	v_mfma_f32_16x16x32_bf16 v[16:19], v[100:103], v[92:95], v[16:19]
	global_load_lds_dwordx4 v[26:27], off
	v_lshl_add_u64 v[26:27], v[26:27], 0, s[94:95]
	v_mfma_f32_16x16x32_bf16 v[20:23], v[104:107], v[80:83], v[20:23]
	s_add_i32 m0, vcc_lo, 0x800
	v_mfma_f32_16x16x32_bf16 v[32:35], v[104:107], v[84:87], v[32:35]
	global_load_lds_dwordx4 v[30:31], off
	v_lshl_add_u64 v[30:31], v[30:31], 0, s[94:95]
	v_mfma_f32_16x16x32_bf16 v[36:39], v[104:107], v[88:91], v[36:39]
	s_add_i32 m0, vcc_lo, 0xc00
	v_mfma_f32_16x16x32_bf16 v[40:43], v[104:107], v[92:95], v[40:43]
	global_load_lds_dwordx4 v[70:71], off
	v_lshl_add_u64 v[70:71], v[70:71], 0, s[94:95]
	v_mfma_f32_16x16x32_bf16 v[44:47], v[108:111], v[80:83], v[44:47]
	s_add_i32 m0, vcc_lo, 0x1000
	v_mfma_f32_16x16x32_bf16 v[48:51], v[108:111], v[84:87], v[48:51]
	global_load_lds_dwordx4 v[98:99], off
	v_lshl_add_u64 v[98:99], v[98:99], 0, s[94:95]
	v_mfma_f32_16x16x32_bf16 v[52:55], v[108:111], v[88:91], v[52:55]
	s_add_i32 m0, vcc_lo, 0x1400
	v_mfma_f32_16x16x32_bf16 v[56:59], v[108:111], v[92:95], v[56:59]
	global_load_lds_dwordx4 v[116:117], off
	v_lshl_add_u64 v[116:117], v[116:117], 0, s[94:95]
	v_mfma_f32_16x16x32_bf16 v[60:63], v[112:115], v[80:83], v[60:63]
	s_add_i32 m0, vcc_lo, 0x1800
	v_mfma_f32_16x16x32_bf16 v[64:67], v[112:115], v[84:87], v[64:67]
	global_load_lds_dwordx4 v[118:119], off
	v_lshl_add_u64 v[118:119], v[118:119], 0, s[94:95]
	v_mfma_f32_16x16x32_bf16 v[72:75], v[112:115], v[88:91], v[72:75]
	s_add_i32 m0, vcc_lo, 0x1c00
	v_mfma_f32_16x16x32_bf16 v[76:79], v[112:115], v[92:95], v[76:79]
	global_load_lds_dwordx4 v[120:121], off
	v_lshl_add_u64 v[120:121], v[120:121], 0, s[94:95]
	s_waitcnt vmcnt(8)
	ds_read_b128 v[80:83], v130 offset:8192
	ds_read_b128 v[84:87], v130 offset:9216
	ds_read_b128 v[88:91], v130 offset:10240
	ds_read_b128 v[92:95], v130 offset:11264
	ds_read_b128 v[100:103], v130 offset:12288
	ds_read_b128 v[104:107], v130 offset:13312
	ds_read_b128 v[108:111], v130 offset:14336
	ds_read_b128 v[112:115], v130 offset:15360
	s_waitcnt lgkmcnt(0)
	v_mfma_f32_16x16x32_bf16 v[0:3], v[100:103], v[80:83], v[0:3]
	s_add_i32 m0, vcc_lo, 0x2000
	v_mfma_f32_16x16x32_bf16 v[4:7], v[100:103], v[84:87], v[4:7]
	global_load_lds_dwordx4 v[14:15], off
	v_lshl_add_u64 v[14:15], v[14:15], 0, s[94:95]
	v_mfma_f32_16x16x32_bf16 v[8:11], v[100:103], v[88:91], v[8:11]
	s_add_i32 m0, vcc_lo, 0x2400
	v_mfma_f32_16x16x32_bf16 v[16:19], v[100:103], v[92:95], v[16:19]
	global_load_lds_dwordx4 v[26:27], off
	v_lshl_add_u64 v[26:27], v[26:27], 0, s[94:95]
	v_mfma_f32_16x16x32_bf16 v[20:23], v[104:107], v[80:83], v[20:23]
	s_add_i32 m0, vcc_lo, 0x2800
	v_mfma_f32_16x16x32_bf16 v[32:35], v[104:107], v[84:87], v[32:35]
	global_load_lds_dwordx4 v[30:31], off
	v_lshl_add_u64 v[30:31], v[30:31], 0, s[94:95]
	v_mfma_f32_16x16x32_bf16 v[36:39], v[104:107], v[88:91], v[36:39]
	s_add_i32 m0, vcc_lo, 0x2c00
	v_mfma_f32_16x16x32_bf16 v[40:43], v[104:107], v[92:95], v[40:43]
	global_load_lds_dwordx4 v[70:71], off
	v_lshl_add_u64 v[70:71], v[70:71], 0, s[94:95]
	v_mfma_f32_16x16x32_bf16 v[44:47], v[108:111], v[80:83], v[44:47]
	s_add_i32 m0, vcc_lo, 0x3000
	v_mfma_f32_16x16x32_bf16 v[48:51], v[108:111], v[84:87], v[48:51]
	global_load_lds_dwordx4 v[98:99], off
	v_lshl_add_u64 v[98:99], v[98:99], 0, s[94:95]
	v_mfma_f32_16x16x32_bf16 v[52:55], v[108:111], v[88:91], v[52:55]
	s_add_i32 m0, vcc_lo, 0x3400
	v_mfma_f32_16x16x32_bf16 v[56:59], v[108:111], v[92:95], v[56:59]
	global_load_lds_dwordx4 v[116:117], off
	v_lshl_add_u64 v[116:117], v[116:117], 0, s[94:95]
	v_mfma_f32_16x16x32_bf16 v[60:63], v[112:115], v[80:83], v[60:63]
	s_add_i32 m0, vcc_lo, 0x3800
	v_mfma_f32_16x16x32_bf16 v[64:67], v[112:115], v[84:87], v[64:67]
	global_load_lds_dwordx4 v[118:119], off
	v_lshl_add_u64 v[118:119], v[118:119], 0, s[94:95]
	v_mfma_f32_16x16x32_bf16 v[72:75], v[112:115], v[88:91], v[72:75]
	s_add_i32 m0, vcc_lo, 0x3c00
	v_mfma_f32_16x16x32_bf16 v[76:79], v[112:115], v[92:95], v[76:79]
	global_load_lds_dwordx4 v[120:121], off
	v_lshl_add_u64 v[120:121], v[120:121], 0, s[94:95]
	s_waitcnt vmcnt(8)
	ds_read_b128 v[80:83], v130
	ds_read_b128 v[84:87], v130 offset:1024
	ds_read_b128 v[88:91], v130 offset:2048
	ds_read_b128 v[92:95], v130 offset:3072
	ds_read_b128 v[100:103], v130 offset:4096
	ds_read_b128 v[104:107], v130 offset:5120
	ds_read_b128 v[108:111], v130 offset:6144
	ds_read_b128 v[112:115], v130 offset:7168
	s_waitcnt lgkmcnt(0)
	v_mfma_f32_16x16x32_bf16 v[0:3], v[100:103], v[80:83], v[0:3]
	s_add_i32 m0, vcc_lo, 0x0
	v_mfma_f32_16x16x32_bf16 v[4:7], v[100:103], v[84:87], v[4:7]
	global_load_lds_dwordx4 v[14:15], off
	v_lshl_add_u64 v[14:15], v[14:15], 0, s[94:95]
	v_mfma_f32_16x16x32_bf16 v[8:11], v[100:103], v[88:91], v[8:11]
	s_add_i32 m0, vcc_lo, 0x400
	v_mfma_f32_16x16x32_bf16 v[16:19], v[100:103], v[92:95], v[16:19]
	global_load_lds_dwordx4 v[26:27], off
	v_lshl_add_u64 v[26:27], v[26:27], 0, s[94:95]
	v_mfma_f32_16x16x32_bf16 v[20:23], v[104:107], v[80:83], v[20:23]
	s_add_i32 m0, vcc_lo, 0x800
	v_mfma_f32_16x16x32_bf16 v[32:35], v[104:107], v[84:87], v[32:35]
	global_load_lds_dwordx4 v[30:31], off
	v_lshl_add_u64 v[30:31], v[30:31], 0, s[94:95]
	v_mfma_f32_16x16x32_bf16 v[36:39], v[104:107], v[88:91], v[36:39]
	s_add_i32 m0, vcc_lo, 0xc00
	v_mfma_f32_16x16x32_bf16 v[40:43], v[104:107], v[92:95], v[40:43]
	global_load_lds_dwordx4 v[70:71], off
	v_lshl_add_u64 v[70:71], v[70:71], 0, s[94:95]
	v_mfma_f32_16x16x32_bf16 v[44:47], v[108:111], v[80:83], v[44:47]
	s_add_i32 m0, vcc_lo, 0x1000
	v_mfma_f32_16x16x32_bf16 v[48:51], v[108:111], v[84:87], v[48:51]
	global_load_lds_dwordx4 v[98:99], off
	v_lshl_add_u64 v[98:99], v[98:99], 0, s[94:95]
	v_mfma_f32_16x16x32_bf16 v[52:55], v[108:111], v[88:91], v[52:55]
	s_add_i32 m0, vcc_lo, 0x1400
	v_mfma_f32_16x16x32_bf16 v[56:59], v[108:111], v[92:95], v[56:59]
	global_load_lds_dwordx4 v[116:117], off
	v_lshl_add_u64 v[116:117], v[116:117], 0, s[94:95]
	v_mfma_f32_16x16x32_bf16 v[60:63], v[112:115], v[80:83], v[60:63]
	s_add_i32 m0, vcc_lo, 0x1800
	v_mfma_f32_16x16x32_bf16 v[64:67], v[112:115], v[84:87], v[64:67]
	global_load_lds_dwordx4 v[118:119], off
	v_lshl_add_u64 v[118:119], v[118:119], 0, s[94:95]
	v_mfma_f32_16x16x32_bf16 v[72:75], v[112:115], v[88:91], v[72:75]
	s_add_i32 m0, vcc_lo, 0x1c00
	v_mfma_f32_16x16x32_bf16 v[76:79], v[112:115], v[92:95], v[76:79]
	global_load_lds_dwordx4 v[120:121], off
	v_lshl_add_u64 v[120:121], v[120:121], 0, s[94:95]
	s_waitcnt vmcnt(8)
	ds_read_b128 v[80:83], v130 offset:8192
	ds_read_b128 v[84:87], v130 offset:9216
	ds_read_b128 v[88:91], v130 offset:10240
	ds_read_b128 v[92:95], v130 offset:11264
	ds_read_b128 v[100:103], v130 offset:12288
	ds_read_b128 v[104:107], v130 offset:13312
	ds_read_b128 v[108:111], v130 offset:14336
	ds_read_b128 v[112:115], v130 offset:15360
	s_waitcnt lgkmcnt(0)
	v_mfma_f32_16x16x32_bf16 v[0:3], v[100:103], v[80:83], v[0:3]
	s_add_i32 m0, vcc_lo, 0x2000
	v_mfma_f32_16x16x32_bf16 v[4:7], v[100:103], v[84:87], v[4:7]
	global_load_lds_dwordx4 v[14:15], off
	v_lshl_add_u64 v[14:15], v[14:15], 0, s[94:95]
	v_mfma_f32_16x16x32_bf16 v[8:11], v[100:103], v[88:91], v[8:11]
	s_add_i32 m0, vcc_lo, 0x2400
	v_mfma_f32_16x16x32_bf16 v[16:19], v[100:103], v[92:95], v[16:19]
	global_load_lds_dwordx4 v[26:27], off
	v_lshl_add_u64 v[26:27], v[26:27], 0, s[94:95]
	v_mfma_f32_16x16x32_bf16 v[20:23], v[104:107], v[80:83], v[20:23]
	s_add_i32 m0, vcc_lo, 0x2800
	v_mfma_f32_16x16x32_bf16 v[32:35], v[104:107], v[84:87], v[32:35]
	global_load_lds_dwordx4 v[30:31], off
	v_lshl_add_u64 v[30:31], v[30:31], 0, s[94:95]
	v_mfma_f32_16x16x32_bf16 v[36:39], v[104:107], v[88:91], v[36:39]
	s_add_i32 m0, vcc_lo, 0x2c00
	v_mfma_f32_16x16x32_bf16 v[40:43], v[104:107], v[92:95], v[40:43]
	global_load_lds_dwordx4 v[70:71], off
	v_lshl_add_u64 v[70:71], v[70:71], 0, s[94:95]
	v_mfma_f32_16x16x32_bf16 v[44:47], v[108:111], v[80:83], v[44:47]
	s_add_i32 m0, vcc_lo, 0x3000
	v_mfma_f32_16x16x32_bf16 v[48:51], v[108:111], v[84:87], v[48:51]
	global_load_lds_dwordx4 v[98:99], off
	v_lshl_add_u64 v[98:99], v[98:99], 0, s[94:95]
	v_mfma_f32_16x16x32_bf16 v[52:55], v[108:111], v[88:91], v[52:55]
	s_add_i32 m0, vcc_lo, 0x3400
	v_mfma_f32_16x16x32_bf16 v[56:59], v[108:111], v[92:95], v[56:59]
	global_load_lds_dwordx4 v[116:117], off
	v_lshl_add_u64 v[116:117], v[116:117], 0, s[94:95]
	v_mfma_f32_16x16x32_bf16 v[60:63], v[112:115], v[80:83], v[60:63]
	s_add_i32 m0, vcc_lo, 0x3800
	v_mfma_f32_16x16x32_bf16 v[64:67], v[112:115], v[84:87], v[64:67]
	global_load_lds_dwordx4 v[118:119], off
	v_lshl_add_u64 v[118:119], v[118:119], 0, s[94:95]
	v_mfma_f32_16x16x32_bf16 v[72:75], v[112:115], v[88:91], v[72:75]
	s_add_i32 m0, vcc_lo, 0x3c00
	v_mfma_f32_16x16x32_bf16 v[76:79], v[112:115], v[92:95], v[76:79]
	global_load_lds_dwordx4 v[120:121], off
	v_lshl_add_u64 v[120:121], v[120:121], 0, s[94:95]
	s_waitcnt vmcnt(8)
	ds_read_b128 v[80:83], v130
	ds_read_b128 v[84:87], v130 offset:1024
	ds_read_b128 v[88:91], v130 offset:2048
	ds_read_b128 v[92:95], v130 offset:3072
	ds_read_b128 v[100:103], v130 offset:4096
	ds_read_b128 v[104:107], v130 offset:5120
	ds_read_b128 v[108:111], v130 offset:6144
	ds_read_b128 v[112:115], v130 offset:7168
	s_waitcnt lgkmcnt(0)
	v_mfma_f32_16x16x32_bf16 v[0:3], v[100:103], v[80:83], v[0:3]
	s_add_i32 m0, vcc_lo, 0x0
	v_mfma_f32_16x16x32_bf16 v[4:7], v[100:103], v[84:87], v[4:7]
	global_load_lds_dwordx4 v[14:15], off
	v_lshl_add_u64 v[14:15], v[14:15], 0, s[94:95]
	v_mfma_f32_16x16x32_bf16 v[8:11], v[100:103], v[88:91], v[8:11]
	s_add_i32 m0, vcc_lo, 0x400
	v_mfma_f32_16x16x32_bf16 v[16:19], v[100:103], v[92:95], v[16:19]
	global_load_lds_dwordx4 v[26:27], off
	v_lshl_add_u64 v[26:27], v[26:27], 0, s[94:95]
	v_mfma_f32_16x16x32_bf16 v[20:23], v[104:107], v[80:83], v[20:23]
	s_add_i32 m0, vcc_lo, 0x800
	v_mfma_f32_16x16x32_bf16 v[32:35], v[104:107], v[84:87], v[32:35]
	global_load_lds_dwordx4 v[30:31], off
	v_lshl_add_u64 v[30:31], v[30:31], 0, s[94:95]
	v_mfma_f32_16x16x32_bf16 v[36:39], v[104:107], v[88:91], v[36:39]
	s_add_i32 m0, vcc_lo, 0xc00
	v_mfma_f32_16x16x32_bf16 v[40:43], v[104:107], v[92:95], v[40:43]
	global_load_lds_dwordx4 v[70:71], off
	v_lshl_add_u64 v[70:71], v[70:71], 0, s[94:95]
	v_mfma_f32_16x16x32_bf16 v[44:47], v[108:111], v[80:83], v[44:47]
	s_add_i32 m0, vcc_lo, 0x1000
	v_mfma_f32_16x16x32_bf16 v[48:51], v[108:111], v[84:87], v[48:51]
	global_load_lds_dwordx4 v[98:99], off
	v_lshl_add_u64 v[98:99], v[98:99], 0, s[94:95]
	v_mfma_f32_16x16x32_bf16 v[52:55], v[108:111], v[88:91], v[52:55]
	s_add_i32 m0, vcc_lo, 0x1400
	v_mfma_f32_16x16x32_bf16 v[56:59], v[108:111], v[92:95], v[56:59]
	global_load_lds_dwordx4 v[116:117], off
	v_lshl_add_u64 v[116:117], v[116:117], 0, s[94:95]
	v_mfma_f32_16x16x32_bf16 v[60:63], v[112:115], v[80:83], v[60:63]
	s_add_i32 m0, vcc_lo, 0x1800
	v_mfma_f32_16x16x32_bf16 v[64:67], v[112:115], v[84:87], v[64:67]
	global_load_lds_dwordx4 v[118:119], off
	v_lshl_add_u64 v[118:119], v[118:119], 0, s[94:95]
	v_mfma_f32_16x16x32_bf16 v[72:75], v[112:115], v[88:91], v[72:75]
	s_add_i32 m0, vcc_lo, 0x1c00
	v_mfma_f32_16x16x32_bf16 v[76:79], v[112:115], v[92:95], v[76:79]
	global_load_lds_dwordx4 v[120:121], off
	v_lshl_add_u64 v[120:121], v[120:121], 0, s[94:95]
	s_waitcnt vmcnt(8)
	ds_read_b128 v[80:83], v130 offset:8192
	ds_read_b128 v[84:87], v130 offset:9216
	ds_read_b128 v[88:91], v130 offset:10240
	ds_read_b128 v[92:95], v130 offset:11264
	ds_read_b128 v[100:103], v130 offset:12288
	ds_read_b128 v[104:107], v130 offset:13312
	ds_read_b128 v[108:111], v130 offset:14336
	ds_read_b128 v[112:115], v130 offset:15360
	s_waitcnt lgkmcnt(0)
	v_mfma_f32_16x16x32_bf16 v[0:3], v[100:103], v[80:83], v[0:3]
	s_add_i32 m0, vcc_lo, 0x2000
	v_mfma_f32_16x16x32_bf16 v[4:7], v[100:103], v[84:87], v[4:7]
	global_load_lds_dwordx4 v[14:15], off
	v_lshl_add_u64 v[14:15], v[14:15], 0, s[94:95]
	v_mfma_f32_16x16x32_bf16 v[8:11], v[100:103], v[88:91], v[8:11]
	s_add_i32 m0, vcc_lo, 0x2400
	v_mfma_f32_16x16x32_bf16 v[16:19], v[100:103], v[92:95], v[16:19]
	global_load_lds_dwordx4 v[26:27], off
	v_lshl_add_u64 v[26:27], v[26:27], 0, s[94:95]
	v_mfma_f32_16x16x32_bf16 v[20:23], v[104:107], v[80:83], v[20:23]
	s_add_i32 m0, vcc_lo, 0x2800
	v_mfma_f32_16x16x32_bf16 v[32:35], v[104:107], v[84:87], v[32:35]
	global_load_lds_dwordx4 v[30:31], off
	v_lshl_add_u64 v[30:31], v[30:31], 0, s[94:95]
	v_mfma_f32_16x16x32_bf16 v[36:39], v[104:107], v[88:91], v[36:39]
	s_add_i32 m0, vcc_lo, 0x2c00
	v_mfma_f32_16x16x32_bf16 v[40:43], v[104:107], v[92:95], v[40:43]
	global_load_lds_dwordx4 v[70:71], off
	v_lshl_add_u64 v[70:71], v[70:71], 0, s[94:95]
	v_mfma_f32_16x16x32_bf16 v[44:47], v[108:111], v[80:83], v[44:47]
	s_add_i32 m0, vcc_lo, 0x3000
	v_mfma_f32_16x16x32_bf16 v[48:51], v[108:111], v[84:87], v[48:51]
	global_load_lds_dwordx4 v[98:99], off
	v_lshl_add_u64 v[98:99], v[98:99], 0, s[94:95]
	v_mfma_f32_16x16x32_bf16 v[52:55], v[108:111], v[88:91], v[52:55]
	s_add_i32 m0, vcc_lo, 0x3400
	v_mfma_f32_16x16x32_bf16 v[56:59], v[108:111], v[92:95], v[56:59]
	global_load_lds_dwordx4 v[116:117], off
	v_lshl_add_u64 v[116:117], v[116:117], 0, s[94:95]
	v_mfma_f32_16x16x32_bf16 v[60:63], v[112:115], v[80:83], v[60:63]
	s_add_i32 m0, vcc_lo, 0x3800
	v_mfma_f32_16x16x32_bf16 v[64:67], v[112:115], v[84:87], v[64:67]
	global_load_lds_dwordx4 v[118:119], off
	v_lshl_add_u64 v[118:119], v[118:119], 0, s[94:95]
	v_mfma_f32_16x16x32_bf16 v[72:75], v[112:115], v[88:91], v[72:75]
	s_add_i32 m0, vcc_lo, 0x3c00
	v_mfma_f32_16x16x32_bf16 v[76:79], v[112:115], v[92:95], v[76:79]
	global_load_lds_dwordx4 v[120:121], off
	v_lshl_add_u64 v[120:121], v[120:121], 0, s[94:95]
	s_waitcnt vmcnt(8)
	ds_read_b128 v[80:83], v130
	ds_read_b128 v[84:87], v130 offset:1024
	ds_read_b128 v[88:91], v130 offset:2048
	ds_read_b128 v[92:95], v130 offset:3072
	ds_read_b128 v[100:103], v130 offset:4096
	ds_read_b128 v[104:107], v130 offset:5120
	ds_read_b128 v[108:111], v130 offset:6144
	ds_read_b128 v[112:115], v130 offset:7168
	s_waitcnt lgkmcnt(0)
	v_mfma_f32_16x16x32_bf16 v[0:3], v[100:103], v[80:83], v[0:3]
	s_add_i32 m0, vcc_lo, 0x0
	v_mfma_f32_16x16x32_bf16 v[4:7], v[100:103], v[84:87], v[4:7]
	global_load_lds_dwordx4 v[14:15], off
	v_lshl_add_u64 v[14:15], v[14:15], 0, s[94:95]
	v_mfma_f32_16x16x32_bf16 v[8:11], v[100:103], v[88:91], v[8:11]
	s_add_i32 m0, vcc_lo, 0x400
	v_mfma_f32_16x16x32_bf16 v[16:19], v[100:103], v[92:95], v[16:19]
	global_load_lds_dwordx4 v[26:27], off
	v_lshl_add_u64 v[26:27], v[26:27], 0, s[94:95]
	v_mfma_f32_16x16x32_bf16 v[20:23], v[104:107], v[80:83], v[20:23]
	s_add_i32 m0, vcc_lo, 0x800
	v_mfma_f32_16x16x32_bf16 v[32:35], v[104:107], v[84:87], v[32:35]
	global_load_lds_dwordx4 v[30:31], off
	v_lshl_add_u64 v[30:31], v[30:31], 0, s[94:95]
	v_mfma_f32_16x16x32_bf16 v[36:39], v[104:107], v[88:91], v[36:39]
	s_add_i32 m0, vcc_lo, 0xc00
	v_mfma_f32_16x16x32_bf16 v[40:43], v[104:107], v[92:95], v[40:43]
	global_load_lds_dwordx4 v[70:71], off
	v_lshl_add_u64 v[70:71], v[70:71], 0, s[94:95]
	v_mfma_f32_16x16x32_bf16 v[44:47], v[108:111], v[80:83], v[44:47]
	s_add_i32 m0, vcc_lo, 0x1000
	v_mfma_f32_16x16x32_bf16 v[48:51], v[108:111], v[84:87], v[48:51]
	global_load_lds_dwordx4 v[98:99], off
	v_lshl_add_u64 v[98:99], v[98:99], 0, s[94:95]
	v_mfma_f32_16x16x32_bf16 v[52:55], v[108:111], v[88:91], v[52:55]
	s_add_i32 m0, vcc_lo, 0x1400
	v_mfma_f32_16x16x32_bf16 v[56:59], v[108:111], v[92:95], v[56:59]
	global_load_lds_dwordx4 v[116:117], off
	v_lshl_add_u64 v[116:117], v[116:117], 0, s[94:95]
	v_mfma_f32_16x16x32_bf16 v[60:63], v[112:115], v[80:83], v[60:63]
	s_add_i32 m0, vcc_lo, 0x1800
	v_mfma_f32_16x16x32_bf16 v[64:67], v[112:115], v[84:87], v[64:67]
	global_load_lds_dwordx4 v[118:119], off
	v_lshl_add_u64 v[118:119], v[118:119], 0, s[94:95]
	v_mfma_f32_16x16x32_bf16 v[72:75], v[112:115], v[88:91], v[72:75]
	s_add_i32 m0, vcc_lo, 0x1c00
	v_mfma_f32_16x16x32_bf16 v[76:79], v[112:115], v[92:95], v[76:79]
	global_load_lds_dwordx4 v[120:121], off
	v_lshl_add_u64 v[120:121], v[120:121], 0, s[94:95]
	s_waitcnt vmcnt(8)
	ds_read_b128 v[80:83], v130 offset:8192
	ds_read_b128 v[84:87], v130 offset:9216
	ds_read_b128 v[88:91], v130 offset:10240
	ds_read_b128 v[92:95], v130 offset:11264
	ds_read_b128 v[100:103], v130 offset:12288
	ds_read_b128 v[104:107], v130 offset:13312
	ds_read_b128 v[108:111], v130 offset:14336
	ds_read_b128 v[112:115], v130 offset:15360
	s_waitcnt lgkmcnt(0)
	v_mfma_f32_16x16x32_bf16 v[0:3], v[100:103], v[80:83], v[0:3]
	s_add_i32 m0, vcc_lo, 0x2000
	v_mfma_f32_16x16x32_bf16 v[4:7], v[100:103], v[84:87], v[4:7]
	global_load_lds_dwordx4 v[14:15], off
	v_lshl_add_u64 v[14:15], v[14:15], 0, s[94:95]
	v_mfma_f32_16x16x32_bf16 v[8:11], v[100:103], v[88:91], v[8:11]
	s_add_i32 m0, vcc_lo, 0x2400
	v_mfma_f32_16x16x32_bf16 v[16:19], v[100:103], v[92:95], v[16:19]
	global_load_lds_dwordx4 v[26:27], off
	v_lshl_add_u64 v[26:27], v[26:27], 0, s[94:95]
	v_mfma_f32_16x16x32_bf16 v[20:23], v[104:107], v[80:83], v[20:23]
	s_add_i32 m0, vcc_lo, 0x2800
	v_mfma_f32_16x16x32_bf16 v[32:35], v[104:107], v[84:87], v[32:35]
	global_load_lds_dwordx4 v[30:31], off
	v_lshl_add_u64 v[30:31], v[30:31], 0, s[94:95]
	v_mfma_f32_16x16x32_bf16 v[36:39], v[104:107], v[88:91], v[36:39]
	s_add_i32 m0, vcc_lo, 0x2c00
	v_mfma_f32_16x16x32_bf16 v[40:43], v[104:107], v[92:95], v[40:43]
	global_load_lds_dwordx4 v[70:71], off
	v_lshl_add_u64 v[70:71], v[70:71], 0, s[94:95]
	v_mfma_f32_16x16x32_bf16 v[44:47], v[108:111], v[80:83], v[44:47]
	s_add_i32 m0, vcc_lo, 0x3000
	v_mfma_f32_16x16x32_bf16 v[48:51], v[108:111], v[84:87], v[48:51]
	global_load_lds_dwordx4 v[98:99], off
	v_lshl_add_u64 v[98:99], v[98:99], 0, s[94:95]
	v_mfma_f32_16x16x32_bf16 v[52:55], v[108:111], v[88:91], v[52:55]
	s_add_i32 m0, vcc_lo, 0x3400
	v_mfma_f32_16x16x32_bf16 v[56:59], v[108:111], v[92:95], v[56:59]
	global_load_lds_dwordx4 v[116:117], off
	v_lshl_add_u64 v[116:117], v[116:117], 0, s[94:95]
	v_mfma_f32_16x16x32_bf16 v[60:63], v[112:115], v[80:83], v[60:63]
	s_add_i32 m0, vcc_lo, 0x3800
	v_mfma_f32_16x16x32_bf16 v[64:67], v[112:115], v[84:87], v[64:67]
	global_load_lds_dwordx4 v[118:119], off
	v_lshl_add_u64 v[118:119], v[118:119], 0, s[94:95]
	v_mfma_f32_16x16x32_bf16 v[72:75], v[112:115], v[88:91], v[72:75]
	s_add_i32 m0, vcc_lo, 0x3c00
	v_mfma_f32_16x16x32_bf16 v[76:79], v[112:115], v[92:95], v[76:79]
	global_load_lds_dwordx4 v[120:121], off
	v_lshl_add_u64 v[120:121], v[120:121], 0, s[94:95]
	s_waitcnt vmcnt(8)
	ds_read_b128 v[80:83], v130
	ds_read_b128 v[84:87], v130 offset:1024
	ds_read_b128 v[88:91], v130 offset:2048
	ds_read_b128 v[92:95], v130 offset:3072
	ds_read_b128 v[100:103], v130 offset:4096
	ds_read_b128 v[104:107], v130 offset:5120
	ds_read_b128 v[108:111], v130 offset:6144
	ds_read_b128 v[112:115], v130 offset:7168
	s_waitcnt lgkmcnt(0)
	v_mfma_f32_16x16x32_bf16 v[0:3], v[100:103], v[80:83], v[0:3]
	s_add_i32 m0, vcc_lo, 0x0
	v_mfma_f32_16x16x32_bf16 v[4:7], v[100:103], v[84:87], v[4:7]
	global_load_lds_dwordx4 v[14:15], off
	v_lshl_add_u64 v[14:15], v[14:15], 0, s[94:95]
	v_mfma_f32_16x16x32_bf16 v[8:11], v[100:103], v[88:91], v[8:11]
	s_add_i32 m0, vcc_lo, 0x400
	v_mfma_f32_16x16x32_bf16 v[16:19], v[100:103], v[92:95], v[16:19]
	global_load_lds_dwordx4 v[26:27], off
	v_lshl_add_u64 v[26:27], v[26:27], 0, s[94:95]
	v_mfma_f32_16x16x32_bf16 v[20:23], v[104:107], v[80:83], v[20:23]
	s_add_i32 m0, vcc_lo, 0x800
	v_mfma_f32_16x16x32_bf16 v[32:35], v[104:107], v[84:87], v[32:35]
	global_load_lds_dwordx4 v[30:31], off
	v_lshl_add_u64 v[30:31], v[30:31], 0, s[94:95]
	v_mfma_f32_16x16x32_bf16 v[36:39], v[104:107], v[88:91], v[36:39]
	s_add_i32 m0, vcc_lo, 0xc00
	v_mfma_f32_16x16x32_bf16 v[40:43], v[104:107], v[92:95], v[40:43]
	global_load_lds_dwordx4 v[70:71], off
	v_lshl_add_u64 v[70:71], v[70:71], 0, s[94:95]
	v_mfma_f32_16x16x32_bf16 v[44:47], v[108:111], v[80:83], v[44:47]
	s_add_i32 m0, vcc_lo, 0x1000
	v_mfma_f32_16x16x32_bf16 v[48:51], v[108:111], v[84:87], v[48:51]
	global_load_lds_dwordx4 v[98:99], off
	v_lshl_add_u64 v[98:99], v[98:99], 0, s[94:95]
	v_mfma_f32_16x16x32_bf16 v[52:55], v[108:111], v[88:91], v[52:55]
	s_add_i32 m0, vcc_lo, 0x1400
	v_mfma_f32_16x16x32_bf16 v[56:59], v[108:111], v[92:95], v[56:59]
	global_load_lds_dwordx4 v[116:117], off
	v_lshl_add_u64 v[116:117], v[116:117], 0, s[94:95]
	v_mfma_f32_16x16x32_bf16 v[60:63], v[112:115], v[80:83], v[60:63]
	s_add_i32 m0, vcc_lo, 0x1800
	v_mfma_f32_16x16x32_bf16 v[64:67], v[112:115], v[84:87], v[64:67]
	global_load_lds_dwordx4 v[118:119], off
	v_lshl_add_u64 v[118:119], v[118:119], 0, s[94:95]
	v_mfma_f32_16x16x32_bf16 v[72:75], v[112:115], v[88:91], v[72:75]
	s_add_i32 m0, vcc_lo, 0x1c00
	v_mfma_f32_16x16x32_bf16 v[76:79], v[112:115], v[92:95], v[76:79]
	global_load_lds_dwordx4 v[120:121], off
	v_lshl_add_u64 v[120:121], v[120:121], 0, s[94:95]
	s_waitcnt vmcnt(8)
	ds_read_b128 v[80:83], v130 offset:8192
	ds_read_b128 v[84:87], v130 offset:9216
	ds_read_b128 v[88:91], v130 offset:10240
	ds_read_b128 v[92:95], v130 offset:11264
	ds_read_b128 v[100:103], v130 offset:12288
	ds_read_b128 v[104:107], v130 offset:13312
	ds_read_b128 v[108:111], v130 offset:14336
	ds_read_b128 v[112:115], v130 offset:15360
	s_waitcnt lgkmcnt(0)
	v_mfma_f32_16x16x32_bf16 v[0:3], v[100:103], v[80:83], v[0:3]
	s_add_i32 m0, vcc_lo, 0x2000
	v_mfma_f32_16x16x32_bf16 v[4:7], v[100:103], v[84:87], v[4:7]
	global_load_lds_dwordx4 v[14:15], off
	v_lshl_add_u64 v[14:15], v[14:15], 0, s[94:95]
	v_mfma_f32_16x16x32_bf16 v[8:11], v[100:103], v[88:91], v[8:11]
	s_add_i32 m0, vcc_lo, 0x2400
	v_mfma_f32_16x16x32_bf16 v[16:19], v[100:103], v[92:95], v[16:19]
	global_load_lds_dwordx4 v[26:27], off
	v_lshl_add_u64 v[26:27], v[26:27], 0, s[94:95]
	v_mfma_f32_16x16x32_bf16 v[20:23], v[104:107], v[80:83], v[20:23]
	s_add_i32 m0, vcc_lo, 0x2800
	v_mfma_f32_16x16x32_bf16 v[32:35], v[104:107], v[84:87], v[32:35]
	global_load_lds_dwordx4 v[30:31], off
	v_lshl_add_u64 v[30:31], v[30:31], 0, s[94:95]
	v_mfma_f32_16x16x32_bf16 v[36:39], v[104:107], v[88:91], v[36:39]
	s_add_i32 m0, vcc_lo, 0x2c00
	v_mfma_f32_16x16x32_bf16 v[40:43], v[104:107], v[92:95], v[40:43]
	global_load_lds_dwordx4 v[70:71], off
	v_lshl_add_u64 v[70:71], v[70:71], 0, s[94:95]
	v_mfma_f32_16x16x32_bf16 v[44:47], v[108:111], v[80:83], v[44:47]
	s_add_i32 m0, vcc_lo, 0x3000
	v_mfma_f32_16x16x32_bf16 v[48:51], v[108:111], v[84:87], v[48:51]
	global_load_lds_dwordx4 v[98:99], off
	v_lshl_add_u64 v[98:99], v[98:99], 0, s[94:95]
	v_mfma_f32_16x16x32_bf16 v[52:55], v[108:111], v[88:91], v[52:55]
	s_add_i32 m0, vcc_lo, 0x3400
	v_mfma_f32_16x16x32_bf16 v[56:59], v[108:111], v[92:95], v[56:59]
	global_load_lds_dwordx4 v[116:117], off
	v_lshl_add_u64 v[116:117], v[116:117], 0, s[94:95]
	v_mfma_f32_16x16x32_bf16 v[60:63], v[112:115], v[80:83], v[60:63]
	s_add_i32 m0, vcc_lo, 0x3800
	v_mfma_f32_16x16x32_bf16 v[64:67], v[112:115], v[84:87], v[64:67]
	global_load_lds_dwordx4 v[118:119], off
	v_lshl_add_u64 v[118:119], v[118:119], 0, s[94:95]
	v_mfma_f32_16x16x32_bf16 v[72:75], v[112:115], v[88:91], v[72:75]
	s_add_i32 m0, vcc_lo, 0x3c00
	v_mfma_f32_16x16x32_bf16 v[76:79], v[112:115], v[92:95], v[76:79]
	global_load_lds_dwordx4 v[120:121], off
	v_lshl_add_u64 v[120:121], v[120:121], 0, s[94:95]
	s_waitcnt vmcnt(8)
	ds_read_b128 v[80:83], v130
	ds_read_b128 v[84:87], v130 offset:1024
	ds_read_b128 v[88:91], v130 offset:2048
	ds_read_b128 v[92:95], v130 offset:3072
	ds_read_b128 v[100:103], v130 offset:4096
	ds_read_b128 v[104:107], v130 offset:5120
	ds_read_b128 v[108:111], v130 offset:6144
	ds_read_b128 v[112:115], v130 offset:7168
	s_waitcnt lgkmcnt(0)
	v_mfma_f32_16x16x32_bf16 v[0:3], v[100:103], v[80:83], v[0:3]
	v_mfma_f32_16x16x32_bf16 v[4:7], v[100:103], v[84:87], v[4:7]
	v_mfma_f32_16x16x32_bf16 v[8:11], v[100:103], v[88:91], v[8:11]
	v_mfma_f32_16x16x32_bf16 v[16:19], v[100:103], v[92:95], v[16:19]
	v_mfma_f32_16x16x32_bf16 v[20:23], v[104:107], v[80:83], v[20:23]
	v_mfma_f32_16x16x32_bf16 v[32:35], v[104:107], v[84:87], v[32:35]
	v_mfma_f32_16x16x32_bf16 v[36:39], v[104:107], v[88:91], v[36:39]
	v_mfma_f32_16x16x32_bf16 v[40:43], v[104:107], v[92:95], v[40:43]
	v_mfma_f32_16x16x32_bf16 v[44:47], v[108:111], v[80:83], v[44:47]
	v_mfma_f32_16x16x32_bf16 v[48:51], v[108:111], v[84:87], v[48:51]
	v_mfma_f32_16x16x32_bf16 v[52:55], v[108:111], v[88:91], v[52:55]
	v_mfma_f32_16x16x32_bf16 v[56:59], v[108:111], v[92:95], v[56:59]
	v_mfma_f32_16x16x32_bf16 v[60:63], v[112:115], v[80:83], v[60:63]
	v_mfma_f32_16x16x32_bf16 v[64:67], v[112:115], v[84:87], v[64:67]
	v_mfma_f32_16x16x32_bf16 v[72:75], v[112:115], v[88:91], v[72:75]
	v_mfma_f32_16x16x32_bf16 v[76:79], v[112:115], v[92:95], v[76:79]
	s_waitcnt vmcnt(0)
	ds_read_b128 v[80:83], v130 offset:8192
	ds_read_b128 v[84:87], v130 offset:9216
	ds_read_b128 v[88:91], v130 offset:10240
	ds_read_b128 v[92:95], v130 offset:11264
	ds_read_b128 v[100:103], v130 offset:12288
	ds_read_b128 v[104:107], v130 offset:13312
	ds_read_b128 v[108:111], v130 offset:14336
	ds_read_b128 v[112:115], v130 offset:15360
	s_waitcnt lgkmcnt(0)
	v_mfma_f32_16x16x32_bf16 v[0:3], v[100:103], v[80:83], v[0:3]
	v_mfma_f32_16x16x32_bf16 v[4:7], v[100:103], v[84:87], v[4:7]
	v_mfma_f32_16x16x32_bf16 v[8:11], v[100:103], v[88:91], v[8:11]
	v_mfma_f32_16x16x32_bf16 v[16:19], v[100:103], v[92:95], v[16:19]
	v_mfma_f32_16x16x32_bf16 v[20:23], v[104:107], v[80:83], v[20:23]
	v_mfma_f32_16x16x32_bf16 v[32:35], v[104:107], v[84:87], v[32:35]
	v_mfma_f32_16x16x32_bf16 v[36:39], v[104:107], v[88:91], v[36:39]
	v_mfma_f32_16x16x32_bf16 v[40:43], v[104:107], v[92:95], v[40:43]
	v_mfma_f32_16x16x32_bf16 v[44:47], v[108:111], v[80:83], v[44:47]
	v_mfma_f32_16x16x32_bf16 v[48:51], v[108:111], v[84:87], v[48:51]
	v_mfma_f32_16x16x32_bf16 v[52:55], v[108:111], v[88:91], v[52:55]
	v_mfma_f32_16x16x32_bf16 v[56:59], v[108:111], v[92:95], v[56:59]
	v_mfma_f32_16x16x32_bf16 v[60:63], v[112:115], v[80:83], v[60:63]
	v_mfma_f32_16x16x32_bf16 v[64:67], v[112:115], v[84:87], v[64:67]
	v_mfma_f32_16x16x32_bf16 v[72:75], v[112:115], v[88:91], v[72:75]
	v_mfma_f32_16x16x32_bf16 v[76:79], v[112:115], v[92:95], v[76:79]
	s_nop 7
	s_nop 3
	v_and_b32_e32 v68, 63, v96
	v_lshl_add_u32 v68, v68, 4, 0
	v_lshl_add_u32 v69, s3, 14, v68
	ds_write_b128 v69, v[0:3]
	ds_write_b128 v69, v[4:7] offset:1024
	ds_write_b128 v69, v[8:11] offset:2048
	ds_write_b128 v69, v[16:19] offset:3072
	ds_write_b128 v69, v[20:23] offset:4096
	ds_write_b128 v69, v[32:35] offset:5120
	ds_write_b128 v69, v[36:39] offset:6144
	ds_write_b128 v69, v[40:43] offset:7168
	ds_write_b128 v69, v[44:47] offset:8192
	ds_write_b128 v69, v[48:51] offset:9216
	ds_write_b128 v69, v[52:55] offset:10240
	ds_write_b128 v69, v[56:59] offset:11264
	ds_write_b128 v69, v[60:63] offset:12288
	ds_write_b128 v69, v[64:67] offset:13312
	ds_write_b128 v69, v[72:75] offset:14336
	ds_write_b128 v69, v[76:79] offset:15360
	s_lshl_b32 s3, s1, 4
	s_addk_i32 s3, 0x4000
	s_waitcnt vmcnt(0) lgkmcnt(0)
	s_nop 2
	s_nop 2
	s_nop 5
	s_nop 5
	s_nop 5
	s_nop 2
	v_or_b32_e32 v12, s3, v97
	v_ashrrev_i32_e32 v13, 31, v12
	s_nop 2
	v_lshrrev_b32_e32 v0, 2, v96
	v_and_b32_e32 v0, 12, v0
	v_lshl_or_b32 v0, s4, 4, v0
	v_or_b32_e32 v26, s0, v0
	v_lshlrev_b64 v[0:1], 12, v[12:13]
	s_ashr_i32 s3, s2, 31
	v_lshl_add_u64 v[0:1], s[8:9], 0, v[0:1]
	v_lshl_add_u64 v[0:1], s[2:3], 1, v[0:1]
	v_lshlrev_b32_e32 v128, 1, v26
	v_lshl_add_u64 v[0:1], v[0:1], 0, v[128:129]
	s_waitcnt lgkmcnt(0)
	s_barrier
	global_load_dwordx2 v[14:15], v[0:1], off
	global_load_dwordx2 v[16:17], v[0:1], off offset:256
	s_lshl_b32 s0, s4, 2
	s_add_i32 s0, s0, s1
	v_lshl_add_u32 v13, s0, 10, v68
	ds_read_b128 v[0:3], v13
	ds_read_b128 v[4:7], v13 offset:8192
	ds_read_b128 v[8:11], v13 offset:16384
	v_lshlrev_b32_e32 v128, 2, v26
	s_waitcnt lgkmcnt(0)
	v_pk_add_f32 v[18:19], v[2:3], 0 op_sel_hi:[1,0]
	v_pk_add_f32 v[20:21], v[0:1], 0 op_sel_hi:[1,0]
	ds_read_b128 v[0:3], v13 offset:24576
	v_pk_add_f32 v[18:19], v[18:19], v[10:11]
	v_pk_add_f32 v[20:21], v[20:21], v[8:9]
	ds_read_b128 v[8:11], v13 offset:40960
	v_pk_add_f32 v[22:23], v[6:7], 0 op_sel_hi:[1,0]
	v_pk_add_f32 v[24:25], v[4:5], 0 op_sel_hi:[1,0]
	ds_read_b128 v[4:7], v13 offset:32768
	s_waitcnt lgkmcnt(0)
	v_pk_add_f32 v[22:23], v[22:23], v[2:3]
	v_pk_add_f32 v[24:25], v[24:25], v[0:1]
	ds_read_b128 v[0:3], v13 offset:49152
	v_pk_add_f32 v[24:25], v[24:25], v[8:9]
	v_add_u32_e32 v8, 0x12000, v13
	v_pk_add_f32 v[22:23], v[22:23], v[10:11]
	ds_read_b128 v[8:11], v8
	v_pk_add_f32 v[18:19], v[18:19], v[6:7]
	v_pk_add_f32 v[20:21], v[20:21], v[4:5]
	ds_read_b128 v[4:7], v13 offset:57344
	s_waitcnt lgkmcnt(0)
	v_pk_add_f32 v[20:21], v[20:21], v[0:1]
	v_add_u32_e32 v0, 0x10000, v13
	v_pk_add_f32 v[18:19], v[18:19], v[2:3]
	ds_read_b128 v[0:3], v0
	v_pk_add_f32 v[4:5], v[24:25], v[4:5]
	v_pk_add_f32 v[6:7], v[22:23], v[6:7]
	v_pk_add_f32 v[24:25], v[4:5], v[8:9]
	v_add_u32_e32 v4, 0x16000, v13
	v_pk_add_f32 v[22:23], v[6:7], v[10:11]
	ds_read_b128 v[4:7], v4
	s_waitcnt lgkmcnt(0)
	v_pk_add_f32 v[20:21], v[20:21], v[0:1]
	v_add_u32_e32 v0, 0x14000, v13
	v_pk_add_f32 v[18:19], v[18:19], v[2:3]
	ds_read_b128 v[0:3], v0
	v_add_u32_e32 v8, 0x18000, v13
	ds_read_b128 v[8:11], v8
	v_pk_add_f32 v[24:25], v[24:25], v[4:5]
	v_add_u32_e32 v4, 0x1c000, v13
	v_pk_add_f32 v[22:23], v[22:23], v[6:7]
	ds_read_b128 v[4:7], v4
	s_waitcnt lgkmcnt(0)
	v_pk_add_f32 v[20:21], v[20:21], v[0:1]
	v_add_u32_e32 v0, 0x1a000, v13
	v_pk_add_f32 v[18:19], v[18:19], v[2:3]
	ds_read_b128 v[0:3], v0
	v_pk_add_f32 v[20:21], v[20:21], v[8:9]
	v_add_u32_e32 v8, 0x1e000, v13
	v_pk_add_f32 v[18:19], v[18:19], v[10:11]
	ds_read_b128 v[8:11], v8
	s_waitcnt lgkmcnt(0)
	v_pk_add_f32 v[0:1], v[24:25], v[0:1]
	v_pk_add_f32 v[4:5], v[20:21], v[4:5]
	v_pk_add_f32 v[2:3], v[22:23], v[2:3]
	v_pk_add_f32 v[6:7], v[18:19], v[6:7]
	v_pk_add_f32 v[8:9], v[0:1], v[8:9]
	v_pk_add_f32 v[10:11], v[2:3], v[10:11]
	s_waitcnt vmcnt(0)
	v_lshlrev_b32_e32 v0, 16, v14
	v_and_b32_e32 v1, 0xffff0000, v14
	v_pk_add_f32 v[0:1], v[4:5], v[0:1]
	v_lshlrev_b32_e32 v4, 16, v16
	v_and_b32_e32 v5, 0xffff0000, v16
	v_pk_add_f32 v[4:5], v[8:9], v[4:5]
	v_mul_hi_i32 v8, v12, s97
	v_lshlrev_b32_e32 v2, 16, v15
	v_and_b32_e32 v3, 0xffff0000, v15
	v_lshrrev_b32_e32 v9, 31, v8
	v_ashrrev_i32_e32 v8, 11, v8
	v_pk_add_f32 v[2:3], v[6:7], v[2:3]
	v_lshlrev_b32_e32 v6, 16, v17
	v_and_b32_e32 v7, 0xffff0000, v17
	v_add_u32_e32 v8, v8, v9
	v_pk_add_f32 v[6:7], v[10:11], v[6:7]
	v_mul_i32_i24_e32 v10, 0xffffeff0, v8
	v_ashrrev_i32_e32 v9, 31, v8
	v_add3_u32 v10, v12, v10, -16
	v_ashrrev_i32_e32 v11, 31, v10
	v_lshlrev_b64 v[8:9], 25, v[8:9]
	v_lshl_add_u64 v[8:9], s[6:7], 0, v[8:9]
	v_lshlrev_b64 v[10:11], 13, v[10:11]
	v_lshl_add_u64 v[8:9], v[8:9], 0, v[10:11]
	v_lshl_add_u64 v[8:9], s[2:3], 2, v[8:9]
	v_lshl_add_u64 v[8:9], v[8:9], 0, v[128:129]
	global_store_dwordx4 v[8:9], v[0:3], off
	global_store_dwordx4 v[8:9], v[4:7], off offset:512
	s_waitcnt lgkmcnt(0)
	s_barrier
